# comb7 + epilogue row reductions: ds_bpermute xor-16/32 round trips replaced by v_permlane16/32_swap (154 sites), dead bpermutes in the mix-in rstd block removed
# speedup vs baseline: 1.0035x; 1.0001x over previous
; __device__ __forceinline__ unsigned cvt_pk_bf16(float lo, float hi) { unsigned r; asm volatile("v_cvt_pk_bf16_f32 %0, %1, %2" : "=v"(r) : "v"(lo), "v"(hi)); return r; }
; __global__ void __launch_bounds__(NTHR, 2) fwd_megakernel(Args args) {
;     ...
;             for (int r = 0; r < 4; ++r) { const int m = m0 + r * NGW; if (m < T) { u32x2* o = (u32x2*)(XB + (size_t)m * D) + lane; float s = 0.f;
; #pragma unroll
;                 for (int j = 0; j < 8; ++j) { const f32x4 v = xv[r][j]; s += (v[0] * v[0] + v[1] * v[1]) + (v[2] * v[2] + v[3] * v[3]); u32x2 w; w.x = cvt_pk_bf16(v[0], v[1]); w.y = cvt_pk_bf16(v[2], v[3]); o[64 * j] = w; }
;                 s += __shfl_xor(s, 32); if (lane < 32) PART[(size_t)m * NPART + lane] = s; } }
.LBB0_151:
	v_lshl_add_u64 v[142:143], s[14:15], 0, v[136:137]
	s_waitcnt vmcnt(7)
	v_mul_f32_e32 v144, v125, v125
	v_mul_f32_e32 v145, v127, v127
	v_fmac_f32_e32 v144, v124, v124
	v_fmac_f32_e32 v145, v126, v126
	v_cvt_pk_bf16_f32 v124, v124, v125
	v_cvt_pk_bf16_f32 v125, v126, v127
	v_add_co_u32_e32 v126, vcc, s43, v142
	v_add_f32_e32 v144, v144, v145
	s_nop 0
	v_addc_co_u32_e32 v127, vcc, 0, v143, vcc
	global_store_dwordx2 v[126:127], v[124:125], off
	s_waitcnt vmcnt(7)
	v_mul_f32_e32 v124, v121, v121
	v_fmac_f32_e32 v124, v120, v120
	v_cvt_pk_bf16_f32 v120, v120, v121
	v_cvt_pk_bf16_f32 v121, v122, v123
	global_store_dwordx2 v[126:127], v[120:121], off offset:512
	s_waitcnt vmcnt(7)
	v_mul_f32_e32 v120, v117, v117
	v_fmac_f32_e32 v120, v116, v116
	v_cvt_pk_bf16_f32 v116, v116, v117
	v_cvt_pk_bf16_f32 v117, v118, v119
	global_store_dwordx2 v[126:127], v[116:117], off offset:1024
	s_waitcnt vmcnt(7)
	v_mul_f32_e32 v116, v113, v113
	v_mul_f32_e32 v125, v123, v123
	v_fmac_f32_e32 v116, v112, v112
	v_cvt_pk_bf16_f32 v112, v112, v113
	v_fmac_f32_e32 v125, v122, v122
	v_mul_f32_e32 v121, v119, v119
	v_cvt_pk_bf16_f32 v113, v114, v115
	global_store_dwordx2 v[126:127], v[112:113], off offset:1536
	s_waitcnt vmcnt(7)
	v_mul_f32_e32 v112, v109, v109
	v_add_f32_e32 v124, v124, v125
	v_fmac_f32_e32 v121, v118, v118
	v_mul_f32_e32 v117, v115, v115
	v_fmac_f32_e32 v112, v108, v108
	v_cvt_pk_bf16_f32 v108, v108, v109
	v_add_f32_e32 v124, v144, v124
	v_add_f32_e32 v120, v120, v121
	v_fmac_f32_e32 v117, v114, v114
	v_mul_f32_e32 v113, v111, v111
	v_cvt_pk_bf16_f32 v109, v110, v111
	global_store_dwordx2 v[126:127], v[108:109], off offset:2048
	s_waitcnt vmcnt(7)
	v_mul_f32_e32 v108, v105, v105
	v_add_f32_e32 v120, v124, v120
	v_add_f32_e32 v116, v116, v117
	v_fmac_f32_e32 v113, v110, v110
	v_fmac_f32_e32 v108, v104, v104
	v_mul_f32_e32 v109, v107, v107
	v_cvt_pk_bf16_f32 v104, v104, v105
	v_cvt_pk_bf16_f32 v105, v106, v107
	v_add_f32_e32 v116, v120, v116
	v_add_f32_e32 v112, v112, v113
	v_fmac_f32_e32 v109, v106, v106
	global_store_dwordx2 v[126:127], v[104:105], off offset:2560
	s_waitcnt vmcnt(7)
	v_mul_f32_e32 v104, v101, v101
	v_mul_f32_e32 v105, v103, v103
	v_add_f32_e32 v112, v116, v112
	v_add_f32_e32 v108, v108, v109
	v_fmac_f32_e32 v104, v100, v100
	v_fmac_f32_e32 v105, v102, v102
	v_add_f32_e32 v108, v112, v108
	v_add_f32_e32 v104, v104, v105
	v_add_f32_e32 v106, v108, v104
	v_cvt_pk_bf16_f32 v104, v100, v101
	s_waitcnt vmcnt(6)
	v_mul_f32_e32 v100, v97, v97
	v_mul_f32_e32 v101, v99, v99
	v_fmac_f32_e32 v100, v96, v96
	v_fmac_f32_e32 v101, v98, v98
	v_cvt_pk_bf16_f32 v105, v102, v103
	v_add_f32_e32 v100, v100, v101
	v_and_b32_e32 v102, 64, v129
	v_add_f32_e32 v101, v106, v100
	v_xor_b32_e32 v100, 32, v129
	v_add_u32_e32 v102, 64, v102
	v_cmp_lt_i32_e32 vcc, v100, v102
	global_store_dwordx2 v[126:127], v[104:105], off offset:3072
	v_cvt_pk_bf16_f32 v96, v96, v97
	v_cvt_pk_bf16_f32 v97, v98, v99
	global_store_dwordx2 v[126:127], v[96:97], off offset:3584
	v_cndmask_b32_e32 v100, v129, v100, vcc
	v_lshlrev_b32_e32 v100, 2, v100
	v_mov_b32_e32 v102, v101
	s_nop 1
	v_permlane32_swap_b32_e32 v101, v102
	s_nop 1
	s_and_saveexec_b64 s[40:41], s[2:3]
	s_cbranch_execz .LBB0_157
	v_lshl_add_u64 v[96:97], s[14:15], 0, v[138:139]
	s_waitcnt lgkmcnt(0)
	v_add_f32_e32 v98, v101, v102
	global_store_dword v[96:97], v98, off
	s_or_b64 exec, exec, s[40:41]
	s_andn2_b64 vcc, exec, s[38:39]
	s_cbranch_vccz .LBB0_158

; __device__ __forceinline__ unsigned cvt_pk_bf16(float lo, float hi) { unsigned r; asm volatile("v_cvt_pk_bf16_f32 %0, %1, %2" : "=v"(r) : "v"(lo), "v"(hi)); return r; }
; __global__ void __launch_bounds__(NTHR, 2) fwd_megakernel(Args args) {
;     ...
;             for (int r = 0; r < 4; ++r) { const int m = m0 + r * NGW; if (m < T) { u32x2* o = (u32x2*)(XB + (size_t)m * D) + lane; float s = 0.f;
; #pragma unroll
;                 for (int j = 0; j < 8; ++j) { const f32x4 v = xv[r][j]; s += (v[0] * v[0] + v[1] * v[1]) + (v[2] * v[2] + v[3] * v[3]); u32x2 w; w.x = cvt_pk_bf16(v[0], v[1]); w.y = cvt_pk_bf16(v[2], v[3]); o[64 * j] = w; }
;                 s += __shfl_xor(s, 32); if (lane < 32) PART[(size_t)m * NPART + lane] = s; } }
.LBB0_154:
	s_ashr_i32 s27, s26, 31
	v_mul_f32_e32 v96, v17, v17
	s_waitcnt lgkmcnt(0)
	v_mul_f32_e32 v97, v19, v19
	s_lshl_b64 s[30:31], s[26:27], 12
	v_fmac_f32_e32 v96, v16, v16
	v_fmac_f32_e32 v97, v18, v18
	v_lshl_add_u64 v[98:99], v[132:133], 0, s[30:31]
	v_add_f32_e32 v101, v96, v97
	v_cvt_pk_bf16_f32 v96, v16, v17
	v_cvt_pk_bf16_f32 v97, v18, v19
	global_store_dwordx2 v[98:99], v[96:97], off
	v_mul_f32_e32 v96, v21, v21
	v_mul_f32_e32 v97, v23, v23
	v_fmac_f32_e32 v96, v20, v20
	v_fmac_f32_e32 v97, v22, v22
	v_add_f32_e32 v96, v96, v97
	v_add_f32_e32 v101, v101, v96
	v_cvt_pk_bf16_f32 v96, v20, v21
	v_cvt_pk_bf16_f32 v97, v22, v23
	global_store_dwordx2 v[98:99], v[96:97], off offset:512
	v_mul_f32_e32 v96, v25, v25
	v_mul_f32_e32 v97, v27, v27
	v_fmac_f32_e32 v96, v24, v24
	v_fmac_f32_e32 v97, v26, v26
	v_add_f32_e32 v96, v96, v97
	v_add_f32_e32 v101, v101, v96
	v_cvt_pk_bf16_f32 v96, v24, v25
	v_cvt_pk_bf16_f32 v97, v26, v27
	global_store_dwordx2 v[98:99], v[96:97], off offset:1024
	v_mul_f32_e32 v96, v33, v33
	v_mul_f32_e32 v97, v35, v35
	v_fmac_f32_e32 v96, v32, v32
	v_fmac_f32_e32 v97, v34, v34
	v_add_f32_e32 v96, v96, v97
	v_add_f32_e32 v101, v101, v96
	v_cvt_pk_bf16_f32 v96, v32, v33
	v_cvt_pk_bf16_f32 v97, v34, v35
	global_store_dwordx2 v[98:99], v[96:97], off offset:1536
	v_mul_f32_e32 v96, v61, v61
	v_mul_f32_e32 v97, v63, v63
	v_fmac_f32_e32 v96, v60, v60
	v_fmac_f32_e32 v97, v62, v62
	v_add_f32_e32 v96, v96, v97
	v_add_f32_e32 v101, v101, v96
	v_cvt_pk_bf16_f32 v96, v60, v61
	v_cvt_pk_bf16_f32 v97, v62, v63
	global_store_dwordx2 v[98:99], v[96:97], off offset:2048
	v_mul_f32_e32 v96, v69, v69
	v_mul_f32_e32 v97, v71, v71
	v_fmac_f32_e32 v96, v68, v68
	v_fmac_f32_e32 v97, v70, v70
	v_add_f32_e32 v96, v96, v97
	v_add_f32_e32 v101, v101, v96
	v_cvt_pk_bf16_f32 v96, v68, v69
	v_cvt_pk_bf16_f32 v97, v70, v71
	global_store_dwordx2 v[98:99], v[96:97], off offset:2560
	v_mul_f32_e32 v96, v73, v73
	v_mul_f32_e32 v97, v75, v75
	v_fmac_f32_e32 v96, v72, v72
	v_fmac_f32_e32 v97, v74, v74
	v_add_f32_e32 v96, v96, v97
	v_add_f32_e32 v96, v101, v96
	v_mul_f32_e32 v97, v77, v77
	v_mul_f32_e32 v101, v79, v79
	v_fmac_f32_e32 v97, v76, v76
	v_fmac_f32_e32 v101, v78, v78
	v_add_f32_e32 v97, v97, v101
	v_add_f32_e32 v96, v96, v97
	v_mov_b32_e32 v97, v96
	s_nop 1
	v_permlane32_swap_b32_e32 v96, v97
	s_nop 1
	v_cvt_pk_bf16_f32 v102, v72, v73
	v_cvt_pk_bf16_f32 v103, v74, v75
	global_store_dwordx2 v[98:99], v[102:103], off offset:3072
	v_cvt_pk_bf16_f32 v102, v76, v77
	v_cvt_pk_bf16_f32 v103, v78, v79
	global_store_dwordx2 v[98:99], v[102:103], off offset:3584
	s_and_saveexec_b64 s[30:31], s[2:3]
	s_cbranch_execz .LBB0_156
	s_lshl_b64 s[26:27], s[26:27], 7
	v_lshl_add_u64 v[98:99], v[134:135], 0, s[26:27]
	s_waitcnt lgkmcnt(0)
	v_add_f32_e32 v96, v96, v97
	global_store_dword v[98:99], v96, off

; __device__ __forceinline__ unsigned cvt_pk_bf16(float lo, float hi) { unsigned r; asm volatile("v_cvt_pk_bf16_f32 %0, %1, %2" : "=v"(r) : "v"(lo), "v"(hi)); return r; }
; __global__ void __launch_bounds__(NTHR, 2) fwd_megakernel(Args args) {
;     ...
;             for (int r = 0; r < 4; ++r) { const int m = m0 + r * NGW; if (m < T) { u32x2* o = (u32x2*)(XB + (size_t)m * D) + lane; float s = 0.f;
; #pragma unroll
;                 for (int j = 0; j < 8; ++j) { const f32x4 v = xv[r][j]; s += (v[0] * v[0] + v[1] * v[1]) + (v[2] * v[2] + v[3] * v[3]); u32x2 w; w.x = cvt_pk_bf16(v[0], v[1]); w.y = cvt_pk_bf16(v[2], v[3]); o[64 * j] = w; }
;                 s += __shfl_xor(s, 32); if (lane < 32) PART[(size_t)m * NPART + lane] = s; } }
.LBB0_158:
	s_ashr_i32 s31, s30, 31
	v_mul_f32_e32 v96, v1, v1
	v_mul_f32_e32 v97, v3, v3
	s_lshl_b64 s[38:39], s[30:31], 12
	v_fmac_f32_e32 v96, v0, v0
	v_fmac_f32_e32 v97, v2, v2
	v_lshl_add_u64 v[98:99], v[132:133], 0, s[38:39]
	v_add_f32_e32 v101, v96, v97
	v_cvt_pk_bf16_f32 v96, v0, v1
	v_cvt_pk_bf16_f32 v97, v2, v3
	global_store_dwordx2 v[98:99], v[96:97], off
	v_mul_f32_e32 v96, v5, v5
	v_mul_f32_e32 v97, v7, v7
	v_fmac_f32_e32 v96, v4, v4
	v_fmac_f32_e32 v97, v6, v6
	v_add_f32_e32 v96, v96, v97
	v_add_f32_e32 v101, v101, v96
	v_cvt_pk_bf16_f32 v96, v4, v5
	v_cvt_pk_bf16_f32 v97, v6, v7
	global_store_dwordx2 v[98:99], v[96:97], off offset:512
	v_mul_f32_e32 v96, v9, v9
	v_mul_f32_e32 v97, v11, v11
	v_fmac_f32_e32 v96, v8, v8
	v_fmac_f32_e32 v97, v10, v10
	v_add_f32_e32 v96, v96, v97
	v_add_f32_e32 v101, v101, v96
	v_cvt_pk_bf16_f32 v96, v8, v9
	v_cvt_pk_bf16_f32 v97, v10, v11
	global_store_dwordx2 v[98:99], v[96:97], off offset:1024
	v_mul_f32_e32 v96, v13, v13
	v_mul_f32_e32 v97, v15, v15
	v_fmac_f32_e32 v96, v12, v12
	v_fmac_f32_e32 v97, v14, v14
	v_add_f32_e32 v96, v96, v97
	v_add_f32_e32 v101, v101, v96
	v_cvt_pk_bf16_f32 v96, v12, v13
	v_cvt_pk_bf16_f32 v97, v14, v15
	global_store_dwordx2 v[98:99], v[96:97], off offset:1536
	v_mul_f32_e32 v96, v29, v29
	v_mul_f32_e32 v97, v31, v31
	v_fmac_f32_e32 v96, v28, v28
	v_fmac_f32_e32 v97, v30, v30
	v_add_f32_e32 v96, v96, v97
	v_add_f32_e32 v101, v101, v96
	v_cvt_pk_bf16_f32 v96, v28, v29
	v_cvt_pk_bf16_f32 v97, v30, v31
	global_store_dwordx2 v[98:99], v[96:97], off offset:2048
	v_mul_f32_e32 v96, v37, v37
	v_mul_f32_e32 v97, v39, v39
	v_fmac_f32_e32 v96, v36, v36
	v_fmac_f32_e32 v97, v38, v38
	v_add_f32_e32 v96, v96, v97
	v_add_f32_e32 v101, v101, v96
	v_cvt_pk_bf16_f32 v96, v36, v37
	v_cvt_pk_bf16_f32 v97, v38, v39
	global_store_dwordx2 v[98:99], v[96:97], off offset:2560
	v_mul_f32_e32 v96, v45, v45
	v_mul_f32_e32 v97, v47, v47
	v_fmac_f32_e32 v96, v44, v44
	v_fmac_f32_e32 v97, v46, v46
	v_add_f32_e32 v96, v96, v97
	v_add_f32_e32 v96, v101, v96
	v_mul_f32_e32 v97, v53, v53
	v_mul_f32_e32 v101, v55, v55
	v_fmac_f32_e32 v97, v52, v52
	v_fmac_f32_e32 v101, v54, v54
	v_add_f32_e32 v97, v97, v101
	v_add_f32_e32 v96, v96, v97
	v_mov_b32_e32 v97, v96
	s_nop 1
	v_permlane32_swap_b32_e32 v96, v97
	s_nop 1
	s_waitcnt lgkmcnt(1)
	v_cvt_pk_bf16_f32 v102, v44, v45
	v_cvt_pk_bf16_f32 v103, v46, v47
	global_store_dwordx2 v[98:99], v[102:103], off offset:3072
	v_cvt_pk_bf16_f32 v102, v52, v53
	v_cvt_pk_bf16_f32 v103, v54, v55
	global_store_dwordx2 v[98:99], v[102:103], off offset:3584
	s_and_saveexec_b64 s[38:39], s[2:3]
	s_cbranch_execz .LBB0_160
	s_lshl_b64 s[30:31], s[30:31], 7
	v_lshl_add_u64 v[98:99], v[134:135], 0, s[30:31]
	s_waitcnt lgkmcnt(0)
	v_add_f32_e32 v96, v96, v97
	global_store_dword v[98:99], v96, off

; __device__ __forceinline__ unsigned cvt_pk_bf16(float lo, float hi) { unsigned r; asm volatile("v_cvt_pk_bf16_f32 %0, %1, %2" : "=v"(r) : "v"(lo), "v"(hi)); return r; }
; __global__ void __launch_bounds__(NTHR, 2) fwd_megakernel(Args args) {
;     ...
;             for (int r = 0; r < 4; ++r) { const int m = m0 + r * NGW; if (m < T) { u32x2* o = (u32x2*)(XB + (size_t)m * D) + lane; float s = 0.f;
; #pragma unroll
;                 for (int j = 0; j < 8; ++j) { const f32x4 v = xv[r][j]; s += (v[0] * v[0] + v[1] * v[1]) + (v[2] * v[2] + v[3] * v[3]); u32x2 w; w.x = cvt_pk_bf16(v[0], v[1]); w.y = cvt_pk_bf16(v[2], v[3]); o[64 * j] = w; }
;                 s += __shfl_xor(s, 32); if (lane < 32) PART[(size_t)m * NPART + lane] = s; } }
.LBB0_162:
	s_ashr_i32 s25, s24, 31
	v_mul_f32_e32 v96, v41, v41
	s_waitcnt lgkmcnt(0)
	v_mul_f32_e32 v97, v43, v43
	s_lshl_b64 s[26:27], s[24:25], 12
	v_fmac_f32_e32 v96, v40, v40
	v_fmac_f32_e32 v97, v42, v42
	v_lshl_add_u64 v[98:99], v[132:133], 0, s[26:27]
	v_add_f32_e32 v101, v96, v97
	v_cvt_pk_bf16_f32 v96, v40, v41
	v_cvt_pk_bf16_f32 v97, v42, v43
	global_store_dwordx2 v[98:99], v[96:97], off
	v_mul_f32_e32 v96, v49, v49
	v_mul_f32_e32 v97, v51, v51
	v_fmac_f32_e32 v96, v48, v48
	v_fmac_f32_e32 v97, v50, v50
	v_add_f32_e32 v96, v96, v97
	v_add_f32_e32 v101, v101, v96
	v_cvt_pk_bf16_f32 v96, v48, v49
	v_cvt_pk_bf16_f32 v97, v50, v51
	global_store_dwordx2 v[98:99], v[96:97], off offset:512
	v_mul_f32_e32 v96, v57, v57
	v_mul_f32_e32 v97, v59, v59
	v_fmac_f32_e32 v96, v56, v56
	v_fmac_f32_e32 v97, v58, v58
	v_add_f32_e32 v96, v96, v97
	v_add_f32_e32 v101, v101, v96
	v_cvt_pk_bf16_f32 v96, v56, v57
	v_cvt_pk_bf16_f32 v97, v58, v59
	global_store_dwordx2 v[98:99], v[96:97], off offset:1024
	v_mul_f32_e32 v96, v65, v65
	v_mul_f32_e32 v97, v67, v67
	v_fmac_f32_e32 v96, v64, v64
	v_fmac_f32_e32 v97, v66, v66
	v_add_f32_e32 v96, v96, v97
	v_add_f32_e32 v101, v101, v96
	v_cvt_pk_bf16_f32 v96, v64, v65
	v_cvt_pk_bf16_f32 v97, v66, v67
	global_store_dwordx2 v[98:99], v[96:97], off offset:1536
	v_mul_f32_e32 v96, v81, v81
	v_mul_f32_e32 v97, v83, v83
	v_fmac_f32_e32 v96, v80, v80
	v_fmac_f32_e32 v97, v82, v82
	v_add_f32_e32 v96, v96, v97
	v_add_f32_e32 v101, v101, v96
	v_cvt_pk_bf16_f32 v96, v80, v81
	v_cvt_pk_bf16_f32 v97, v82, v83
	global_store_dwordx2 v[98:99], v[96:97], off offset:2048
	v_mul_f32_e32 v96, v85, v85
	v_mul_f32_e32 v97, v87, v87
	v_fmac_f32_e32 v96, v84, v84
	v_fmac_f32_e32 v97, v86, v86
	v_add_f32_e32 v96, v96, v97
	v_add_f32_e32 v101, v101, v96
	v_cvt_pk_bf16_f32 v96, v84, v85
	v_cvt_pk_bf16_f32 v97, v86, v87
	global_store_dwordx2 v[98:99], v[96:97], off offset:2560
	v_mul_f32_e32 v96, v89, v89
	v_mul_f32_e32 v97, v91, v91
	v_fmac_f32_e32 v96, v88, v88
	v_fmac_f32_e32 v97, v90, v90
	v_add_f32_e32 v96, v96, v97
	v_add_f32_e32 v96, v101, v96
	v_mul_f32_e32 v97, v93, v93
	v_mul_f32_e32 v101, v95, v95
	v_fmac_f32_e32 v97, v92, v92
	v_fmac_f32_e32 v101, v94, v94
	v_add_f32_e32 v97, v97, v101
	v_add_f32_e32 v96, v96, v97
	v_mov_b32_e32 v97, v96
	s_nop 1
	v_permlane32_swap_b32_e32 v96, v97
	s_nop 1
	v_cvt_pk_bf16_f32 v102, v88, v89
	v_cvt_pk_bf16_f32 v103, v90, v91
	global_store_dwordx2 v[98:99], v[102:103], off offset:3072
	v_cvt_pk_bf16_f32 v100, v92, v93
	v_cvt_pk_bf16_f32 v101, v94, v95
	global_store_dwordx2 v[98:99], v[100:101], off offset:3584
	s_and_saveexec_b64 s[26:27], s[2:3]
	s_cbranch_execz .LBB0_143
	s_lshl_b64 s[24:25], s[24:25], 7
	v_lshl_add_u64 v[98:99], v[134:135], 0, s[24:25]
	s_waitcnt lgkmcnt(0)
	v_add_f32_e32 v96, v96, v97
	global_store_dword v[98:99], v96, off
	s_branch .LBB0_143

; __device__ __forceinline__ unsigned cvt_pk_bf16(float lo, float hi) { unsigned r; asm volatile("v_cvt_pk_bf16_f32 %0, %1, %2" : "=v"(r) : "v"(lo), "v"(hi)); return r; }
; #define KIN(i) (*(const float* const __attribute__((address_space(4)))*)(kp + kz + 8 * (i)))
; __device__ __forceinline__ float wave_sum(float v) {
; #pragma unroll
;     for (int o = 1; o < 64; o <<= 1) v += __shfl_xor(v, o);
;     return v;
; }
; __global__ void __launch_bounds__(NTHR, 2) fwd_megakernel(Args args) {
;     ...
;         for (int m = gw; m < 2 * NMEM; m += NGW) {
;             const f32x4* xr = (const f32x4*)(KIN(I_MEM) + (size_t)m * D) + lane; const f32x4* gr = (const f32x4*)KIN(I_MEM_NORM) + lane; u32x2* o = (u32x2*)(MEMN + (size_t)m * D) + lane;
;             f32x4 v[8]; float s = 0.f;
; #pragma unroll
;             for (int j = 0; j < 8; ++j) { v[j] = xr[64 * j]; s += (v[j][0] * v[j][0] + v[j][1] * v[j][1]) + (v[j][2] * v[j][2] + v[j][3] * v[j][3]); }
;             const float rstd = rsqrtf(wave_sum(s) * (1.0f / D) + RMS_EPS);
; #pragma unroll
;             for (int j = 0; j < 8; ++j) { const f32x4 gg = gr[64 * j]; const f32x4 y = v[j] * rstd * gg; u32x2 w; w.x = cvt_pk_bf16(y[0], y[1]); w.y = cvt_pk_bf16(y[2], y[3]); o[64 * j] = w; }
;         }
.LBB0_166:
	v_add_co_u32_e32 v0, vcc, 0xfffff000, v16
	global_load_dwordx4 v[26:29], v[16:17], off offset:-3072
	global_load_dwordx4 v[30:33], v[16:17], off offset:-2048
	global_load_dwordx4 v[34:37], v[16:17], off offset:-1024
	v_addc_co_u32_e32 v1, vcc, -1, v17, vcc
	global_load_dwordx4 v[38:41], v[0:1], off offset:-3072
	global_load_dwordx4 v[42:45], v[0:1], off offset:-2048
	global_load_dwordx4 v[46:49], v[0:1], off offset:-1024
	global_load_dwordx4 v[50:53], v[16:17], off offset:-4096
	s_nop 0
	global_load_dwordx4 v[0:3], v[16:17], off
	global_load_dwordx4 v[54:57], v[4:5], off
	s_add_i32 s66, s66, s68
	s_cmpk_gt_i32 s66, 0x1ff
	v_lshl_add_u64 v[16:17], v[16:17], 0, s[4:5]
	s_waitcnt vmcnt(5)
	v_mov_b32_e32 v68, v39
	v_pk_mul_f32 v[58:59], v[32:33], v[32:33]
	v_pk_mul_f32 v[60:61], v[30:31], v[30:31]
	v_mul_f32_e32 v62, v35, v35
	v_mul_f32_e32 v64, v37, v37
	s_waitcnt vmcnt(1)
	v_mul_f32_e32 v79, v2, v2
	v_mul_f32_e32 v86, v3, v3
	v_pk_mov_b32 v[66:67], v[60:61], v[58:59] op_sel:[1,0]
	v_mov_b32_e32 v61, v59
	v_pk_fma_f32 v[58:59], v[34:35], v[34:35], v[62:63] op_sel_hi:[1,1,0]
	v_pk_fma_f32 v[62:63], v[36:37], v[36:37], v[64:65] op_sel_hi:[1,1,0]
	v_mov_b32_e32 v69, v43
	v_mov_b32_e32 v72, v41
	v_mov_b32_e32 v73, v45
	v_mov_b32_e32 v64, v38
	v_mov_b32_e32 v65, v42
	v_mov_b32_e32 v70, v40
	v_mov_b32_e32 v71, v44
	v_pk_mul_f32 v[74:75], v[48:49], v[48:49]
	v_pk_mul_f32 v[76:77], v[46:47], v[46:47]
	v_pk_add_f32 v[60:61], v[66:67], v[60:61]
	v_mov_b32_e32 v59, v79
	v_mov_b32_e32 v63, v86
	v_pk_mul_f32 v[66:67], v[68:69], v[68:69]
	v_pk_mul_f32 v[68:69], v[72:73], v[72:73]
	v_pk_mov_b32 v[72:73], v[76:77], v[74:75] op_sel:[1,0]
	v_mov_b32_e32 v77, v75
	v_pk_add_f32 v[58:59], v[58:59], v[62:63]
	v_pk_fma_f32 v[62:63], v[64:65], v[64:65], v[66:67]
	v_pk_fma_f32 v[64:65], v[70:71], v[70:71], v[68:69]
	v_mul_f32_e32 v81, v27, v27
	v_mul_f32_e32 v78, v51, v51
	v_mul_f32_e32 v80, v53, v53
	v_pk_add_f32 v[66:67], v[72:73], v[76:77]
	v_pk_add_f32 v[62:63], v[62:63], v[64:65]
	v_mul_f32_e32 v25, v26, v26
	v_mul_f32_e32 v82, v28, v28
	v_mul_f32_e32 v83, v29, v29
	v_pk_fma_f32 v[74:75], v[50:51], v[50:51], v[78:79] op_sel_hi:[1,1,0]
	v_pk_fma_f32 v[78:79], v[52:53], v[52:53], v[80:81] op_sel_hi:[1,1,0]
	v_pk_add_f32 v[64:65], v[66:67], v[66:67] op_sel:[0,1] op_sel_hi:[1,0]
	v_pk_add_f32 v[62:63], v[62:63], v[62:63] op_sel:[0,1] op_sel_hi:[1,0]
	v_mov_b32_e32 v75, v82
	v_mov_b32_e32 v79, v83
	v_mov_b32_e32 v65, v81
	v_mov_b32_e32 v63, v25
	v_pk_add_f32 v[66:67], v[74:75], v[78:79]
	v_pk_add_f32 v[62:63], v[62:63], v[64:65]
	v_mul_f32_e32 v84, v0, v0
	v_pk_add_f32 v[62:63], v[62:63], v[66:67]
	v_mul_f32_e32 v85, v1, v1
	v_pk_add_f32 v[60:61], v[60:61], v[60:61] op_sel:[0,1] op_sel_hi:[1,0]
	v_pk_add_f32 v[62:63], v[62:63], v[62:63] op_sel:[0,1] op_sel_hi:[1,0]
	v_mov_b32_e32 v61, v85
	v_mov_b32_e32 v63, v84
	v_pk_add_f32 v[60:61], v[62:63], v[60:61]
	s_nop 0
	v_pk_add_f32 v[58:59], v[60:61], v[58:59]
	s_nop 0
	v_add_f32_e32 v25, v58, v59
	ds_bpermute_b32 v58, v18, v25
	s_waitcnt lgkmcnt(0)
	v_add_f32_e32 v25, v25, v58
	ds_bpermute_b32 v58, v19, v25
	s_waitcnt lgkmcnt(0)
	v_add_f32_e32 v25, v25, v58
	ds_bpermute_b32 v58, v20, v25
	s_waitcnt lgkmcnt(0)
	v_add_f32_e32 v25, v25, v58
	ds_bpermute_b32 v58, v21, v25
	s_waitcnt lgkmcnt(0)
	v_add_f32_e32 v25, v25, v58
	v_mov_b32_e32 v58, v25
	s_nop 1
	v_permlane16_swap_b32_e32 v25, v58
	s_nop 1
	s_waitcnt lgkmcnt(0)
	v_add_f32_e32 v25, v25, v58
	v_mov_b32_e32 v58, v25
	s_nop 1
	v_permlane32_swap_b32_e32 v25, v58
	s_nop 1
	s_waitcnt lgkmcnt(0)
	v_add_f32_e32 v25, v25, v58
	v_fmamk_f32 v25, v25, 0x3a000000, v24
	v_mul_f32_e32 v58, 0x4b800000, v25
	v_cmp_gt_f32_e32 vcc, s6, v25
	s_nop 1
	v_cndmask_b32_e32 v25, v25, v58, vcc
	v_rsq_f32_e32 v25, v25
	s_nop 0
	v_mul_f32_e32 v58, 0x45800000, v25
	v_cndmask_b32_e32 v58, v25, v58, vcc
	v_pk_mul_f32 v[38:39], v[58:59], v[38:39] op_sel_hi:[0,1]
	v_pk_mul_f32 v[40:41], v[58:59], v[40:41] op_sel_hi:[0,1]
	s_waitcnt vmcnt(0)
	v_pk_mul_f32 v[38:39], v[54:55], v[38:39]
	v_pk_mul_f32 v[40:41], v[56:57], v[40:41]
	v_cvt_pk_bf16_f32 v38, v38, v39
	v_pk_mul_f32 v[42:43], v[58:59], v[42:43] op_sel_hi:[0,1]
	v_cvt_pk_bf16_f32 v39, v40, v41
	global_store_dwordx2 v[14:15], v[38:39], off offset:-3584
	global_load_dwordx4 v[38:41], v[4:5], off offset:1024
	v_pk_mul_f32 v[44:45], v[58:59], v[44:45] op_sel_hi:[0,1]
	v_pk_mul_f32 v[26:27], v[58:59], v[26:27] op_sel_hi:[0,1]
	v_pk_mul_f32 v[28:29], v[58:59], v[28:29] op_sel_hi:[0,1]
	v_pk_mul_f32 v[30:31], v[58:59], v[30:31] op_sel_hi:[0,1]
	v_pk_mul_f32 v[32:33], v[58:59], v[32:33] op_sel_hi:[0,1]
	v_pk_mul_f32 v[0:1], v[58:59], v[0:1] op_sel_hi:[0,1]
	v_pk_mul_f32 v[2:3], v[58:59], v[2:3] op_sel_hi:[0,1]
	s_waitcnt vmcnt(0)
	v_pk_mul_f32 v[38:39], v[38:39], v[42:43]
	v_pk_mul_f32 v[40:41], v[40:41], v[44:45]
	v_cvt_pk_bf16_f32 v38, v38, v39
	v_pk_mul_f32 v[42:43], v[58:59], v[46:47] op_sel_hi:[0,1]
	v_cvt_pk_bf16_f32 v39, v40, v41
	global_store_dwordx2 v[14:15], v[38:39], off offset:-3072
	global_load_dwordx4 v[38:41], v[4:5], off offset:2048
	v_pk_mul_f32 v[44:45], v[58:59], v[48:49] op_sel_hi:[0,1]
	s_waitcnt vmcnt(0)
	v_pk_mul_f32 v[38:39], v[38:39], v[42:43]
	v_pk_mul_f32 v[40:41], v[40:41], v[44:45]
	v_cvt_pk_bf16_f32 v38, v38, v39
	v_pk_mul_f32 v[42:43], v[58:59], v[50:51] op_sel_hi:[0,1]
	v_cvt_pk_bf16_f32 v39, v40, v41
	global_store_dwordx2 v[14:15], v[38:39], off offset:-2560
	global_load_dwordx4 v[38:41], v[4:5], off offset:3072
	v_pk_mul_f32 v[44:45], v[58:59], v[52:53] op_sel_hi:[0,1]
	s_waitcnt vmcnt(0)
	v_pk_mul_f32 v[38:39], v[38:39], v[42:43]
	v_pk_mul_f32 v[40:41], v[40:41], v[44:45]
	v_cvt_pk_bf16_f32 v38, v38, v39
	s_nop 0
	v_cvt_pk_bf16_f32 v39, v40, v41
	global_store_dwordx2 v[14:15], v[38:39], off offset:-2048
	global_load_dwordx4 v[38:41], v[6:7], off
	s_waitcnt vmcnt(0)
	v_pk_mul_f32 v[26:27], v[38:39], v[26:27]
	v_pk_mul_f32 v[28:29], v[40:41], v[28:29]
	v_cvt_pk_bf16_f32 v26, v26, v27
	s_nop 0
	v_cvt_pk_bf16_f32 v27, v28, v29
	global_store_dwordx2 v[14:15], v[26:27], off offset:-1536
	global_load_dwordx4 v[26:29], v[8:9], off
	s_waitcnt vmcnt(0)
	v_pk_mul_f32 v[26:27], v[26:27], v[30:31]
	v_pk_mul_f32 v[28:29], v[28:29], v[32:33]
	v_cvt_pk_bf16_f32 v26, v26, v27
	v_pk_mul_f32 v[30:31], v[58:59], v[34:35] op_sel_hi:[0,1]
	v_cvt_pk_bf16_f32 v27, v28, v29
	global_store_dwordx2 v[14:15], v[26:27], off offset:-1024
	global_load_dwordx4 v[26:29], v[10:11], off
	v_pk_mul_f32 v[32:33], v[58:59], v[36:37] op_sel_hi:[0,1]
	s_waitcnt vmcnt(0)
	v_pk_mul_f32 v[26:27], v[26:27], v[30:31]
	v_pk_mul_f32 v[28:29], v[28:29], v[32:33]
	v_cvt_pk_bf16_f32 v26, v26, v27
	s_nop 0
	v_cvt_pk_bf16_f32 v27, v28, v29
	global_store_dwordx2 v[14:15], v[26:27], off offset:-512
	global_load_dwordx4 v[26:29], v[12:13], off
	s_waitcnt vmcnt(0)
	v_pk_mul_f32 v[0:1], v[26:27], v[0:1]
	v_pk_mul_f32 v[2:3], v[28:29], v[2:3]
	v_cvt_pk_bf16_f32 v0, v0, v1
	s_nop 0
	v_cvt_pk_bf16_f32 v1, v2, v3
	global_store_dwordx2 v[14:15], v[0:1], off
	v_lshl_add_u64 v[14:15], v[14:15], 0, s[2:3]
	s_cbranch_scc0 .LBB0_166

; __device__ __forceinline__ unsigned cvt_pk_bf16(float lo, float hi) { unsigned r; asm volatile("v_cvt_pk_bf16_f32 %0, %1, %2" : "=v"(r) : "v"(lo), "v"(hi)); return r; }
; __device__ __forceinline__ float bf_lo(unsigned u) { return __uint_as_float(u << 16); }
; __device__ __forceinline__ float bf_hi(unsigned u) { return __uint_as_float(u & 0xffff0000u); }
;     __device__ __forceinline__ void operator()(const f32x4 (&acc)[2][2][4][2], const Unit& u, int wr, int wc, int fr, int fq) const {
;     ...
;             for (int m = 0; m < 4; ++m) { const int row = row0 + ai * HALF + m * 16; bf16_t* rowp = XB + (size_t)row * D + col0; float ss = 0.f;
; #pragma unroll
;                 for (int bj = 0; bj < 2; ++bj) { const u32x4 r = *(const u32x4*)(rowp + bj * HALF);
;                     const f32x4 o0 = (f32x4){bf_lo(r.x), bf_hi(r.x), bf_lo(r.y), bf_hi(r.y)} + acc[ai][bj][m][0] * alpha, o1 = (f32x4){bf_lo(r.z), bf_hi(r.z), bf_lo(r.w), bf_hi(r.w)} + acc[ai][bj][m][1] * alpha;
;                     ss += ((o0[0] * o0[0] + o0[1] * o0[1]) + (o0[2] * o0[2] + o0[3] * o0[3])) + ((o1[0] * o1[0] + o1[1] * o1[1]) + (o1[2] * o1[2] + o1[3] * o1[3]));
;                     u32x4 w; w.x = cvt_pk_bf16(o0[0], o0[1]); w.y = cvt_pk_bf16(o0[2], o0[3]); w.z = cvt_pk_bf16(o1[0], o1[1]); w.w = cvt_pk_bf16(o1[2], o1[3]);
;                     *(u32x4*)(rowp + bj * HALF) = w; }
;                 ss += __shfl_xor(ss, 16); ss += __shfl_xor(ss, 32);
;                 if (fq == 0) part[(size_t)row * NPART + u.pn * 4 + wc] = ss; }
.LBB0_364:
	v_lshl_add_u32 v146, s11, 8, v148
	v_ashrrev_i32_e32 v147, 31, v146
	v_lshl_or_b32 v144, s64, 8, v150
	v_lshlrev_b64 v[156:157], 12, v[146:147]
	v_ashrrev_i32_e32 v145, 31, v144
	v_lshl_add_u64 v[156:157], s[50:51], 0, v[156:157]
	v_lshl_add_u64 v[160:161], v[144:145], 1, v[156:157]
	global_load_dwordx4 v[156:159], v[160:161], off
	v_xor_b32_e32 v155, 32, v154
	s_waitcnt vmcnt(0)
	v_lshlrev_b32_e32 v162, 16, v156
	v_and_b32_e32 v163, 0xffff0000, v156
	v_lshlrev_b32_e32 v156, 16, v157
	v_and_b32_e32 v157, 0xffff0000, v157
	v_lshlrev_b32_e32 v164, 16, v158
	v_and_b32_e32 v165, 0xffff0000, v158
	v_lshlrev_b32_e32 v158, 16, v159
	v_and_b32_e32 v159, 0xffff0000, v159
	v_pk_fma_f32 v[126:127], v[126:127], 0.5, v[156:157] op_sel_hi:[1,0,1]
	v_pk_fma_f32 v[162:163], v[124:125], 0.5, v[162:163] op_sel_hi:[1,0,1]
	v_pk_fma_f32 v[166:167], v[122:123], 0.5, v[158:159] op_sel_hi:[1,0,1]
	v_pk_fma_f32 v[164:165], v[120:121], 0.5, v[164:165] op_sel_hi:[1,0,1]
	v_cvt_pk_bf16_f32 v122, v162, v163
	v_cvt_pk_bf16_f32 v123, v126, v127
	v_mul_f32_e32 v163, v163, v163
	v_cvt_pk_bf16_f32 v124, v164, v165
	v_cvt_pk_bf16_f32 v125, v166, v167
	global_load_dwordx4 v[156:159], v[160:161], off offset:256
	v_mul_f32_e32 v127, v127, v127
	v_mul_f32_e32 v165, v165, v165
	v_mul_f32_e32 v167, v167, v167
	v_fmac_f32_e32 v163, v162, v162
	v_fmac_f32_e32 v127, v126, v126
	v_fmac_f32_e32 v165, v164, v164
	v_fmac_f32_e32 v167, v166, v166
	v_add_f32_e32 v126, v163, v127
	v_add_f32_e32 v127, v165, v167
	v_add_f32_e32 v164, v126, v127
	v_and_b32_e32 v121, 64, v154
	v_xor_b32_e32 v120, 16, v154
	v_add_u32_e32 v121, 64, v121
	v_cmp_lt_i32_e32 vcc, v120, v121
	global_store_dwordx4 v[160:161], v[122:125], off
	s_waitcnt vmcnt(1)
	v_lshlrev_b32_e32 v126, 16, v156
	v_and_b32_e32 v127, 0xffff0000, v156
	v_lshlrev_b32_e32 v156, 16, v157
	v_and_b32_e32 v157, 0xffff0000, v157
	v_lshlrev_b32_e32 v162, 16, v158
	v_and_b32_e32 v163, 0xffff0000, v158
	v_lshlrev_b32_e32 v158, 16, v159
	v_and_b32_e32 v159, 0xffff0000, v159
	v_pk_fma_f32 v[118:119], v[118:119], 0.5, v[156:157] op_sel_hi:[1,0,1]
	v_pk_fma_f32 v[116:117], v[116:117], 0.5, v[126:127] op_sel_hi:[1,0,1]
	v_pk_fma_f32 v[126:127], v[114:115], 0.5, v[158:159] op_sel_hi:[1,0,1]
	v_pk_fma_f32 v[156:157], v[112:113], 0.5, v[162:163] op_sel_hi:[1,0,1]
	v_mul_f32_e32 v112, v117, v117
	v_mul_f32_e32 v113, v119, v119
	v_mul_f32_e32 v114, v157, v157
	v_mul_f32_e32 v115, v127, v127
	v_fmac_f32_e32 v112, v116, v116
	v_fmac_f32_e32 v113, v118, v118
	v_fmac_f32_e32 v114, v156, v156
	v_fmac_f32_e32 v115, v126, v126
	v_add_f32_e32 v112, v112, v113
	v_add_f32_e32 v113, v114, v115
	v_cndmask_b32_e32 v120, v154, v120, vcc
	v_add_f32_e32 v112, v112, v113
	v_lshlrev_b32_e32 v120, 2, v120
	v_add_f32_e32 v112, v164, v112
	v_mov_b32_e32 v113, v112
	s_nop 1
	v_permlane16_swap_b32_e32 v112, v113
	s_nop 1
	v_cmp_lt_i32_e32 vcc, v155, v121
	v_cvt_pk_bf16_f32 v116, v116, v117
	v_cvt_pk_bf16_f32 v117, v118, v119
	v_cvt_pk_bf16_f32 v118, v156, v157
	s_waitcnt lgkmcnt(0)
	v_add_f32_e32 v112, v112, v113
	v_cvt_pk_bf16_f32 v119, v126, v127
	v_cndmask_b32_e32 v114, v154, v155, vcc
	v_lshlrev_b32_e32 v114, 2, v114
	v_mov_b32_e32 v113, v112
	s_nop 1
	v_permlane32_swap_b32_e32 v112, v113
	s_nop 1
	global_store_dwordx4 v[160:161], v[116:119], off offset:256
	s_and_saveexec_b64 s[42:43], s[2:3]
	s_cbranch_execz .LBB0_366
	s_waitcnt lgkmcnt(0)
	v_add_f32_e32 v115, v112, v113
	s_lshl_b32 s44, s64, 2
	v_lshlrev_b64 v[112:113], 7, v[146:147]
	s_ashr_i32 s45, s44, 31
	v_lshl_add_u64 v[112:113], s[48:49], 0, v[112:113]
	v_lshl_add_u64 v[112:113], s[44:45], 2, v[112:113]
	s_lshl_b32 s44, s70, 2
	s_mov_b32 s45, s21
	v_lshl_add_u64 v[112:113], v[112:113], 0, s[44:45]
	global_store_dword v[112:113], v115, off
.LBB0_366:
	s_or_b64 exec, exec, s[42:43]
	v_or_b32_e32 v112, 16, v146
	s_waitcnt lgkmcnt(0)
	v_ashrrev_i32_e32 v113, 31, v112
	v_lshlrev_b64 v[116:117], 12, v[112:113]
	v_lshl_add_u64 v[116:117], s[50:51], 0, v[116:117]
	v_lshl_add_u64 v[122:123], v[144:145], 1, v[116:117]
	global_load_dwordx4 v[116:119], v[122:123], off
	s_waitcnt vmcnt(0)
	v_lshlrev_b32_e32 v124, 16, v116
	v_and_b32_e32 v125, 0xffff0000, v116
	v_lshlrev_b32_e32 v116, 16, v117
	v_and_b32_e32 v117, 0xffff0000, v117
	v_lshlrev_b32_e32 v126, 16, v118
	v_and_b32_e32 v127, 0xffff0000, v118
	v_lshlrev_b32_e32 v118, 16, v119
	v_and_b32_e32 v119, 0xffff0000, v119
	v_pk_fma_f32 v[116:117], v[110:111], 0.5, v[116:117] op_sel_hi:[1,0,1]
	v_pk_fma_f32 v[124:125], v[108:109], 0.5, v[124:125] op_sel_hi:[1,0,1]
	v_pk_fma_f32 v[118:119], v[106:107], 0.5, v[118:119] op_sel_hi:[1,0,1]
	v_pk_fma_f32 v[126:127], v[104:105], 0.5, v[126:127] op_sel_hi:[1,0,1]
	v_cvt_pk_bf16_f32 v104, v124, v125
	v_cvt_pk_bf16_f32 v105, v116, v117
	v_mul_f32_e32 v115, v125, v125
	v_cvt_pk_bf16_f32 v106, v126, v127
	v_cvt_pk_bf16_f32 v107, v118, v119
	global_load_dwordx4 v[108:111], v[122:123], off offset:256
	v_mul_f32_e32 v117, v117, v117
	v_mul_f32_e32 v121, v127, v127
	v_mul_f32_e32 v119, v119, v119
	v_fmac_f32_e32 v115, v124, v124
	v_fmac_f32_e32 v117, v116, v116
	v_fmac_f32_e32 v121, v126, v126
	v_fmac_f32_e32 v119, v118, v118
	v_add_f32_e32 v115, v115, v117
	v_add_f32_e32 v116, v121, v119
	v_add_f32_e32 v115, v115, v116
	global_store_dwordx4 v[122:123], v[104:107], off
	s_waitcnt vmcnt(1)
	v_lshlrev_b32_e32 v116, 16, v108
	v_and_b32_e32 v117, 0xffff0000, v108
	v_lshlrev_b32_e32 v108, 16, v109
	v_and_b32_e32 v109, 0xffff0000, v109
	v_lshlrev_b32_e32 v118, 16, v110
	v_and_b32_e32 v119, 0xffff0000, v110
	v_lshlrev_b32_e32 v110, 16, v111
	v_and_b32_e32 v111, 0xffff0000, v111
	v_pk_fma_f32 v[102:103], v[102:103], 0.5, v[108:109] op_sel_hi:[1,0,1]
	v_pk_fma_f32 v[100:101], v[100:101], 0.5, v[116:117] op_sel_hi:[1,0,1]
	v_pk_fma_f32 v[108:109], v[98:99], 0.5, v[110:111] op_sel_hi:[1,0,1]
	v_pk_fma_f32 v[110:111], v[96:97], 0.5, v[118:119] op_sel_hi:[1,0,1]
	v_mul_f32_e32 v96, v101, v101
	v_mul_f32_e32 v97, v103, v103
	v_mul_f32_e32 v98, v111, v111
	v_mul_f32_e32 v99, v109, v109
	v_fmac_f32_e32 v96, v100, v100
	v_fmac_f32_e32 v97, v102, v102
	v_fmac_f32_e32 v98, v110, v110
	v_fmac_f32_e32 v99, v108, v108
	v_add_f32_e32 v96, v96, v97
	v_add_f32_e32 v97, v98, v99
	v_add_f32_e32 v96, v96, v97
	v_add_f32_e32 v96, v115, v96
	v_mov_b32_e32 v97, v96
	s_nop 1
	v_permlane16_swap_b32_e32 v96, v97
	s_nop 1
	v_cvt_pk_bf16_f32 v98, v100, v101
	v_cvt_pk_bf16_f32 v99, v102, v103
	v_cvt_pk_bf16_f32 v100, v110, v111
	v_cvt_pk_bf16_f32 v101, v108, v109
	s_waitcnt lgkmcnt(0)
	v_add_f32_e32 v96, v96, v97
	v_mov_b32_e32 v97, v96
	s_nop 1
	v_permlane32_swap_b32_e32 v96, v97
	s_nop 1
	global_store_dwordx4 v[122:123], v[98:101], off offset:256
	s_and_saveexec_b64 s[42:43], s[2:3]
	s_cbranch_execz .LBB0_368
; __device__ __forceinline__ unsigned cvt_pk_bf16(float lo, float hi) { unsigned r; asm volatile("v_cvt_pk_bf16_f32 %0, %1, %2" : "=v"(r) : "v"(lo), "v"(hi)); return r; }
; __device__ __forceinline__ float bf_lo(unsigned u) { return __uint_as_float(u << 16); }
; __device__ __forceinline__ float bf_hi(unsigned u) { return __uint_as_float(u & 0xffff0000u); }
;     __device__ __forceinline__ void operator()(const f32x4 (&acc)[2][2][4][2], const Unit& u, int wr, int wc, int fr, int fq) const {
;     ...
;             for (int m = 0; m < 4; ++m) { const int row = row0 + ai * HALF + m * 16; bf16_t* rowp = XB + (size_t)row * D + col0; float ss = 0.f;
; #pragma unroll
;                 for (int bj = 0; bj < 2; ++bj) { const u32x4 r = *(const u32x4*)(rowp + bj * HALF);
;                     const f32x4 o0 = (f32x4){bf_lo(r.x), bf_hi(r.x), bf_lo(r.y), bf_hi(r.y)} + acc[ai][bj][m][0] * alpha, o1 = (f32x4){bf_lo(r.z), bf_hi(r.z), bf_lo(r.w), bf_hi(r.w)} + acc[ai][bj][m][1] * alpha;
;                     ss += ((o0[0] * o0[0] + o0[1] * o0[1]) + (o0[2] * o0[2] + o0[3] * o0[3])) + ((o1[0] * o1[0] + o1[1] * o1[1]) + (o1[2] * o1[2] + o1[3] * o1[3]));
;                     u32x4 w; w.x = cvt_pk_bf16(o0[0], o0[1]); w.y = cvt_pk_bf16(o0[2], o0[3]); w.z = cvt_pk_bf16(o1[0], o1[1]); w.w = cvt_pk_bf16(o1[2], o1[3]);
;                     *(u32x4*)(rowp + bj * HALF) = w; }
;                 ss += __shfl_xor(ss, 16); ss += __shfl_xor(ss, 32);
;                 if (fq == 0) part[(size_t)row * NPART + u.pn * 4 + wc] = ss; }
	s_waitcnt lgkmcnt(0)
	v_add_f32_e32 v98, v96, v97
	s_lshl_b32 s44, s64, 2
	v_lshlrev_b64 v[96:97], 7, v[112:113]
	s_ashr_i32 s45, s44, 31
	v_lshl_add_u64 v[96:97], s[48:49], 0, v[96:97]
	v_lshl_add_u64 v[96:97], s[44:45], 2, v[96:97]
	s_lshl_b32 s44, s70, 2
	s_mov_b32 s45, s21
	v_lshl_add_u64 v[96:97], v[96:97], 0, s[44:45]
	global_store_dword v[96:97], v98, off
.LBB0_368:
	s_or_b64 exec, exec, s[42:43]
	v_or_b32_e32 v96, 32, v146
	s_waitcnt lgkmcnt(0)
	v_ashrrev_i32_e32 v97, 31, v96
	v_lshlrev_b64 v[98:99], 12, v[96:97]
	v_lshl_add_u64 v[98:99], s[50:51], 0, v[98:99]
	v_lshl_add_u64 v[102:103], v[144:145], 1, v[98:99]
	global_load_dwordx4 v[98:101], v[102:103], off
	s_waitcnt vmcnt(0)
	v_lshlrev_b32_e32 v104, 16, v98
	v_and_b32_e32 v105, 0xffff0000, v98
	v_lshlrev_b32_e32 v98, 16, v99
	v_and_b32_e32 v99, 0xffff0000, v99
	v_lshlrev_b32_e32 v106, 16, v100
	v_and_b32_e32 v107, 0xffff0000, v100
	v_lshlrev_b32_e32 v100, 16, v101
	v_and_b32_e32 v101, 0xffff0000, v101
	v_pk_fma_f32 v[98:99], v[94:95], 0.5, v[98:99] op_sel_hi:[1,0,1]
	v_pk_fma_f32 v[104:105], v[92:93], 0.5, v[104:105] op_sel_hi:[1,0,1]
	v_pk_fma_f32 v[100:101], v[90:91], 0.5, v[100:101] op_sel_hi:[1,0,1]
	v_pk_fma_f32 v[106:107], v[88:89], 0.5, v[106:107] op_sel_hi:[1,0,1]
	v_cvt_pk_bf16_f32 v88, v104, v105
	v_cvt_pk_bf16_f32 v89, v98, v99
	v_mul_f32_e32 v105, v105, v105
	v_cvt_pk_bf16_f32 v90, v106, v107
	v_cvt_pk_bf16_f32 v91, v100, v101
	global_load_dwordx4 v[92:95], v[102:103], off offset:256
	v_mul_f32_e32 v99, v99, v99
	v_mul_f32_e32 v107, v107, v107
	v_mul_f32_e32 v101, v101, v101
	v_fmac_f32_e32 v105, v104, v104
	v_fmac_f32_e32 v99, v98, v98
	v_fmac_f32_e32 v107, v106, v106
	v_fmac_f32_e32 v101, v100, v100
	v_add_f32_e32 v98, v105, v99
	v_add_f32_e32 v99, v107, v101
	v_add_f32_e32 v104, v98, v99
	global_store_dwordx4 v[102:103], v[88:91], off
	s_waitcnt vmcnt(1)
	v_lshlrev_b32_e32 v98, 16, v92
	v_and_b32_e32 v99, 0xffff0000, v92
	v_lshlrev_b32_e32 v92, 16, v93
	v_and_b32_e32 v93, 0xffff0000, v93
	v_lshlrev_b32_e32 v100, 16, v94
	v_and_b32_e32 v101, 0xffff0000, v94
	v_lshlrev_b32_e32 v94, 16, v95
	v_and_b32_e32 v95, 0xffff0000, v95
	v_pk_fma_f32 v[86:87], v[86:87], 0.5, v[92:93] op_sel_hi:[1,0,1]
	v_pk_fma_f32 v[84:85], v[84:85], 0.5, v[98:99] op_sel_hi:[1,0,1]
	v_pk_fma_f32 v[92:93], v[82:83], 0.5, v[94:95] op_sel_hi:[1,0,1]
	v_pk_fma_f32 v[94:95], v[80:81], 0.5, v[100:101] op_sel_hi:[1,0,1]
	v_mul_f32_e32 v80, v85, v85
	v_mul_f32_e32 v81, v87, v87
	v_mul_f32_e32 v82, v95, v95
	v_mul_f32_e32 v83, v93, v93
	v_fmac_f32_e32 v80, v84, v84
	v_fmac_f32_e32 v81, v86, v86
	v_fmac_f32_e32 v82, v94, v94
	v_fmac_f32_e32 v83, v92, v92
	v_add_f32_e32 v80, v80, v81
	v_add_f32_e32 v81, v82, v83
	v_add_f32_e32 v80, v80, v81
	v_add_f32_e32 v80, v104, v80
	v_mov_b32_e32 v81, v80
	s_nop 1
	v_permlane16_swap_b32_e32 v80, v81
	s_nop 1
	v_cvt_pk_bf16_f32 v82, v84, v85
	v_cvt_pk_bf16_f32 v83, v86, v87
	v_cvt_pk_bf16_f32 v84, v94, v95
	v_cvt_pk_bf16_f32 v85, v92, v93
	s_waitcnt lgkmcnt(0)
	v_add_f32_e32 v80, v80, v81
	v_mov_b32_e32 v81, v80
	s_nop 1
	v_permlane32_swap_b32_e32 v80, v81
	s_nop 1
	global_store_dwordx4 v[102:103], v[82:85], off offset:256
	s_and_saveexec_b64 s[42:43], s[2:3]
	s_cbranch_execz .LBB0_370
	s_waitcnt lgkmcnt(0)
	v_add_f32_e32 v82, v80, v81
	s_lshl_b32 s44, s64, 2
	v_lshlrev_b64 v[80:81], 7, v[96:97]
	s_ashr_i32 s45, s44, 31
	v_lshl_add_u64 v[80:81], s[48:49], 0, v[80:81]
	v_lshl_add_u64 v[80:81], s[44:45], 2, v[80:81]
	s_lshl_b32 s44, s70, 2
	s_mov_b32 s45, s21
	v_lshl_add_u64 v[80:81], v[80:81], 0, s[44:45]
	global_store_dword v[80:81], v82, off
.LBB0_370:
	s_or_b64 exec, exec, s[42:43]
	v_or_b32_e32 v80, 48, v146
	s_waitcnt lgkmcnt(0)
	v_ashrrev_i32_e32 v81, 31, v80
	v_lshlrev_b64 v[82:83], 12, v[80:81]
	v_lshl_add_u64 v[82:83], s[50:51], 0, v[82:83]
	v_lshl_add_u64 v[86:87], v[144:145], 1, v[82:83]
	global_load_dwordx4 v[82:85], v[86:87], off
	s_waitcnt vmcnt(0)
	v_lshlrev_b32_e32 v88, 16, v82
	v_and_b32_e32 v89, 0xffff0000, v82
	v_lshlrev_b32_e32 v82, 16, v83
	v_and_b32_e32 v83, 0xffff0000, v83
	v_lshlrev_b32_e32 v90, 16, v84
	v_and_b32_e32 v91, 0xffff0000, v84
	v_lshlrev_b32_e32 v84, 16, v85
	v_and_b32_e32 v85, 0xffff0000, v85
	v_pk_fma_f32 v[82:83], v[78:79], 0.5, v[82:83] op_sel_hi:[1,0,1]
	v_pk_fma_f32 v[88:89], v[76:77], 0.5, v[88:89] op_sel_hi:[1,0,1]
	v_pk_fma_f32 v[84:85], v[74:75], 0.5, v[84:85] op_sel_hi:[1,0,1]
	v_pk_fma_f32 v[90:91], v[72:73], 0.5, v[90:91] op_sel_hi:[1,0,1]
	v_cvt_pk_bf16_f32 v72, v88, v89
	v_cvt_pk_bf16_f32 v73, v82, v83
	v_mul_f32_e32 v89, v89, v89
	v_cvt_pk_bf16_f32 v74, v90, v91
	v_cvt_pk_bf16_f32 v75, v84, v85
	global_load_dwordx4 v[76:79], v[86:87], off offset:256
	v_mul_f32_e32 v83, v83, v83
	v_mul_f32_e32 v91, v91, v91
	v_mul_f32_e32 v85, v85, v85
	v_fmac_f32_e32 v89, v88, v88
	v_fmac_f32_e32 v83, v82, v82
	v_fmac_f32_e32 v91, v90, v90
	v_fmac_f32_e32 v85, v84, v84
	v_add_f32_e32 v82, v89, v83
	v_add_f32_e32 v83, v91, v85
	v_add_f32_e32 v88, v82, v83
	global_store_dwordx4 v[86:87], v[72:75], off
	s_waitcnt vmcnt(1)
	v_lshlrev_b32_e32 v82, 16, v76
	v_and_b32_e32 v83, 0xffff0000, v76
	v_lshlrev_b32_e32 v76, 16, v77
	v_and_b32_e32 v77, 0xffff0000, v77
	v_lshlrev_b32_e32 v84, 16, v78
	v_and_b32_e32 v85, 0xffff0000, v78
	v_lshlrev_b32_e32 v78, 16, v79
	v_and_b32_e32 v79, 0xffff0000, v79
	v_pk_fma_f32 v[70:71], v[70:71], 0.5, v[76:77] op_sel_hi:[1,0,1]
	v_pk_fma_f32 v[68:69], v[68:69], 0.5, v[82:83] op_sel_hi:[1,0,1]
	v_pk_fma_f32 v[76:77], v[66:67], 0.5, v[78:79] op_sel_hi:[1,0,1]
	v_pk_fma_f32 v[78:79], v[64:65], 0.5, v[84:85] op_sel_hi:[1,0,1]
	v_mul_f32_e32 v64, v69, v69
	v_mul_f32_e32 v65, v71, v71
	v_mul_f32_e32 v66, v79, v79
	v_mul_f32_e32 v67, v77, v77
	v_fmac_f32_e32 v64, v68, v68
	v_fmac_f32_e32 v65, v70, v70
	v_fmac_f32_e32 v66, v78, v78
	v_fmac_f32_e32 v67, v76, v76
	v_add_f32_e32 v64, v64, v65
	v_add_f32_e32 v65, v66, v67
	v_add_f32_e32 v64, v64, v65
	v_add_f32_e32 v64, v88, v64
	v_mov_b32_e32 v65, v64
	s_nop 1
	v_permlane16_swap_b32_e32 v64, v65
	s_nop 1
	v_cvt_pk_bf16_f32 v66, v68, v69
	v_cvt_pk_bf16_f32 v67, v70, v71
	v_cvt_pk_bf16_f32 v68, v78, v79
	v_cvt_pk_bf16_f32 v69, v76, v77
	s_waitcnt lgkmcnt(0)
	v_add_f32_e32 v64, v64, v65
	v_mov_b32_e32 v65, v64
	s_nop 1
	v_permlane32_swap_b32_e32 v64, v65
	s_nop 1
	global_store_dwordx4 v[86:87], v[66:69], off offset:256
	s_and_saveexec_b64 s[42:43], s[2:3]
	s_cbranch_execz .LBB0_372
	s_waitcnt lgkmcnt(0)
	v_add_f32_e32 v66, v64, v65
	s_lshl_b32 s44, s64, 2
	v_lshlrev_b64 v[64:65], 7, v[80:81]
	s_ashr_i32 s45, s44, 31
	v_lshl_add_u64 v[64:65], s[48:49], 0, v[64:65]
	v_lshl_add_u64 v[64:65], s[44:45], 2, v[64:65]
	s_lshl_b32 s44, s70, 2
	s_mov_b32 s45, s21
	v_lshl_add_u64 v[64:65], v[64:65], 0, s[44:45]
	global_store_dword v[64:65], v66, off
; __device__ __forceinline__ unsigned cvt_pk_bf16(float lo, float hi) { unsigned r; asm volatile("v_cvt_pk_bf16_f32 %0, %1, %2" : "=v"(r) : "v"(lo), "v"(hi)); return r; }
; __device__ __forceinline__ float bf_lo(unsigned u) { return __uint_as_float(u << 16); }
; __device__ __forceinline__ float bf_hi(unsigned u) { return __uint_as_float(u & 0xffff0000u); }
;     __device__ __forceinline__ void operator()(const f32x4 (&acc)[2][2][4][2], const Unit& u, int wr, int wc, int fr, int fq) const {
;     ...
;             for (int m = 0; m < 4; ++m) { const int row = row0 + ai * HALF + m * 16; bf16_t* rowp = XB + (size_t)row * D + col0; float ss = 0.f;
; #pragma unroll
;                 for (int bj = 0; bj < 2; ++bj) { const u32x4 r = *(const u32x4*)(rowp + bj * HALF);
;                     const f32x4 o0 = (f32x4){bf_lo(r.x), bf_hi(r.x), bf_lo(r.y), bf_hi(r.y)} + acc[ai][bj][m][0] * alpha, o1 = (f32x4){bf_lo(r.z), bf_hi(r.z), bf_lo(r.w), bf_hi(r.w)} + acc[ai][bj][m][1] * alpha;
;                     ss += ((o0[0] * o0[0] + o0[1] * o0[1]) + (o0[2] * o0[2] + o0[3] * o0[3])) + ((o1[0] * o1[0] + o1[1] * o1[1]) + (o1[2] * o1[2] + o1[3] * o1[3]));
;                     u32x4 w; w.x = cvt_pk_bf16(o0[0], o0[1]); w.y = cvt_pk_bf16(o0[2], o0[3]); w.z = cvt_pk_bf16(o1[0], o1[1]); w.w = cvt_pk_bf16(o1[2], o1[3]);
;                     *(u32x4*)(rowp + bj * HALF) = w; }
;                 ss += __shfl_xor(ss, 16); ss += __shfl_xor(ss, 32);
;                 if (fq == 0) part[(size_t)row * NPART + u.pn * 4 + wc] = ss; }
.LBB0_372:
	s_or_b64 exec, exec, s[42:43]
	v_add_u32_e32 v64, 0x80, v146
	s_waitcnt lgkmcnt(0)
	v_ashrrev_i32_e32 v65, 31, v64
	v_lshlrev_b64 v[66:67], 12, v[64:65]
	v_lshl_add_u64 v[66:67], s[50:51], 0, v[66:67]
	v_lshl_add_u64 v[70:71], v[144:145], 1, v[66:67]
	global_load_dwordx4 v[66:69], v[70:71], off
	s_waitcnt vmcnt(0)
	v_lshlrev_b32_e32 v72, 16, v66
	v_and_b32_e32 v73, 0xffff0000, v66
	v_lshlrev_b32_e32 v66, 16, v67
	v_and_b32_e32 v67, 0xffff0000, v67
	v_lshlrev_b32_e32 v74, 16, v68
	v_and_b32_e32 v75, 0xffff0000, v68
	v_lshlrev_b32_e32 v68, 16, v69
	v_and_b32_e32 v69, 0xffff0000, v69
	v_pk_fma_f32 v[66:67], v[62:63], 0.5, v[66:67] op_sel_hi:[1,0,1]
	v_pk_fma_f32 v[72:73], v[60:61], 0.5, v[72:73] op_sel_hi:[1,0,1]
	v_pk_fma_f32 v[68:69], v[58:59], 0.5, v[68:69] op_sel_hi:[1,0,1]
	v_pk_fma_f32 v[74:75], v[56:57], 0.5, v[74:75] op_sel_hi:[1,0,1]
	v_cvt_pk_bf16_f32 v56, v72, v73
	v_cvt_pk_bf16_f32 v57, v66, v67
	v_mul_f32_e32 v73, v73, v73
	v_cvt_pk_bf16_f32 v58, v74, v75
	v_cvt_pk_bf16_f32 v59, v68, v69
	global_load_dwordx4 v[60:63], v[70:71], off offset:256
	v_mul_f32_e32 v67, v67, v67
	v_mul_f32_e32 v75, v75, v75
	v_mul_f32_e32 v69, v69, v69
	v_fmac_f32_e32 v73, v72, v72
	v_fmac_f32_e32 v67, v66, v66
	v_fmac_f32_e32 v75, v74, v74
	v_fmac_f32_e32 v69, v68, v68
	v_add_f32_e32 v66, v73, v67
	v_add_f32_e32 v67, v75, v69
	v_add_f32_e32 v72, v66, v67
	global_store_dwordx4 v[70:71], v[56:59], off
	s_waitcnt vmcnt(1)
	v_lshlrev_b32_e32 v66, 16, v60
	v_and_b32_e32 v67, 0xffff0000, v60
	v_lshlrev_b32_e32 v60, 16, v61
	v_and_b32_e32 v61, 0xffff0000, v61
	v_lshlrev_b32_e32 v68, 16, v62
	v_and_b32_e32 v69, 0xffff0000, v62
	v_lshlrev_b32_e32 v62, 16, v63
	v_and_b32_e32 v63, 0xffff0000, v63
	v_pk_fma_f32 v[54:55], v[54:55], 0.5, v[60:61] op_sel_hi:[1,0,1]
	v_pk_fma_f32 v[52:53], v[52:53], 0.5, v[66:67] op_sel_hi:[1,0,1]
	v_pk_fma_f32 v[60:61], v[50:51], 0.5, v[62:63] op_sel_hi:[1,0,1]
	v_pk_fma_f32 v[62:63], v[48:49], 0.5, v[68:69] op_sel_hi:[1,0,1]
	v_mul_f32_e32 v48, v53, v53
	v_mul_f32_e32 v49, v55, v55
	v_mul_f32_e32 v50, v63, v63
	v_mul_f32_e32 v51, v61, v61
	v_fmac_f32_e32 v48, v52, v52
	v_fmac_f32_e32 v49, v54, v54
	v_fmac_f32_e32 v50, v62, v62
	v_fmac_f32_e32 v51, v60, v60
	v_add_f32_e32 v48, v48, v49
	v_add_f32_e32 v49, v50, v51
	v_add_f32_e32 v48, v48, v49
	v_add_f32_e32 v48, v72, v48
	v_mov_b32_e32 v49, v48
	s_nop 1
	v_permlane16_swap_b32_e32 v48, v49
	s_nop 1
	v_cvt_pk_bf16_f32 v50, v52, v53
	v_cvt_pk_bf16_f32 v51, v54, v55
	v_cvt_pk_bf16_f32 v52, v62, v63
	v_cvt_pk_bf16_f32 v53, v60, v61
	s_waitcnt lgkmcnt(0)
	v_add_f32_e32 v48, v48, v49
	v_mov_b32_e32 v49, v48
	s_nop 1
	v_permlane32_swap_b32_e32 v48, v49
	s_nop 1
	global_store_dwordx4 v[70:71], v[50:53], off offset:256
	s_and_saveexec_b64 s[42:43], s[2:3]
	s_cbranch_execz .LBB0_374
	s_waitcnt lgkmcnt(0)
	v_add_f32_e32 v50, v48, v49
	s_lshl_b32 s44, s64, 2
	v_lshlrev_b64 v[48:49], 7, v[64:65]
	s_ashr_i32 s45, s44, 31
	v_lshl_add_u64 v[48:49], s[48:49], 0, v[48:49]
	v_lshl_add_u64 v[48:49], s[44:45], 2, v[48:49]
	s_lshl_b32 s44, s70, 2
	s_mov_b32 s45, s21
	v_lshl_add_u64 v[48:49], v[48:49], 0, s[44:45]
	global_store_dword v[48:49], v50, off
.LBB0_374:
	s_or_b64 exec, exec, s[42:43]
	v_add_u32_e32 v48, 0x90, v146
	s_waitcnt lgkmcnt(0)
	v_ashrrev_i32_e32 v49, 31, v48
	v_lshlrev_b64 v[50:51], 12, v[48:49]
	v_lshl_add_u64 v[50:51], s[50:51], 0, v[50:51]
	v_lshl_add_u64 v[54:55], v[144:145], 1, v[50:51]
	global_load_dwordx4 v[50:53], v[54:55], off
	s_waitcnt vmcnt(0)
	v_lshlrev_b32_e32 v56, 16, v50
	v_and_b32_e32 v57, 0xffff0000, v50
	v_lshlrev_b32_e32 v50, 16, v51
	v_and_b32_e32 v51, 0xffff0000, v51
	v_lshlrev_b32_e32 v58, 16, v52
	v_and_b32_e32 v59, 0xffff0000, v52
	v_lshlrev_b32_e32 v52, 16, v53
	v_and_b32_e32 v53, 0xffff0000, v53
	v_pk_fma_f32 v[50:51], v[46:47], 0.5, v[50:51] op_sel_hi:[1,0,1]
	v_pk_fma_f32 v[56:57], v[44:45], 0.5, v[56:57] op_sel_hi:[1,0,1]
	v_pk_fma_f32 v[52:53], v[42:43], 0.5, v[52:53] op_sel_hi:[1,0,1]
	v_pk_fma_f32 v[58:59], v[40:41], 0.5, v[58:59] op_sel_hi:[1,0,1]
	v_cvt_pk_bf16_f32 v40, v56, v57
	v_cvt_pk_bf16_f32 v41, v50, v51
	v_mul_f32_e32 v57, v57, v57
	v_cvt_pk_bf16_f32 v42, v58, v59
	v_cvt_pk_bf16_f32 v43, v52, v53
	global_load_dwordx4 v[44:47], v[54:55], off offset:256
	v_mul_f32_e32 v51, v51, v51
	v_mul_f32_e32 v59, v59, v59
	v_mul_f32_e32 v53, v53, v53
	v_fmac_f32_e32 v57, v56, v56
	v_fmac_f32_e32 v51, v50, v50
	v_fmac_f32_e32 v59, v58, v58
	v_fmac_f32_e32 v53, v52, v52
	v_add_f32_e32 v50, v57, v51
	v_add_f32_e32 v51, v59, v53
	v_add_f32_e32 v56, v50, v51
	global_store_dwordx4 v[54:55], v[40:43], off
	s_waitcnt vmcnt(1)
	v_lshlrev_b32_e32 v50, 16, v44
	v_and_b32_e32 v51, 0xffff0000, v44
	v_lshlrev_b32_e32 v44, 16, v45
	v_and_b32_e32 v45, 0xffff0000, v45
	v_lshlrev_b32_e32 v52, 16, v46
	v_and_b32_e32 v53, 0xffff0000, v46
	v_lshlrev_b32_e32 v46, 16, v47
	v_and_b32_e32 v47, 0xffff0000, v47
	v_pk_fma_f32 v[38:39], v[38:39], 0.5, v[44:45] op_sel_hi:[1,0,1]
	v_pk_fma_f32 v[36:37], v[36:37], 0.5, v[50:51] op_sel_hi:[1,0,1]
	v_pk_fma_f32 v[44:45], v[34:35], 0.5, v[46:47] op_sel_hi:[1,0,1]
	v_pk_fma_f32 v[46:47], v[32:33], 0.5, v[52:53] op_sel_hi:[1,0,1]
	v_mul_f32_e32 v32, v37, v37
	v_mul_f32_e32 v33, v39, v39
	v_mul_f32_e32 v34, v47, v47
	v_mul_f32_e32 v35, v45, v45
	v_fmac_f32_e32 v32, v36, v36
	v_fmac_f32_e32 v33, v38, v38
	v_fmac_f32_e32 v34, v46, v46
	v_fmac_f32_e32 v35, v44, v44
	v_add_f32_e32 v32, v32, v33
	v_add_f32_e32 v33, v34, v35
	v_add_f32_e32 v32, v32, v33
	v_add_f32_e32 v32, v56, v32
	v_mov_b32_e32 v33, v32
	s_nop 1
	v_permlane16_swap_b32_e32 v32, v33
	s_nop 1
	v_cvt_pk_bf16_f32 v34, v36, v37
	v_cvt_pk_bf16_f32 v35, v38, v39
	v_cvt_pk_bf16_f32 v36, v46, v47
	v_cvt_pk_bf16_f32 v37, v44, v45
	s_waitcnt lgkmcnt(0)
	v_add_f32_e32 v32, v32, v33
	v_mov_b32_e32 v33, v32
	s_nop 1
	v_permlane32_swap_b32_e32 v32, v33
	s_nop 1
	global_store_dwordx4 v[54:55], v[34:37], off offset:256
	s_and_saveexec_b64 s[42:43], s[2:3]
	s_cbranch_execz .LBB0_376
	s_waitcnt lgkmcnt(0)
	v_add_f32_e32 v34, v32, v33
	s_lshl_b32 s44, s64, 2
	v_lshlrev_b64 v[32:33], 7, v[48:49]
	s_ashr_i32 s45, s44, 31
	v_lshl_add_u64 v[32:33], s[48:49], 0, v[32:33]
	v_lshl_add_u64 v[32:33], s[44:45], 2, v[32:33]
	s_lshl_b32 s44, s70, 2
	s_mov_b32 s45, s21
	v_lshl_add_u64 v[32:33], v[32:33], 0, s[44:45]
	global_store_dword v[32:33], v34, off
; __device__ __forceinline__ unsigned cvt_pk_bf16(float lo, float hi) { unsigned r; asm volatile("v_cvt_pk_bf16_f32 %0, %1, %2" : "=v"(r) : "v"(lo), "v"(hi)); return r; }
; __device__ __forceinline__ float bf_lo(unsigned u) { return __uint_as_float(u << 16); }
; __device__ __forceinline__ float bf_hi(unsigned u) { return __uint_as_float(u & 0xffff0000u); }
;     __device__ __forceinline__ void operator()(const f32x4 (&acc)[2][2][4][2], const Unit& u, int wr, int wc, int fr, int fq) const {
;     ...
;             for (int m = 0; m < 4; ++m) { const int row = row0 + ai * HALF + m * 16; bf16_t* rowp = XB + (size_t)row * D + col0; float ss = 0.f;
; #pragma unroll
;                 for (int bj = 0; bj < 2; ++bj) { const u32x4 r = *(const u32x4*)(rowp + bj * HALF);
;                     const f32x4 o0 = (f32x4){bf_lo(r.x), bf_hi(r.x), bf_lo(r.y), bf_hi(r.y)} + acc[ai][bj][m][0] * alpha, o1 = (f32x4){bf_lo(r.z), bf_hi(r.z), bf_lo(r.w), bf_hi(r.w)} + acc[ai][bj][m][1] * alpha;
;                     ss += ((o0[0] * o0[0] + o0[1] * o0[1]) + (o0[2] * o0[2] + o0[3] * o0[3])) + ((o1[0] * o1[0] + o1[1] * o1[1]) + (o1[2] * o1[2] + o1[3] * o1[3]));
;                     u32x4 w; w.x = cvt_pk_bf16(o0[0], o0[1]); w.y = cvt_pk_bf16(o0[2], o0[3]); w.z = cvt_pk_bf16(o1[0], o1[1]); w.w = cvt_pk_bf16(o1[2], o1[3]);
;                     *(u32x4*)(rowp + bj * HALF) = w; }
;                 ss += __shfl_xor(ss, 16); ss += __shfl_xor(ss, 32);
;                 if (fq == 0) part[(size_t)row * NPART + u.pn * 4 + wc] = ss; }
.LBB0_376:
	s_or_b64 exec, exec, s[42:43]
	v_add_u32_e32 v32, 0xa0, v146
	s_waitcnt lgkmcnt(0)
	v_ashrrev_i32_e32 v33, 31, v32
	v_lshlrev_b64 v[34:35], 12, v[32:33]
	v_lshl_add_u64 v[34:35], s[50:51], 0, v[34:35]
	v_lshl_add_u64 v[38:39], v[144:145], 1, v[34:35]
	global_load_dwordx4 v[34:37], v[38:39], off
	s_waitcnt vmcnt(0)
	v_lshlrev_b32_e32 v40, 16, v34
	v_and_b32_e32 v41, 0xffff0000, v34
	v_lshlrev_b32_e32 v34, 16, v35
	v_and_b32_e32 v35, 0xffff0000, v35
	v_lshlrev_b32_e32 v42, 16, v36
	v_and_b32_e32 v43, 0xffff0000, v36
	v_lshlrev_b32_e32 v36, 16, v37
	v_and_b32_e32 v37, 0xffff0000, v37
	v_pk_fma_f32 v[34:35], v[30:31], 0.5, v[34:35] op_sel_hi:[1,0,1]
	v_pk_fma_f32 v[40:41], v[28:29], 0.5, v[40:41] op_sel_hi:[1,0,1]
	v_pk_fma_f32 v[36:37], v[26:27], 0.5, v[36:37] op_sel_hi:[1,0,1]
	v_pk_fma_f32 v[42:43], v[24:25], 0.5, v[42:43] op_sel_hi:[1,0,1]
	v_cvt_pk_bf16_f32 v24, v40, v41
	v_cvt_pk_bf16_f32 v25, v34, v35
	v_mul_f32_e32 v41, v41, v41
	v_cvt_pk_bf16_f32 v26, v42, v43
	v_cvt_pk_bf16_f32 v27, v36, v37
	global_load_dwordx4 v[28:31], v[38:39], off offset:256
	v_mul_f32_e32 v35, v35, v35
	v_mul_f32_e32 v43, v43, v43
	v_mul_f32_e32 v37, v37, v37
	v_fmac_f32_e32 v41, v40, v40
	v_fmac_f32_e32 v35, v34, v34
	v_fmac_f32_e32 v43, v42, v42
	v_fmac_f32_e32 v37, v36, v36
	v_add_f32_e32 v34, v41, v35
	v_add_f32_e32 v35, v43, v37
	v_add_f32_e32 v40, v34, v35
	global_store_dwordx4 v[38:39], v[24:27], off
	s_waitcnt vmcnt(1)
	v_lshlrev_b32_e32 v34, 16, v28
	v_and_b32_e32 v35, 0xffff0000, v28
	v_lshlrev_b32_e32 v28, 16, v29
	v_and_b32_e32 v29, 0xffff0000, v29
	v_lshlrev_b32_e32 v36, 16, v30
	v_and_b32_e32 v37, 0xffff0000, v30
	v_lshlrev_b32_e32 v30, 16, v31
	v_and_b32_e32 v31, 0xffff0000, v31
	v_pk_fma_f32 v[22:23], v[22:23], 0.5, v[28:29] op_sel_hi:[1,0,1]
	v_pk_fma_f32 v[20:21], v[20:21], 0.5, v[34:35] op_sel_hi:[1,0,1]
	v_pk_fma_f32 v[28:29], v[18:19], 0.5, v[30:31] op_sel_hi:[1,0,1]
	v_pk_fma_f32 v[30:31], v[16:17], 0.5, v[36:37] op_sel_hi:[1,0,1]
	v_mul_f32_e32 v16, v21, v21
	v_mul_f32_e32 v17, v23, v23
	v_mul_f32_e32 v18, v31, v31
	v_mul_f32_e32 v19, v29, v29
	v_fmac_f32_e32 v16, v20, v20
	v_fmac_f32_e32 v17, v22, v22
	v_fmac_f32_e32 v18, v30, v30
	v_fmac_f32_e32 v19, v28, v28
	v_add_f32_e32 v16, v16, v17
	v_add_f32_e32 v17, v18, v19
	v_add_f32_e32 v16, v16, v17
	v_add_f32_e32 v16, v40, v16
	v_mov_b32_e32 v17, v16
	s_nop 1
	v_permlane16_swap_b32_e32 v16, v17
	s_nop 1
	v_cvt_pk_bf16_f32 v18, v20, v21
	v_cvt_pk_bf16_f32 v19, v22, v23
	v_cvt_pk_bf16_f32 v20, v30, v31
	v_cvt_pk_bf16_f32 v21, v28, v29
	s_waitcnt lgkmcnt(0)
	v_add_f32_e32 v16, v16, v17
	v_mov_b32_e32 v17, v16
	s_nop 1
	v_permlane32_swap_b32_e32 v16, v17
	s_nop 1
	global_store_dwordx4 v[38:39], v[18:21], off offset:256
	s_and_saveexec_b64 s[42:43], s[2:3]
	s_cbranch_execz .LBB0_378
	s_waitcnt lgkmcnt(0)
	v_add_f32_e32 v18, v16, v17
	s_lshl_b32 s44, s64, 2
	v_lshlrev_b64 v[16:17], 7, v[32:33]
	s_ashr_i32 s45, s44, 31
	v_lshl_add_u64 v[16:17], s[48:49], 0, v[16:17]
	v_lshl_add_u64 v[16:17], s[44:45], 2, v[16:17]
	s_lshl_b32 s44, s70, 2
	s_mov_b32 s45, s21
	v_lshl_add_u64 v[16:17], v[16:17], 0, s[44:45]
	global_store_dword v[16:17], v18, off
.LBB0_378:
	s_or_b64 exec, exec, s[42:43]
	v_add_u32_e32 v16, 0xb0, v146
	s_waitcnt lgkmcnt(0)
	v_ashrrev_i32_e32 v17, 31, v16
	v_lshlrev_b64 v[18:19], 12, v[16:17]
	v_lshl_add_u64 v[18:19], s[50:51], 0, v[18:19]
	v_lshl_add_u64 v[22:23], v[144:145], 1, v[18:19]
	global_load_dwordx4 v[18:21], v[22:23], off
	s_waitcnt vmcnt(0)
	v_lshlrev_b32_e32 v24, 16, v18
	v_and_b32_e32 v25, 0xffff0000, v18
	v_lshlrev_b32_e32 v18, 16, v19
	v_and_b32_e32 v19, 0xffff0000, v19
	v_lshlrev_b32_e32 v26, 16, v20
	v_and_b32_e32 v27, 0xffff0000, v20
	v_lshlrev_b32_e32 v20, 16, v21
	v_and_b32_e32 v21, 0xffff0000, v21
	v_pk_fma_f32 v[18:19], v[14:15], 0.5, v[18:19] op_sel_hi:[1,0,1]
	v_pk_fma_f32 v[24:25], v[12:13], 0.5, v[24:25] op_sel_hi:[1,0,1]
	v_pk_fma_f32 v[20:21], v[10:11], 0.5, v[20:21] op_sel_hi:[1,0,1]
	v_pk_fma_f32 v[26:27], v[8:9], 0.5, v[26:27] op_sel_hi:[1,0,1]
	v_cvt_pk_bf16_f32 v8, v24, v25
	v_cvt_pk_bf16_f32 v9, v18, v19
	v_mul_f32_e32 v25, v25, v25
	v_cvt_pk_bf16_f32 v10, v26, v27
	v_cvt_pk_bf16_f32 v11, v20, v21
	global_load_dwordx4 v[12:15], v[22:23], off offset:256
	v_mul_f32_e32 v19, v19, v19
	v_mul_f32_e32 v27, v27, v27
	v_mul_f32_e32 v21, v21, v21
	v_fmac_f32_e32 v25, v24, v24
	v_fmac_f32_e32 v19, v18, v18
	v_fmac_f32_e32 v27, v26, v26
	v_fmac_f32_e32 v21, v20, v20
	v_add_f32_e32 v18, v25, v19
	v_add_f32_e32 v19, v27, v21
	v_add_f32_e32 v24, v18, v19
	global_store_dwordx4 v[22:23], v[8:11], off
	s_waitcnt vmcnt(1)
	v_lshlrev_b32_e32 v18, 16, v12
	v_and_b32_e32 v19, 0xffff0000, v12
	v_lshlrev_b32_e32 v12, 16, v13
	v_and_b32_e32 v13, 0xffff0000, v13
	v_lshlrev_b32_e32 v20, 16, v14
	v_and_b32_e32 v21, 0xffff0000, v14
	v_lshlrev_b32_e32 v14, 16, v15
	v_and_b32_e32 v15, 0xffff0000, v15
	v_pk_fma_f32 v[6:7], v[6:7], 0.5, v[12:13] op_sel_hi:[1,0,1]
	v_pk_fma_f32 v[4:5], v[4:5], 0.5, v[18:19] op_sel_hi:[1,0,1]
	v_pk_fma_f32 v[12:13], v[2:3], 0.5, v[14:15] op_sel_hi:[1,0,1]
	v_pk_fma_f32 v[14:15], v[0:1], 0.5, v[20:21] op_sel_hi:[1,0,1]
	v_mul_f32_e32 v0, v5, v5
	v_mul_f32_e32 v1, v7, v7
	v_mul_f32_e32 v2, v15, v15
	v_mul_f32_e32 v3, v13, v13
	v_fmac_f32_e32 v0, v4, v4
	v_fmac_f32_e32 v1, v6, v6
	v_fmac_f32_e32 v2, v14, v14
	v_fmac_f32_e32 v3, v12, v12
	v_add_f32_e32 v0, v0, v1
	v_add_f32_e32 v1, v2, v3
	v_add_f32_e32 v0, v0, v1
	v_add_f32_e32 v0, v24, v0
	v_mov_b32_e32 v1, v0
	s_nop 1
	v_permlane16_swap_b32_e32 v0, v1
	s_nop 1
	v_cvt_pk_bf16_f32 v2, v4, v5
	v_cvt_pk_bf16_f32 v3, v6, v7
	v_cvt_pk_bf16_f32 v4, v14, v15
	v_cvt_pk_bf16_f32 v5, v12, v13
	s_waitcnt lgkmcnt(0)
	v_add_f32_e32 v0, v0, v1
	v_mov_b32_e32 v1, v0
	s_nop 1
	v_permlane32_swap_b32_e32 v0, v1
	s_nop 1
	global_store_dwordx4 v[22:23], v[2:5], off offset:256
	s_and_saveexec_b64 s[42:43], s[2:3]
	s_cbranch_execz .LBB0_380
	s_waitcnt lgkmcnt(0)
	v_add_f32_e32 v2, v0, v1
	s_lshl_b32 s44, s64, 2
	v_lshlrev_b64 v[0:1], 7, v[16:17]
	s_ashr_i32 s45, s44, 31
	v_lshl_add_u64 v[0:1], s[48:49], 0, v[0:1]
	v_lshl_add_u64 v[0:1], s[44:45], 2, v[0:1]
	s_lshl_b32 s44, s70, 2
	s_mov_b32 s45, s21
	v_lshl_add_u64 v[0:1], v[0:1], 0, s[44:45]
	global_store_dword v[0:1], v2, off

; __device__ __forceinline__ void load_rstd(const float* part, int row0, int fq, float (&rs)[2][4]) {
;     ...
;         for (int m = 0; m < 4; ++m) { const float* p = part + (size_t)(row0 + ai * HALF + m * 16) * NPART + fq * 8;
;             const f32x4 a = *(const f32x4*)p, b = *(const f32x4*)(p + 4); float s = ((a[0] + a[1]) + (a[2] + a[3])) + ((b[0] + b[1]) + (b[2] + b[3]));
;             s += __shfl_xor(s, 16); s += __shfl_xor(s, 32); rs[ai][m] = rsqrtf(s * (1.0f / D) + RMS_EPS); }
.LBB0_469:
	v_and_b32_e32 v129, 64, v222
	v_xor_b32_e32 v128, 16, v222
	v_add_u32_e32 v129, 64, v129
	v_cmp_lt_i32_e32 vcc, v128, v129
	v_lshl_add_u32 v198, s97, 8, v159
	v_ashrrev_i32_e32 v199, 31, v198
	v_cndmask_b32_e32 v128, v222, v128, vcc
	v_lshlrev_b32_e32 v224, 2, v128
	v_xor_b32_e32 v128, 32, v222
	v_cmp_lt_i32_e32 vcc, v128, v129
	v_lshlrev_b64 v[196:197], 7, v[198:199]
	v_lshl_add_u64 v[132:133], v[146:147], 0, v[196:197]
	v_cndmask_b32_e32 v128, v222, v128, vcc
	v_lshlrev_b32_e32 v223, 2, v128
	s_nop 0
	s_nop 0
	s_nop 0
	s_mov_b32 s6, 0x358637bd
	v_mov_b64_e32 v[200:201], s[6:7]
	s_cmp_gt_i32 s96, 7
	s_nop 0
	v_mov_b32_e32 v156, v128
	v_mov_b32_e32 v157, v132
	v_mov_b32_e32 v132, v129
	v_pk_add_f32 v[128:129], v[156:157], v[132:133]
	v_or_b32_e32 v156, 16, v198
	v_ashrrev_i32_e32 v157, 31, v156
	v_mov_b32_e32 v132, v130
	v_mov_b32_e32 v133, v134
	v_mov_b32_e32 v134, v131
	v_lshlrev_b64 v[194:195], 7, v[156:157]
	v_pk_add_f32 v[130:131], v[132:133], v[134:135]
	v_lshl_add_u64 v[132:133], v[146:147], 0, v[194:195]
	v_pk_add_f32 v[160:161], v[128:129], v[130:131]
	s_nop 0
	s_nop 0
	s_nop 0
	s_nop 0
	v_mov_b32_e32 v162, v128
	s_nop 0
	v_mov_b32_e32 v163, v132
	v_mov_b32_e32 v132, v129
	v_pk_add_f32 v[128:129], v[162:163], v[132:133]
	v_mov_b32_e32 v132, v130
	v_mov_b32_e32 v133, v134
	v_mov_b32_e32 v134, v131
	v_pk_add_f32 v[130:131], v[132:133], v[134:135]
	v_or_b32_e32 v162, 32, v198
	v_pk_add_f32 v[128:129], v[128:129], v[130:131]
	v_mov_b32_e32 v131, v160
	v_mov_b32_e32 v130, v128
	v_mov_b32_e32 v160, v129
	v_pk_add_f32 v[128:129], v[130:131], v[160:161]
	s_nop 0
	s_nop 0
	v_ashrrev_i32_e32 v163, 31, v162
	v_lshlrev_b64 v[192:193], 7, v[162:163]
	v_lshl_add_u64 v[132:133], v[146:147], 0, v[192:193]
	s_waitcnt lgkmcnt(0)
	v_pk_add_f32 v[128:129], v[128:129], v[130:131]
	s_nop 0
	s_nop 0
	s_waitcnt lgkmcnt(0)
	v_pk_add_f32 v[128:129], v[128:129], v[130:131]
	s_nop 0
	v_pk_fma_f32 v[128:129], v[128:129], s[58:59], v[200:201] op_sel_hi:[1,0,0]
	s_nop 0
	v_mul_f32_e32 v130, 0x4b800000, v129
	v_cmp_gt_f32_e64 s[6:7], s94, v129
	v_cmp_gt_f32_e32 vcc, s94, v128
	s_nop 0
	v_cndmask_b32_e64 v129, v129, v130, s[6:7]
	v_rsq_f32_e32 v129, v129
	s_nop 0
	v_mul_f32_e32 v130, 0x45800000, v129
	v_cndmask_b32_e64 v166, v129, v130, s[6:7]
	v_mul_f32_e32 v129, 0x4b800000, v128
	v_cndmask_b32_e32 v128, v128, v129, vcc
	v_rsq_f32_e32 v128, v128
	s_nop 0
	v_mul_f32_e32 v129, 0x45800000, v128
	v_cndmask_b32_e32 v158, v128, v129, vcc
	s_nop 0
	s_nop 0
	s_nop 0
	s_nop 0
	v_mov_b32_e32 v160, v128
	s_nop 0
	v_mov_b32_e32 v161, v132
	v_mov_b32_e32 v132, v129
	v_pk_add_f32 v[128:129], v[160:161], v[132:133]
	v_or_b32_e32 v160, 48, v198
	v_ashrrev_i32_e32 v161, 31, v160
	v_mov_b32_e32 v132, v130
	v_mov_b32_e32 v133, v134
	v_mov_b32_e32 v134, v131
	v_lshlrev_b64 v[190:191], 7, v[160:161]
	v_pk_add_f32 v[130:131], v[132:133], v[134:135]
	v_lshl_add_u64 v[132:133], v[146:147], 0, v[190:191]
	v_pk_add_f32 v[168:169], v[128:129], v[130:131]
	s_nop 0
	s_nop 0
	s_nop 0
	s_nop 0
	v_mov_b32_e32 v170, v128
	s_nop 0
	v_mov_b32_e32 v171, v132
	v_mov_b32_e32 v132, v129
	v_pk_add_f32 v[128:129], v[170:171], v[132:133]
	v_mov_b32_e32 v132, v130
	v_mov_b32_e32 v133, v134
	v_mov_b32_e32 v134, v131
	v_pk_add_f32 v[130:131], v[132:133], v[134:135]
	v_add_u32_e32 v170, 0x80, v198
	v_pk_add_f32 v[128:129], v[128:129], v[130:131]
	v_mov_b32_e32 v131, v168
	v_mov_b32_e32 v130, v128
	v_mov_b32_e32 v168, v129
	v_pk_add_f32 v[128:129], v[130:131], v[168:169]
	s_nop 0
	s_nop 0
	v_ashrrev_i32_e32 v171, 31, v170
	v_lshlrev_b64 v[188:189], 7, v[170:171]
	v_lshl_add_u64 v[132:133], v[146:147], 0, v[188:189]
	s_waitcnt lgkmcnt(0)
	v_pk_add_f32 v[128:129], v[128:129], v[130:131]
	s_nop 0
	s_nop 0
	s_waitcnt lgkmcnt(0)
	v_pk_add_f32 v[128:129], v[128:129], v[130:131]
	s_nop 0
	v_pk_fma_f32 v[128:129], v[128:129], s[58:59], v[200:201] op_sel_hi:[1,0,0]
	s_nop 0
	v_mul_f32_e32 v130, 0x4b800000, v129
	v_cmp_gt_f32_e64 s[6:7], s94, v129
	v_cmp_gt_f32_e32 vcc, s94, v128
	s_nop 0
	v_cndmask_b32_e64 v129, v129, v130, s[6:7]
	v_rsq_f32_e32 v129, v129
	s_nop 0
	v_mul_f32_e32 v130, 0x45800000, v129
	v_cndmask_b32_e64 v172, v129, v130, s[6:7]
	v_mul_f32_e32 v129, 0x4b800000, v128
	v_cndmask_b32_e32 v128, v128, v129, vcc
	v_rsq_f32_e32 v128, v128
	s_nop 0
	v_mul_f32_e32 v129, 0x45800000, v128
	v_cndmask_b32_e32 v164, v128, v129, vcc
	s_nop 0
	s_nop 0
	s_nop 0
	s_nop 0
	v_mov_b32_e32 v168, v128
	s_nop 0
	v_mov_b32_e32 v169, v132
	v_mov_b32_e32 v132, v129
	v_pk_add_f32 v[128:129], v[168:169], v[132:133]
	v_add_u32_e32 v168, 0x90, v198
	v_ashrrev_i32_e32 v169, 31, v168
	v_mov_b32_e32 v132, v130
	v_mov_b32_e32 v133, v134
	v_mov_b32_e32 v134, v131
	v_lshlrev_b64 v[186:187], 7, v[168:169]
	v_pk_add_f32 v[130:131], v[132:133], v[134:135]
	v_lshl_add_u64 v[132:133], v[146:147], 0, v[186:187]
	v_pk_add_f32 v[176:177], v[128:129], v[130:131]
	s_nop 0
	s_nop 0
	s_nop 0
	s_nop 0
	v_mov_b32_e32 v178, v128
	s_nop 0
	v_mov_b32_e32 v179, v132
	v_mov_b32_e32 v132, v129
	v_pk_add_f32 v[128:129], v[178:179], v[132:133]
	v_mov_b32_e32 v132, v130
	v_mov_b32_e32 v133, v134
	v_mov_b32_e32 v134, v131
	v_pk_add_f32 v[130:131], v[132:133], v[134:135]
	v_add_u32_e32 v178, 0xa0, v198
	v_pk_add_f32 v[128:129], v[128:129], v[130:131]
	v_mov_b32_e32 v131, v176
	v_mov_b32_e32 v130, v128
	v_mov_b32_e32 v176, v129
	v_pk_add_f32 v[128:129], v[130:131], v[176:177]
	s_nop 0
	s_nop 0
	v_ashrrev_i32_e32 v179, 31, v178
	v_lshlrev_b64 v[184:185], 7, v[178:179]
	v_lshl_add_u64 v[132:133], v[146:147], 0, v[184:185]
	s_waitcnt lgkmcnt(0)
	v_pk_add_f32 v[128:129], v[128:129], v[130:131]
	s_nop 0
	s_nop 0
	s_waitcnt lgkmcnt(0)
; __device__ __forceinline__ unsigned cvt_pk_bf16(float lo, float hi) { unsigned r; asm volatile("v_cvt_pk_bf16_f32 %0, %1, %2" : "=v"(r) : "v"(lo), "v"(hi)); return r; }
; __device__ __forceinline__ f32x4 gelu4(f32x4 v) { f32x2 a = gelu_pk((f32x2){v[0], v[1]}), b = gelu_pk((f32x2){v[2], v[3]}); return (f32x4){a.x, a.y, b.x, b.y}; }
; __device__ __forceinline__ void load_rstd(const float* part, int row0, int fq, float (&rs)[2][4]) {
;     ...
;         for (int m = 0; m < 4; ++m) { const float* p = part + (size_t)(row0 + ai * HALF + m * 16) * NPART + fq * 8;
;             const f32x4 a = *(const f32x4*)p, b = *(const f32x4*)(p + 4); float s = ((a[0] + a[1]) + (a[2] + a[3])) + ((b[0] + b[1]) + (b[2] + b[3]));
;             s += __shfl_xor(s, 16); s += __shfl_xor(s, 32); rs[ai][m] = rsqrtf(s * (1.0f / D) + RMS_EPS); }
;     __device__ __forceinline__ void operator()(const f32x4 (&acc)[2][2][4][2], const Unit& u, int wr, int wc, int fr, int fq) const {
;     ...
;             const bool isv = u.pn >= 12; bf16_t* dst = isv ? VB : UB; const int tq = isv ? u.pn - 12 : u.pn - 8;
;             const int col0 = tq * BM + wc * 32 + 8 * fq;
; #pragma unroll
;             for (int ai = 0; ai < 2; ++ai)
; #pragma unroll
;                 for (int m = 0; m < 4; ++m) { const float sc = rs[ai][m]; const int row = row0 + ai * HALF + m * 16; float s1 = 0.f, s2 = 0.f;
; #pragma unroll
;                     for (int bj = 0; bj < 2; ++bj) { const f32x4 v0 = gelu4(acc[ai][bj][m][0] * sc), v1 = gelu4(acc[ai][bj][m][1] * sc);
;                         s1 += ((v0[0] + v0[1]) + (v0[2] + v0[3])) + ((v1[0] + v1[1]) + (v1[2] + v1[3]));
;                         s2 += ((v0[0] * v0[0] + v0[1] * v0[1]) + (v0[2] * v0[2] + v0[3] * v0[3])) + ((v1[0] * v1[0] + v1[1] * v1[1]) + (v1[2] * v1[2] + v1[3] * v1[3]));
;                         u32x4 w; w.x = cvt_pk_bf16(v0[0], v0[1]); w.y = cvt_pk_bf16(v0[2], v0[3]); w.z = cvt_pk_bf16(v1[0], v1[1]); w.w = cvt_pk_bf16(v1[2], v1[3]);
;                         *(u32x4*)(dst + (size_t)row * CCH + col0 + bj * HALF) = w; }
	v_pk_add_f32 v[128:129], v[128:129], v[130:131]
	s_nop 0
	v_pk_fma_f32 v[128:129], v[128:129], s[58:59], v[200:201] op_sel_hi:[1,0,0]
	s_nop 0
	v_mul_f32_e32 v130, 0x4b800000, v129
	v_cmp_gt_f32_e64 s[6:7], s94, v129
	v_cmp_gt_f32_e32 vcc, s94, v128
	s_nop 0
	v_cndmask_b32_e64 v129, v129, v130, s[6:7]
	v_rsq_f32_e32 v129, v129
	s_nop 0
	v_mul_f32_e32 v130, 0x45800000, v129
	v_cndmask_b32_e64 v180, v129, v130, s[6:7]
	v_mul_f32_e32 v129, 0x4b800000, v128
	v_cndmask_b32_e32 v128, v128, v129, vcc
	v_rsq_f32_e32 v128, v128
	s_nop 0
	v_mul_f32_e32 v129, 0x45800000, v128
	v_cndmask_b32_e32 v174, v128, v129, vcc
	s_nop 0
	s_nop 0
	s_nop 0
	s_nop 0
	v_mov_b32_e32 v176, v128
	s_nop 0
	v_mov_b32_e32 v177, v132
	v_mov_b32_e32 v132, v129
	v_pk_add_f32 v[128:129], v[176:177], v[132:133]
	v_add_u32_e32 v176, 0xb0, v198
	v_mov_b32_e32 v132, v130
	v_mov_b32_e32 v133, v134
	v_mov_b32_e32 v134, v131
	v_ashrrev_i32_e32 v177, 31, v176
	v_pk_add_f32 v[130:131], v[132:133], v[134:135]
	v_lshlrev_b64 v[182:183], 7, v[176:177]
	v_pk_add_f32 v[202:203], v[128:129], v[130:131]
	v_lshl_add_u64 v[128:129], v[146:147], 0, v[182:183]
	s_nop 0
	s_nop 0
	s_nop 0
	s_nop 0
	v_mov_b32_e32 v204, v132
	s_nop 0
	v_mov_b32_e32 v205, v128
	v_mov_b32_e32 v128, v133
	v_mov_b32_e32 v132, v134
	v_mov_b32_e32 v133, v130
	v_mov_b32_e32 v130, v135
	v_pk_add_f32 v[128:129], v[204:205], v[128:129]
	v_pk_add_f32 v[130:131], v[132:133], v[130:131]
	v_lshlrev_b64 v[132:133], 11, v[198:199]
	v_pk_add_f32 v[128:129], v[128:129], v[130:131]
	v_mov_b32_e32 v131, v202
	v_mov_b32_e32 v130, v128
	v_mov_b32_e32 v202, v129
	v_pk_add_f32 v[128:129], v[130:131], v[202:203]
	s_nop 0
	s_nop 0
	s_waitcnt lgkmcnt(0)
	v_pk_add_f32 v[128:129], v[128:129], v[130:131]
	s_nop 0
	s_nop 0
	s_waitcnt lgkmcnt(0)
	v_pk_add_f32 v[128:129], v[128:129], v[130:131]
	s_nop 0
	v_pk_fma_f32 v[128:129], v[128:129], s[58:59], v[200:201] op_sel_hi:[1,0,0]
	s_nop 0
	v_mul_f32_e32 v130, 0x4b800000, v129
	v_cmp_gt_f32_e64 s[6:7], s94, v129
	v_cmp_gt_f32_e32 vcc, s94, v128
	s_nop 0
	v_cndmask_b32_e64 v129, v129, v130, s[6:7]
	v_rsq_f32_e32 v129, v129
	s_nop 0
	v_mul_f32_e32 v130, 0x45800000, v129
	v_cndmask_b32_e64 v130, v129, v130, s[6:7]
	v_mul_f32_e32 v129, 0x4b800000, v128
	v_cndmask_b32_e32 v128, v128, v129, vcc
	v_rsq_f32_e32 v128, v128
	s_mov_b64 s[6:7], -1
	v_mul_f32_e32 v129, 0x45800000, v128
	v_cndmask_b32_e32 v128, v128, v129, vcc
	v_lshlrev_b32_e32 v131, 2, v159
	v_add_u32_e32 v131, 0x21000, v131
	ds_read_b32 v166, v131
	ds_read_b32 v158, v131 offset:64
	ds_read_b32 v172, v131 offset:128
	ds_read_b32 v164, v131 offset:192
	ds_read_b32 v180, v131 offset:512
	ds_read_b32 v174, v131 offset:576
	ds_read_b32 v130, v131 offset:640
	ds_read_b32 v128, v131 offset:704
	s_waitcnt lgkmcnt(0)
	s_cbranch_scc0 .LBB0_504
	s_cmp_gt_u32 s96, 11
	s_cselect_b64 s[82:83], -1, 0
	s_and_b64 s[6:7], s[82:83], exec
	s_cselect_b32 s18, s36, s88
	s_cselect_b32 s19, s37, s89
	s_add_i32 s33, s96, -12
	s_add_i32 s44, s96, -8
	s_and_b64 s[6:7], s[82:83], exec
	s_cselect_b32 s44, s33, s44
	v_lshl_or_b32 v198, s44, 8, v167
	v_mov_b32_e32 v134, s18
	v_mov_b32_e32 v135, s19
	v_ashrrev_i32_e32 v199, 31, v198
	v_pk_mul_f32 v[202:203], v[124:125], v[166:167] op_sel_hi:[1,0]
	v_lshl_add_u64 v[134:135], v[198:199], 1, v[134:135]
	v_and_b32_e32 v199, 0x7fffffff, v203
	v_and_b32_e32 v198, 0x7fffffff, v202
	v_pk_fma_f32 v[198:199], v[198:199], s[60:61], 1.0 op_sel_hi:[1,0,0]
	v_pk_mul_f32 v[204:205], v[126:127], v[166:167] op_sel_hi:[1,0]
	v_rcp_f32_e32 v200, v198
	v_rcp_f32_e32 v201, v199
	v_mov_b64_e32 v[226:227], s[64:65]
	v_pk_mul_f32 v[208:209], v[202:203], v[202:203]
	v_and_b32_e32 v211, 0x7fffffff, v205
	v_pk_fma_f32 v[206:207], v[200:201], s[62:63], v[226:227] op_sel_hi:[1,0,0]
	v_pk_mul_f32 v[208:209], v[208:209], s[72:73] op_sel_hi:[1,0]
	v_and_b32_e32 v210, 0x7fffffff, v204
	v_pk_fma_f32 v[206:207], v[200:201], v[206:207], s[66:67] op_sel_hi:[1,1,0]
	v_exp_f32_e32 v208, v208
	v_exp_f32_e32 v209, v209
	v_pk_fma_f32 v[210:211], v[210:211], s[60:61], 1.0 op_sel_hi:[1,0,0]
	v_pk_fma_f32 v[206:207], v[200:201], v[206:207], s[68:69] op_sel_hi:[1,1,0]
	v_rcp_f32_e32 v210, v210
	v_rcp_f32_e32 v211, v211
	v_pk_fma_f32 v[206:207], v[200:201], v[206:207], s[70:71] op_sel_hi:[1,1,0]
	v_pk_mul_f32 v[228:229], v[118:119], v[166:167] op_sel_hi:[1,0]
	v_pk_mul_f32 v[200:201], v[200:201], v[206:207]
	v_pk_mul_f32 v[206:207], v[204:205], v[204:205]
	v_pk_mul_f32 v[200:201], v[208:209], v[200:201]
	v_pk_mul_f32 v[206:207], v[206:207], s[72:73] op_sel_hi:[1,0]
	v_pk_mul_f32 v[208:209], v[202:203], v[200:201]
	v_pk_fma_f32 v[212:213], v[202:203], v[200:201], v[202:203] neg_lo:[1,0,0] neg_hi:[1,0,0]
	v_pk_fma_f32 v[200:201], v[210:211], s[62:63], v[226:227] op_sel_hi:[1,0,0]
	v_exp_f32_e32 v206, v206
	v_pk_fma_f32 v[200:201], v[210:211], v[200:201], s[66:67] op_sel_hi:[1,1,0]
	v_exp_f32_e32 v207, v207
	v_pk_fma_f32 v[200:201], v[210:211], v[200:201], s[68:69] op_sel_hi:[1,1,0]
	v_and_b32_e32 v231, 0x7fffffff, v229
	v_pk_fma_f32 v[200:201], v[210:211], v[200:201], s[70:71] op_sel_hi:[1,1,0]
	v_and_b32_e32 v230, 0x7fffffff, v228
	v_pk_mul_f32 v[200:201], v[210:211], v[200:201]
	v_pk_fma_f32 v[230:231], v[230:231], s[60:61], 1.0 op_sel_hi:[1,0,0]
	v_pk_mul_f32 v[200:201], v[206:207], v[200:201]
	v_pk_mul_f32 v[206:207], v[116:117], v[166:167] op_sel_hi:[1,0]
	v_pk_mul_f32 v[214:215], v[204:205], v[200:201]
	v_and_b32_e32 v211, 0x7fffffff, v207
	v_and_b32_e32 v210, 0x7fffffff, v206
	v_pk_fma_f32 v[210:211], v[210:211], s[60:61], 1.0 op_sel_hi:[1,0,0]
	v_pk_mul_f32 v[216:217], v[206:207], v[206:207]
	v_rcp_f32_e32 v210, v210
	v_rcp_f32_e32 v211, v211
; __device__ __forceinline__ unsigned cvt_pk_bf16(float lo, float hi) { unsigned r; asm volatile("v_cvt_pk_bf16_f32 %0, %1, %2" : "=v"(r) : "v"(lo), "v"(hi)); return r; }
; __device__ __forceinline__ f32x2 gelu_pk(f32x2 v) {
;     const f32x2 av = __builtin_elementwise_abs(v), d = av * 0.2316418882f + 1.0f;
;     f32x2 t; t.x = __builtin_amdgcn_rcpf(d.x); t.y = __builtin_amdgcn_rcpf(d.y);
;     f32x2 q = t * 0.5307027145f + (-0.7265760135f); q = q * t + 0.7107068705f; q = q * t + (-0.142248368f); q = q * t + 0.127414796f; q = q * t;
;     const f32x2 s = (v * v) * (-0.72134752044f);
;     f32x2 e; e.x = __builtin_amdgcn_exp2f(s.x); e.y = __builtin_amdgcn_exp2f(s.y);
;     const f32x2 m = v * (q * e), r = v - m;
;     f32x2 o; o.x = v.x < 0.f ? m.x : r.x; o.y = v.y < 0.f ? m.y : r.y; return o;
; }
; __device__ __forceinline__ f32x4 gelu4(f32x4 v) { f32x2 a = gelu_pk((f32x2){v[0], v[1]}), b = gelu_pk((f32x2){v[2], v[3]}); return (f32x4){a.x, a.y, b.x, b.y}; }
;     __device__ __forceinline__ void operator()(const f32x4 (&acc)[2][2][4][2], const Unit& u, int wr, int wc, int fr, int fq) const {
;     ...
;                     for (int bj = 0; bj < 2; ++bj) { const f32x4 v0 = gelu4(acc[ai][bj][m][0] * sc), v1 = gelu4(acc[ai][bj][m][1] * sc);
;                         s1 += ((v0[0] + v0[1]) + (v0[2] + v0[3])) + ((v1[0] + v1[1]) + (v1[2] + v1[3]));
;                         s2 += ((v0[0] * v0[0] + v0[1] * v0[1]) + (v0[2] * v0[2] + v0[3] * v0[3])) + ((v1[0] * v1[0] + v1[1] * v1[1]) + (v1[2] * v1[2] + v1[3] * v1[3]));
;                         u32x4 w; w.x = cvt_pk_bf16(v0[0], v0[1]); w.y = cvt_pk_bf16(v0[2], v0[3]); w.z = cvt_pk_bf16(v1[0], v1[1]); w.w = cvt_pk_bf16(v1[2], v1[3]);
;                         *(u32x4*)(dst + (size_t)row * CCH + col0 + bj * HALF) = w; }
	v_pk_fma_f32 v[218:219], v[204:205], v[200:201], v[204:205] neg_lo:[1,0,0] neg_hi:[1,0,0]
	v_pk_mul_f32 v[216:217], v[216:217], s[72:73] op_sel_hi:[1,0]
	v_rcp_f32_e32 v230, v230
	v_pk_fma_f32 v[200:201], v[210:211], s[62:63], v[226:227] op_sel_hi:[1,0,0]
	v_exp_f32_e32 v216, v216
	v_pk_fma_f32 v[200:201], v[210:211], v[200:201], s[66:67] op_sel_hi:[1,1,0]
	v_exp_f32_e32 v217, v217
	v_pk_fma_f32 v[200:201], v[210:211], v[200:201], s[68:69] op_sel_hi:[1,1,0]
	v_rcp_f32_e32 v231, v231
	v_pk_fma_f32 v[200:201], v[210:211], v[200:201], s[70:71] op_sel_hi:[1,1,0]
	v_pk_mul_f32 v[238:239], v[122:123], v[166:167] op_sel_hi:[1,0]
	v_pk_mul_f32 v[200:201], v[210:211], v[200:201]
	v_pk_mul_f32 v[210:211], v[228:229], v[228:229]
	v_pk_mul_f32 v[200:201], v[216:217], v[200:201]
	v_pk_mul_f32 v[210:211], v[210:211], s[72:73] op_sel_hi:[1,0]
	v_pk_mul_f32 v[232:233], v[206:207], v[200:201]
	v_pk_fma_f32 v[234:235], v[206:207], v[200:201], v[206:207] neg_lo:[1,0,0] neg_hi:[1,0,0]
	v_pk_fma_f32 v[200:201], v[230:231], s[62:63], v[226:227] op_sel_hi:[1,0,0]
	v_exp_f32_e32 v210, v210
	v_pk_fma_f32 v[200:201], v[230:231], v[200:201], s[66:67] op_sel_hi:[1,1,0]
	v_exp_f32_e32 v211, v211
	v_pk_fma_f32 v[200:201], v[230:231], v[200:201], s[68:69] op_sel_hi:[1,1,0]
	v_and_b32_e32 v243, 0x7fffffff, v239
	v_pk_fma_f32 v[200:201], v[230:231], v[200:201], s[70:71] op_sel_hi:[1,1,0]
	v_and_b32_e32 v242, 0x7fffffff, v238
	v_pk_mul_f32 v[200:201], v[230:231], v[200:201]
	v_pk_fma_f32 v[242:243], v[242:243], s[60:61], 1.0 op_sel_hi:[1,0,0]
	v_pk_mul_f32 v[200:201], v[210:211], v[200:201]
	v_pk_mul_f32 v[210:211], v[120:121], v[166:167] op_sel_hi:[1,0]
	v_pk_mul_f32 v[230:231], v[228:229], v[200:201]
	v_and_b32_e32 v217, 0x7fffffff, v211
	v_and_b32_e32 v216, 0x7fffffff, v210
	v_pk_fma_f32 v[216:217], v[216:217], s[60:61], 1.0 op_sel_hi:[1,0,0]
	v_pk_mul_f32 v[240:241], v[210:211], v[210:211]
	v_rcp_f32_e32 v216, v216
	v_rcp_f32_e32 v217, v217
	v_pk_fma_f32 v[236:237], v[228:229], v[200:201], v[228:229] neg_lo:[1,0,0] neg_hi:[1,0,0]
	v_pk_mul_f32 v[240:241], v[240:241], s[72:73] op_sel_hi:[1,0]
	v_rcp_f32_e32 v242, v242
	v_pk_fma_f32 v[200:201], v[216:217], s[62:63], v[226:227] op_sel_hi:[1,0,0]
	v_exp_f32_e32 v240, v240
	v_pk_fma_f32 v[200:201], v[216:217], v[200:201], s[66:67] op_sel_hi:[1,1,0]
	v_exp_f32_e32 v241, v241
	v_pk_fma_f32 v[200:201], v[216:217], v[200:201], s[68:69] op_sel_hi:[1,1,0]
	v_rcp_f32_e32 v243, v243
	v_pk_fma_f32 v[200:201], v[216:217], v[200:201], s[70:71] op_sel_hi:[1,1,0]
	v_cmp_gt_f32_e32 vcc, 0, v202
	v_pk_mul_f32 v[200:201], v[216:217], v[200:201]
	v_pk_mul_f32 v[216:217], v[238:239], v[238:239]
	v_pk_mul_f32 v[200:201], v[240:241], v[200:201]
	v_pk_mul_f32 v[216:217], v[216:217], s[72:73] op_sel_hi:[1,0]
	v_pk_mul_f32 v[240:241], v[210:211], v[200:201]
	v_pk_fma_f32 v[244:245], v[210:211], v[200:201], v[210:211] neg_lo:[1,0,0] neg_hi:[1,0,0]
	v_pk_fma_f32 v[200:201], v[242:243], s[62:63], v[226:227] op_sel_hi:[1,0,0]
	v_exp_f32_e32 v216, v216
	v_pk_fma_f32 v[200:201], v[242:243], v[200:201], s[66:67] op_sel_hi:[1,1,0]
	v_exp_f32_e32 v217, v217
	v_pk_fma_f32 v[200:201], v[242:243], v[200:201], s[68:69] op_sel_hi:[1,1,0]
	v_lshl_add_u64 v[198:199], v[134:135], 0, v[132:133]
	v_pk_fma_f32 v[200:201], v[242:243], v[200:201], s[70:71] op_sel_hi:[1,1,0]
	s_lshl_b32 s6, s33, 2
	v_pk_mul_f32 v[200:201], v[242:243], v[200:201]
	s_ashr_i32 s7, s6, 31
	v_pk_mul_f32 v[200:201], v[216:217], v[200:201]
	s_or_b64 s[80:81], s[6:7], s[26:27]
	v_pk_mul_f32 v[242:243], v[238:239], v[200:201]
	v_pk_fma_f32 v[246:247], v[238:239], v[200:201], v[238:239] neg_lo:[1,0,0] neg_hi:[1,0,0]
	v_cndmask_b32_e32 v200, v212, v208, vcc
	v_cmp_gt_f32_e32 vcc, 0, v210
	s_cmp_lt_u32 s96, 12
	s_nop 0
	v_cndmask_b32_e32 v201, v244, v240, vcc
	v_cmp_gt_f32_e32 vcc, 0, v203
	s_nop 1
	v_cndmask_b32_e32 v208, v213, v209, vcc
	v_cmp_gt_f32_e32 vcc, 0, v204
	v_cvt_pk_bf16_f32 v216, v200, v208
	s_nop 1
	v_cndmask_b32_e32 v202, v218, v214, vcc
	v_cmp_gt_f32_e32 vcc, 0, v211
	s_nop 1
	v_cndmask_b32_e32 v203, v245, v241, vcc
	v_cmp_gt_f32_e32 vcc, 0, v205
	s_nop 1
	v_cndmask_b32_e32 v210, v219, v215, vcc
	v_cmp_gt_f32_e32 vcc, 0, v206
	v_cvt_pk_bf16_f32 v217, v202, v210
	s_nop 1
	v_cndmask_b32_e32 v204, v234, v232, vcc
	v_cmp_gt_f32_e32 vcc, 0, v238
	s_nop 1
	v_cndmask_b32_e32 v205, v246, v242, vcc
	v_cmp_gt_f32_e32 vcc, 0, v207
	s_nop 1
	v_cndmask_b32_e32 v212, v235, v233, vcc
	v_cmp_gt_f32_e32 vcc, 0, v228
	v_cvt_pk_bf16_f32 v218, v204, v212
	s_nop 1
	v_cndmask_b32_e32 v206, v236, v230, vcc
	v_cmp_gt_f32_e32 vcc, 0, v239
	s_nop 1
	v_cndmask_b32_e32 v207, v247, v243, vcc
	v_cmp_gt_f32_e32 vcc, 0, v229
	v_pk_mul_f32 v[228:229], v[112:113], v[166:167] op_sel_hi:[1,0]
	s_nop 0
	v_cndmask_b32_e32 v214, v237, v231, vcc
	v_and_b32_e32 v231, 0x7fffffff, v229
	v_and_b32_e32 v230, 0x7fffffff, v228
	v_pk_fma_f32 v[230:231], v[230:231], s[60:61], 1.0 op_sel_hi:[1,0,0]
	v_cvt_pk_bf16_f32 v219, v206, v214
	global_store_dwordx4 v[198:199], v[216:219], off
	v_rcp_f32_e32 v230, v230
	v_rcp_f32_e32 v231, v231
	v_pk_mul_f32 v[218:219], v[114:115], v[166:167] op_sel_hi:[1,0]
	v_pk_mul_f32 v[232:233], v[228:229], v[228:229]
; __device__ __forceinline__ unsigned cvt_pk_bf16(float lo, float hi) { unsigned r; asm volatile("v_cvt_pk_bf16_f32 %0, %1, %2" : "=v"(r) : "v"(lo), "v"(hi)); return r; }
; __device__ __forceinline__ f32x4 gelu4(f32x4 v) { f32x2 a = gelu_pk((f32x2){v[0], v[1]}), b = gelu_pk((f32x2){v[2], v[3]}); return (f32x4){a.x, a.y, b.x, b.y}; }
;     __device__ __forceinline__ void operator()(const f32x4 (&acc)[2][2][4][2], const Unit& u, int wr, int wc, int fr, int fq) const {
;     ...
;                     for (int bj = 0; bj < 2; ++bj) { const f32x4 v0 = gelu4(acc[ai][bj][m][0] * sc), v1 = gelu4(acc[ai][bj][m][1] * sc);
;                         s1 += ((v0[0] + v0[1]) + (v0[2] + v0[3])) + ((v1[0] + v1[1]) + (v1[2] + v1[3]));
;                         s2 += ((v0[0] * v0[0] + v0[1] * v0[1]) + (v0[2] * v0[2] + v0[3] * v0[3])) + ((v1[0] * v1[0] + v1[1] * v1[1]) + (v1[2] * v1[2] + v1[3] * v1[3]));
;                         u32x4 w; w.x = cvt_pk_bf16(v0[0], v0[1]); w.y = cvt_pk_bf16(v0[2], v0[3]); w.z = cvt_pk_bf16(v1[0], v1[1]); w.w = cvt_pk_bf16(v1[2], v1[3]);
;                         *(u32x4*)(dst + (size_t)row * CCH + col0 + bj * HALF) = w; }
;                     if (isv) { s1 += __shfl_xor(s1, 16); s1 += __shfl_xor(s1, 32); s2 += __shfl_xor(s2, 16); s2 += __shfl_xor(s2, 32);
;                         if (fq == 0) *(f32x2*)(vstat + ((size_t)row * 16 + tq * 4 + wc) * 2) = (f32x2){s1, s2}; } }
	v_and_b32_e32 v235, 0x7fffffff, v219
	v_pk_fma_f32 v[216:217], v[230:231], s[62:63], v[226:227] op_sel_hi:[1,0,0]
	v_pk_mul_f32 v[232:233], v[232:233], s[72:73] op_sel_hi:[1,0]
	v_and_b32_e32 v234, 0x7fffffff, v218
	v_pk_fma_f32 v[216:217], v[230:231], v[216:217], s[66:67] op_sel_hi:[1,1,0]
	v_exp_f32_e32 v232, v232
	v_exp_f32_e32 v233, v233
	v_pk_fma_f32 v[234:235], v[234:235], s[60:61], 1.0 op_sel_hi:[1,0,0]
	v_pk_fma_f32 v[216:217], v[230:231], v[216:217], s[68:69] op_sel_hi:[1,1,0]
	v_rcp_f32_e32 v234, v234
	v_rcp_f32_e32 v235, v235
	v_pk_fma_f32 v[216:217], v[230:231], v[216:217], s[70:71] op_sel_hi:[1,1,0]
	v_cmp_gt_f32_e32 vcc, 0, v218
	v_pk_mul_f32 v[216:217], v[230:231], v[216:217]
	v_pk_mul_f32 v[230:231], v[218:219], v[218:219]
	v_pk_mul_f32 v[216:217], v[232:233], v[216:217]
	s_nop 0
	v_pk_mul_f32 v[232:233], v[228:229], v[216:217]
	v_pk_fma_f32 v[236:237], v[228:229], v[216:217], v[228:229] neg_lo:[1,0,0] neg_hi:[1,0,0]
	v_pk_fma_f32 v[216:217], v[234:235], s[62:63], v[226:227] op_sel_hi:[1,0,0]
	v_pk_mul_f32 v[226:227], v[230:231], s[72:73] op_sel_hi:[1,0]
	v_pk_fma_f32 v[216:217], v[234:235], v[216:217], s[66:67] op_sel_hi:[1,1,0]
	v_exp_f32_e32 v226, v226
	v_exp_f32_e32 v227, v227
	v_pk_fma_f32 v[216:217], v[234:235], v[216:217], s[68:69] op_sel_hi:[1,1,0]
	s_nop 0
	v_pk_fma_f32 v[216:217], v[234:235], v[216:217], s[70:71] op_sel_hi:[1,1,0]
	s_nop 0
	v_pk_mul_f32 v[216:217], v[234:235], v[216:217]
	s_nop 0
	v_pk_mul_f32 v[216:217], v[226:227], v[216:217]
	s_nop 0
	v_pk_mul_f32 v[226:227], v[218:219], v[216:217]
	v_pk_fma_f32 v[230:231], v[218:219], v[216:217], v[218:219] neg_lo:[1,0,0] neg_hi:[1,0,0]
	s_nop 0
	v_cndmask_b32_e32 v217, v230, v226, vcc
	v_cmp_gt_f32_e32 vcc, 0, v228
	v_cvt_pk_bf16_f32 v226, v201, v203
	s_nop 1
	v_cndmask_b32_e32 v216, v236, v232, vcc
	v_cmp_gt_f32_e32 vcc, 0, v219
	s_nop 1
	v_cndmask_b32_e32 v219, v231, v227, vcc
	v_cmp_gt_f32_e32 vcc, 0, v229
	v_cvt_pk_bf16_f32 v227, v205, v207
	s_nop 1
	v_cndmask_b32_e32 v218, v237, v233, vcc
	v_cvt_pk_bf16_f32 v228, v216, v218
	v_cvt_pk_bf16_f32 v229, v217, v219
	global_store_dwordx4 v[198:199], v[226:229], off offset:256
	s_cbranch_scc1 .LBB0_474
	v_mov_b32_e32 v209, v201
	v_mov_b32_e32 v211, v203
	v_pk_mul_f32 v[198:199], v[200:201], v[200:201]
	v_pk_mul_f32 v[226:227], v[208:209], v[208:209]
	v_pk_add_f32 v[240:241], v[200:201], v[208:209]
	v_pk_mul_f32 v[208:209], v[200:201], v[208:209]
	v_mov_b32_e32 v213, v205
	v_pk_mul_f32 v[228:229], v[202:203], v[202:203]
	v_pk_mul_f32 v[230:231], v[210:211], v[210:211]
	v_mov_b32_e32 v241, v209
	v_pk_add_f32 v[208:209], v[202:203], v[210:211]
	v_pk_mul_f32 v[210:211], v[202:203], v[210:211]
	v_pk_mov_b32 v[198:199], v[200:201], v[198:199] op_sel:[1,0]
	v_pk_mov_b32 v[200:201], v[202:203], v[226:227] op_sel:[1,0]
	v_mov_b32_e32 v215, v207
	v_pk_mul_f32 v[234:235], v[212:213], v[212:213]
	v_mov_b32_e32 v209, v211
	v_pk_add_f32 v[210:211], v[204:205], v[212:213]
	v_pk_mul_f32 v[212:213], v[204:205], v[212:213]
	v_pk_add_f32 v[198:199], v[198:199], v[200:201]
	v_pk_mov_b32 v[200:201], v[204:205], v[228:229] op_sel:[1,0]
	v_pk_mov_b32 v[202:203], v[206:207], v[230:231] op_sel:[1,0]
	v_pk_mul_f32 v[232:233], v[204:205], v[204:205]
	v_pk_mul_f32 v[238:239], v[214:215], v[214:215]
	v_mov_b32_e32 v211, v213
	v_pk_add_f32 v[212:213], v[206:207], v[214:215]
	v_pk_mul_f32 v[214:215], v[206:207], v[214:215]
	v_pk_add_f32 v[200:201], v[200:201], v[202:203]
	v_pk_mul_f32 v[236:237], v[206:207], v[206:207]
	v_mov_b32_e32 v213, v215
	v_pk_mul_f32 v[214:215], v[218:219], v[218:219]
	v_pk_add_f32 v[198:199], v[198:199], v[200:201]
	v_mov_b32_e32 v200, v216
	v_mov_b32_e32 v201, v232
	v_mov_b32_e32 v202, v218
	v_mov_b32_e32 v203, v234
	v_pk_fma_f32 v[214:215], v[216:217], v[216:217], v[214:215]
	v_pk_add_f32 v[200:201], v[200:201], v[202:203]
	v_pk_mov_b32 v[202:203], v[216:217], v[236:237] op_sel:[1,0]
	v_pk_mov_b32 v[204:205], v[218:219], v[238:239] op_sel:[1,0]
	v_pk_add_f32 v[214:215], v[214:215], v[214:215] op_sel_hi:[0,1]
	v_pk_add_f32 v[208:209], v[240:241], v[208:209]
	v_pk_add_f32 v[210:211], v[210:211], v[212:213]
	v_pk_add_f32 v[202:203], v[202:203], v[204:205]
	v_pk_add_f32 v[208:209], v[208:209], v[210:211]
	v_mov_b32_e32 v145, v215
	v_pk_add_f32 v[200:201], v[200:201], v[202:203]
	v_pk_add_f32 v[208:209], v[208:209], v[144:145]
	v_pk_add_f32 v[198:199], v[198:199], v[200:201]
	s_nop 0
	v_pk_add_f32 v[198:199], v[198:199], v[208:209]
	v_mov_b32_e32 v200, v198
	s_nop 1
	v_permlane16_swap_b32_e32 v198, v200
	s_nop 1
	v_mov_b32_e32 v201, v199
	s_nop 1
	v_permlane16_swap_b32_e32 v199, v201
	s_nop 1
	s_waitcnt lgkmcnt(0)
	v_pk_add_f32 v[198:199], v[198:199], v[200:201]
	v_mov_b32_e32 v200, v198
	s_nop 1
	v_permlane32_swap_b32_e32 v198, v200
	s_nop 1
	v_mov_b32_e32 v201, v199
	s_nop 1
	v_permlane32_swap_b32_e32 v199, v201
	s_nop 1
	s_and_saveexec_b64 s[6:7], s[2:3]
	s_cbranch_execz .LBB0_473
	v_lshl_add_u64 v[196:197], s[38:39], 0, v[196:197]
	v_lshl_add_u64 v[196:197], s[80:81], 3, v[196:197]
	s_waitcnt lgkmcnt(0)
	v_pk_add_f32 v[198:199], v[198:199], v[200:201]
	global_store_dwordx2 v[196:197], v[198:199], off

; __device__ __forceinline__ unsigned cvt_pk_bf16(float lo, float hi) { unsigned r; asm volatile("v_cvt_pk_bf16_f32 %0, %1, %2" : "=v"(r) : "v"(lo), "v"(hi)); return r; }
; __device__ __forceinline__ f32x2 gelu_pk(f32x2 v) {
;     const f32x2 av = __builtin_elementwise_abs(v), d = av * 0.2316418882f + 1.0f;
;     f32x2 t; t.x = __builtin_amdgcn_rcpf(d.x); t.y = __builtin_amdgcn_rcpf(d.y);
;     f32x2 q = t * 0.5307027145f + (-0.7265760135f); q = q * t + 0.7107068705f; q = q * t + (-0.142248368f); q = q * t + 0.127414796f; q = q * t;
;     const f32x2 s = (v * v) * (-0.72134752044f);
;     f32x2 e; e.x = __builtin_amdgcn_exp2f(s.x); e.y = __builtin_amdgcn_exp2f(s.y);
;     const f32x2 m = v * (q * e), r = v - m;
;     f32x2 o; o.x = v.x < 0.f ? m.x : r.x; o.y = v.y < 0.f ? m.y : r.y; return o;
; }
; __device__ __forceinline__ f32x4 gelu4(f32x4 v) { f32x2 a = gelu_pk((f32x2){v[0], v[1]}), b = gelu_pk((f32x2){v[2], v[3]}); return (f32x4){a.x, a.y, b.x, b.y}; }
;     __device__ __forceinline__ void operator()(const f32x4 (&acc)[2][2][4][2], const Unit& u, int wr, int wc, int fr, int fq) const {
;     ...
;                 for (int m = 0; m < 4; ++m) { const float sc = rs[ai][m]; const int row = row0 + ai * HALF + m * 16; float s1 = 0.f, s2 = 0.f;
; #pragma unroll
;                     for (int bj = 0; bj < 2; ++bj) { const f32x4 v0 = gelu4(acc[ai][bj][m][0] * sc), v1 = gelu4(acc[ai][bj][m][1] * sc);
;                         s1 += ((v0[0] + v0[1]) + (v0[2] + v0[3])) + ((v1[0] + v1[1]) + (v1[2] + v1[3]));
;                         s2 += ((v0[0] * v0[0] + v0[1] * v0[1]) + (v0[2] * v0[2] + v0[3] * v0[3])) + ((v1[0] * v1[0] + v1[1] * v1[1]) + (v1[2] * v1[2] + v1[3] * v1[3]));
;                         u32x4 w; w.x = cvt_pk_bf16(v0[0], v0[1]); w.y = cvt_pk_bf16(v0[2], v0[3]); w.z = cvt_pk_bf16(v1[0], v1[1]); w.w = cvt_pk_bf16(v1[2], v1[3]);
;                         *(u32x4*)(dst + (size_t)row * CCH + col0 + bj * HALF) = w; }
.LBB0_474:
	s_waitcnt lgkmcnt(0)
	v_pk_mul_f32 v[200:201], v[108:109], v[158:159] op_sel_hi:[1,0]
	v_pk_mul_f32 v[202:203], v[110:111], v[158:159] op_sel_hi:[1,0]
	v_and_b32_e32 v199, 0x7fffffff, v201
	v_and_b32_e32 v198, 0x7fffffff, v200
	v_pk_fma_f32 v[198:199], v[198:199], s[60:61], 1.0 op_sel_hi:[1,0,0]
	v_mov_b64_e32 v[218:219], s[64:65]
	v_rcp_f32_e32 v198, v198
	v_rcp_f32_e32 v199, v199
	v_pk_mul_f32 v[206:207], v[200:201], v[200:201]
	v_and_b32_e32 v209, 0x7fffffff, v203
	v_pk_mul_f32 v[206:207], v[206:207], s[72:73] op_sel_hi:[1,0]
	v_pk_fma_f32 v[204:205], v[198:199], s[62:63], v[218:219] op_sel_hi:[1,0,0]
	v_and_b32_e32 v208, 0x7fffffff, v202
	v_pk_fma_f32 v[204:205], v[198:199], v[204:205], s[66:67] op_sel_hi:[1,1,0]
	v_exp_f32_e32 v206, v206
	v_exp_f32_e32 v207, v207
	v_pk_fma_f32 v[208:209], v[208:209], s[60:61], 1.0 op_sel_hi:[1,0,0]
	v_pk_fma_f32 v[204:205], v[198:199], v[204:205], s[68:69] op_sel_hi:[1,1,0]
	v_rcp_f32_e32 v208, v208
	v_rcp_f32_e32 v209, v209
	v_pk_fma_f32 v[204:205], v[198:199], v[204:205], s[70:71] op_sel_hi:[1,1,0]
	v_pk_mul_f32 v[226:227], v[102:103], v[158:159] op_sel_hi:[1,0]
	v_pk_mul_f32 v[198:199], v[198:199], v[204:205]
	v_pk_mul_f32 v[204:205], v[202:203], v[202:203]
	v_pk_mul_f32 v[198:199], v[206:207], v[198:199]
	v_pk_mul_f32 v[204:205], v[204:205], s[72:73] op_sel_hi:[1,0]
	v_pk_mul_f32 v[206:207], v[200:201], v[198:199]
	v_pk_fma_f32 v[210:211], v[200:201], v[198:199], v[200:201] neg_lo:[1,0,0] neg_hi:[1,0,0]
	v_pk_fma_f32 v[198:199], v[208:209], s[62:63], v[218:219] op_sel_hi:[1,0,0]
	v_exp_f32_e32 v204, v204
	v_pk_fma_f32 v[198:199], v[208:209], v[198:199], s[66:67] op_sel_hi:[1,1,0]
	v_exp_f32_e32 v205, v205
	v_pk_fma_f32 v[198:199], v[208:209], v[198:199], s[68:69] op_sel_hi:[1,1,0]
	v_and_b32_e32 v229, 0x7fffffff, v227
	v_pk_fma_f32 v[198:199], v[208:209], v[198:199], s[70:71] op_sel_hi:[1,1,0]
	v_and_b32_e32 v228, 0x7fffffff, v226
	v_pk_mul_f32 v[198:199], v[208:209], v[198:199]
	v_pk_fma_f32 v[228:229], v[228:229], s[60:61], 1.0 op_sel_hi:[1,0,0]
	v_pk_mul_f32 v[198:199], v[204:205], v[198:199]
	v_pk_mul_f32 v[204:205], v[100:101], v[158:159] op_sel_hi:[1,0]
	v_pk_mul_f32 v[212:213], v[202:203], v[198:199]
	v_and_b32_e32 v209, 0x7fffffff, v205
	v_and_b32_e32 v208, 0x7fffffff, v204
	v_pk_fma_f32 v[208:209], v[208:209], s[60:61], 1.0 op_sel_hi:[1,0,0]
	v_pk_mul_f32 v[214:215], v[204:205], v[204:205]
	v_rcp_f32_e32 v208, v208
	v_rcp_f32_e32 v209, v209
	v_pk_fma_f32 v[216:217], v[202:203], v[198:199], v[202:203] neg_lo:[1,0,0] neg_hi:[1,0,0]
	v_pk_mul_f32 v[214:215], v[214:215], s[72:73] op_sel_hi:[1,0]
	v_rcp_f32_e32 v228, v228
	v_pk_fma_f32 v[198:199], v[208:209], s[62:63], v[218:219] op_sel_hi:[1,0,0]
	v_exp_f32_e32 v214, v214
	v_pk_fma_f32 v[198:199], v[208:209], v[198:199], s[66:67] op_sel_hi:[1,1,0]
	v_exp_f32_e32 v215, v215
	v_pk_fma_f32 v[198:199], v[208:209], v[198:199], s[68:69] op_sel_hi:[1,1,0]
	v_rcp_f32_e32 v229, v229
	v_pk_fma_f32 v[198:199], v[208:209], v[198:199], s[70:71] op_sel_hi:[1,1,0]
	v_pk_mul_f32 v[236:237], v[106:107], v[158:159] op_sel_hi:[1,0]
	v_pk_mul_f32 v[198:199], v[208:209], v[198:199]
	v_pk_mul_f32 v[208:209], v[226:227], v[226:227]
	v_pk_mul_f32 v[198:199], v[214:215], v[198:199]
	v_pk_mul_f32 v[208:209], v[208:209], s[72:73] op_sel_hi:[1,0]
	v_pk_mul_f32 v[230:231], v[204:205], v[198:199]
	v_pk_fma_f32 v[232:233], v[204:205], v[198:199], v[204:205] neg_lo:[1,0,0] neg_hi:[1,0,0]
	v_pk_fma_f32 v[198:199], v[228:229], s[62:63], v[218:219] op_sel_hi:[1,0,0]
	v_exp_f32_e32 v208, v208
	v_pk_fma_f32 v[198:199], v[228:229], v[198:199], s[66:67] op_sel_hi:[1,1,0]
	v_exp_f32_e32 v209, v209
	v_pk_fma_f32 v[198:199], v[228:229], v[198:199], s[68:69] op_sel_hi:[1,1,0]
	v_and_b32_e32 v241, 0x7fffffff, v237
	v_pk_fma_f32 v[198:199], v[228:229], v[198:199], s[70:71] op_sel_hi:[1,1,0]
	v_and_b32_e32 v240, 0x7fffffff, v236
	v_pk_mul_f32 v[198:199], v[228:229], v[198:199]
	v_pk_fma_f32 v[240:241], v[240:241], s[60:61], 1.0 op_sel_hi:[1,0,0]
	v_pk_mul_f32 v[198:199], v[208:209], v[198:199]
	v_pk_mul_f32 v[208:209], v[104:105], v[158:159] op_sel_hi:[1,0]
	v_pk_mul_f32 v[228:229], v[226:227], v[198:199]
	v_and_b32_e32 v215, 0x7fffffff, v209
	v_and_b32_e32 v214, 0x7fffffff, v208
	v_pk_fma_f32 v[214:215], v[214:215], s[60:61], 1.0 op_sel_hi:[1,0,0]
	v_pk_mul_f32 v[238:239], v[208:209], v[208:209]
	v_rcp_f32_e32 v214, v214
	v_rcp_f32_e32 v215, v215
	v_pk_fma_f32 v[234:235], v[226:227], v[198:199], v[226:227] neg_lo:[1,0,0] neg_hi:[1,0,0]
	v_pk_mul_f32 v[238:239], v[238:239], s[72:73] op_sel_hi:[1,0]
	v_rcp_f32_e32 v240, v240
	v_pk_fma_f32 v[198:199], v[214:215], s[62:63], v[218:219] op_sel_hi:[1,0,0]
	v_exp_f32_e32 v238, v238
	v_pk_fma_f32 v[198:199], v[214:215], v[198:199], s[66:67] op_sel_hi:[1,1,0]
	v_exp_f32_e32 v239, v239
	v_pk_fma_f32 v[198:199], v[214:215], v[198:199], s[68:69] op_sel_hi:[1,1,0]
	v_rcp_f32_e32 v241, v241
	v_pk_fma_f32 v[198:199], v[214:215], v[198:199], s[70:71] op_sel_hi:[1,1,0]
	v_cmp_gt_f32_e32 vcc, 0, v200
	v_pk_mul_f32 v[198:199], v[214:215], v[198:199]
	v_pk_mul_f32 v[214:215], v[236:237], v[236:237]
	v_pk_mul_f32 v[198:199], v[238:239], v[198:199]
	v_pk_mul_f32 v[214:215], v[214:215], s[72:73] op_sel_hi:[1,0]
	v_pk_mul_f32 v[238:239], v[208:209], v[198:199]
	v_pk_fma_f32 v[242:243], v[208:209], v[198:199], v[208:209] neg_lo:[1,0,0] neg_hi:[1,0,0]
	v_pk_fma_f32 v[198:199], v[240:241], s[62:63], v[218:219] op_sel_hi:[1,0,0]
	v_exp_f32_e32 v214, v214
	v_pk_fma_f32 v[198:199], v[240:241], v[198:199], s[66:67] op_sel_hi:[1,1,0]
	v_exp_f32_e32 v215, v215
	v_pk_fma_f32 v[198:199], v[240:241], v[198:199], s[68:69] op_sel_hi:[1,1,0]
; __device__ __forceinline__ unsigned cvt_pk_bf16(float lo, float hi) { unsigned r; asm volatile("v_cvt_pk_bf16_f32 %0, %1, %2" : "=v"(r) : "v"(lo), "v"(hi)); return r; }
; __device__ __forceinline__ f32x4 gelu4(f32x4 v) { f32x2 a = gelu_pk((f32x2){v[0], v[1]}), b = gelu_pk((f32x2){v[2], v[3]}); return (f32x4){a.x, a.y, b.x, b.y}; }
;     __device__ __forceinline__ void operator()(const f32x4 (&acc)[2][2][4][2], const Unit& u, int wr, int wc, int fr, int fq) const {
;     ...
;                     for (int bj = 0; bj < 2; ++bj) { const f32x4 v0 = gelu4(acc[ai][bj][m][0] * sc), v1 = gelu4(acc[ai][bj][m][1] * sc);
;                         s1 += ((v0[0] + v0[1]) + (v0[2] + v0[3])) + ((v1[0] + v1[1]) + (v1[2] + v1[3]));
;                         s2 += ((v0[0] * v0[0] + v0[1] * v0[1]) + (v0[2] * v0[2] + v0[3] * v0[3])) + ((v1[0] * v1[0] + v1[1] * v1[1]) + (v1[2] * v1[2] + v1[3] * v1[3]));
;                         u32x4 w; w.x = cvt_pk_bf16(v0[0], v0[1]); w.y = cvt_pk_bf16(v0[2], v0[3]); w.z = cvt_pk_bf16(v1[0], v1[1]); w.w = cvt_pk_bf16(v1[2], v1[3]);
;                         *(u32x4*)(dst + (size_t)row * CCH + col0 + bj * HALF) = w; }
;                     if (isv) { s1 += __shfl_xor(s1, 16); s1 += __shfl_xor(s1, 32); s2 += __shfl_xor(s2, 16); s2 += __shfl_xor(s2, 32);
	v_lshlrev_b64 v[196:197], 11, v[156:157]
	v_pk_fma_f32 v[198:199], v[240:241], v[198:199], s[70:71] op_sel_hi:[1,1,0]
	v_lshl_add_u64 v[196:197], v[134:135], 0, v[196:197]
	v_pk_mul_f32 v[198:199], v[240:241], v[198:199]
	v_cndmask_b32_e64 v129, 0, 1, s[82:83]
	v_pk_mul_f32 v[198:199], v[214:215], v[198:199]
	v_cmp_ne_u32_e64 s[6:7], 1, v129
	v_pk_mul_f32 v[240:241], v[236:237], v[198:199]
	v_pk_fma_f32 v[244:245], v[236:237], v[198:199], v[236:237] neg_lo:[1,0,0] neg_hi:[1,0,0]
	v_cndmask_b32_e32 v198, v210, v206, vcc
	v_cmp_gt_f32_e32 vcc, 0, v208
	s_nop 1
	v_cndmask_b32_e32 v199, v242, v238, vcc
	v_cmp_gt_f32_e32 vcc, 0, v201
	s_nop 1
	v_cndmask_b32_e32 v206, v211, v207, vcc
	v_cmp_gt_f32_e32 vcc, 0, v202
	v_cvt_pk_bf16_f32 v214, v198, v206
	s_nop 1
	v_cndmask_b32_e32 v200, v216, v212, vcc
	v_cmp_gt_f32_e32 vcc, 0, v209
	s_nop 1
	v_cndmask_b32_e32 v201, v243, v239, vcc
	v_cmp_gt_f32_e32 vcc, 0, v203
	s_nop 1
	v_cndmask_b32_e32 v208, v217, v213, vcc
	v_cmp_gt_f32_e32 vcc, 0, v204
	v_cvt_pk_bf16_f32 v215, v200, v208
	s_nop 1
	v_cndmask_b32_e32 v202, v232, v230, vcc
	v_cmp_gt_f32_e32 vcc, 0, v236
	s_nop 1
	v_cndmask_b32_e32 v203, v244, v240, vcc
	v_cmp_gt_f32_e32 vcc, 0, v205
	s_nop 1
	v_cndmask_b32_e32 v210, v233, v231, vcc
	v_cmp_gt_f32_e32 vcc, 0, v226
	v_cvt_pk_bf16_f32 v216, v202, v210
	s_nop 1
	v_cndmask_b32_e32 v204, v234, v228, vcc
	v_cmp_gt_f32_e32 vcc, 0, v237
	s_nop 1
	v_cndmask_b32_e32 v205, v245, v241, vcc
	v_cmp_gt_f32_e32 vcc, 0, v227
	v_pk_mul_f32 v[226:227], v[96:97], v[158:159] op_sel_hi:[1,0]
	s_nop 0
	v_cndmask_b32_e32 v212, v235, v229, vcc
	v_and_b32_e32 v229, 0x7fffffff, v227
	v_and_b32_e32 v228, 0x7fffffff, v226
	v_pk_fma_f32 v[228:229], v[228:229], s[60:61], 1.0 op_sel_hi:[1,0,0]
	v_cvt_pk_bf16_f32 v217, v204, v212
	global_store_dwordx4 v[196:197], v[214:217], off
	v_rcp_f32_e32 v228, v228
	v_rcp_f32_e32 v229, v229
	v_pk_mul_f32 v[216:217], v[98:99], v[158:159] op_sel_hi:[1,0]
	v_pk_mul_f32 v[230:231], v[226:227], v[226:227]
	v_and_b32_e32 v233, 0x7fffffff, v217
	v_pk_fma_f32 v[214:215], v[228:229], s[62:63], v[218:219] op_sel_hi:[1,0,0]
	v_pk_mul_f32 v[230:231], v[230:231], s[72:73] op_sel_hi:[1,0]
	v_and_b32_e32 v232, 0x7fffffff, v216
	v_pk_fma_f32 v[214:215], v[228:229], v[214:215], s[66:67] op_sel_hi:[1,1,0]
	v_exp_f32_e32 v230, v230
	v_exp_f32_e32 v231, v231
	v_pk_fma_f32 v[232:233], v[232:233], s[60:61], 1.0 op_sel_hi:[1,0,0]
	v_pk_fma_f32 v[214:215], v[228:229], v[214:215], s[68:69] op_sel_hi:[1,1,0]
	v_rcp_f32_e32 v232, v232
	v_rcp_f32_e32 v233, v233
	v_pk_fma_f32 v[214:215], v[228:229], v[214:215], s[70:71] op_sel_hi:[1,1,0]
	v_cmp_gt_f32_e32 vcc, 0, v216
	v_pk_mul_f32 v[214:215], v[228:229], v[214:215]
	v_pk_mul_f32 v[228:229], v[216:217], v[216:217]
	v_pk_mul_f32 v[214:215], v[230:231], v[214:215]
	s_nop 0
	v_pk_mul_f32 v[230:231], v[226:227], v[214:215]
	v_pk_fma_f32 v[234:235], v[226:227], v[214:215], v[226:227] neg_lo:[1,0,0] neg_hi:[1,0,0]
	v_pk_fma_f32 v[214:215], v[232:233], s[62:63], v[218:219] op_sel_hi:[1,0,0]
	v_pk_mul_f32 v[218:219], v[228:229], s[72:73] op_sel_hi:[1,0]
	v_pk_fma_f32 v[214:215], v[232:233], v[214:215], s[66:67] op_sel_hi:[1,1,0]
	v_exp_f32_e32 v218, v218
	v_exp_f32_e32 v219, v219
	v_pk_fma_f32 v[214:215], v[232:233], v[214:215], s[68:69] op_sel_hi:[1,1,0]
	s_nop 0
	v_pk_fma_f32 v[214:215], v[232:233], v[214:215], s[70:71] op_sel_hi:[1,1,0]
	s_nop 0
	v_pk_mul_f32 v[214:215], v[232:233], v[214:215]
	s_nop 0
	v_pk_mul_f32 v[214:215], v[218:219], v[214:215]
	s_nop 0
	v_pk_mul_f32 v[218:219], v[216:217], v[214:215]
	v_pk_fma_f32 v[228:229], v[216:217], v[214:215], v[216:217] neg_lo:[1,0,0] neg_hi:[1,0,0]
	s_nop 0
	v_cndmask_b32_e32 v215, v228, v218, vcc
	v_cmp_gt_f32_e32 vcc, 0, v226
	v_cvt_pk_bf16_f32 v226, v199, v201
	s_nop 1
	v_cndmask_b32_e32 v214, v234, v230, vcc
	v_cmp_gt_f32_e32 vcc, 0, v217
	s_nop 1
	v_cndmask_b32_e32 v217, v229, v219, vcc
	v_cmp_gt_f32_e32 vcc, 0, v227
	v_cvt_pk_bf16_f32 v227, v203, v205
	s_nop 1
	v_cndmask_b32_e32 v216, v235, v231, vcc
	s_andn2_b64 vcc, exec, s[82:83]
	v_cvt_pk_bf16_f32 v228, v214, v216
	v_cvt_pk_bf16_f32 v229, v215, v217
	global_store_dwordx4 v[196:197], v[226:229], off offset:256
	s_cbranch_vccnz .LBB0_478
; __device__ __forceinline__ unsigned cvt_pk_bf16(float lo, float hi) { unsigned r; asm volatile("v_cvt_pk_bf16_f32 %0, %1, %2" : "=v"(r) : "v"(lo), "v"(hi)); return r; }
;     __device__ __forceinline__ void operator()(const f32x4 (&acc)[2][2][4][2], const Unit& u, int wr, int wc, int fr, int fq) const {
;     ...
;                         s1 += ((v0[0] + v0[1]) + (v0[2] + v0[3])) + ((v1[0] + v1[1]) + (v1[2] + v1[3]));
;                         s2 += ((v0[0] * v0[0] + v0[1] * v0[1]) + (v0[2] * v0[2] + v0[3] * v0[3])) + ((v1[0] * v1[0] + v1[1] * v1[1]) + (v1[2] * v1[2] + v1[3] * v1[3]));
;                         u32x4 w; w.x = cvt_pk_bf16(v0[0], v0[1]); w.y = cvt_pk_bf16(v0[2], v0[3]); w.z = cvt_pk_bf16(v1[0], v1[1]); w.w = cvt_pk_bf16(v1[2], v1[3]);
;                         *(u32x4*)(dst + (size_t)row * CCH + col0 + bj * HALF) = w; }
;                     if (isv) { s1 += __shfl_xor(s1, 16); s1 += __shfl_xor(s1, 32); s2 += __shfl_xor(s2, 16); s2 += __shfl_xor(s2, 32);
;                         if (fq == 0) *(f32x2*)(vstat + ((size_t)row * 16 + tq * 4 + wc) * 2) = (f32x2){s1, s2}; } }
	v_mov_b32_e32 v207, v199
	v_mov_b32_e32 v209, v201
	v_pk_mul_f32 v[196:197], v[198:199], v[198:199]
	v_pk_mul_f32 v[218:219], v[206:207], v[206:207]
	v_pk_add_f32 v[238:239], v[198:199], v[206:207]
	v_pk_mul_f32 v[206:207], v[198:199], v[206:207]
	v_mov_b32_e32 v211, v203
	v_pk_mul_f32 v[226:227], v[200:201], v[200:201]
	v_pk_mul_f32 v[228:229], v[208:209], v[208:209]
	v_mov_b32_e32 v239, v207
	v_pk_add_f32 v[206:207], v[200:201], v[208:209]
	v_pk_mul_f32 v[208:209], v[200:201], v[208:209]
	v_pk_mov_b32 v[196:197], v[198:199], v[196:197] op_sel:[1,0]
	v_pk_mov_b32 v[198:199], v[200:201], v[218:219] op_sel:[1,0]
	v_mov_b32_e32 v213, v205
	v_pk_mul_f32 v[232:233], v[210:211], v[210:211]
	v_mov_b32_e32 v207, v209
	v_pk_add_f32 v[208:209], v[202:203], v[210:211]
	v_pk_mul_f32 v[210:211], v[202:203], v[210:211]
	v_pk_add_f32 v[196:197], v[196:197], v[198:199]
	v_pk_mov_b32 v[198:199], v[202:203], v[226:227] op_sel:[1,0]
	v_pk_mov_b32 v[200:201], v[204:205], v[228:229] op_sel:[1,0]
	v_pk_mul_f32 v[230:231], v[202:203], v[202:203]
	v_pk_mul_f32 v[236:237], v[212:213], v[212:213]
	v_mov_b32_e32 v209, v211
	v_pk_add_f32 v[210:211], v[204:205], v[212:213]
	v_pk_mul_f32 v[212:213], v[204:205], v[212:213]
	v_pk_add_f32 v[198:199], v[198:199], v[200:201]
	v_pk_mul_f32 v[234:235], v[204:205], v[204:205]
	v_mov_b32_e32 v211, v213
	v_pk_mul_f32 v[212:213], v[216:217], v[216:217]
	v_pk_add_f32 v[196:197], v[196:197], v[198:199]
	v_mov_b32_e32 v198, v214
	v_mov_b32_e32 v199, v230
	v_mov_b32_e32 v200, v216
	v_mov_b32_e32 v201, v232
	v_pk_fma_f32 v[212:213], v[214:215], v[214:215], v[212:213]
	v_pk_add_f32 v[198:199], v[198:199], v[200:201]
	v_pk_mov_b32 v[200:201], v[214:215], v[234:235] op_sel:[1,0]
	v_pk_mov_b32 v[202:203], v[216:217], v[236:237] op_sel:[1,0]
	v_pk_add_f32 v[212:213], v[212:213], v[212:213] op_sel_hi:[0,1]
	v_pk_add_f32 v[206:207], v[238:239], v[206:207]
	v_pk_add_f32 v[208:209], v[208:209], v[210:211]
	v_pk_add_f32 v[200:201], v[200:201], v[202:203]
	v_pk_add_f32 v[206:207], v[206:207], v[208:209]
	v_mov_b32_e32 v145, v213
	v_pk_add_f32 v[198:199], v[198:199], v[200:201]
	v_pk_add_f32 v[206:207], v[206:207], v[144:145]
	v_pk_add_f32 v[196:197], v[196:197], v[198:199]
	s_nop 0
	v_pk_add_f32 v[196:197], v[196:197], v[206:207]
	v_mov_b32_e32 v198, v196
	s_nop 1
	v_permlane16_swap_b32_e32 v196, v198
	s_nop 1
	v_mov_b32_e32 v199, v197
	s_nop 1
	v_permlane16_swap_b32_e32 v197, v199
	s_nop 1
	s_waitcnt lgkmcnt(0)
	v_pk_add_f32 v[196:197], v[196:197], v[198:199]
	v_mov_b32_e32 v198, v196
	s_nop 1
	v_permlane32_swap_b32_e32 v196, v198
	s_nop 1
	v_mov_b32_e32 v199, v197
	s_nop 1
	v_permlane32_swap_b32_e32 v197, v199
	s_nop 1
	s_and_saveexec_b64 s[82:83], s[2:3]
	s_cbranch_execz .LBB0_477
	v_lshl_add_u64 v[194:195], s[38:39], 0, v[194:195]
	v_lshl_add_u64 v[194:195], s[80:81], 3, v[194:195]
	s_waitcnt lgkmcnt(0)
	v_pk_add_f32 v[196:197], v[196:197], v[198:199]
	global_store_dwordx2 v[194:195], v[196:197], off

; __device__ __forceinline__ unsigned cvt_pk_bf16(float lo, float hi) { unsigned r; asm volatile("v_cvt_pk_bf16_f32 %0, %1, %2" : "=v"(r) : "v"(lo), "v"(hi)); return r; }
; __device__ __forceinline__ f32x2 gelu_pk(f32x2 v) {
;     const f32x2 av = __builtin_elementwise_abs(v), d = av * 0.2316418882f + 1.0f;
;     f32x2 t; t.x = __builtin_amdgcn_rcpf(d.x); t.y = __builtin_amdgcn_rcpf(d.y);
;     f32x2 q = t * 0.5307027145f + (-0.7265760135f); q = q * t + 0.7107068705f; q = q * t + (-0.142248368f); q = q * t + 0.127414796f; q = q * t;
;     const f32x2 s = (v * v) * (-0.72134752044f);
;     f32x2 e; e.x = __builtin_amdgcn_exp2f(s.x); e.y = __builtin_amdgcn_exp2f(s.y);
;     const f32x2 m = v * (q * e), r = v - m;
;     f32x2 o; o.x = v.x < 0.f ? m.x : r.x; o.y = v.y < 0.f ? m.y : r.y; return o;
; }
; __device__ __forceinline__ f32x4 gelu4(f32x4 v) { f32x2 a = gelu_pk((f32x2){v[0], v[1]}), b = gelu_pk((f32x2){v[2], v[3]}); return (f32x4){a.x, a.y, b.x, b.y}; }
;     __device__ __forceinline__ void operator()(const f32x4 (&acc)[2][2][4][2], const Unit& u, int wr, int wc, int fr, int fq) const {
;     ...
;                 for (int m = 0; m < 4; ++m) { const float sc = rs[ai][m]; const int row = row0 + ai * HALF + m * 16; float s1 = 0.f, s2 = 0.f;
; #pragma unroll
;                     for (int bj = 0; bj < 2; ++bj) { const f32x4 v0 = gelu4(acc[ai][bj][m][0] * sc), v1 = gelu4(acc[ai][bj][m][1] * sc);
;                         s1 += ((v0[0] + v0[1]) + (v0[2] + v0[3])) + ((v1[0] + v1[1]) + (v1[2] + v1[3]));
;                         s2 += ((v0[0] * v0[0] + v0[1] * v0[1]) + (v0[2] * v0[2] + v0[3] * v0[3])) + ((v1[0] * v1[0] + v1[1] * v1[1]) + (v1[2] * v1[2] + v1[3] * v1[3]));
;                         u32x4 w; w.x = cvt_pk_bf16(v0[0], v0[1]); w.y = cvt_pk_bf16(v0[2], v0[3]); w.z = cvt_pk_bf16(v1[0], v1[1]); w.w = cvt_pk_bf16(v1[2], v1[3]);
;                         *(u32x4*)(dst + (size_t)row * CCH + col0 + bj * HALF) = w; }
.LBB0_478:
	s_waitcnt lgkmcnt(0)
	v_pk_mul_f32 v[198:199], v[92:93], v[172:173] op_sel_hi:[1,0]
	v_pk_mul_f32 v[200:201], v[94:95], v[172:173] op_sel_hi:[1,0]
	v_and_b32_e32 v197, 0x7fffffff, v199
	v_and_b32_e32 v196, 0x7fffffff, v198
	v_pk_fma_f32 v[196:197], v[196:197], s[60:61], 1.0 op_sel_hi:[1,0,0]
	v_mov_b64_e32 v[216:217], s[64:65]
	v_rcp_f32_e32 v196, v196
	v_rcp_f32_e32 v197, v197
	v_pk_mul_f32 v[204:205], v[198:199], v[198:199]
	v_and_b32_e32 v207, 0x7fffffff, v201
	v_pk_mul_f32 v[204:205], v[204:205], s[72:73] op_sel_hi:[1,0]
	v_pk_fma_f32 v[202:203], v[196:197], s[62:63], v[216:217] op_sel_hi:[1,0,0]
	v_and_b32_e32 v206, 0x7fffffff, v200
	v_pk_fma_f32 v[202:203], v[196:197], v[202:203], s[66:67] op_sel_hi:[1,1,0]
	v_exp_f32_e32 v204, v204
	v_exp_f32_e32 v205, v205
	v_pk_fma_f32 v[206:207], v[206:207], s[60:61], 1.0 op_sel_hi:[1,0,0]
	v_pk_fma_f32 v[202:203], v[196:197], v[202:203], s[68:69] op_sel_hi:[1,1,0]
	v_rcp_f32_e32 v206, v206
	v_rcp_f32_e32 v207, v207
	v_pk_fma_f32 v[202:203], v[196:197], v[202:203], s[70:71] op_sel_hi:[1,1,0]
	v_pk_mul_f32 v[218:219], v[86:87], v[172:173] op_sel_hi:[1,0]
	v_pk_mul_f32 v[196:197], v[196:197], v[202:203]
	v_pk_mul_f32 v[202:203], v[200:201], v[200:201]
	v_pk_mul_f32 v[196:197], v[204:205], v[196:197]
	v_pk_mul_f32 v[202:203], v[202:203], s[72:73] op_sel_hi:[1,0]
	v_pk_mul_f32 v[204:205], v[198:199], v[196:197]
	v_pk_fma_f32 v[208:209], v[198:199], v[196:197], v[198:199] neg_lo:[1,0,0] neg_hi:[1,0,0]
	v_pk_fma_f32 v[196:197], v[206:207], s[62:63], v[216:217] op_sel_hi:[1,0,0]
	v_exp_f32_e32 v202, v202
	v_pk_fma_f32 v[196:197], v[206:207], v[196:197], s[66:67] op_sel_hi:[1,1,0]
	v_exp_f32_e32 v203, v203
	v_pk_fma_f32 v[196:197], v[206:207], v[196:197], s[68:69] op_sel_hi:[1,1,0]
	v_and_b32_e32 v227, 0x7fffffff, v219
	v_pk_fma_f32 v[196:197], v[206:207], v[196:197], s[70:71] op_sel_hi:[1,1,0]
	v_and_b32_e32 v226, 0x7fffffff, v218
	v_pk_mul_f32 v[196:197], v[206:207], v[196:197]
	v_pk_fma_f32 v[226:227], v[226:227], s[60:61], 1.0 op_sel_hi:[1,0,0]
	v_pk_mul_f32 v[196:197], v[202:203], v[196:197]
	v_pk_mul_f32 v[202:203], v[84:85], v[172:173] op_sel_hi:[1,0]
	v_pk_mul_f32 v[210:211], v[200:201], v[196:197]
	v_and_b32_e32 v207, 0x7fffffff, v203
	v_and_b32_e32 v206, 0x7fffffff, v202
	v_pk_fma_f32 v[206:207], v[206:207], s[60:61], 1.0 op_sel_hi:[1,0,0]
	v_pk_mul_f32 v[212:213], v[202:203], v[202:203]
	v_rcp_f32_e32 v206, v206
	v_rcp_f32_e32 v207, v207
	v_pk_fma_f32 v[214:215], v[200:201], v[196:197], v[200:201] neg_lo:[1,0,0] neg_hi:[1,0,0]
	v_pk_mul_f32 v[212:213], v[212:213], s[72:73] op_sel_hi:[1,0]
	v_rcp_f32_e32 v226, v226
	v_pk_fma_f32 v[196:197], v[206:207], s[62:63], v[216:217] op_sel_hi:[1,0,0]
	v_exp_f32_e32 v212, v212
	v_pk_fma_f32 v[196:197], v[206:207], v[196:197], s[66:67] op_sel_hi:[1,1,0]
	v_exp_f32_e32 v213, v213
	v_pk_fma_f32 v[196:197], v[206:207], v[196:197], s[68:69] op_sel_hi:[1,1,0]
	v_rcp_f32_e32 v227, v227
	v_pk_fma_f32 v[196:197], v[206:207], v[196:197], s[70:71] op_sel_hi:[1,1,0]
	v_pk_mul_f32 v[234:235], v[90:91], v[172:173] op_sel_hi:[1,0]
	v_pk_mul_f32 v[196:197], v[206:207], v[196:197]
	v_pk_mul_f32 v[206:207], v[218:219], v[218:219]
	v_pk_mul_f32 v[196:197], v[212:213], v[196:197]
	v_pk_mul_f32 v[206:207], v[206:207], s[72:73] op_sel_hi:[1,0]
	v_pk_mul_f32 v[228:229], v[202:203], v[196:197]
	v_pk_fma_f32 v[230:231], v[202:203], v[196:197], v[202:203] neg_lo:[1,0,0] neg_hi:[1,0,0]
	v_pk_fma_f32 v[196:197], v[226:227], s[62:63], v[216:217] op_sel_hi:[1,0,0]
	v_exp_f32_e32 v206, v206
	v_pk_fma_f32 v[196:197], v[226:227], v[196:197], s[66:67] op_sel_hi:[1,1,0]
	v_exp_f32_e32 v207, v207
	v_pk_fma_f32 v[196:197], v[226:227], v[196:197], s[68:69] op_sel_hi:[1,1,0]
	v_and_b32_e32 v239, 0x7fffffff, v235
	v_pk_fma_f32 v[196:197], v[226:227], v[196:197], s[70:71] op_sel_hi:[1,1,0]
	v_and_b32_e32 v238, 0x7fffffff, v234
	v_pk_mul_f32 v[196:197], v[226:227], v[196:197]
	v_pk_fma_f32 v[238:239], v[238:239], s[60:61], 1.0 op_sel_hi:[1,0,0]
	v_pk_mul_f32 v[196:197], v[206:207], v[196:197]
	v_pk_mul_f32 v[206:207], v[88:89], v[172:173] op_sel_hi:[1,0]
	v_pk_mul_f32 v[226:227], v[218:219], v[196:197]
	v_and_b32_e32 v213, 0x7fffffff, v207
	v_and_b32_e32 v212, 0x7fffffff, v206
	v_pk_fma_f32 v[212:213], v[212:213], s[60:61], 1.0 op_sel_hi:[1,0,0]
	v_pk_mul_f32 v[236:237], v[206:207], v[206:207]
	v_rcp_f32_e32 v212, v212
	v_rcp_f32_e32 v213, v213
	v_pk_fma_f32 v[232:233], v[218:219], v[196:197], v[218:219] neg_lo:[1,0,0] neg_hi:[1,0,0]
	v_pk_mul_f32 v[236:237], v[236:237], s[72:73] op_sel_hi:[1,0]
	v_rcp_f32_e32 v238, v238
	v_pk_fma_f32 v[196:197], v[212:213], s[62:63], v[216:217] op_sel_hi:[1,0,0]
	v_exp_f32_e32 v236, v236
	v_pk_fma_f32 v[196:197], v[212:213], v[196:197], s[66:67] op_sel_hi:[1,1,0]
	v_exp_f32_e32 v237, v237
	v_pk_fma_f32 v[196:197], v[212:213], v[196:197], s[68:69] op_sel_hi:[1,1,0]
	v_rcp_f32_e32 v239, v239
	v_pk_fma_f32 v[196:197], v[212:213], v[196:197], s[70:71] op_sel_hi:[1,1,0]
	v_cmp_gt_f32_e32 vcc, 0, v198
	v_pk_mul_f32 v[196:197], v[212:213], v[196:197]
	v_pk_mul_f32 v[212:213], v[234:235], v[234:235]
	v_pk_mul_f32 v[196:197], v[236:237], v[196:197]
	v_pk_mul_f32 v[212:213], v[212:213], s[72:73] op_sel_hi:[1,0]
	v_pk_mul_f32 v[236:237], v[206:207], v[196:197]
	v_pk_fma_f32 v[240:241], v[206:207], v[196:197], v[206:207] neg_lo:[1,0,0] neg_hi:[1,0,0]
	v_pk_fma_f32 v[196:197], v[238:239], s[62:63], v[216:217] op_sel_hi:[1,0,0]
	v_exp_f32_e32 v212, v212
	v_pk_fma_f32 v[196:197], v[238:239], v[196:197], s[66:67] op_sel_hi:[1,1,0]
	v_exp_f32_e32 v213, v213
	v_pk_fma_f32 v[196:197], v[238:239], v[196:197], s[68:69] op_sel_hi:[1,1,0]
	v_lshlrev_b64 v[194:195], 11, v[162:163]
; __device__ __forceinline__ unsigned cvt_pk_bf16(float lo, float hi) { unsigned r; asm volatile("v_cvt_pk_bf16_f32 %0, %1, %2" : "=v"(r) : "v"(lo), "v"(hi)); return r; }
; __device__ __forceinline__ f32x4 gelu4(f32x4 v) { f32x2 a = gelu_pk((f32x2){v[0], v[1]}), b = gelu_pk((f32x2){v[2], v[3]}); return (f32x4){a.x, a.y, b.x, b.y}; }
;     __device__ __forceinline__ void operator()(const f32x4 (&acc)[2][2][4][2], const Unit& u, int wr, int wc, int fr, int fq) const {
;     ...
;                     for (int bj = 0; bj < 2; ++bj) { const f32x4 v0 = gelu4(acc[ai][bj][m][0] * sc), v1 = gelu4(acc[ai][bj][m][1] * sc);
;                         s1 += ((v0[0] + v0[1]) + (v0[2] + v0[3])) + ((v1[0] + v1[1]) + (v1[2] + v1[3]));
;                         s2 += ((v0[0] * v0[0] + v0[1] * v0[1]) + (v0[2] * v0[2] + v0[3] * v0[3])) + ((v1[0] * v1[0] + v1[1] * v1[1]) + (v1[2] * v1[2] + v1[3] * v1[3]));
;                         u32x4 w; w.x = cvt_pk_bf16(v0[0], v0[1]); w.y = cvt_pk_bf16(v0[2], v0[3]); w.z = cvt_pk_bf16(v1[0], v1[1]); w.w = cvt_pk_bf16(v1[2], v1[3]);
;                         *(u32x4*)(dst + (size_t)row * CCH + col0 + bj * HALF) = w; }
;                     if (isv) { s1 += __shfl_xor(s1, 16); s1 += __shfl_xor(s1, 32); s2 += __shfl_xor(s2, 16); s2 += __shfl_xor(s2, 32);
;                         if (fq == 0) *(f32x2*)(vstat + ((size_t)row * 16 + tq * 4 + wc) * 2) = (f32x2){s1, s2}; } }
	v_pk_fma_f32 v[196:197], v[238:239], v[196:197], s[70:71] op_sel_hi:[1,1,0]
	v_lshl_add_u64 v[194:195], v[134:135], 0, v[194:195]
	v_pk_mul_f32 v[196:197], v[238:239], v[196:197]
	s_nop 0
	v_pk_mul_f32 v[196:197], v[212:213], v[196:197]
	s_nop 0
	v_pk_mul_f32 v[238:239], v[234:235], v[196:197]
	v_pk_fma_f32 v[242:243], v[234:235], v[196:197], v[234:235] neg_lo:[1,0,0] neg_hi:[1,0,0]
	v_cndmask_b32_e32 v196, v208, v204, vcc
	v_cmp_gt_f32_e32 vcc, 0, v206
	s_nop 1
	v_cndmask_b32_e32 v197, v240, v236, vcc
	v_cmp_gt_f32_e32 vcc, 0, v199
	s_nop 1
	v_cndmask_b32_e32 v204, v209, v205, vcc
	v_cmp_gt_f32_e32 vcc, 0, v200
	v_cvt_pk_bf16_f32 v212, v196, v204
	s_nop 1
	v_cndmask_b32_e32 v198, v214, v210, vcc
	v_cmp_gt_f32_e32 vcc, 0, v207
	s_nop 1
	v_cndmask_b32_e32 v199, v241, v237, vcc
	v_cmp_gt_f32_e32 vcc, 0, v201
	s_nop 1
	v_cndmask_b32_e32 v206, v215, v211, vcc
	v_cmp_gt_f32_e32 vcc, 0, v202
	v_cvt_pk_bf16_f32 v213, v198, v206
	s_nop 1
	v_cndmask_b32_e32 v200, v230, v228, vcc
	v_cmp_gt_f32_e32 vcc, 0, v234
	s_nop 1
	v_cndmask_b32_e32 v201, v242, v238, vcc
	v_cmp_gt_f32_e32 vcc, 0, v203
	s_nop 1
	v_cndmask_b32_e32 v208, v231, v229, vcc
	v_cmp_gt_f32_e32 vcc, 0, v218
	v_cvt_pk_bf16_f32 v214, v200, v208
	s_nop 1
	v_cndmask_b32_e32 v202, v232, v226, vcc
	v_cmp_gt_f32_e32 vcc, 0, v235
	s_nop 1
	v_cndmask_b32_e32 v203, v243, v239, vcc
	v_cmp_gt_f32_e32 vcc, 0, v219
	v_pk_mul_f32 v[218:219], v[80:81], v[172:173] op_sel_hi:[1,0]
	s_nop 0
	v_cndmask_b32_e32 v210, v233, v227, vcc
	v_and_b32_e32 v227, 0x7fffffff, v219
	v_and_b32_e32 v226, 0x7fffffff, v218
	v_pk_fma_f32 v[226:227], v[226:227], s[60:61], 1.0 op_sel_hi:[1,0,0]
	v_cvt_pk_bf16_f32 v215, v202, v210
	global_store_dwordx4 v[194:195], v[212:215], off
	v_rcp_f32_e32 v226, v226
	v_rcp_f32_e32 v227, v227
	v_pk_mul_f32 v[214:215], v[82:83], v[172:173] op_sel_hi:[1,0]
	v_pk_mul_f32 v[228:229], v[218:219], v[218:219]
	v_and_b32_e32 v231, 0x7fffffff, v215
	v_pk_fma_f32 v[212:213], v[226:227], s[62:63], v[216:217] op_sel_hi:[1,0,0]
	v_pk_mul_f32 v[228:229], v[228:229], s[72:73] op_sel_hi:[1,0]
	v_and_b32_e32 v230, 0x7fffffff, v214
	v_pk_fma_f32 v[212:213], v[226:227], v[212:213], s[66:67] op_sel_hi:[1,1,0]
	v_exp_f32_e32 v228, v228
	v_exp_f32_e32 v229, v229
	v_pk_fma_f32 v[230:231], v[230:231], s[60:61], 1.0 op_sel_hi:[1,0,0]
	v_pk_fma_f32 v[212:213], v[226:227], v[212:213], s[68:69] op_sel_hi:[1,1,0]
	v_rcp_f32_e32 v230, v230
	v_rcp_f32_e32 v231, v231
	v_pk_fma_f32 v[212:213], v[226:227], v[212:213], s[70:71] op_sel_hi:[1,1,0]
	v_cmp_gt_f32_e32 vcc, 0, v214
	v_pk_mul_f32 v[212:213], v[226:227], v[212:213]
	v_pk_mul_f32 v[226:227], v[214:215], v[214:215]
	v_pk_mul_f32 v[212:213], v[228:229], v[212:213]
	s_nop 0
	v_pk_mul_f32 v[228:229], v[218:219], v[212:213]
	v_pk_fma_f32 v[232:233], v[218:219], v[212:213], v[218:219] neg_lo:[1,0,0] neg_hi:[1,0,0]
	v_pk_fma_f32 v[212:213], v[230:231], s[62:63], v[216:217] op_sel_hi:[1,0,0]
	v_pk_mul_f32 v[216:217], v[226:227], s[72:73] op_sel_hi:[1,0]
	v_pk_fma_f32 v[212:213], v[230:231], v[212:213], s[66:67] op_sel_hi:[1,1,0]
	v_exp_f32_e32 v216, v216
	v_exp_f32_e32 v217, v217
	v_pk_fma_f32 v[212:213], v[230:231], v[212:213], s[68:69] op_sel_hi:[1,1,0]
	s_nop 0
	v_pk_fma_f32 v[212:213], v[230:231], v[212:213], s[70:71] op_sel_hi:[1,1,0]
	s_nop 0
	v_pk_mul_f32 v[212:213], v[230:231], v[212:213]
	s_nop 0
	v_pk_mul_f32 v[212:213], v[216:217], v[212:213]
	s_nop 0
	v_pk_mul_f32 v[216:217], v[214:215], v[212:213]
	v_pk_fma_f32 v[226:227], v[214:215], v[212:213], v[214:215] neg_lo:[1,0,0] neg_hi:[1,0,0]
	s_nop 0
	v_cndmask_b32_e32 v213, v226, v216, vcc
	v_cmp_gt_f32_e32 vcc, 0, v218
	v_cvt_pk_bf16_f32 v216, v197, v199
	s_nop 1
	v_cndmask_b32_e32 v212, v232, v228, vcc
	v_cmp_gt_f32_e32 vcc, 0, v215
	s_nop 1
	v_cndmask_b32_e32 v215, v227, v217, vcc
	v_cmp_gt_f32_e32 vcc, 0, v219
	v_cvt_pk_bf16_f32 v217, v201, v203
	s_nop 1
	v_cndmask_b32_e32 v214, v233, v229, vcc
	s_and_b64 vcc, exec, s[6:7]
	v_cvt_pk_bf16_f32 v218, v212, v214
	v_cvt_pk_bf16_f32 v219, v213, v215
	global_store_dwordx4 v[194:195], v[216:219], off offset:256
	s_cbranch_vccnz .LBB0_482
	v_mov_b32_e32 v205, v197
	v_mov_b32_e32 v207, v199
	v_pk_mul_f32 v[194:195], v[196:197], v[196:197]
	v_pk_mul_f32 v[216:217], v[204:205], v[204:205]
	v_pk_add_f32 v[236:237], v[196:197], v[204:205]
	v_pk_mul_f32 v[204:205], v[196:197], v[204:205]
	v_mov_b32_e32 v209, v201
	v_pk_mul_f32 v[218:219], v[198:199], v[198:199]
	v_pk_mul_f32 v[226:227], v[206:207], v[206:207]
	v_mov_b32_e32 v237, v205
	v_pk_add_f32 v[204:205], v[198:199], v[206:207]
	v_pk_mul_f32 v[206:207], v[198:199], v[206:207]
	v_pk_mov_b32 v[194:195], v[196:197], v[194:195] op_sel:[1,0]
	v_pk_mov_b32 v[196:197], v[198:199], v[216:217] op_sel:[1,0]
	v_mov_b32_e32 v211, v203
	v_pk_mul_f32 v[230:231], v[208:209], v[208:209]
	v_mov_b32_e32 v205, v207
	v_pk_add_f32 v[206:207], v[200:201], v[208:209]
	v_pk_mul_f32 v[208:209], v[200:201], v[208:209]
	v_pk_add_f32 v[194:195], v[194:195], v[196:197]
	v_pk_mov_b32 v[196:197], v[200:201], v[218:219] op_sel:[1,0]
	v_pk_mov_b32 v[198:199], v[202:203], v[226:227] op_sel:[1,0]
	v_pk_mul_f32 v[228:229], v[200:201], v[200:201]
	v_pk_mul_f32 v[234:235], v[210:211], v[210:211]
	v_mov_b32_e32 v207, v209
	v_pk_add_f32 v[208:209], v[202:203], v[210:211]
	v_pk_mul_f32 v[210:211], v[202:203], v[210:211]
	v_pk_add_f32 v[196:197], v[196:197], v[198:199]
	v_pk_mul_f32 v[232:233], v[202:203], v[202:203]
	v_mov_b32_e32 v209, v211
	v_pk_mul_f32 v[210:211], v[214:215], v[214:215]
	v_pk_add_f32 v[194:195], v[194:195], v[196:197]
	v_mov_b32_e32 v196, v212
	v_mov_b32_e32 v197, v228
	v_mov_b32_e32 v198, v214
	v_mov_b32_e32 v199, v230
	v_pk_fma_f32 v[210:211], v[212:213], v[212:213], v[210:211]
	v_pk_add_f32 v[196:197], v[196:197], v[198:199]
	v_pk_mov_b32 v[198:199], v[212:213], v[232:233] op_sel:[1,0]
	v_pk_mov_b32 v[200:201], v[214:215], v[234:235] op_sel:[1,0]
	v_pk_add_f32 v[210:211], v[210:211], v[210:211] op_sel_hi:[0,1]
	v_pk_add_f32 v[204:205], v[236:237], v[204:205]
	v_pk_add_f32 v[206:207], v[206:207], v[208:209]
	v_pk_add_f32 v[198:199], v[198:199], v[200:201]
	v_pk_add_f32 v[204:205], v[204:205], v[206:207]
	v_mov_b32_e32 v145, v211
	v_pk_add_f32 v[196:197], v[196:197], v[198:199]
	v_pk_add_f32 v[204:205], v[204:205], v[144:145]
	v_pk_add_f32 v[194:195], v[194:195], v[196:197]
	s_nop 0
	v_pk_add_f32 v[194:195], v[194:195], v[204:205]
	v_mov_b32_e32 v196, v194
	s_nop 1
	v_permlane16_swap_b32_e32 v194, v196
	s_nop 1
	v_mov_b32_e32 v197, v195
	s_nop 1
	v_permlane16_swap_b32_e32 v195, v197
	s_nop 1
	s_waitcnt lgkmcnt(0)
	v_pk_add_f32 v[194:195], v[194:195], v[196:197]
	v_mov_b32_e32 v196, v194
	s_nop 1
	v_permlane32_swap_b32_e32 v194, v196
	s_nop 1
	v_mov_b32_e32 v197, v195
	s_nop 1
	v_permlane32_swap_b32_e32 v195, v197
	s_nop 1
	s_and_saveexec_b64 s[82:83], s[2:3]
	s_cbranch_execz .LBB0_481
	v_lshl_add_u64 v[192:193], s[38:39], 0, v[192:193]
	v_lshl_add_u64 v[192:193], s[80:81], 3, v[192:193]
	s_waitcnt lgkmcnt(0)
	v_pk_add_f32 v[194:195], v[194:195], v[196:197]
	global_store_dwordx2 v[192:193], v[194:195], off

; __device__ __forceinline__ unsigned cvt_pk_bf16(float lo, float hi) { unsigned r; asm volatile("v_cvt_pk_bf16_f32 %0, %1, %2" : "=v"(r) : "v"(lo), "v"(hi)); return r; }
; __device__ __forceinline__ f32x2 gelu_pk(f32x2 v) {
;     const f32x2 av = __builtin_elementwise_abs(v), d = av * 0.2316418882f + 1.0f;
;     f32x2 t; t.x = __builtin_amdgcn_rcpf(d.x); t.y = __builtin_amdgcn_rcpf(d.y);
;     f32x2 q = t * 0.5307027145f + (-0.7265760135f); q = q * t + 0.7107068705f; q = q * t + (-0.142248368f); q = q * t + 0.127414796f; q = q * t;
;     const f32x2 s = (v * v) * (-0.72134752044f);
;     f32x2 e; e.x = __builtin_amdgcn_exp2f(s.x); e.y = __builtin_amdgcn_exp2f(s.y);
;     const f32x2 m = v * (q * e), r = v - m;
;     f32x2 o; o.x = v.x < 0.f ? m.x : r.x; o.y = v.y < 0.f ? m.y : r.y; return o;
; }
; __device__ __forceinline__ f32x4 gelu4(f32x4 v) { f32x2 a = gelu_pk((f32x2){v[0], v[1]}), b = gelu_pk((f32x2){v[2], v[3]}); return (f32x4){a.x, a.y, b.x, b.y}; }
;     __device__ __forceinline__ void operator()(const f32x4 (&acc)[2][2][4][2], const Unit& u, int wr, int wc, int fr, int fq) const {
;     ...
;                 for (int m = 0; m < 4; ++m) { const float sc = rs[ai][m]; const int row = row0 + ai * HALF + m * 16; float s1 = 0.f, s2 = 0.f;
; #pragma unroll
;                     for (int bj = 0; bj < 2; ++bj) { const f32x4 v0 = gelu4(acc[ai][bj][m][0] * sc), v1 = gelu4(acc[ai][bj][m][1] * sc);
;                         s1 += ((v0[0] + v0[1]) + (v0[2] + v0[3])) + ((v1[0] + v1[1]) + (v1[2] + v1[3]));
;                         s2 += ((v0[0] * v0[0] + v0[1] * v0[1]) + (v0[2] * v0[2] + v0[3] * v0[3])) + ((v1[0] * v1[0] + v1[1] * v1[1]) + (v1[2] * v1[2] + v1[3] * v1[3]));
;                         u32x4 w; w.x = cvt_pk_bf16(v0[0], v0[1]); w.y = cvt_pk_bf16(v0[2], v0[3]); w.z = cvt_pk_bf16(v1[0], v1[1]); w.w = cvt_pk_bf16(v1[2], v1[3]);
;                         *(u32x4*)(dst + (size_t)row * CCH + col0 + bj * HALF) = w; }
.LBB0_482:
	s_waitcnt lgkmcnt(0)
	v_pk_mul_f32 v[196:197], v[76:77], v[164:165] op_sel_hi:[1,0]
	v_pk_mul_f32 v[198:199], v[78:79], v[164:165] op_sel_hi:[1,0]
	v_and_b32_e32 v195, 0x7fffffff, v197
	v_and_b32_e32 v194, 0x7fffffff, v196
	v_pk_fma_f32 v[194:195], v[194:195], s[60:61], 1.0 op_sel_hi:[1,0,0]
	v_mov_b64_e32 v[214:215], s[64:65]
	v_rcp_f32_e32 v194, v194
	v_rcp_f32_e32 v195, v195
	v_pk_mul_f32 v[202:203], v[196:197], v[196:197]
	v_and_b32_e32 v205, 0x7fffffff, v199
	v_pk_mul_f32 v[202:203], v[202:203], s[72:73] op_sel_hi:[1,0]
	v_pk_fma_f32 v[200:201], v[194:195], s[62:63], v[214:215] op_sel_hi:[1,0,0]
	v_and_b32_e32 v204, 0x7fffffff, v198
	v_pk_fma_f32 v[200:201], v[194:195], v[200:201], s[66:67] op_sel_hi:[1,1,0]
	v_exp_f32_e32 v202, v202
	v_exp_f32_e32 v203, v203
	v_pk_fma_f32 v[204:205], v[204:205], s[60:61], 1.0 op_sel_hi:[1,0,0]
	v_pk_fma_f32 v[200:201], v[194:195], v[200:201], s[68:69] op_sel_hi:[1,1,0]
	v_rcp_f32_e32 v204, v204
	v_rcp_f32_e32 v205, v205
	v_pk_fma_f32 v[200:201], v[194:195], v[200:201], s[70:71] op_sel_hi:[1,1,0]
	v_pk_mul_f32 v[216:217], v[70:71], v[164:165] op_sel_hi:[1,0]
	v_pk_mul_f32 v[194:195], v[194:195], v[200:201]
	v_pk_mul_f32 v[200:201], v[198:199], v[198:199]
	v_pk_mul_f32 v[194:195], v[202:203], v[194:195]
	v_pk_mul_f32 v[200:201], v[200:201], s[72:73] op_sel_hi:[1,0]
	v_pk_mul_f32 v[202:203], v[196:197], v[194:195]
	v_pk_fma_f32 v[206:207], v[196:197], v[194:195], v[196:197] neg_lo:[1,0,0] neg_hi:[1,0,0]
	v_pk_fma_f32 v[194:195], v[204:205], s[62:63], v[214:215] op_sel_hi:[1,0,0]
	v_exp_f32_e32 v200, v200
	v_pk_fma_f32 v[194:195], v[204:205], v[194:195], s[66:67] op_sel_hi:[1,1,0]
	v_exp_f32_e32 v201, v201
	v_pk_fma_f32 v[194:195], v[204:205], v[194:195], s[68:69] op_sel_hi:[1,1,0]
	v_and_b32_e32 v219, 0x7fffffff, v217
	v_pk_fma_f32 v[194:195], v[204:205], v[194:195], s[70:71] op_sel_hi:[1,1,0]
	v_and_b32_e32 v218, 0x7fffffff, v216
	v_pk_mul_f32 v[194:195], v[204:205], v[194:195]
	v_pk_fma_f32 v[218:219], v[218:219], s[60:61], 1.0 op_sel_hi:[1,0,0]
	v_pk_mul_f32 v[194:195], v[200:201], v[194:195]
	v_pk_mul_f32 v[200:201], v[68:69], v[164:165] op_sel_hi:[1,0]
	v_pk_mul_f32 v[208:209], v[198:199], v[194:195]
	v_and_b32_e32 v205, 0x7fffffff, v201
	v_and_b32_e32 v204, 0x7fffffff, v200
	v_pk_fma_f32 v[204:205], v[204:205], s[60:61], 1.0 op_sel_hi:[1,0,0]
	v_pk_mul_f32 v[210:211], v[200:201], v[200:201]
	v_rcp_f32_e32 v204, v204
	v_rcp_f32_e32 v205, v205
	v_pk_fma_f32 v[212:213], v[198:199], v[194:195], v[198:199] neg_lo:[1,0,0] neg_hi:[1,0,0]
	v_pk_mul_f32 v[210:211], v[210:211], s[72:73] op_sel_hi:[1,0]
	v_rcp_f32_e32 v218, v218
	v_pk_fma_f32 v[194:195], v[204:205], s[62:63], v[214:215] op_sel_hi:[1,0,0]
	v_exp_f32_e32 v210, v210
	v_pk_fma_f32 v[194:195], v[204:205], v[194:195], s[66:67] op_sel_hi:[1,1,0]
	v_exp_f32_e32 v211, v211
	v_pk_fma_f32 v[194:195], v[204:205], v[194:195], s[68:69] op_sel_hi:[1,1,0]
	v_rcp_f32_e32 v219, v219
	v_pk_fma_f32 v[194:195], v[204:205], v[194:195], s[70:71] op_sel_hi:[1,1,0]
	v_pk_mul_f32 v[232:233], v[74:75], v[164:165] op_sel_hi:[1,0]
	v_pk_mul_f32 v[194:195], v[204:205], v[194:195]
	v_pk_mul_f32 v[204:205], v[216:217], v[216:217]
	v_pk_mul_f32 v[194:195], v[210:211], v[194:195]
	v_pk_mul_f32 v[204:205], v[204:205], s[72:73] op_sel_hi:[1,0]
	v_pk_mul_f32 v[226:227], v[200:201], v[194:195]
	v_pk_fma_f32 v[228:229], v[200:201], v[194:195], v[200:201] neg_lo:[1,0,0] neg_hi:[1,0,0]
	v_pk_fma_f32 v[194:195], v[218:219], s[62:63], v[214:215] op_sel_hi:[1,0,0]
	v_exp_f32_e32 v204, v204
	v_pk_fma_f32 v[194:195], v[218:219], v[194:195], s[66:67] op_sel_hi:[1,1,0]
	v_exp_f32_e32 v205, v205
	v_pk_fma_f32 v[194:195], v[218:219], v[194:195], s[68:69] op_sel_hi:[1,1,0]
	v_and_b32_e32 v237, 0x7fffffff, v233
	v_pk_fma_f32 v[194:195], v[218:219], v[194:195], s[70:71] op_sel_hi:[1,1,0]
	v_and_b32_e32 v236, 0x7fffffff, v232
	v_pk_mul_f32 v[194:195], v[218:219], v[194:195]
	v_pk_fma_f32 v[236:237], v[236:237], s[60:61], 1.0 op_sel_hi:[1,0,0]
	v_pk_mul_f32 v[194:195], v[204:205], v[194:195]
	v_pk_mul_f32 v[204:205], v[72:73], v[164:165] op_sel_hi:[1,0]
	v_pk_mul_f32 v[218:219], v[216:217], v[194:195]
	v_and_b32_e32 v211, 0x7fffffff, v205
	v_and_b32_e32 v210, 0x7fffffff, v204
	v_pk_fma_f32 v[210:211], v[210:211], s[60:61], 1.0 op_sel_hi:[1,0,0]
	v_pk_mul_f32 v[234:235], v[204:205], v[204:205]
	v_rcp_f32_e32 v210, v210
	v_rcp_f32_e32 v211, v211
	v_pk_fma_f32 v[230:231], v[216:217], v[194:195], v[216:217] neg_lo:[1,0,0] neg_hi:[1,0,0]
	v_pk_mul_f32 v[234:235], v[234:235], s[72:73] op_sel_hi:[1,0]
	v_rcp_f32_e32 v236, v236
	v_pk_fma_f32 v[194:195], v[210:211], s[62:63], v[214:215] op_sel_hi:[1,0,0]
	v_exp_f32_e32 v234, v234
	v_pk_fma_f32 v[194:195], v[210:211], v[194:195], s[66:67] op_sel_hi:[1,1,0]
	v_exp_f32_e32 v235, v235
	v_pk_fma_f32 v[194:195], v[210:211], v[194:195], s[68:69] op_sel_hi:[1,1,0]
	v_rcp_f32_e32 v237, v237
	v_pk_fma_f32 v[194:195], v[210:211], v[194:195], s[70:71] op_sel_hi:[1,1,0]
	v_cmp_gt_f32_e32 vcc, 0, v196
	v_pk_mul_f32 v[194:195], v[210:211], v[194:195]
	v_pk_mul_f32 v[210:211], v[232:233], v[232:233]
	v_pk_mul_f32 v[194:195], v[234:235], v[194:195]
	v_pk_mul_f32 v[210:211], v[210:211], s[72:73] op_sel_hi:[1,0]
	v_pk_mul_f32 v[234:235], v[204:205], v[194:195]
	v_pk_fma_f32 v[238:239], v[204:205], v[194:195], v[204:205] neg_lo:[1,0,0] neg_hi:[1,0,0]
	v_pk_fma_f32 v[194:195], v[236:237], s[62:63], v[214:215] op_sel_hi:[1,0,0]
	v_exp_f32_e32 v210, v210
	v_pk_fma_f32 v[194:195], v[236:237], v[194:195], s[66:67] op_sel_hi:[1,1,0]
	v_exp_f32_e32 v211, v211
	v_pk_fma_f32 v[194:195], v[236:237], v[194:195], s[68:69] op_sel_hi:[1,1,0]
	v_lshlrev_b64 v[192:193], 11, v[160:161]
; __device__ __forceinline__ unsigned cvt_pk_bf16(float lo, float hi) { unsigned r; asm volatile("v_cvt_pk_bf16_f32 %0, %1, %2" : "=v"(r) : "v"(lo), "v"(hi)); return r; }
; __device__ __forceinline__ f32x4 gelu4(f32x4 v) { f32x2 a = gelu_pk((f32x2){v[0], v[1]}), b = gelu_pk((f32x2){v[2], v[3]}); return (f32x4){a.x, a.y, b.x, b.y}; }
;     __device__ __forceinline__ void operator()(const f32x4 (&acc)[2][2][4][2], const Unit& u, int wr, int wc, int fr, int fq) const {
;     ...
;                     for (int bj = 0; bj < 2; ++bj) { const f32x4 v0 = gelu4(acc[ai][bj][m][0] * sc), v1 = gelu4(acc[ai][bj][m][1] * sc);
;                         s1 += ((v0[0] + v0[1]) + (v0[2] + v0[3])) + ((v1[0] + v1[1]) + (v1[2] + v1[3]));
;                         s2 += ((v0[0] * v0[0] + v0[1] * v0[1]) + (v0[2] * v0[2] + v0[3] * v0[3])) + ((v1[0] * v1[0] + v1[1] * v1[1]) + (v1[2] * v1[2] + v1[3] * v1[3]));
;                         u32x4 w; w.x = cvt_pk_bf16(v0[0], v0[1]); w.y = cvt_pk_bf16(v0[2], v0[3]); w.z = cvt_pk_bf16(v1[0], v1[1]); w.w = cvt_pk_bf16(v1[2], v1[3]);
;                         *(u32x4*)(dst + (size_t)row * CCH + col0 + bj * HALF) = w; }
;                     if (isv) { s1 += __shfl_xor(s1, 16); s1 += __shfl_xor(s1, 32); s2 += __shfl_xor(s2, 16); s2 += __shfl_xor(s2, 32);
;                         if (fq == 0) *(f32x2*)(vstat + ((size_t)row * 16 + tq * 4 + wc) * 2) = (f32x2){s1, s2}; } }
	v_pk_fma_f32 v[194:195], v[236:237], v[194:195], s[70:71] op_sel_hi:[1,1,0]
	v_lshl_add_u64 v[192:193], v[134:135], 0, v[192:193]
	v_pk_mul_f32 v[194:195], v[236:237], v[194:195]
	s_nop 0
	v_pk_mul_f32 v[194:195], v[210:211], v[194:195]
	s_nop 0
	v_pk_mul_f32 v[236:237], v[232:233], v[194:195]
	v_pk_fma_f32 v[240:241], v[232:233], v[194:195], v[232:233] neg_lo:[1,0,0] neg_hi:[1,0,0]
	v_cndmask_b32_e32 v194, v206, v202, vcc
	v_cmp_gt_f32_e32 vcc, 0, v204
	s_nop 1
	v_cndmask_b32_e32 v195, v238, v234, vcc
	v_cmp_gt_f32_e32 vcc, 0, v197
	s_nop 1
	v_cndmask_b32_e32 v202, v207, v203, vcc
	v_cmp_gt_f32_e32 vcc, 0, v198
	v_cvt_pk_bf16_f32 v210, v194, v202
	s_nop 1
	v_cndmask_b32_e32 v196, v212, v208, vcc
	v_cmp_gt_f32_e32 vcc, 0, v205
	s_nop 1
	v_cndmask_b32_e32 v197, v239, v235, vcc
	v_cmp_gt_f32_e32 vcc, 0, v199
	s_nop 1
	v_cndmask_b32_e32 v204, v213, v209, vcc
	v_cmp_gt_f32_e32 vcc, 0, v200
	v_cvt_pk_bf16_f32 v211, v196, v204
	s_nop 1
	v_cndmask_b32_e32 v198, v228, v226, vcc
	v_cmp_gt_f32_e32 vcc, 0, v232
	s_nop 1
	v_cndmask_b32_e32 v199, v240, v236, vcc
	v_cmp_gt_f32_e32 vcc, 0, v201
	s_nop 1
	v_cndmask_b32_e32 v206, v229, v227, vcc
	v_cmp_gt_f32_e32 vcc, 0, v216
	v_cvt_pk_bf16_f32 v212, v198, v206
	s_nop 1
	v_cndmask_b32_e32 v200, v230, v218, vcc
	v_cmp_gt_f32_e32 vcc, 0, v233
	s_nop 1
	v_cndmask_b32_e32 v201, v241, v237, vcc
	v_cmp_gt_f32_e32 vcc, 0, v217
	v_pk_mul_f32 v[216:217], v[64:65], v[164:165] op_sel_hi:[1,0]
	s_nop 0
	v_cndmask_b32_e32 v208, v231, v219, vcc
	v_and_b32_e32 v219, 0x7fffffff, v217
	v_and_b32_e32 v218, 0x7fffffff, v216
	v_pk_fma_f32 v[218:219], v[218:219], s[60:61], 1.0 op_sel_hi:[1,0,0]
	v_cvt_pk_bf16_f32 v213, v200, v208
	global_store_dwordx4 v[192:193], v[210:213], off
	v_rcp_f32_e32 v218, v218
	v_rcp_f32_e32 v219, v219
	v_pk_mul_f32 v[212:213], v[66:67], v[164:165] op_sel_hi:[1,0]
	v_pk_mul_f32 v[226:227], v[216:217], v[216:217]
	v_and_b32_e32 v229, 0x7fffffff, v213
	v_pk_fma_f32 v[210:211], v[218:219], s[62:63], v[214:215] op_sel_hi:[1,0,0]
	v_pk_mul_f32 v[226:227], v[226:227], s[72:73] op_sel_hi:[1,0]
	v_and_b32_e32 v228, 0x7fffffff, v212
	v_pk_fma_f32 v[210:211], v[218:219], v[210:211], s[66:67] op_sel_hi:[1,1,0]
	v_exp_f32_e32 v226, v226
	v_exp_f32_e32 v227, v227
	v_pk_fma_f32 v[228:229], v[228:229], s[60:61], 1.0 op_sel_hi:[1,0,0]
	v_pk_fma_f32 v[210:211], v[218:219], v[210:211], s[68:69] op_sel_hi:[1,1,0]
	v_rcp_f32_e32 v228, v228
	v_rcp_f32_e32 v229, v229
	v_pk_fma_f32 v[210:211], v[218:219], v[210:211], s[70:71] op_sel_hi:[1,1,0]
	v_cmp_gt_f32_e32 vcc, 0, v212
	v_pk_mul_f32 v[210:211], v[218:219], v[210:211]
	v_pk_mul_f32 v[218:219], v[212:213], v[212:213]
	v_pk_mul_f32 v[210:211], v[226:227], v[210:211]
	s_nop 0
	v_pk_mul_f32 v[226:227], v[216:217], v[210:211]
	v_pk_fma_f32 v[230:231], v[216:217], v[210:211], v[216:217] neg_lo:[1,0,0] neg_hi:[1,0,0]
	v_pk_fma_f32 v[210:211], v[228:229], s[62:63], v[214:215] op_sel_hi:[1,0,0]
	v_pk_mul_f32 v[214:215], v[218:219], s[72:73] op_sel_hi:[1,0]
	v_pk_fma_f32 v[210:211], v[228:229], v[210:211], s[66:67] op_sel_hi:[1,1,0]
	v_exp_f32_e32 v214, v214
	v_exp_f32_e32 v215, v215
	v_pk_fma_f32 v[210:211], v[228:229], v[210:211], s[68:69] op_sel_hi:[1,1,0]
	s_nop 0
	v_pk_fma_f32 v[210:211], v[228:229], v[210:211], s[70:71] op_sel_hi:[1,1,0]
	s_nop 0
	v_pk_mul_f32 v[210:211], v[228:229], v[210:211]
	s_nop 0
	v_pk_mul_f32 v[210:211], v[214:215], v[210:211]
	s_nop 0
	v_pk_mul_f32 v[214:215], v[212:213], v[210:211]
	v_pk_fma_f32 v[218:219], v[212:213], v[210:211], v[212:213] neg_lo:[1,0,0] neg_hi:[1,0,0]
	s_nop 0
	v_cndmask_b32_e32 v211, v218, v214, vcc
	v_cmp_gt_f32_e32 vcc, 0, v216
	v_cvt_pk_bf16_f32 v214, v195, v197
	s_nop 1
	v_cndmask_b32_e32 v210, v230, v226, vcc
	v_cmp_gt_f32_e32 vcc, 0, v213
	s_nop 1
	v_cndmask_b32_e32 v213, v219, v215, vcc
	v_cmp_gt_f32_e32 vcc, 0, v217
	v_cvt_pk_bf16_f32 v215, v199, v201
	s_nop 1
	v_cndmask_b32_e32 v212, v231, v227, vcc
	s_and_b64 vcc, exec, s[6:7]
	v_cvt_pk_bf16_f32 v216, v210, v212
	v_cvt_pk_bf16_f32 v217, v211, v213
	global_store_dwordx4 v[192:193], v[214:217], off offset:256
	s_cbranch_vccnz .LBB0_486
	v_mov_b32_e32 v203, v195
	v_mov_b32_e32 v205, v197
	v_pk_mul_f32 v[192:193], v[194:195], v[194:195]
	v_pk_mul_f32 v[214:215], v[202:203], v[202:203]
	v_pk_add_f32 v[234:235], v[194:195], v[202:203]
	v_pk_mul_f32 v[202:203], v[194:195], v[202:203]
	v_mov_b32_e32 v207, v199
	v_pk_mul_f32 v[216:217], v[196:197], v[196:197]
	v_pk_mul_f32 v[218:219], v[204:205], v[204:205]
	v_mov_b32_e32 v235, v203
	v_pk_add_f32 v[202:203], v[196:197], v[204:205]
	v_pk_mul_f32 v[204:205], v[196:197], v[204:205]
	v_pk_mov_b32 v[192:193], v[194:195], v[192:193] op_sel:[1,0]
	v_pk_mov_b32 v[194:195], v[196:197], v[214:215] op_sel:[1,0]
	v_mov_b32_e32 v209, v201
	v_pk_mul_f32 v[228:229], v[206:207], v[206:207]
	v_mov_b32_e32 v203, v205
	v_pk_add_f32 v[204:205], v[198:199], v[206:207]
	v_pk_mul_f32 v[206:207], v[198:199], v[206:207]
	v_pk_add_f32 v[192:193], v[192:193], v[194:195]
	v_pk_mov_b32 v[194:195], v[198:199], v[216:217] op_sel:[1,0]
	v_pk_mov_b32 v[196:197], v[200:201], v[218:219] op_sel:[1,0]
	v_pk_mul_f32 v[226:227], v[198:199], v[198:199]
	v_pk_mul_f32 v[232:233], v[208:209], v[208:209]
	v_mov_b32_e32 v205, v207
	v_pk_add_f32 v[206:207], v[200:201], v[208:209]
	v_pk_mul_f32 v[208:209], v[200:201], v[208:209]
	v_pk_add_f32 v[194:195], v[194:195], v[196:197]
	v_pk_mul_f32 v[230:231], v[200:201], v[200:201]
	v_mov_b32_e32 v207, v209
	v_pk_mul_f32 v[208:209], v[212:213], v[212:213]
	v_pk_add_f32 v[192:193], v[192:193], v[194:195]
	v_mov_b32_e32 v194, v210
	v_mov_b32_e32 v195, v226
	v_mov_b32_e32 v196, v212
	v_mov_b32_e32 v197, v228
	v_pk_fma_f32 v[208:209], v[210:211], v[210:211], v[208:209]
	v_pk_add_f32 v[194:195], v[194:195], v[196:197]
	v_pk_mov_b32 v[196:197], v[210:211], v[230:231] op_sel:[1,0]
	v_pk_mov_b32 v[198:199], v[212:213], v[232:233] op_sel:[1,0]
	v_pk_add_f32 v[208:209], v[208:209], v[208:209] op_sel_hi:[0,1]
	v_pk_add_f32 v[202:203], v[234:235], v[202:203]
	v_pk_add_f32 v[204:205], v[204:205], v[206:207]
	v_pk_add_f32 v[196:197], v[196:197], v[198:199]
	v_pk_add_f32 v[202:203], v[202:203], v[204:205]
	v_mov_b32_e32 v145, v209
	v_pk_add_f32 v[194:195], v[194:195], v[196:197]
	v_pk_add_f32 v[202:203], v[202:203], v[144:145]
	v_pk_add_f32 v[192:193], v[192:193], v[194:195]
	s_nop 0
	v_pk_add_f32 v[192:193], v[192:193], v[202:203]
	v_mov_b32_e32 v194, v192
	s_nop 1
	v_permlane16_swap_b32_e32 v192, v194
	s_nop 1
	v_mov_b32_e32 v195, v193
	s_nop 1
	v_permlane16_swap_b32_e32 v193, v195
	s_nop 1
	s_waitcnt lgkmcnt(0)
	v_pk_add_f32 v[192:193], v[192:193], v[194:195]
	v_mov_b32_e32 v194, v192
	s_nop 1
	v_permlane32_swap_b32_e32 v192, v194
	s_nop 1
	v_mov_b32_e32 v195, v193
	s_nop 1
	v_permlane32_swap_b32_e32 v193, v195
	s_nop 1
	s_and_saveexec_b64 s[82:83], s[2:3]
	s_cbranch_execz .LBB0_485
	v_lshl_add_u64 v[190:191], s[38:39], 0, v[190:191]
	v_lshl_add_u64 v[190:191], s[80:81], 3, v[190:191]
	s_waitcnt lgkmcnt(0)
	v_pk_add_f32 v[192:193], v[192:193], v[194:195]
	global_store_dwordx2 v[190:191], v[192:193], off

; #define LAS __attribute__((address_space(3)))
; __device__ __forceinline__ float wave_sum(float v) {
; #pragma unroll
;     for (int o = 1; o < 64; o <<= 1) v += __shfl_xor(v, o);
;     return v;
; __global__ void __launch_bounds__(NTHR, 2) fwd_megakernel(Args args) {
;     ...
;             for (int rr = 0; rr < 4; ++rr) { const int r = wave * 4 + rr; f32x4 x[4]; float s = 0.f;
; #pragma unroll
;                 for (int j = 0; j < 4; ++j) { x[j] = *(const LAS f32x4*)(Os + r * CCH + j * 256 + 4 * lane); s += (x[j][0] + x[j][1]) + (x[j][2] + x[j][3]); }
;                 const float mean = wave_sum(s) * (1.0f / CCH); float q = 0.f;
.LBB0_562:
	s_waitcnt lgkmcnt(0)
	s_barrier
	global_load_dwordx4 v[204:207], v[26:27], off
	global_load_dwordx4 v[232:235], v[28:29], off
	global_load_dwordx4 v[208:211], v[26:27], off offset:1024
	global_load_dwordx4 v[236:239], v[28:29], off offset:1024
	global_load_dwordx4 v[212:215], v[26:27], off offset:2048
	global_load_dwordx4 v[240:243], v[28:29], off offset:2048
	global_load_dwordx4 v[228:231], v[26:27], off offset:3072
	global_load_dwordx4 v[0:3], v[28:29], off offset:3072
	global_load_dwordx4 v[4:7], v[30:31], off
	global_load_dwordx4 v[8:11], v[30:31], off offset:1024
	global_load_dwordx4 v[12:15], v[30:31], off offset:2048
	global_load_dwordx4 v[16:19], v[30:31], off offset:3072
	v_add_u32_e32 v98, s24, v219
	v_add_u32_e32 v99, s26, v219
	v_add_u32_e32 v100, s57, v219
	v_add_u32_e32 v101, s59, v219
	ds_read_b128 v[140:143], v98
	ds_read_b128 v[144:147], v98 offset:1024
	ds_read_b128 v[148:151], v98 offset:2048
	ds_read_b128 v[152:155], v98 offset:3072
	ds_read_b128 v[156:159], v99
	ds_read_b128 v[160:163], v99 offset:1024
	ds_read_b128 v[164:167], v99 offset:2048
	ds_read_b128 v[168:171], v99 offset:3072
	ds_read_b128 v[172:175], v100
	ds_read_b128 v[176:179], v100 offset:1024
	ds_read_b128 v[180:183], v100 offset:2048
	ds_read_b128 v[184:187], v100 offset:3072
	ds_read_b128 v[188:191], v101
	ds_read_b128 v[192:195], v101 offset:1024
	ds_read_b128 v[196:199], v101 offset:2048
	ds_read_b128 v[200:203], v101 offset:3072
	s_add_i32 s2, s56, s62
	s_ashr_i32 s3, s2, 31
	s_lshl_b64 s[2:3], s[2:3], 12
	v_lshl_add_u64 v[126:127], v[32:33], 0, s[2:3]
	s_add_i32 s2, s25, s62
	s_ashr_i32 s3, s2, 31
	s_lshl_b64 s[2:3], s[2:3], 12
	v_lshl_add_u64 v[128:129], v[32:33], 0, s[2:3]
	s_add_i32 s2, s27, s62
	s_ashr_i32 s3, s2, 31
	s_lshl_b64 s[2:3], s[2:3], 12
	v_lshl_add_u64 v[130:131], v[32:33], 0, s[2:3]
	s_add_i32 s2, s58, s62
	s_ashr_i32 s3, s2, 31
	s_lshl_b64 s[2:3], s[2:3], 12
	v_lshl_add_u64 v[132:133], v[32:33], 0, s[2:3]
	s_waitcnt lgkmcnt(0)
	v_add_f32_e32 v110, v140, v141
	v_add_f32_e32 v111, v142, v143
	v_add_f32_e32 v114, v156, v157
	v_add_f32_e32 v115, v158, v159
	v_add_f32_e32 v118, v172, v173
	v_add_f32_e32 v119, v174, v175
	v_add_f32_e32 v122, v188, v189
	v_add_f32_e32 v123, v190, v191
	v_add_f32_e32 v110, v110, v111
	v_add_f32_e32 v114, v114, v115
	v_add_f32_e32 v118, v118, v119
	v_add_f32_e32 v122, v122, v123
	v_mov_b32_e32 v94, v110
	v_mov_b32_e32 v95, v114
	v_mov_b32_e32 v96, v118
	v_mov_b32_e32 v97, v122
	v_add_f32_e32 v110, v144, v145
	v_add_f32_e32 v111, v146, v147
	v_add_f32_e32 v114, v160, v161
	v_add_f32_e32 v115, v162, v163
	v_add_f32_e32 v118, v176, v177
	v_add_f32_e32 v119, v178, v179
	v_add_f32_e32 v122, v192, v193
	v_add_f32_e32 v123, v194, v195
	v_add_f32_e32 v110, v110, v111
	v_add_f32_e32 v114, v114, v115
	v_add_f32_e32 v118, v118, v119
	v_add_f32_e32 v122, v122, v123
	v_add_f32_e32 v94, v94, v110
	v_add_f32_e32 v95, v95, v114
	v_add_f32_e32 v96, v96, v118
	v_add_f32_e32 v97, v97, v122
	v_add_f32_e32 v110, v148, v149
	v_add_f32_e32 v111, v150, v151
	v_add_f32_e32 v114, v164, v165
	v_add_f32_e32 v115, v166, v167
	v_add_f32_e32 v118, v180, v181
	v_add_f32_e32 v119, v182, v183
	v_add_f32_e32 v122, v196, v197
	v_add_f32_e32 v123, v198, v199
	v_add_f32_e32 v110, v110, v111
	v_add_f32_e32 v114, v114, v115
	v_add_f32_e32 v118, v118, v119
	v_add_f32_e32 v122, v122, v123
	v_add_f32_e32 v94, v94, v110
	v_add_f32_e32 v95, v95, v114
	v_add_f32_e32 v96, v96, v118
	v_add_f32_e32 v97, v97, v122
	v_add_f32_e32 v110, v152, v153
	v_add_f32_e32 v111, v154, v155
	v_add_f32_e32 v114, v168, v169
	v_add_f32_e32 v115, v170, v171
	v_add_f32_e32 v118, v184, v185
	v_add_f32_e32 v119, v186, v187
	v_add_f32_e32 v122, v200, v201
	v_add_f32_e32 v123, v202, v203
	v_add_f32_e32 v110, v110, v111
	v_add_f32_e32 v114, v114, v115
	v_add_f32_e32 v118, v118, v119
	v_add_f32_e32 v122, v122, v123
	v_add_f32_e32 v94, v94, v110
	v_add_f32_e32 v95, v95, v114
	v_add_f32_e32 v96, v96, v118
	v_add_f32_e32 v97, v97, v122
	ds_bpermute_b32 v98, v222, v94
	ds_bpermute_b32 v99, v222, v95
	ds_bpermute_b32 v100, v222, v96
	ds_bpermute_b32 v101, v222, v97
	s_waitcnt lgkmcnt(0)
	v_add_f32_e32 v94, v94, v98
	v_add_f32_e32 v95, v95, v99
	v_add_f32_e32 v96, v96, v100
	v_add_f32_e32 v97, v97, v101
	ds_bpermute_b32 v98, v223, v94
	ds_bpermute_b32 v99, v223, v95
	ds_bpermute_b32 v100, v223, v96
	ds_bpermute_b32 v101, v223, v97
	s_waitcnt lgkmcnt(0)
	v_add_f32_e32 v94, v94, v98
	v_add_f32_e32 v95, v95, v99
	v_add_f32_e32 v96, v96, v100
	v_add_f32_e32 v97, v97, v101
	ds_bpermute_b32 v98, v224, v94
	ds_bpermute_b32 v99, v224, v95
	ds_bpermute_b32 v100, v224, v96
	ds_bpermute_b32 v101, v224, v97
	s_waitcnt lgkmcnt(0)
	v_add_f32_e32 v94, v94, v98
	v_add_f32_e32 v95, v95, v99
	v_add_f32_e32 v96, v96, v100
	v_add_f32_e32 v97, v97, v101
	ds_bpermute_b32 v98, v225, v94
	ds_bpermute_b32 v99, v225, v95
	ds_bpermute_b32 v100, v225, v96
	ds_bpermute_b32 v101, v225, v97
	s_waitcnt lgkmcnt(0)
	v_add_f32_e32 v94, v94, v98
	v_add_f32_e32 v95, v95, v99
	v_add_f32_e32 v96, v96, v100
	v_add_f32_e32 v97, v97, v101
	v_mov_b32_e32 v98, v94
	s_nop 1
	v_permlane16_swap_b32_e32 v94, v98
	s_nop 1
	v_mov_b32_e32 v99, v95
	s_nop 1
	v_permlane16_swap_b32_e32 v95, v99
	s_nop 1
	v_mov_b32_e32 v100, v96
	s_nop 1
	v_permlane16_swap_b32_e32 v96, v100
	s_nop 1
	v_mov_b32_e32 v101, v97
	s_nop 1
	v_permlane16_swap_b32_e32 v97, v101
	s_nop 1
	s_waitcnt lgkmcnt(0)
	v_add_f32_e32 v94, v94, v98
	v_add_f32_e32 v95, v95, v99
	v_add_f32_e32 v96, v96, v100
	v_add_f32_e32 v97, v97, v101
	v_mov_b32_e32 v98, v94
	s_nop 1
	v_permlane32_swap_b32_e32 v94, v98
	s_nop 1
	v_mov_b32_e32 v99, v95
	s_nop 1
	v_permlane32_swap_b32_e32 v95, v99
	s_nop 1
	v_mov_b32_e32 v100, v96
	s_nop 1
	v_permlane32_swap_b32_e32 v96, v100
	s_nop 1
	v_mov_b32_e32 v101, v97
	s_nop 1
	v_permlane32_swap_b32_e32 v97, v101
	s_nop 1
	s_waitcnt lgkmcnt(0)
; __global__ void __launch_bounds__(NTHR, 2) fwd_megakernel(Args args) {
;     ...
; #pragma unroll
;                 for (int j = 0; j < 4; ++j) { x[j] = x[j] - mean; q += (x[j][0] * x[j][0] + x[j][1] * x[j][1]) + (x[j][2] * x[j][2] + x[j][3] * x[j][3]); }
;                 const float rstd = rsqrtf(wave_sum(q) * (1.0f / CCH) + LN_EPS); float z2 = 0.f;
	v_add_f32_e32 v94, v94, v98
	v_add_f32_e32 v95, v95, v99
	v_add_f32_e32 v96, v96, v100
	v_add_f32_e32 v97, v97, v101
	v_fmamk_f32 v140, v94, 0xba800000, v140
	v_fmamk_f32 v141, v94, 0xba800000, v141
	v_fmamk_f32 v142, v94, 0xba800000, v142
	v_fmamk_f32 v143, v94, 0xba800000, v143
	v_fmamk_f32 v144, v94, 0xba800000, v144
	v_fmamk_f32 v145, v94, 0xba800000, v145
	v_fmamk_f32 v146, v94, 0xba800000, v146
	v_fmamk_f32 v147, v94, 0xba800000, v147
	v_fmamk_f32 v148, v94, 0xba800000, v148
	v_fmamk_f32 v149, v94, 0xba800000, v149
	v_fmamk_f32 v150, v94, 0xba800000, v150
	v_fmamk_f32 v151, v94, 0xba800000, v151
	v_fmamk_f32 v152, v94, 0xba800000, v152
	v_fmamk_f32 v153, v94, 0xba800000, v153
	v_fmamk_f32 v154, v94, 0xba800000, v154
	v_fmamk_f32 v155, v94, 0xba800000, v155
	v_fmamk_f32 v156, v95, 0xba800000, v156
	v_fmamk_f32 v157, v95, 0xba800000, v157
	v_fmamk_f32 v158, v95, 0xba800000, v158
	v_fmamk_f32 v159, v95, 0xba800000, v159
	v_fmamk_f32 v160, v95, 0xba800000, v160
	v_fmamk_f32 v161, v95, 0xba800000, v161
	v_fmamk_f32 v162, v95, 0xba800000, v162
	v_fmamk_f32 v163, v95, 0xba800000, v163
	v_fmamk_f32 v164, v95, 0xba800000, v164
	v_fmamk_f32 v165, v95, 0xba800000, v165
	v_fmamk_f32 v166, v95, 0xba800000, v166
	v_fmamk_f32 v167, v95, 0xba800000, v167
	v_fmamk_f32 v168, v95, 0xba800000, v168
	v_fmamk_f32 v169, v95, 0xba800000, v169
	v_fmamk_f32 v170, v95, 0xba800000, v170
	v_fmamk_f32 v171, v95, 0xba800000, v171
	v_fmamk_f32 v172, v96, 0xba800000, v172
	v_fmamk_f32 v173, v96, 0xba800000, v173
	v_fmamk_f32 v174, v96, 0xba800000, v174
	v_fmamk_f32 v175, v96, 0xba800000, v175
	v_fmamk_f32 v176, v96, 0xba800000, v176
	v_fmamk_f32 v177, v96, 0xba800000, v177
	v_fmamk_f32 v178, v96, 0xba800000, v178
	v_fmamk_f32 v179, v96, 0xba800000, v179
	v_fmamk_f32 v180, v96, 0xba800000, v180
	v_fmamk_f32 v181, v96, 0xba800000, v181
	v_fmamk_f32 v182, v96, 0xba800000, v182
	v_fmamk_f32 v183, v96, 0xba800000, v183
	v_fmamk_f32 v184, v96, 0xba800000, v184
	v_fmamk_f32 v185, v96, 0xba800000, v185
	v_fmamk_f32 v186, v96, 0xba800000, v186
	v_fmamk_f32 v187, v96, 0xba800000, v187
	v_fmamk_f32 v188, v97, 0xba800000, v188
	v_fmamk_f32 v189, v97, 0xba800000, v189
	v_fmamk_f32 v190, v97, 0xba800000, v190
	v_fmamk_f32 v191, v97, 0xba800000, v191
	v_fmamk_f32 v192, v97, 0xba800000, v192
	v_fmamk_f32 v193, v97, 0xba800000, v193
	v_fmamk_f32 v194, v97, 0xba800000, v194
	v_fmamk_f32 v195, v97, 0xba800000, v195
	v_fmamk_f32 v196, v97, 0xba800000, v196
	v_fmamk_f32 v197, v97, 0xba800000, v197
	v_fmamk_f32 v198, v97, 0xba800000, v198
	v_fmamk_f32 v199, v97, 0xba800000, v199
	v_fmamk_f32 v200, v97, 0xba800000, v200
	v_fmamk_f32 v201, v97, 0xba800000, v201
	v_fmamk_f32 v202, v97, 0xba800000, v202
	v_fmamk_f32 v203, v97, 0xba800000, v203
	v_mul_f32_e32 v110, v140, v140
	v_mul_f32_e32 v111, v142, v142
	v_mul_f32_e32 v114, v156, v156
	v_mul_f32_e32 v115, v158, v158
	v_mul_f32_e32 v118, v172, v172
	v_mul_f32_e32 v119, v174, v174
	v_mul_f32_e32 v122, v188, v188
	v_mul_f32_e32 v123, v190, v190
	v_fmac_f32_e32 v110, v141, v141
	v_fmac_f32_e32 v111, v143, v143
	v_fmac_f32_e32 v114, v157, v157
	v_fmac_f32_e32 v115, v159, v159
	v_fmac_f32_e32 v118, v173, v173
	v_fmac_f32_e32 v119, v175, v175
	v_fmac_f32_e32 v122, v189, v189
	v_fmac_f32_e32 v123, v191, v191
	v_add_f32_e32 v110, v110, v111
	v_add_f32_e32 v114, v114, v115
	v_add_f32_e32 v118, v118, v119
	v_add_f32_e32 v122, v122, v123
	v_mov_b32_e32 v102, v110
	v_mov_b32_e32 v103, v114
	v_mov_b32_e32 v104, v118
	v_mov_b32_e32 v105, v122
	v_mul_f32_e32 v110, v144, v144
	v_mul_f32_e32 v111, v146, v146
	v_mul_f32_e32 v114, v160, v160
	v_mul_f32_e32 v115, v162, v162
	v_mul_f32_e32 v118, v176, v176
	v_mul_f32_e32 v119, v178, v178
	v_mul_f32_e32 v122, v192, v192
	v_mul_f32_e32 v123, v194, v194
	v_fmac_f32_e32 v110, v145, v145
	v_fmac_f32_e32 v111, v147, v147
	v_fmac_f32_e32 v114, v161, v161
	v_fmac_f32_e32 v115, v163, v163
	v_fmac_f32_e32 v118, v177, v177
	v_fmac_f32_e32 v119, v179, v179
	v_fmac_f32_e32 v122, v193, v193
	v_fmac_f32_e32 v123, v195, v195
	v_add_f32_e32 v110, v110, v111
	v_add_f32_e32 v114, v114, v115
	v_add_f32_e32 v118, v118, v119
	v_add_f32_e32 v122, v122, v123
	v_add_f32_e32 v102, v102, v110
	v_add_f32_e32 v103, v103, v114
	v_add_f32_e32 v104, v104, v118
	v_add_f32_e32 v105, v105, v122
	v_mul_f32_e32 v110, v148, v148
	v_mul_f32_e32 v111, v150, v150
	v_mul_f32_e32 v114, v164, v164
	v_mul_f32_e32 v115, v166, v166
	v_mul_f32_e32 v118, v180, v180
	v_mul_f32_e32 v119, v182, v182
	v_mul_f32_e32 v122, v196, v196
	v_mul_f32_e32 v123, v198, v198
	v_fmac_f32_e32 v110, v149, v149
	v_fmac_f32_e32 v111, v151, v151
	v_fmac_f32_e32 v114, v165, v165
	v_fmac_f32_e32 v115, v167, v167
	v_fmac_f32_e32 v118, v181, v181
	v_fmac_f32_e32 v119, v183, v183
	v_fmac_f32_e32 v122, v197, v197
	v_fmac_f32_e32 v123, v199, v199
	v_add_f32_e32 v110, v110, v111
	v_add_f32_e32 v114, v114, v115
	v_add_f32_e32 v118, v118, v119
	v_add_f32_e32 v122, v122, v123
	v_add_f32_e32 v102, v102, v110
	v_add_f32_e32 v103, v103, v114
	v_add_f32_e32 v104, v104, v118
	v_add_f32_e32 v105, v105, v122
	v_mul_f32_e32 v110, v152, v152
	v_mul_f32_e32 v111, v154, v154
	v_mul_f32_e32 v114, v168, v168
	v_mul_f32_e32 v115, v170, v170
	v_mul_f32_e32 v118, v184, v184
	v_mul_f32_e32 v119, v186, v186
	v_mul_f32_e32 v122, v200, v200
	v_mul_f32_e32 v123, v202, v202
	v_fmac_f32_e32 v110, v153, v153
	v_fmac_f32_e32 v111, v155, v155
	v_fmac_f32_e32 v114, v169, v169
	v_fmac_f32_e32 v115, v171, v171
	v_fmac_f32_e32 v118, v185, v185
	v_fmac_f32_e32 v119, v187, v187
	v_fmac_f32_e32 v122, v201, v201
	v_fmac_f32_e32 v123, v203, v203
	v_add_f32_e32 v110, v110, v111
	v_add_f32_e32 v114, v114, v115
	v_add_f32_e32 v118, v118, v119
	v_add_f32_e32 v122, v122, v123
	v_add_f32_e32 v102, v102, v110
	v_add_f32_e32 v103, v103, v114
	v_add_f32_e32 v104, v104, v118
	v_add_f32_e32 v105, v105, v122
	ds_bpermute_b32 v98, v222, v102
	ds_bpermute_b32 v99, v222, v103
	ds_bpermute_b32 v100, v222, v104
	ds_bpermute_b32 v101, v222, v105
	s_waitcnt lgkmcnt(0)
; __device__ __forceinline__ float sigmoidf_(float x) { return fast_rcp(1.0f + fast_exp2(-1.4426950408889634f * x)); }
; #define KIN(i) (*(const float* const __attribute__((address_space(4)))*)(kp + kz + 8 * (i)))
; __global__ void __launch_bounds__(NTHR, 2) fwd_megakernel(Args args) {
;     ...
;                 const float rstd = rsqrtf(wave_sum(q) * (1.0f / CCH) + LN_EPS); float z2 = 0.f;
; #pragma unroll
;                 for (int j = 0; j < 4; ++j) { const f32x4 gg = *(const f32x4*)(KIN(I_CONV_LN_G) + j * 256 + 4 * lane), bb = *(const f32x4*)(KIN(I_CONV_LN_B) + j * 256 + 4 * lane);
;                     f32x4 y = x[j] * rstd * gg + bb;
; #pragma unroll
;                     for (int e = 0; e < 4; ++e) { y[e] = y[e] * sigmoidf_(y[e]); z2 += y[e] * y[e]; }
	v_add_f32_e32 v102, v102, v98
	v_add_f32_e32 v103, v103, v99
	v_add_f32_e32 v104, v104, v100
	v_add_f32_e32 v105, v105, v101
	ds_bpermute_b32 v98, v223, v102
	ds_bpermute_b32 v99, v223, v103
	ds_bpermute_b32 v100, v223, v104
	ds_bpermute_b32 v101, v223, v105
	s_waitcnt lgkmcnt(0)
	v_add_f32_e32 v102, v102, v98
	v_add_f32_e32 v103, v103, v99
	v_add_f32_e32 v104, v104, v100
	v_add_f32_e32 v105, v105, v101
	ds_bpermute_b32 v98, v224, v102
	ds_bpermute_b32 v99, v224, v103
	ds_bpermute_b32 v100, v224, v104
	ds_bpermute_b32 v101, v224, v105
	s_waitcnt lgkmcnt(0)
	v_add_f32_e32 v102, v102, v98
	v_add_f32_e32 v103, v103, v99
	v_add_f32_e32 v104, v104, v100
	v_add_f32_e32 v105, v105, v101
	ds_bpermute_b32 v98, v225, v102
	ds_bpermute_b32 v99, v225, v103
	ds_bpermute_b32 v100, v225, v104
	ds_bpermute_b32 v101, v225, v105
	s_waitcnt lgkmcnt(0)
	v_add_f32_e32 v102, v102, v98
	v_add_f32_e32 v103, v103, v99
	v_add_f32_e32 v104, v104, v100
	v_add_f32_e32 v105, v105, v101
	v_mov_b32_e32 v98, v102
	s_nop 1
	v_permlane16_swap_b32_e32 v102, v98
	s_nop 1
	v_mov_b32_e32 v99, v103
	s_nop 1
	v_permlane16_swap_b32_e32 v103, v99
	s_nop 1
	v_mov_b32_e32 v100, v104
	s_nop 1
	v_permlane16_swap_b32_e32 v104, v100
	s_nop 1
	v_mov_b32_e32 v101, v105
	s_nop 1
	v_permlane16_swap_b32_e32 v105, v101
	s_nop 1
	s_waitcnt lgkmcnt(0)
	v_add_f32_e32 v102, v102, v98
	v_add_f32_e32 v103, v103, v99
	v_add_f32_e32 v104, v104, v100
	v_add_f32_e32 v105, v105, v101
	v_mov_b32_e32 v98, v102
	s_nop 1
	v_permlane32_swap_b32_e32 v102, v98
	s_nop 1
	v_mov_b32_e32 v99, v103
	s_nop 1
	v_permlane32_swap_b32_e32 v103, v99
	s_nop 1
	v_mov_b32_e32 v100, v104
	s_nop 1
	v_permlane32_swap_b32_e32 v104, v100
	s_nop 1
	v_mov_b32_e32 v101, v105
	s_nop 1
	v_permlane32_swap_b32_e32 v105, v101
	s_nop 1
	s_waitcnt lgkmcnt(0)
	v_add_f32_e32 v102, v102, v98
	v_add_f32_e32 v103, v103, v99
	v_add_f32_e32 v104, v104, v100
	v_add_f32_e32 v105, v105, v101
	v_fmamk_f32 v106, v102, 0x3a800000, v226
	v_fmamk_f32 v107, v103, 0x3a800000, v226
	v_fmamk_f32 v108, v104, 0x3a800000, v226
	v_fmamk_f32 v109, v105, 0x3a800000, v226
	v_rsq_f32_e32 v106, v106
	v_rsq_f32_e32 v107, v107
	v_rsq_f32_e32 v108, v108
	v_rsq_f32_e32 v109, v109
	s_waitcnt vmcnt(0)
	v_mov_b32_e32 v102, 0
	v_mov_b32_e32 v103, 0
	v_mov_b32_e32 v104, 0
	v_mov_b32_e32 v105, 0
	v_mul_f32_e32 v140, v140, v106
	v_mul_f32_e32 v141, v141, v106
	v_mul_f32_e32 v142, v142, v106
	v_mul_f32_e32 v143, v143, v106
	v_mul_f32_e32 v156, v156, v107
	v_mul_f32_e32 v157, v157, v107
	v_mul_f32_e32 v158, v158, v107
	v_mul_f32_e32 v159, v159, v107
	v_mul_f32_e32 v172, v172, v108
	v_mul_f32_e32 v173, v173, v108
	v_mul_f32_e32 v174, v174, v108
	v_mul_f32_e32 v175, v175, v108
	v_mul_f32_e32 v188, v188, v109
	v_mul_f32_e32 v189, v189, v109
	v_mul_f32_e32 v190, v190, v109
	v_mul_f32_e32 v191, v191, v109
	v_fma_f32 v140, v140, v204, v232
	v_fma_f32 v141, v141, v205, v233
	v_fma_f32 v142, v142, v206, v234
	v_fma_f32 v143, v143, v207, v235
	v_fma_f32 v156, v156, v204, v232
	v_fma_f32 v157, v157, v205, v233
	v_fma_f32 v158, v158, v206, v234
	v_fma_f32 v159, v159, v207, v235
	v_fma_f32 v172, v172, v204, v232
	v_fma_f32 v173, v173, v205, v233
	v_fma_f32 v174, v174, v206, v234
	v_fma_f32 v175, v175, v207, v235
	v_fma_f32 v188, v188, v204, v232
	v_fma_f32 v189, v189, v205, v233
	v_fma_f32 v190, v190, v206, v234
	v_fma_f32 v191, v191, v207, v235
	v_mul_f32_e32 v110, 0xbfb8aa3b, v140
	v_mul_f32_e32 v111, 0xbfb8aa3b, v141
	v_mul_f32_e32 v112, 0xbfb8aa3b, v142
	v_mul_f32_e32 v113, 0xbfb8aa3b, v143
	v_mul_f32_e32 v114, 0xbfb8aa3b, v156
	v_mul_f32_e32 v115, 0xbfb8aa3b, v157
	v_mul_f32_e32 v116, 0xbfb8aa3b, v158
	v_mul_f32_e32 v117, 0xbfb8aa3b, v159
	v_mul_f32_e32 v118, 0xbfb8aa3b, v172
	v_mul_f32_e32 v119, 0xbfb8aa3b, v173
	v_mul_f32_e32 v120, 0xbfb8aa3b, v174
	v_mul_f32_e32 v121, 0xbfb8aa3b, v175
	v_mul_f32_e32 v122, 0xbfb8aa3b, v188
	v_mul_f32_e32 v123, 0xbfb8aa3b, v189
	v_mul_f32_e32 v124, 0xbfb8aa3b, v190
	v_mul_f32_e32 v125, 0xbfb8aa3b, v191
	v_exp_f32_e32 v110, v110
	v_exp_f32_e32 v111, v111
	v_exp_f32_e32 v112, v112
	v_exp_f32_e32 v113, v113
	v_exp_f32_e32 v114, v114
	v_exp_f32_e32 v115, v115
	v_exp_f32_e32 v116, v116
	v_exp_f32_e32 v117, v117
	v_exp_f32_e32 v118, v118
	v_exp_f32_e32 v119, v119
	v_exp_f32_e32 v120, v120
	v_exp_f32_e32 v121, v121
	v_exp_f32_e32 v122, v122
	v_exp_f32_e32 v123, v123
	v_exp_f32_e32 v124, v124
	v_exp_f32_e32 v125, v125
	v_add_f32_e32 v110, 1.0, v110
	v_add_f32_e32 v111, 1.0, v111
	v_add_f32_e32 v112, 1.0, v112
	v_add_f32_e32 v113, 1.0, v113
	v_add_f32_e32 v114, 1.0, v114
	v_add_f32_e32 v115, 1.0, v115
	v_add_f32_e32 v116, 1.0, v116
	v_add_f32_e32 v117, 1.0, v117
	v_add_f32_e32 v118, 1.0, v118
	v_add_f32_e32 v119, 1.0, v119
	v_add_f32_e32 v120, 1.0, v120
	v_add_f32_e32 v121, 1.0, v121
	v_add_f32_e32 v122, 1.0, v122
	v_add_f32_e32 v123, 1.0, v123
	v_add_f32_e32 v124, 1.0, v124
	v_add_f32_e32 v125, 1.0, v125
	v_rcp_f32_e32 v110, v110
	v_rcp_f32_e32 v111, v111
	v_rcp_f32_e32 v112, v112
	v_rcp_f32_e32 v113, v113
	v_rcp_f32_e32 v114, v114
	v_rcp_f32_e32 v115, v115
	v_rcp_f32_e32 v116, v116
	v_rcp_f32_e32 v117, v117
	v_rcp_f32_e32 v118, v118
	v_rcp_f32_e32 v119, v119
	v_rcp_f32_e32 v120, v120
	v_rcp_f32_e32 v121, v121
	v_rcp_f32_e32 v122, v122
	v_rcp_f32_e32 v123, v123
	v_rcp_f32_e32 v124, v124
	v_rcp_f32_e32 v125, v125
	v_mul_f32_e32 v140, v140, v110
	v_mul_f32_e32 v141, v141, v111
	v_mul_f32_e32 v142, v142, v112
	v_mul_f32_e32 v143, v143, v113
	v_mul_f32_e32 v156, v156, v114
	v_mul_f32_e32 v157, v157, v115
	v_mul_f32_e32 v158, v158, v116
	v_mul_f32_e32 v159, v159, v117
	v_mul_f32_e32 v172, v172, v118
	v_mul_f32_e32 v173, v173, v119
	v_mul_f32_e32 v174, v174, v120
; __device__ __forceinline__ float sigmoidf_(float x) { return fast_rcp(1.0f + fast_exp2(-1.4426950408889634f * x)); }
; #define KIN(i) (*(const float* const __attribute__((address_space(4)))*)(kp + kz + 8 * (i)))
; __global__ void __launch_bounds__(NTHR, 2) fwd_megakernel(Args args) {
;     ...
; #pragma unroll
;                 for (int j = 0; j < 4; ++j) { const f32x4 gg = *(const f32x4*)(KIN(I_CONV_LN_G) + j * 256 + 4 * lane), bb = *(const f32x4*)(KIN(I_CONV_LN_B) + j * 256 + 4 * lane);
;                     f32x4 y = x[j] * rstd * gg + bb;
; #pragma unroll
;                     for (int e = 0; e < 4; ++e) { y[e] = y[e] * sigmoidf_(y[e]); z2 += y[e] * y[e]; }
;                     x[j] = y; }
	v_mul_f32_e32 v175, v175, v121
	v_mul_f32_e32 v188, v188, v122
	v_mul_f32_e32 v189, v189, v123
	v_mul_f32_e32 v190, v190, v124
	v_mul_f32_e32 v191, v191, v125
	v_fmac_f32_e32 v102, v140, v140
	v_fmac_f32_e32 v103, v156, v156
	v_fmac_f32_e32 v104, v172, v172
	v_fmac_f32_e32 v105, v188, v188
	v_fmac_f32_e32 v102, v141, v141
	v_fmac_f32_e32 v103, v157, v157
	v_fmac_f32_e32 v104, v173, v173
	v_fmac_f32_e32 v105, v189, v189
	v_fmac_f32_e32 v102, v142, v142
	v_fmac_f32_e32 v103, v158, v158
	v_fmac_f32_e32 v104, v174, v174
	v_fmac_f32_e32 v105, v190, v190
	v_fmac_f32_e32 v102, v143, v143
	v_fmac_f32_e32 v103, v159, v159
	v_fmac_f32_e32 v104, v175, v175
	v_fmac_f32_e32 v105, v191, v191
	v_mul_f32_e32 v144, v144, v106
	v_mul_f32_e32 v145, v145, v106
	v_mul_f32_e32 v146, v146, v106
	v_mul_f32_e32 v147, v147, v106
	v_mul_f32_e32 v160, v160, v107
	v_mul_f32_e32 v161, v161, v107
	v_mul_f32_e32 v162, v162, v107
	v_mul_f32_e32 v163, v163, v107
	v_mul_f32_e32 v176, v176, v108
	v_mul_f32_e32 v177, v177, v108
	v_mul_f32_e32 v178, v178, v108
	v_mul_f32_e32 v179, v179, v108
	v_mul_f32_e32 v192, v192, v109
	v_mul_f32_e32 v193, v193, v109
	v_mul_f32_e32 v194, v194, v109
	v_mul_f32_e32 v195, v195, v109
	v_fma_f32 v144, v144, v208, v236
	v_fma_f32 v145, v145, v209, v237
	v_fma_f32 v146, v146, v210, v238
	v_fma_f32 v147, v147, v211, v239
	v_fma_f32 v160, v160, v208, v236
	v_fma_f32 v161, v161, v209, v237
	v_fma_f32 v162, v162, v210, v238
	v_fma_f32 v163, v163, v211, v239
	v_fma_f32 v176, v176, v208, v236
	v_fma_f32 v177, v177, v209, v237
	v_fma_f32 v178, v178, v210, v238
	v_fma_f32 v179, v179, v211, v239
	v_fma_f32 v192, v192, v208, v236
	v_fma_f32 v193, v193, v209, v237
	v_fma_f32 v194, v194, v210, v238
	v_fma_f32 v195, v195, v211, v239
	v_mul_f32_e32 v110, 0xbfb8aa3b, v144
	v_mul_f32_e32 v111, 0xbfb8aa3b, v145
	v_mul_f32_e32 v112, 0xbfb8aa3b, v146
	v_mul_f32_e32 v113, 0xbfb8aa3b, v147
	v_mul_f32_e32 v114, 0xbfb8aa3b, v160
	v_mul_f32_e32 v115, 0xbfb8aa3b, v161
	v_mul_f32_e32 v116, 0xbfb8aa3b, v162
	v_mul_f32_e32 v117, 0xbfb8aa3b, v163
	v_mul_f32_e32 v118, 0xbfb8aa3b, v176
	v_mul_f32_e32 v119, 0xbfb8aa3b, v177
	v_mul_f32_e32 v120, 0xbfb8aa3b, v178
	v_mul_f32_e32 v121, 0xbfb8aa3b, v179
	v_mul_f32_e32 v122, 0xbfb8aa3b, v192
	v_mul_f32_e32 v123, 0xbfb8aa3b, v193
	v_mul_f32_e32 v124, 0xbfb8aa3b, v194
	v_mul_f32_e32 v125, 0xbfb8aa3b, v195
	v_exp_f32_e32 v110, v110
	v_exp_f32_e32 v111, v111
	v_exp_f32_e32 v112, v112
	v_exp_f32_e32 v113, v113
	v_exp_f32_e32 v114, v114
	v_exp_f32_e32 v115, v115
	v_exp_f32_e32 v116, v116
	v_exp_f32_e32 v117, v117
	v_exp_f32_e32 v118, v118
	v_exp_f32_e32 v119, v119
	v_exp_f32_e32 v120, v120
	v_exp_f32_e32 v121, v121
	v_exp_f32_e32 v122, v122
	v_exp_f32_e32 v123, v123
	v_exp_f32_e32 v124, v124
	v_exp_f32_e32 v125, v125
	v_add_f32_e32 v110, 1.0, v110
	v_add_f32_e32 v111, 1.0, v111
	v_add_f32_e32 v112, 1.0, v112
	v_add_f32_e32 v113, 1.0, v113
	v_add_f32_e32 v114, 1.0, v114
	v_add_f32_e32 v115, 1.0, v115
	v_add_f32_e32 v116, 1.0, v116
	v_add_f32_e32 v117, 1.0, v117
	v_add_f32_e32 v118, 1.0, v118
	v_add_f32_e32 v119, 1.0, v119
	v_add_f32_e32 v120, 1.0, v120
	v_add_f32_e32 v121, 1.0, v121
	v_add_f32_e32 v122, 1.0, v122
	v_add_f32_e32 v123, 1.0, v123
	v_add_f32_e32 v124, 1.0, v124
	v_add_f32_e32 v125, 1.0, v125
	v_rcp_f32_e32 v110, v110
	v_rcp_f32_e32 v111, v111
	v_rcp_f32_e32 v112, v112
	v_rcp_f32_e32 v113, v113
	v_rcp_f32_e32 v114, v114
	v_rcp_f32_e32 v115, v115
	v_rcp_f32_e32 v116, v116
	v_rcp_f32_e32 v117, v117
	v_rcp_f32_e32 v118, v118
	v_rcp_f32_e32 v119, v119
	v_rcp_f32_e32 v120, v120
	v_rcp_f32_e32 v121, v121
	v_rcp_f32_e32 v122, v122
	v_rcp_f32_e32 v123, v123
	v_rcp_f32_e32 v124, v124
	v_rcp_f32_e32 v125, v125
	v_mul_f32_e32 v144, v144, v110
	v_mul_f32_e32 v145, v145, v111
	v_mul_f32_e32 v146, v146, v112
	v_mul_f32_e32 v147, v147, v113
	v_mul_f32_e32 v160, v160, v114
	v_mul_f32_e32 v161, v161, v115
	v_mul_f32_e32 v162, v162, v116
	v_mul_f32_e32 v163, v163, v117
	v_mul_f32_e32 v176, v176, v118
	v_mul_f32_e32 v177, v177, v119
	v_mul_f32_e32 v178, v178, v120
	v_mul_f32_e32 v179, v179, v121
	v_mul_f32_e32 v192, v192, v122
	v_mul_f32_e32 v193, v193, v123
	v_mul_f32_e32 v194, v194, v124
	v_mul_f32_e32 v195, v195, v125
	v_fmac_f32_e32 v102, v144, v144
	v_fmac_f32_e32 v103, v160, v160
	v_fmac_f32_e32 v104, v176, v176
	v_fmac_f32_e32 v105, v192, v192
	v_fmac_f32_e32 v102, v145, v145
	v_fmac_f32_e32 v103, v161, v161
	v_fmac_f32_e32 v104, v177, v177
	v_fmac_f32_e32 v105, v193, v193
	v_fmac_f32_e32 v102, v146, v146
	v_fmac_f32_e32 v103, v162, v162
	v_fmac_f32_e32 v104, v178, v178
	v_fmac_f32_e32 v105, v194, v194
	v_fmac_f32_e32 v102, v147, v147
	v_fmac_f32_e32 v103, v163, v163
	v_fmac_f32_e32 v104, v179, v179
	v_fmac_f32_e32 v105, v195, v195
	v_mul_f32_e32 v148, v148, v106
	v_mul_f32_e32 v149, v149, v106
	v_mul_f32_e32 v150, v150, v106
	v_mul_f32_e32 v151, v151, v106
	v_mul_f32_e32 v164, v164, v107
	v_mul_f32_e32 v165, v165, v107
	v_mul_f32_e32 v166, v166, v107
	v_mul_f32_e32 v167, v167, v107
	v_mul_f32_e32 v180, v180, v108
	v_mul_f32_e32 v181, v181, v108
	v_mul_f32_e32 v182, v182, v108
	v_mul_f32_e32 v183, v183, v108
	v_mul_f32_e32 v196, v196, v109
	v_mul_f32_e32 v197, v197, v109
	v_mul_f32_e32 v198, v198, v109
	v_mul_f32_e32 v199, v199, v109
	v_fma_f32 v148, v148, v212, v240
	v_fma_f32 v149, v149, v213, v241
	v_fma_f32 v150, v150, v214, v242
	v_fma_f32 v151, v151, v215, v243
	v_fma_f32 v164, v164, v212, v240
	v_fma_f32 v165, v165, v213, v241
	v_fma_f32 v166, v166, v214, v242
	v_fma_f32 v167, v167, v215, v243
	v_fma_f32 v180, v180, v212, v240
	v_fma_f32 v181, v181, v213, v241
	v_fma_f32 v182, v182, v214, v242
	v_fma_f32 v183, v183, v215, v243
; __device__ __forceinline__ float sigmoidf_(float x) { return fast_rcp(1.0f + fast_exp2(-1.4426950408889634f * x)); }
; #define KIN(i) (*(const float* const __attribute__((address_space(4)))*)(kp + kz + 8 * (i)))
; __global__ void __launch_bounds__(NTHR, 2) fwd_megakernel(Args args) {
;     ...
; #pragma unroll
;                 for (int j = 0; j < 4; ++j) { const f32x4 gg = *(const f32x4*)(KIN(I_CONV_LN_G) + j * 256 + 4 * lane), bb = *(const f32x4*)(KIN(I_CONV_LN_B) + j * 256 + 4 * lane);
;                     f32x4 y = x[j] * rstd * gg + bb;
; #pragma unroll
;                     for (int e = 0; e < 4; ++e) { y[e] = y[e] * sigmoidf_(y[e]); z2 += y[e] * y[e]; }
;                     x[j] = y; }
	v_fma_f32 v196, v196, v212, v240
	v_fma_f32 v197, v197, v213, v241
	v_fma_f32 v198, v198, v214, v242
	v_fma_f32 v199, v199, v215, v243
	v_mul_f32_e32 v110, 0xbfb8aa3b, v148
	v_mul_f32_e32 v111, 0xbfb8aa3b, v149
	v_mul_f32_e32 v112, 0xbfb8aa3b, v150
	v_mul_f32_e32 v113, 0xbfb8aa3b, v151
	v_mul_f32_e32 v114, 0xbfb8aa3b, v164
	v_mul_f32_e32 v115, 0xbfb8aa3b, v165
	v_mul_f32_e32 v116, 0xbfb8aa3b, v166
	v_mul_f32_e32 v117, 0xbfb8aa3b, v167
	v_mul_f32_e32 v118, 0xbfb8aa3b, v180
	v_mul_f32_e32 v119, 0xbfb8aa3b, v181
	v_mul_f32_e32 v120, 0xbfb8aa3b, v182
	v_mul_f32_e32 v121, 0xbfb8aa3b, v183
	v_mul_f32_e32 v122, 0xbfb8aa3b, v196
	v_mul_f32_e32 v123, 0xbfb8aa3b, v197
	v_mul_f32_e32 v124, 0xbfb8aa3b, v198
	v_mul_f32_e32 v125, 0xbfb8aa3b, v199
	v_exp_f32_e32 v110, v110
	v_exp_f32_e32 v111, v111
	v_exp_f32_e32 v112, v112
	v_exp_f32_e32 v113, v113
	v_exp_f32_e32 v114, v114
	v_exp_f32_e32 v115, v115
	v_exp_f32_e32 v116, v116
	v_exp_f32_e32 v117, v117
	v_exp_f32_e32 v118, v118
	v_exp_f32_e32 v119, v119
	v_exp_f32_e32 v120, v120
	v_exp_f32_e32 v121, v121
	v_exp_f32_e32 v122, v122
	v_exp_f32_e32 v123, v123
	v_exp_f32_e32 v124, v124
	v_exp_f32_e32 v125, v125
	v_add_f32_e32 v110, 1.0, v110
	v_add_f32_e32 v111, 1.0, v111
	v_add_f32_e32 v112, 1.0, v112
	v_add_f32_e32 v113, 1.0, v113
	v_add_f32_e32 v114, 1.0, v114
	v_add_f32_e32 v115, 1.0, v115
	v_add_f32_e32 v116, 1.0, v116
	v_add_f32_e32 v117, 1.0, v117
	v_add_f32_e32 v118, 1.0, v118
	v_add_f32_e32 v119, 1.0, v119
	v_add_f32_e32 v120, 1.0, v120
	v_add_f32_e32 v121, 1.0, v121
	v_add_f32_e32 v122, 1.0, v122
	v_add_f32_e32 v123, 1.0, v123
	v_add_f32_e32 v124, 1.0, v124
	v_add_f32_e32 v125, 1.0, v125
	v_rcp_f32_e32 v110, v110
	v_rcp_f32_e32 v111, v111
	v_rcp_f32_e32 v112, v112
	v_rcp_f32_e32 v113, v113
	v_rcp_f32_e32 v114, v114
	v_rcp_f32_e32 v115, v115
	v_rcp_f32_e32 v116, v116
	v_rcp_f32_e32 v117, v117
	v_rcp_f32_e32 v118, v118
	v_rcp_f32_e32 v119, v119
	v_rcp_f32_e32 v120, v120
	v_rcp_f32_e32 v121, v121
	v_rcp_f32_e32 v122, v122
	v_rcp_f32_e32 v123, v123
	v_rcp_f32_e32 v124, v124
	v_rcp_f32_e32 v125, v125
	v_mul_f32_e32 v148, v148, v110
	v_mul_f32_e32 v149, v149, v111
	v_mul_f32_e32 v150, v150, v112
	v_mul_f32_e32 v151, v151, v113
	v_mul_f32_e32 v164, v164, v114
	v_mul_f32_e32 v165, v165, v115
	v_mul_f32_e32 v166, v166, v116
	v_mul_f32_e32 v167, v167, v117
	v_mul_f32_e32 v180, v180, v118
	v_mul_f32_e32 v181, v181, v119
	v_mul_f32_e32 v182, v182, v120
	v_mul_f32_e32 v183, v183, v121
	v_mul_f32_e32 v196, v196, v122
	v_mul_f32_e32 v197, v197, v123
	v_mul_f32_e32 v198, v198, v124
	v_mul_f32_e32 v199, v199, v125
	v_fmac_f32_e32 v102, v148, v148
	v_fmac_f32_e32 v103, v164, v164
	v_fmac_f32_e32 v104, v180, v180
	v_fmac_f32_e32 v105, v196, v196
	v_fmac_f32_e32 v102, v149, v149
	v_fmac_f32_e32 v103, v165, v165
	v_fmac_f32_e32 v104, v181, v181
	v_fmac_f32_e32 v105, v197, v197
	v_fmac_f32_e32 v102, v150, v150
	v_fmac_f32_e32 v103, v166, v166
	v_fmac_f32_e32 v104, v182, v182
	v_fmac_f32_e32 v105, v198, v198
	v_fmac_f32_e32 v102, v151, v151
	v_fmac_f32_e32 v103, v167, v167
	v_fmac_f32_e32 v104, v183, v183
	v_fmac_f32_e32 v105, v199, v199
	v_mul_f32_e32 v152, v152, v106
	v_mul_f32_e32 v153, v153, v106
	v_mul_f32_e32 v154, v154, v106
	v_mul_f32_e32 v155, v155, v106
	v_mul_f32_e32 v168, v168, v107
	v_mul_f32_e32 v169, v169, v107
	v_mul_f32_e32 v170, v170, v107
	v_mul_f32_e32 v171, v171, v107
	v_mul_f32_e32 v184, v184, v108
	v_mul_f32_e32 v185, v185, v108
	v_mul_f32_e32 v186, v186, v108
	v_mul_f32_e32 v187, v187, v108
	v_mul_f32_e32 v200, v200, v109
	v_mul_f32_e32 v201, v201, v109
	v_mul_f32_e32 v202, v202, v109
	v_mul_f32_e32 v203, v203, v109
	v_fma_f32 v152, v152, v228, v0
	v_fma_f32 v153, v153, v229, v1
	v_fma_f32 v154, v154, v230, v2
	v_fma_f32 v155, v155, v231, v3
	v_fma_f32 v168, v168, v228, v0
	v_fma_f32 v169, v169, v229, v1
	v_fma_f32 v170, v170, v230, v2
	v_fma_f32 v171, v171, v231, v3
	v_fma_f32 v184, v184, v228, v0
	v_fma_f32 v185, v185, v229, v1
	v_fma_f32 v186, v186, v230, v2
	v_fma_f32 v187, v187, v231, v3
	v_fma_f32 v200, v200, v228, v0
	v_fma_f32 v201, v201, v229, v1
	v_fma_f32 v202, v202, v230, v2
	v_fma_f32 v203, v203, v231, v3
	v_mul_f32_e32 v110, 0xbfb8aa3b, v152
	v_mul_f32_e32 v111, 0xbfb8aa3b, v153
	v_mul_f32_e32 v112, 0xbfb8aa3b, v154
	v_mul_f32_e32 v113, 0xbfb8aa3b, v155
	v_mul_f32_e32 v114, 0xbfb8aa3b, v168
	v_mul_f32_e32 v115, 0xbfb8aa3b, v169
	v_mul_f32_e32 v116, 0xbfb8aa3b, v170
	v_mul_f32_e32 v117, 0xbfb8aa3b, v171
	v_mul_f32_e32 v118, 0xbfb8aa3b, v184
	v_mul_f32_e32 v119, 0xbfb8aa3b, v185
	v_mul_f32_e32 v120, 0xbfb8aa3b, v186
	v_mul_f32_e32 v121, 0xbfb8aa3b, v187
	v_mul_f32_e32 v122, 0xbfb8aa3b, v200
	v_mul_f32_e32 v123, 0xbfb8aa3b, v201
	v_mul_f32_e32 v124, 0xbfb8aa3b, v202
	v_mul_f32_e32 v125, 0xbfb8aa3b, v203
	v_exp_f32_e32 v110, v110
	v_exp_f32_e32 v111, v111
	v_exp_f32_e32 v112, v112
	v_exp_f32_e32 v113, v113
	v_exp_f32_e32 v114, v114
	v_exp_f32_e32 v115, v115
	v_exp_f32_e32 v116, v116
	v_exp_f32_e32 v117, v117
	v_exp_f32_e32 v118, v118
	v_exp_f32_e32 v119, v119
	v_exp_f32_e32 v120, v120
	v_exp_f32_e32 v121, v121
	v_exp_f32_e32 v122, v122
	v_exp_f32_e32 v123, v123
	v_exp_f32_e32 v124, v124
	v_exp_f32_e32 v125, v125
	v_add_f32_e32 v110, 1.0, v110
	v_add_f32_e32 v111, 1.0, v111
	v_add_f32_e32 v112, 1.0, v112
	v_add_f32_e32 v113, 1.0, v113
	v_add_f32_e32 v114, 1.0, v114
	v_add_f32_e32 v115, 1.0, v115
	v_add_f32_e32 v116, 1.0, v116
	v_add_f32_e32 v117, 1.0, v117
	v_add_f32_e32 v118, 1.0, v118
	v_add_f32_e32 v119, 1.0, v119
	v_add_f32_e32 v120, 1.0, v120
	v_add_f32_e32 v121, 1.0, v121
	v_add_f32_e32 v122, 1.0, v122
	v_add_f32_e32 v123, 1.0, v123
	v_add_f32_e32 v124, 1.0, v124
; __device__ __forceinline__ float sigmoidf_(float x) { return fast_rcp(1.0f + fast_exp2(-1.4426950408889634f * x)); }
; __global__ void __launch_bounds__(NTHR, 2) fwd_megakernel(Args args) {
;     ...
;                     for (int e = 0; e < 4; ++e) { y[e] = y[e] * sigmoidf_(y[e]); z2 += y[e] * y[e]; }
;                     x[j] = y; }
;                 const float r2 = rsqrtf(wave_sum(z2) * (1.0f / CCH) + RMS_EPS);
	v_add_f32_e32 v125, 1.0, v125
	v_rcp_f32_e32 v110, v110
	v_rcp_f32_e32 v111, v111
	v_rcp_f32_e32 v112, v112
	v_rcp_f32_e32 v113, v113
	v_rcp_f32_e32 v114, v114
	v_rcp_f32_e32 v115, v115
	v_rcp_f32_e32 v116, v116
	v_rcp_f32_e32 v117, v117
	v_rcp_f32_e32 v118, v118
	v_rcp_f32_e32 v119, v119
	v_rcp_f32_e32 v120, v120
	v_rcp_f32_e32 v121, v121
	v_rcp_f32_e32 v122, v122
	v_rcp_f32_e32 v123, v123
	v_rcp_f32_e32 v124, v124
	v_rcp_f32_e32 v125, v125
	v_mul_f32_e32 v152, v152, v110
	v_mul_f32_e32 v153, v153, v111
	v_mul_f32_e32 v154, v154, v112
	v_mul_f32_e32 v155, v155, v113
	v_mul_f32_e32 v168, v168, v114
	v_mul_f32_e32 v169, v169, v115
	v_mul_f32_e32 v170, v170, v116
	v_mul_f32_e32 v171, v171, v117
	v_mul_f32_e32 v184, v184, v118
	v_mul_f32_e32 v185, v185, v119
	v_mul_f32_e32 v186, v186, v120
	v_mul_f32_e32 v187, v187, v121
	v_mul_f32_e32 v200, v200, v122
	v_mul_f32_e32 v201, v201, v123
	v_mul_f32_e32 v202, v202, v124
	v_mul_f32_e32 v203, v203, v125
	v_fmac_f32_e32 v102, v152, v152
	v_fmac_f32_e32 v103, v168, v168
	v_fmac_f32_e32 v104, v184, v184
	v_fmac_f32_e32 v105, v200, v200
	v_fmac_f32_e32 v102, v153, v153
	v_fmac_f32_e32 v103, v169, v169
	v_fmac_f32_e32 v104, v185, v185
	v_fmac_f32_e32 v105, v201, v201
	v_fmac_f32_e32 v102, v154, v154
	v_fmac_f32_e32 v103, v170, v170
	v_fmac_f32_e32 v104, v186, v186
	v_fmac_f32_e32 v105, v202, v202
	v_fmac_f32_e32 v102, v155, v155
	v_fmac_f32_e32 v103, v171, v171
	v_fmac_f32_e32 v104, v187, v187
	v_fmac_f32_e32 v105, v203, v203
	ds_bpermute_b32 v98, v222, v102
	ds_bpermute_b32 v99, v222, v103
	ds_bpermute_b32 v100, v222, v104
	ds_bpermute_b32 v101, v222, v105
	s_waitcnt lgkmcnt(0)
	v_add_f32_e32 v102, v102, v98
	v_add_f32_e32 v103, v103, v99
	v_add_f32_e32 v104, v104, v100
	v_add_f32_e32 v105, v105, v101
	ds_bpermute_b32 v98, v223, v102
	ds_bpermute_b32 v99, v223, v103
	ds_bpermute_b32 v100, v223, v104
	ds_bpermute_b32 v101, v223, v105
	s_waitcnt lgkmcnt(0)
	v_add_f32_e32 v102, v102, v98
	v_add_f32_e32 v103, v103, v99
	v_add_f32_e32 v104, v104, v100
	v_add_f32_e32 v105, v105, v101
	ds_bpermute_b32 v98, v224, v102
	ds_bpermute_b32 v99, v224, v103
	ds_bpermute_b32 v100, v224, v104
	ds_bpermute_b32 v101, v224, v105
	s_waitcnt lgkmcnt(0)
	v_add_f32_e32 v102, v102, v98
	v_add_f32_e32 v103, v103, v99
	v_add_f32_e32 v104, v104, v100
	v_add_f32_e32 v105, v105, v101
	ds_bpermute_b32 v98, v225, v102
	ds_bpermute_b32 v99, v225, v103
	ds_bpermute_b32 v100, v225, v104
	ds_bpermute_b32 v101, v225, v105
	s_waitcnt lgkmcnt(0)
	v_add_f32_e32 v102, v102, v98
	v_add_f32_e32 v103, v103, v99
	v_add_f32_e32 v104, v104, v100
	v_add_f32_e32 v105, v105, v101
	v_mov_b32_e32 v98, v102
	s_nop 1
	v_permlane16_swap_b32_e32 v102, v98
	s_nop 1
	v_mov_b32_e32 v99, v103
	s_nop 1
	v_permlane16_swap_b32_e32 v103, v99
	s_nop 1
	v_mov_b32_e32 v100, v104
	s_nop 1
	v_permlane16_swap_b32_e32 v104, v100
	s_nop 1
	v_mov_b32_e32 v101, v105
	s_nop 1
	v_permlane16_swap_b32_e32 v105, v101
	s_nop 1
	s_waitcnt lgkmcnt(0)
	v_add_f32_e32 v102, v102, v98
	v_add_f32_e32 v103, v103, v99
	v_add_f32_e32 v104, v104, v100
	v_add_f32_e32 v105, v105, v101
	v_mov_b32_e32 v98, v102
	s_nop 1
	v_permlane32_swap_b32_e32 v102, v98
	s_nop 1
	v_mov_b32_e32 v99, v103
	s_nop 1
	v_permlane32_swap_b32_e32 v103, v99
	s_nop 1
	v_mov_b32_e32 v100, v104
	s_nop 1
	v_permlane32_swap_b32_e32 v104, v100
	s_nop 1
	v_mov_b32_e32 v101, v105
	s_nop 1
	v_permlane32_swap_b32_e32 v105, v101
	s_nop 1
	s_waitcnt lgkmcnt(0)
; __device__ __forceinline__ unsigned cvt_pk_bf16(float lo, float hi) { unsigned r; asm volatile("v_cvt_pk_bf16_f32 %0, %1, %2" : "=v"(r) : "v"(lo), "v"(hi)); return r; }
; #define KIN(i) (*(const float* const __attribute__((address_space(4)))*)(kp + kz + 8 * (i)))
; __global__ void __launch_bounds__(NTHR, 2) fwd_megakernel(Args args) {
;     ...
;         for (int cu = bid; cu < T / 32; cu += G) {
;     ...
;                 const float r2 = rsqrtf(wave_sum(z2) * (1.0f / CCH) + RMS_EPS);
; #pragma unroll
;                 for (int j = 0; j < 4; ++j) { const f32x4 gg = *(const f32x4*)(KIN(I_OUT_NORM_CONV) + j * 256 + 4 * lane); const f32x4 y = x[j] * r2 * gg;
;                     u32x2 w; w.x = cvt_pk_bf16(y[0], y[1]); w.y = cvt_pk_bf16(y[2], y[3]); *(u32x2*)(Y + (size_t)(t0 + r) * D + j * 256 + 4 * lane) = w; }
;             }
;             __syncthreads();
	v_add_f32_e32 v102, v102, v98
	v_add_f32_e32 v103, v103, v99
	v_add_f32_e32 v104, v104, v100
	v_add_f32_e32 v105, v105, v101
	v_fmamk_f32 v106, v102, 0x3a800000, v227
	v_fmamk_f32 v107, v103, 0x3a800000, v227
	v_fmamk_f32 v108, v104, 0x3a800000, v227
	v_fmamk_f32 v109, v105, 0x3a800000, v227
	v_rsq_f32_e32 v106, v106
	v_rsq_f32_e32 v107, v107
	v_rsq_f32_e32 v108, v108
	v_rsq_f32_e32 v109, v109
	s_nop 0
	v_mul_f32_e32 v140, v140, v106
	v_mul_f32_e32 v141, v141, v106
	v_mul_f32_e32 v142, v142, v106
	v_mul_f32_e32 v143, v143, v106
	v_mul_f32_e32 v156, v156, v107
	v_mul_f32_e32 v157, v157, v107
	v_mul_f32_e32 v158, v158, v107
	v_mul_f32_e32 v159, v159, v107
	v_mul_f32_e32 v172, v172, v108
	v_mul_f32_e32 v173, v173, v108
	v_mul_f32_e32 v174, v174, v108
	v_mul_f32_e32 v175, v175, v108
	v_mul_f32_e32 v188, v188, v109
	v_mul_f32_e32 v189, v189, v109
	v_mul_f32_e32 v190, v190, v109
	v_mul_f32_e32 v191, v191, v109
	v_mul_f32_e32 v140, v140, v4
	v_mul_f32_e32 v141, v141, v5
	v_mul_f32_e32 v142, v142, v6
	v_mul_f32_e32 v143, v143, v7
	v_mul_f32_e32 v156, v156, v4
	v_mul_f32_e32 v157, v157, v5
	v_mul_f32_e32 v158, v158, v6
	v_mul_f32_e32 v159, v159, v7
	v_mul_f32_e32 v172, v172, v4
	v_mul_f32_e32 v173, v173, v5
	v_mul_f32_e32 v174, v174, v6
	v_mul_f32_e32 v175, v175, v7
	v_mul_f32_e32 v188, v188, v4
	v_mul_f32_e32 v189, v189, v5
	v_mul_f32_e32 v190, v190, v6
	v_mul_f32_e32 v191, v191, v7
	v_cvt_pk_bf16_f32 v134, v140, v141
	v_cvt_pk_bf16_f32 v135, v142, v143
	v_cvt_pk_bf16_f32 v136, v156, v157
	v_cvt_pk_bf16_f32 v137, v158, v159
	v_cvt_pk_bf16_f32 v242, v172, v173
	v_cvt_pk_bf16_f32 v243, v174, v175
	v_cvt_pk_bf16_f32 v244, v188, v189
	v_cvt_pk_bf16_f32 v245, v190, v191
	global_store_dwordx2 v[126:127], v[134:135], off
	global_store_dwordx2 v[128:129], v[136:137], off
	global_store_dwordx2 v[130:131], v[242:243], off
	global_store_dwordx2 v[132:133], v[244:245], off
	s_nop 1
	v_mul_f32_e32 v144, v144, v106
	v_mul_f32_e32 v145, v145, v106
	v_mul_f32_e32 v146, v146, v106
	v_mul_f32_e32 v147, v147, v106
	v_mul_f32_e32 v160, v160, v107
	v_mul_f32_e32 v161, v161, v107
	v_mul_f32_e32 v162, v162, v107
	v_mul_f32_e32 v163, v163, v107
	v_mul_f32_e32 v176, v176, v108
	v_mul_f32_e32 v177, v177, v108
	v_mul_f32_e32 v178, v178, v108
	v_mul_f32_e32 v179, v179, v108
	v_mul_f32_e32 v192, v192, v109
	v_mul_f32_e32 v193, v193, v109
	v_mul_f32_e32 v194, v194, v109
	v_mul_f32_e32 v195, v195, v109
	v_mul_f32_e32 v144, v144, v8
	v_mul_f32_e32 v145, v145, v9
	v_mul_f32_e32 v146, v146, v10
	v_mul_f32_e32 v147, v147, v11
	v_mul_f32_e32 v160, v160, v8
	v_mul_f32_e32 v161, v161, v9
	v_mul_f32_e32 v162, v162, v10
	v_mul_f32_e32 v163, v163, v11
	v_mul_f32_e32 v176, v176, v8
	v_mul_f32_e32 v177, v177, v9
	v_mul_f32_e32 v178, v178, v10
	v_mul_f32_e32 v179, v179, v11
	v_mul_f32_e32 v192, v192, v8
	v_mul_f32_e32 v193, v193, v9
	v_mul_f32_e32 v194, v194, v10
	v_mul_f32_e32 v195, v195, v11
	v_cvt_pk_bf16_f32 v134, v144, v145
	v_cvt_pk_bf16_f32 v135, v146, v147
	v_cvt_pk_bf16_f32 v136, v160, v161
	v_cvt_pk_bf16_f32 v137, v162, v163
	v_cvt_pk_bf16_f32 v242, v176, v177
	v_cvt_pk_bf16_f32 v243, v178, v179
	v_cvt_pk_bf16_f32 v244, v192, v193
	v_cvt_pk_bf16_f32 v245, v194, v195
	global_store_dwordx2 v[126:127], v[134:135], off offset:512
	global_store_dwordx2 v[128:129], v[136:137], off offset:512
	global_store_dwordx2 v[130:131], v[242:243], off offset:512
	global_store_dwordx2 v[132:133], v[244:245], off offset:512
	s_nop 1
	v_mul_f32_e32 v148, v148, v106
	v_mul_f32_e32 v149, v149, v106
	v_mul_f32_e32 v150, v150, v106
	v_mul_f32_e32 v151, v151, v106
	v_mul_f32_e32 v164, v164, v107
	v_mul_f32_e32 v165, v165, v107
	v_mul_f32_e32 v166, v166, v107
	v_mul_f32_e32 v167, v167, v107
	v_mul_f32_e32 v180, v180, v108
	v_mul_f32_e32 v181, v181, v108
	v_mul_f32_e32 v182, v182, v108
	v_mul_f32_e32 v183, v183, v108
	v_mul_f32_e32 v196, v196, v109
	v_mul_f32_e32 v197, v197, v109
	v_mul_f32_e32 v198, v198, v109
	v_mul_f32_e32 v199, v199, v109
	v_mul_f32_e32 v148, v148, v12
	v_mul_f32_e32 v149, v149, v13
	v_mul_f32_e32 v150, v150, v14
	v_mul_f32_e32 v151, v151, v15
	v_mul_f32_e32 v164, v164, v12
	v_mul_f32_e32 v165, v165, v13
	v_mul_f32_e32 v166, v166, v14
	v_mul_f32_e32 v167, v167, v15
	v_mul_f32_e32 v180, v180, v12
	v_mul_f32_e32 v181, v181, v13
	v_mul_f32_e32 v182, v182, v14
	v_mul_f32_e32 v183, v183, v15
	v_mul_f32_e32 v196, v196, v12
	v_mul_f32_e32 v197, v197, v13
	v_mul_f32_e32 v198, v198, v14
	v_mul_f32_e32 v199, v199, v15
	v_cvt_pk_bf16_f32 v134, v148, v149
	v_cvt_pk_bf16_f32 v135, v150, v151
	v_cvt_pk_bf16_f32 v136, v164, v165
	v_cvt_pk_bf16_f32 v137, v166, v167
	v_cvt_pk_bf16_f32 v242, v180, v181
	v_cvt_pk_bf16_f32 v243, v182, v183
	v_cvt_pk_bf16_f32 v244, v196, v197
	v_cvt_pk_bf16_f32 v245, v198, v199
	global_store_dwordx2 v[126:127], v[134:135], off offset:1024
	global_store_dwordx2 v[128:129], v[136:137], off offset:1024
	global_store_dwordx2 v[130:131], v[242:243], off offset:1024
	global_store_dwordx2 v[132:133], v[244:245], off offset:1024
	s_nop 1
	v_mul_f32_e32 v152, v152, v106
	v_mul_f32_e32 v153, v153, v106
	v_mul_f32_e32 v154, v154, v106
	v_mul_f32_e32 v155, v155, v106
	v_mul_f32_e32 v168, v168, v107
	v_mul_f32_e32 v169, v169, v107
	v_mul_f32_e32 v170, v170, v107
	v_mul_f32_e32 v171, v171, v107
	v_mul_f32_e32 v184, v184, v108
	v_mul_f32_e32 v185, v185, v108
	v_mul_f32_e32 v186, v186, v108
	v_mul_f32_e32 v187, v187, v108
	v_mul_f32_e32 v200, v200, v109
	v_mul_f32_e32 v201, v201, v109
	v_mul_f32_e32 v202, v202, v109
	v_mul_f32_e32 v203, v203, v109
	v_mul_f32_e32 v152, v152, v16
	v_mul_f32_e32 v153, v153, v17
	v_mul_f32_e32 v154, v154, v18
	v_mul_f32_e32 v155, v155, v19
	v_mul_f32_e32 v168, v168, v16
	v_mul_f32_e32 v169, v169, v17
	v_mul_f32_e32 v170, v170, v18
	v_mul_f32_e32 v171, v171, v19
	v_mul_f32_e32 v184, v184, v16
	v_mul_f32_e32 v185, v185, v17
	v_mul_f32_e32 v186, v186, v18
	v_mul_f32_e32 v187, v187, v19
	v_mul_f32_e32 v200, v200, v16
	v_mul_f32_e32 v201, v201, v17
	v_mul_f32_e32 v202, v202, v18
	v_mul_f32_e32 v203, v203, v19
	v_cvt_pk_bf16_f32 v134, v152, v153
	v_cvt_pk_bf16_f32 v135, v154, v155
	v_cvt_pk_bf16_f32 v136, v168, v169
	v_cvt_pk_bf16_f32 v137, v170, v171
	v_cvt_pk_bf16_f32 v242, v184, v185
	v_cvt_pk_bf16_f32 v243, v186, v187
	v_cvt_pk_bf16_f32 v244, v200, v201
	v_cvt_pk_bf16_f32 v245, v202, v203
	global_store_dwordx2 v[126:127], v[134:135], off offset:1536
	global_store_dwordx2 v[128:129], v[136:137], off offset:1536
	global_store_dwordx2 v[130:131], v[242:243], off offset:1536
	global_store_dwordx2 v[132:133], v[244:245], off offset:1536
	s_add_i32 s61, s61, s34
	s_cmpk_gt_i32 s61, 0xff
	s_barrier
	s_cbranch_scc1 .LBB0_657

; __device__ __forceinline__ unsigned cvt_pk_bf16(float lo, float hi) { unsigned r; asm volatile("v_cvt_pk_bf16_f32 %0, %1, %2" : "=v"(r) : "v"(lo), "v"(hi)); return r; }
; __device__ __forceinline__ float bf_lo(unsigned u) { return __uint_as_float(u << 16); }
; __device__ __forceinline__ float bf_hi(unsigned u) { return __uint_as_float(u & 0xffff0000u); }
;     __device__ __forceinline__ void operator()(const f32x4 (&acc)[2][2][4][2], const Unit& u, int wr, int wc, int fr, int fq) const {
;     ...
;             for (int m = 0; m < 4; ++m) { const int row = row0 + ai * HALF + m * 16; bf16_t* rowp = XB + (size_t)row * D + col0; float ss = 0.f;
; #pragma unroll
;                 for (int bj = 0; bj < 2; ++bj) { const u32x4 r = *(const u32x4*)(rowp + bj * HALF);
;                     const f32x4 o0 = (f32x4){bf_lo(r.x), bf_hi(r.x), bf_lo(r.y), bf_hi(r.y)} + acc[ai][bj][m][0] * alpha, o1 = (f32x4){bf_lo(r.z), bf_hi(r.z), bf_lo(r.w), bf_hi(r.w)} + acc[ai][bj][m][1] * alpha;
;                     ss += ((o0[0] * o0[0] + o0[1] * o0[1]) + (o0[2] * o0[2] + o0[3] * o0[3])) + ((o1[0] * o1[0] + o1[1] * o1[1]) + (o1[2] * o1[2] + o1[3] * o1[3]));
;                     u32x4 w; w.x = cvt_pk_bf16(o0[0], o0[1]); w.y = cvt_pk_bf16(o0[2], o0[3]); w.z = cvt_pk_bf16(o1[0], o1[1]); w.w = cvt_pk_bf16(o1[2], o1[3]);
;                     *(u32x4*)(rowp + bj * HALF) = w; }
;                 ss += __shfl_xor(ss, 16); ss += __shfl_xor(ss, 32);
;                 if (fq == 0) part[(size_t)row * NPART + u.pn * 4 + wc] = ss; }
.LBB0_848:
	v_lshl_add_u32 v146, s11, 8, v148
	v_ashrrev_i32_e32 v147, 31, v146
	v_lshl_or_b32 v144, s64, 8, v150
	v_lshlrev_b64 v[156:157], 12, v[146:147]
	v_ashrrev_i32_e32 v145, 31, v144
	v_lshl_add_u64 v[156:157], s[50:51], 0, v[156:157]
	v_lshl_add_u64 v[160:161], v[144:145], 1, v[156:157]
	global_load_dwordx4 v[156:159], v[160:161], off
	v_xor_b32_e32 v155, 32, v154
	s_waitcnt vmcnt(0)
	v_lshlrev_b32_e32 v162, 16, v156
	v_and_b32_e32 v163, 0xffff0000, v156
	v_lshlrev_b32_e32 v156, 16, v157
	v_and_b32_e32 v157, 0xffff0000, v157
	v_lshlrev_b32_e32 v164, 16, v158
	v_and_b32_e32 v165, 0xffff0000, v158
	v_lshlrev_b32_e32 v158, 16, v159
	v_and_b32_e32 v159, 0xffff0000, v159
	v_pk_add_f32 v[126:127], v[126:127], v[156:157]
	v_pk_add_f32 v[162:163], v[124:125], v[162:163]
	v_pk_add_f32 v[166:167], v[122:123], v[158:159]
	v_pk_add_f32 v[164:165], v[120:121], v[164:165]
	v_cvt_pk_bf16_f32 v122, v162, v163
	v_cvt_pk_bf16_f32 v123, v126, v127
	v_mul_f32_e32 v163, v163, v163
	v_cvt_pk_bf16_f32 v124, v164, v165
	v_cvt_pk_bf16_f32 v125, v166, v167
	global_load_dwordx4 v[156:159], v[160:161], off offset:256
	v_mul_f32_e32 v127, v127, v127
	v_mul_f32_e32 v165, v165, v165
	v_mul_f32_e32 v167, v167, v167
	v_fmac_f32_e32 v163, v162, v162
	v_fmac_f32_e32 v127, v126, v126
	v_fmac_f32_e32 v165, v164, v164
	v_fmac_f32_e32 v167, v166, v166
	v_add_f32_e32 v126, v163, v127
	v_add_f32_e32 v127, v165, v167
	v_add_f32_e32 v164, v126, v127
	v_and_b32_e32 v121, 64, v154
	v_xor_b32_e32 v120, 16, v154
	v_add_u32_e32 v121, 64, v121
	v_cmp_lt_i32_e32 vcc, v120, v121
	global_store_dwordx4 v[160:161], v[122:125], off
	s_waitcnt vmcnt(1)
	v_lshlrev_b32_e32 v126, 16, v156
	v_and_b32_e32 v127, 0xffff0000, v156
	v_lshlrev_b32_e32 v156, 16, v157
	v_and_b32_e32 v157, 0xffff0000, v157
	v_lshlrev_b32_e32 v162, 16, v158
	v_and_b32_e32 v163, 0xffff0000, v158
	v_lshlrev_b32_e32 v158, 16, v159
	v_and_b32_e32 v159, 0xffff0000, v159
	v_pk_add_f32 v[118:119], v[118:119], v[156:157]
	v_pk_add_f32 v[116:117], v[116:117], v[126:127]
	v_pk_add_f32 v[126:127], v[114:115], v[158:159]
	v_pk_add_f32 v[156:157], v[112:113], v[162:163]
	v_mul_f32_e32 v112, v117, v117
	v_mul_f32_e32 v113, v119, v119
	v_mul_f32_e32 v114, v157, v157
	v_mul_f32_e32 v115, v127, v127
	v_fmac_f32_e32 v112, v116, v116
	v_fmac_f32_e32 v113, v118, v118
	v_fmac_f32_e32 v114, v156, v156
	v_fmac_f32_e32 v115, v126, v126
	v_add_f32_e32 v112, v112, v113
	v_add_f32_e32 v113, v114, v115
	v_cndmask_b32_e32 v120, v154, v120, vcc
	v_add_f32_e32 v112, v112, v113
	v_lshlrev_b32_e32 v120, 2, v120
	v_add_f32_e32 v112, v164, v112
	v_mov_b32_e32 v113, v112
	s_nop 1
	v_permlane16_swap_b32_e32 v112, v113
	s_nop 1
	v_cmp_lt_i32_e32 vcc, v155, v121
	v_cvt_pk_bf16_f32 v116, v116, v117
	v_cvt_pk_bf16_f32 v117, v118, v119
	v_cvt_pk_bf16_f32 v118, v156, v157
	s_waitcnt lgkmcnt(0)
	v_add_f32_e32 v112, v112, v113
	v_cvt_pk_bf16_f32 v119, v126, v127
	v_cndmask_b32_e32 v114, v154, v155, vcc
	v_lshlrev_b32_e32 v114, 2, v114
	v_mov_b32_e32 v113, v112
	s_nop 1
	v_permlane32_swap_b32_e32 v112, v113
	s_nop 1
	global_store_dwordx4 v[160:161], v[116:119], off offset:256
	s_and_saveexec_b64 s[58:59], s[2:3]
	s_cbranch_execz .LBB0_850
	s_waitcnt lgkmcnt(0)
	v_add_f32_e32 v115, v112, v113
	s_lshl_b32 s18, s64, 2
	v_lshlrev_b64 v[112:113], 7, v[146:147]
	s_ashr_i32 s19, s18, 31
	v_lshl_add_u64 v[112:113], s[48:49], 0, v[112:113]
	v_lshl_add_u64 v[112:113], s[18:19], 2, v[112:113]
	s_lshl_b32 s18, s70, 2
	s_mov_b32 s19, s23
	v_lshl_add_u64 v[112:113], v[112:113], 0, s[18:19]
	global_store_dword v[112:113], v115, off
.LBB0_850:
	s_or_b64 exec, exec, s[58:59]
	v_or_b32_e32 v112, 16, v146
	s_waitcnt lgkmcnt(0)
	v_ashrrev_i32_e32 v113, 31, v112
	v_lshlrev_b64 v[116:117], 12, v[112:113]
	v_lshl_add_u64 v[116:117], s[50:51], 0, v[116:117]
	v_lshl_add_u64 v[122:123], v[144:145], 1, v[116:117]
	global_load_dwordx4 v[116:119], v[122:123], off
	s_waitcnt vmcnt(0)
	v_lshlrev_b32_e32 v124, 16, v116
	v_and_b32_e32 v125, 0xffff0000, v116
	v_lshlrev_b32_e32 v116, 16, v117
	v_and_b32_e32 v117, 0xffff0000, v117
	v_lshlrev_b32_e32 v126, 16, v118
	v_and_b32_e32 v127, 0xffff0000, v118
	v_lshlrev_b32_e32 v118, 16, v119
	v_and_b32_e32 v119, 0xffff0000, v119
	v_pk_add_f32 v[116:117], v[110:111], v[116:117]
	v_pk_add_f32 v[124:125], v[108:109], v[124:125]
	v_pk_add_f32 v[118:119], v[106:107], v[118:119]
	v_pk_add_f32 v[126:127], v[104:105], v[126:127]
	v_cvt_pk_bf16_f32 v104, v124, v125
	v_cvt_pk_bf16_f32 v105, v116, v117
	v_mul_f32_e32 v115, v125, v125
	v_cvt_pk_bf16_f32 v106, v126, v127
	v_cvt_pk_bf16_f32 v107, v118, v119
	global_load_dwordx4 v[108:111], v[122:123], off offset:256
	v_mul_f32_e32 v117, v117, v117
	v_mul_f32_e32 v121, v127, v127
	v_mul_f32_e32 v119, v119, v119
	v_fmac_f32_e32 v115, v124, v124
	v_fmac_f32_e32 v117, v116, v116
	v_fmac_f32_e32 v121, v126, v126
	v_fmac_f32_e32 v119, v118, v118
	v_add_f32_e32 v115, v115, v117
	v_add_f32_e32 v116, v121, v119
	v_add_f32_e32 v115, v115, v116
	global_store_dwordx4 v[122:123], v[104:107], off
	s_waitcnt vmcnt(1)
	v_lshlrev_b32_e32 v116, 16, v108
	v_and_b32_e32 v117, 0xffff0000, v108
	v_lshlrev_b32_e32 v108, 16, v109
	v_and_b32_e32 v109, 0xffff0000, v109
	v_lshlrev_b32_e32 v118, 16, v110
	v_and_b32_e32 v119, 0xffff0000, v110
	v_lshlrev_b32_e32 v110, 16, v111
	v_and_b32_e32 v111, 0xffff0000, v111
	v_pk_add_f32 v[102:103], v[102:103], v[108:109]
	v_pk_add_f32 v[100:101], v[100:101], v[116:117]
	v_pk_add_f32 v[108:109], v[98:99], v[110:111]
	v_pk_add_f32 v[110:111], v[96:97], v[118:119]
	v_mul_f32_e32 v96, v101, v101
	v_mul_f32_e32 v97, v103, v103
	v_mul_f32_e32 v98, v111, v111
	v_mul_f32_e32 v99, v109, v109
	v_fmac_f32_e32 v96, v100, v100
	v_fmac_f32_e32 v97, v102, v102
	v_fmac_f32_e32 v98, v110, v110
	v_fmac_f32_e32 v99, v108, v108
	v_add_f32_e32 v96, v96, v97
	v_add_f32_e32 v97, v98, v99
	v_add_f32_e32 v96, v96, v97
	v_add_f32_e32 v96, v115, v96
	v_mov_b32_e32 v97, v96
	s_nop 1
	v_permlane16_swap_b32_e32 v96, v97
	s_nop 1
	v_cvt_pk_bf16_f32 v98, v100, v101
	v_cvt_pk_bf16_f32 v99, v102, v103
	v_cvt_pk_bf16_f32 v100, v110, v111
	v_cvt_pk_bf16_f32 v101, v108, v109
	s_waitcnt lgkmcnt(0)
	v_add_f32_e32 v96, v96, v97
	v_mov_b32_e32 v97, v96
	s_nop 1
	v_permlane32_swap_b32_e32 v96, v97
	s_nop 1
	global_store_dwordx4 v[122:123], v[98:101], off offset:256
	s_and_saveexec_b64 s[58:59], s[2:3]
	s_cbranch_execz .LBB0_852
	s_waitcnt lgkmcnt(0)
	v_add_f32_e32 v98, v96, v97
	s_lshl_b32 s18, s64, 2
	v_lshlrev_b64 v[96:97], 7, v[112:113]
	s_ashr_i32 s19, s18, 31
	v_lshl_add_u64 v[96:97], s[48:49], 0, v[96:97]
	v_lshl_add_u64 v[96:97], s[18:19], 2, v[96:97]
	s_lshl_b32 s18, s70, 2
	s_mov_b32 s19, s23
	v_lshl_add_u64 v[96:97], v[96:97], 0, s[18:19]
	global_store_dword v[96:97], v98, off
; __device__ __forceinline__ unsigned cvt_pk_bf16(float lo, float hi) { unsigned r; asm volatile("v_cvt_pk_bf16_f32 %0, %1, %2" : "=v"(r) : "v"(lo), "v"(hi)); return r; }
; __device__ __forceinline__ float bf_lo(unsigned u) { return __uint_as_float(u << 16); }
; __device__ __forceinline__ float bf_hi(unsigned u) { return __uint_as_float(u & 0xffff0000u); }
;     __device__ __forceinline__ void operator()(const f32x4 (&acc)[2][2][4][2], const Unit& u, int wr, int wc, int fr, int fq) const {
;     ...
;             for (int m = 0; m < 4; ++m) { const int row = row0 + ai * HALF + m * 16; bf16_t* rowp = XB + (size_t)row * D + col0; float ss = 0.f;
; #pragma unroll
;                 for (int bj = 0; bj < 2; ++bj) { const u32x4 r = *(const u32x4*)(rowp + bj * HALF);
;                     const f32x4 o0 = (f32x4){bf_lo(r.x), bf_hi(r.x), bf_lo(r.y), bf_hi(r.y)} + acc[ai][bj][m][0] * alpha, o1 = (f32x4){bf_lo(r.z), bf_hi(r.z), bf_lo(r.w), bf_hi(r.w)} + acc[ai][bj][m][1] * alpha;
;                     ss += ((o0[0] * o0[0] + o0[1] * o0[1]) + (o0[2] * o0[2] + o0[3] * o0[3])) + ((o1[0] * o1[0] + o1[1] * o1[1]) + (o1[2] * o1[2] + o1[3] * o1[3]));
;                     u32x4 w; w.x = cvt_pk_bf16(o0[0], o0[1]); w.y = cvt_pk_bf16(o0[2], o0[3]); w.z = cvt_pk_bf16(o1[0], o1[1]); w.w = cvt_pk_bf16(o1[2], o1[3]);
;                     *(u32x4*)(rowp + bj * HALF) = w; }
;                 ss += __shfl_xor(ss, 16); ss += __shfl_xor(ss, 32);
;                 if (fq == 0) part[(size_t)row * NPART + u.pn * 4 + wc] = ss; }
.LBB0_852:
	s_or_b64 exec, exec, s[58:59]
	v_or_b32_e32 v96, 32, v146
	s_waitcnt lgkmcnt(0)
	v_ashrrev_i32_e32 v97, 31, v96
	v_lshlrev_b64 v[98:99], 12, v[96:97]
	v_lshl_add_u64 v[98:99], s[50:51], 0, v[98:99]
	v_lshl_add_u64 v[102:103], v[144:145], 1, v[98:99]
	global_load_dwordx4 v[98:101], v[102:103], off
	s_waitcnt vmcnt(0)
	v_lshlrev_b32_e32 v104, 16, v98
	v_and_b32_e32 v105, 0xffff0000, v98
	v_lshlrev_b32_e32 v98, 16, v99
	v_and_b32_e32 v99, 0xffff0000, v99
	v_lshlrev_b32_e32 v106, 16, v100
	v_and_b32_e32 v107, 0xffff0000, v100
	v_lshlrev_b32_e32 v100, 16, v101
	v_and_b32_e32 v101, 0xffff0000, v101
	v_pk_add_f32 v[98:99], v[94:95], v[98:99]
	v_pk_add_f32 v[104:105], v[92:93], v[104:105]
	v_pk_add_f32 v[100:101], v[90:91], v[100:101]
	v_pk_add_f32 v[106:107], v[88:89], v[106:107]
	v_cvt_pk_bf16_f32 v88, v104, v105
	v_cvt_pk_bf16_f32 v89, v98, v99
	v_mul_f32_e32 v105, v105, v105
	v_cvt_pk_bf16_f32 v90, v106, v107
	v_cvt_pk_bf16_f32 v91, v100, v101
	global_load_dwordx4 v[92:95], v[102:103], off offset:256
	v_mul_f32_e32 v99, v99, v99
	v_mul_f32_e32 v107, v107, v107
	v_mul_f32_e32 v101, v101, v101
	v_fmac_f32_e32 v105, v104, v104
	v_fmac_f32_e32 v99, v98, v98
	v_fmac_f32_e32 v107, v106, v106
	v_fmac_f32_e32 v101, v100, v100
	v_add_f32_e32 v98, v105, v99
	v_add_f32_e32 v99, v107, v101
	v_add_f32_e32 v104, v98, v99
	global_store_dwordx4 v[102:103], v[88:91], off
	s_waitcnt vmcnt(1)
	v_lshlrev_b32_e32 v98, 16, v92
	v_and_b32_e32 v99, 0xffff0000, v92
	v_lshlrev_b32_e32 v92, 16, v93
	v_and_b32_e32 v93, 0xffff0000, v93
	v_lshlrev_b32_e32 v100, 16, v94
	v_and_b32_e32 v101, 0xffff0000, v94
	v_lshlrev_b32_e32 v94, 16, v95
	v_and_b32_e32 v95, 0xffff0000, v95
	v_pk_add_f32 v[86:87], v[86:87], v[92:93]
	v_pk_add_f32 v[84:85], v[84:85], v[98:99]
	v_pk_add_f32 v[92:93], v[82:83], v[94:95]
	v_pk_add_f32 v[94:95], v[80:81], v[100:101]
	v_mul_f32_e32 v80, v85, v85
	v_mul_f32_e32 v81, v87, v87
	v_mul_f32_e32 v82, v95, v95
	v_mul_f32_e32 v83, v93, v93
	v_fmac_f32_e32 v80, v84, v84
	v_fmac_f32_e32 v81, v86, v86
	v_fmac_f32_e32 v82, v94, v94
	v_fmac_f32_e32 v83, v92, v92
	v_add_f32_e32 v80, v80, v81
	v_add_f32_e32 v81, v82, v83
	v_add_f32_e32 v80, v80, v81
	v_add_f32_e32 v80, v104, v80
	v_mov_b32_e32 v81, v80
	s_nop 1
	v_permlane16_swap_b32_e32 v80, v81
	s_nop 1
	v_cvt_pk_bf16_f32 v82, v84, v85
	v_cvt_pk_bf16_f32 v83, v86, v87
	v_cvt_pk_bf16_f32 v84, v94, v95
	v_cvt_pk_bf16_f32 v85, v92, v93
	s_waitcnt lgkmcnt(0)
	v_add_f32_e32 v80, v80, v81
	v_mov_b32_e32 v81, v80
	s_nop 1
	v_permlane32_swap_b32_e32 v80, v81
	s_nop 1
	global_store_dwordx4 v[102:103], v[82:85], off offset:256
	s_and_saveexec_b64 s[58:59], s[2:3]
	s_cbranch_execz .LBB0_854
	s_waitcnt lgkmcnt(0)
	v_add_f32_e32 v82, v80, v81
	s_lshl_b32 s18, s64, 2
	v_lshlrev_b64 v[80:81], 7, v[96:97]
	s_ashr_i32 s19, s18, 31
	v_lshl_add_u64 v[80:81], s[48:49], 0, v[80:81]
	v_lshl_add_u64 v[80:81], s[18:19], 2, v[80:81]
	s_lshl_b32 s18, s70, 2
	s_mov_b32 s19, s23
	v_lshl_add_u64 v[80:81], v[80:81], 0, s[18:19]
	global_store_dword v[80:81], v82, off
.LBB0_854:
	s_or_b64 exec, exec, s[58:59]
	v_or_b32_e32 v80, 48, v146
	s_waitcnt lgkmcnt(0)
	v_ashrrev_i32_e32 v81, 31, v80
	v_lshlrev_b64 v[82:83], 12, v[80:81]
	v_lshl_add_u64 v[82:83], s[50:51], 0, v[82:83]
	v_lshl_add_u64 v[86:87], v[144:145], 1, v[82:83]
	global_load_dwordx4 v[82:85], v[86:87], off
	s_waitcnt vmcnt(0)
	v_lshlrev_b32_e32 v88, 16, v82
	v_and_b32_e32 v89, 0xffff0000, v82
	v_lshlrev_b32_e32 v82, 16, v83
	v_and_b32_e32 v83, 0xffff0000, v83
	v_lshlrev_b32_e32 v90, 16, v84
	v_and_b32_e32 v91, 0xffff0000, v84
	v_lshlrev_b32_e32 v84, 16, v85
	v_and_b32_e32 v85, 0xffff0000, v85
	v_pk_add_f32 v[82:83], v[78:79], v[82:83]
	v_pk_add_f32 v[88:89], v[76:77], v[88:89]
	v_pk_add_f32 v[84:85], v[74:75], v[84:85]
	v_pk_add_f32 v[90:91], v[72:73], v[90:91]
	v_cvt_pk_bf16_f32 v72, v88, v89
	v_cvt_pk_bf16_f32 v73, v82, v83
	v_mul_f32_e32 v89, v89, v89
	v_cvt_pk_bf16_f32 v74, v90, v91
	v_cvt_pk_bf16_f32 v75, v84, v85
	global_load_dwordx4 v[76:79], v[86:87], off offset:256
	v_mul_f32_e32 v83, v83, v83
	v_mul_f32_e32 v91, v91, v91
	v_mul_f32_e32 v85, v85, v85
	v_fmac_f32_e32 v89, v88, v88
	v_fmac_f32_e32 v83, v82, v82
	v_fmac_f32_e32 v91, v90, v90
	v_fmac_f32_e32 v85, v84, v84
	v_add_f32_e32 v82, v89, v83
	v_add_f32_e32 v83, v91, v85
	v_add_f32_e32 v88, v82, v83
	global_store_dwordx4 v[86:87], v[72:75], off
	s_waitcnt vmcnt(1)
	v_lshlrev_b32_e32 v82, 16, v76
	v_and_b32_e32 v83, 0xffff0000, v76
	v_lshlrev_b32_e32 v76, 16, v77
	v_and_b32_e32 v77, 0xffff0000, v77
	v_lshlrev_b32_e32 v84, 16, v78
	v_and_b32_e32 v85, 0xffff0000, v78
	v_lshlrev_b32_e32 v78, 16, v79
	v_and_b32_e32 v79, 0xffff0000, v79
	v_pk_add_f32 v[70:71], v[70:71], v[76:77]
	v_pk_add_f32 v[68:69], v[68:69], v[82:83]
	v_pk_add_f32 v[76:77], v[66:67], v[78:79]
	v_pk_add_f32 v[78:79], v[64:65], v[84:85]
	v_mul_f32_e32 v64, v69, v69
	v_mul_f32_e32 v65, v71, v71
	v_mul_f32_e32 v66, v79, v79
	v_mul_f32_e32 v67, v77, v77
	v_fmac_f32_e32 v64, v68, v68
	v_fmac_f32_e32 v65, v70, v70
	v_fmac_f32_e32 v66, v78, v78
	v_fmac_f32_e32 v67, v76, v76
	v_add_f32_e32 v64, v64, v65
	v_add_f32_e32 v65, v66, v67
	v_add_f32_e32 v64, v64, v65
	v_add_f32_e32 v64, v88, v64
	v_mov_b32_e32 v65, v64
	s_nop 1
	v_permlane16_swap_b32_e32 v64, v65
	s_nop 1
	v_cvt_pk_bf16_f32 v66, v68, v69
	v_cvt_pk_bf16_f32 v67, v70, v71
	v_cvt_pk_bf16_f32 v68, v78, v79
	v_cvt_pk_bf16_f32 v69, v76, v77
	s_waitcnt lgkmcnt(0)
	v_add_f32_e32 v64, v64, v65
	v_mov_b32_e32 v65, v64
	s_nop 1
	v_permlane32_swap_b32_e32 v64, v65
	s_nop 1
	global_store_dwordx4 v[86:87], v[66:69], off offset:256
	s_and_saveexec_b64 s[58:59], s[2:3]
	s_cbranch_execz .LBB0_856
	s_waitcnt lgkmcnt(0)
	v_add_f32_e32 v66, v64, v65
	s_lshl_b32 s18, s64, 2
	v_lshlrev_b64 v[64:65], 7, v[80:81]
	s_ashr_i32 s19, s18, 31
	v_lshl_add_u64 v[64:65], s[48:49], 0, v[64:65]
	v_lshl_add_u64 v[64:65], s[18:19], 2, v[64:65]
	s_lshl_b32 s18, s70, 2
	s_mov_b32 s19, s23
	v_lshl_add_u64 v[64:65], v[64:65], 0, s[18:19]
	global_store_dword v[64:65], v66, off
; __device__ __forceinline__ unsigned cvt_pk_bf16(float lo, float hi) { unsigned r; asm volatile("v_cvt_pk_bf16_f32 %0, %1, %2" : "=v"(r) : "v"(lo), "v"(hi)); return r; }
; __device__ __forceinline__ float bf_lo(unsigned u) { return __uint_as_float(u << 16); }
; __device__ __forceinline__ float bf_hi(unsigned u) { return __uint_as_float(u & 0xffff0000u); }
;     __device__ __forceinline__ void operator()(const f32x4 (&acc)[2][2][4][2], const Unit& u, int wr, int wc, int fr, int fq) const {
;     ...
;             for (int m = 0; m < 4; ++m) { const int row = row0 + ai * HALF + m * 16; bf16_t* rowp = XB + (size_t)row * D + col0; float ss = 0.f;
; #pragma unroll
;                 for (int bj = 0; bj < 2; ++bj) { const u32x4 r = *(const u32x4*)(rowp + bj * HALF);
;                     const f32x4 o0 = (f32x4){bf_lo(r.x), bf_hi(r.x), bf_lo(r.y), bf_hi(r.y)} + acc[ai][bj][m][0] * alpha, o1 = (f32x4){bf_lo(r.z), bf_hi(r.z), bf_lo(r.w), bf_hi(r.w)} + acc[ai][bj][m][1] * alpha;
;                     ss += ((o0[0] * o0[0] + o0[1] * o0[1]) + (o0[2] * o0[2] + o0[3] * o0[3])) + ((o1[0] * o1[0] + o1[1] * o1[1]) + (o1[2] * o1[2] + o1[3] * o1[3]));
;                     u32x4 w; w.x = cvt_pk_bf16(o0[0], o0[1]); w.y = cvt_pk_bf16(o0[2], o0[3]); w.z = cvt_pk_bf16(o1[0], o1[1]); w.w = cvt_pk_bf16(o1[2], o1[3]);
;                     *(u32x4*)(rowp + bj * HALF) = w; }
;                 ss += __shfl_xor(ss, 16); ss += __shfl_xor(ss, 32);
;                 if (fq == 0) part[(size_t)row * NPART + u.pn * 4 + wc] = ss; }
.LBB0_856:
	s_or_b64 exec, exec, s[58:59]
	v_add_u32_e32 v64, 0x80, v146
	s_waitcnt lgkmcnt(0)
	v_ashrrev_i32_e32 v65, 31, v64
	v_lshlrev_b64 v[66:67], 12, v[64:65]
	v_lshl_add_u64 v[66:67], s[50:51], 0, v[66:67]
	v_lshl_add_u64 v[70:71], v[144:145], 1, v[66:67]
	global_load_dwordx4 v[66:69], v[70:71], off
	s_waitcnt vmcnt(0)
	v_lshlrev_b32_e32 v72, 16, v66
	v_and_b32_e32 v73, 0xffff0000, v66
	v_lshlrev_b32_e32 v66, 16, v67
	v_and_b32_e32 v67, 0xffff0000, v67
	v_lshlrev_b32_e32 v74, 16, v68
	v_and_b32_e32 v75, 0xffff0000, v68
	v_lshlrev_b32_e32 v68, 16, v69
	v_and_b32_e32 v69, 0xffff0000, v69
	v_pk_add_f32 v[66:67], v[62:63], v[66:67]
	v_pk_add_f32 v[72:73], v[60:61], v[72:73]
	v_pk_add_f32 v[68:69], v[58:59], v[68:69]
	v_pk_add_f32 v[74:75], v[56:57], v[74:75]
	v_cvt_pk_bf16_f32 v56, v72, v73
	v_cvt_pk_bf16_f32 v57, v66, v67
	v_mul_f32_e32 v73, v73, v73
	v_cvt_pk_bf16_f32 v58, v74, v75
	v_cvt_pk_bf16_f32 v59, v68, v69
	global_load_dwordx4 v[60:63], v[70:71], off offset:256
	v_mul_f32_e32 v67, v67, v67
	v_mul_f32_e32 v75, v75, v75
	v_mul_f32_e32 v69, v69, v69
	v_fmac_f32_e32 v73, v72, v72
	v_fmac_f32_e32 v67, v66, v66
	v_fmac_f32_e32 v75, v74, v74
	v_fmac_f32_e32 v69, v68, v68
	v_add_f32_e32 v66, v73, v67
	v_add_f32_e32 v67, v75, v69
	v_add_f32_e32 v72, v66, v67
	global_store_dwordx4 v[70:71], v[56:59], off
	s_waitcnt vmcnt(1)
	v_lshlrev_b32_e32 v66, 16, v60
	v_and_b32_e32 v67, 0xffff0000, v60
	v_lshlrev_b32_e32 v60, 16, v61
	v_and_b32_e32 v61, 0xffff0000, v61
	v_lshlrev_b32_e32 v68, 16, v62
	v_and_b32_e32 v69, 0xffff0000, v62
	v_lshlrev_b32_e32 v62, 16, v63
	v_and_b32_e32 v63, 0xffff0000, v63
	v_pk_add_f32 v[54:55], v[54:55], v[60:61]
	v_pk_add_f32 v[52:53], v[52:53], v[66:67]
	v_pk_add_f32 v[60:61], v[50:51], v[62:63]
	v_pk_add_f32 v[62:63], v[48:49], v[68:69]
	v_mul_f32_e32 v48, v53, v53
	v_mul_f32_e32 v49, v55, v55
	v_mul_f32_e32 v50, v63, v63
	v_mul_f32_e32 v51, v61, v61
	v_fmac_f32_e32 v48, v52, v52
	v_fmac_f32_e32 v49, v54, v54
	v_fmac_f32_e32 v50, v62, v62
	v_fmac_f32_e32 v51, v60, v60
	v_add_f32_e32 v48, v48, v49
	v_add_f32_e32 v49, v50, v51
	v_add_f32_e32 v48, v48, v49
	v_add_f32_e32 v48, v72, v48
	v_mov_b32_e32 v49, v48
	s_nop 1
	v_permlane16_swap_b32_e32 v48, v49
	s_nop 1
	v_cvt_pk_bf16_f32 v50, v52, v53
	v_cvt_pk_bf16_f32 v51, v54, v55
	v_cvt_pk_bf16_f32 v52, v62, v63
	v_cvt_pk_bf16_f32 v53, v60, v61
	s_waitcnt lgkmcnt(0)
	v_add_f32_e32 v48, v48, v49
	v_mov_b32_e32 v49, v48
	s_nop 1
	v_permlane32_swap_b32_e32 v48, v49
	s_nop 1
	global_store_dwordx4 v[70:71], v[50:53], off offset:256
	s_and_saveexec_b64 s[58:59], s[2:3]
	s_cbranch_execz .LBB0_858
	s_waitcnt lgkmcnt(0)
	v_add_f32_e32 v50, v48, v49
	s_lshl_b32 s18, s64, 2
	v_lshlrev_b64 v[48:49], 7, v[64:65]
	s_ashr_i32 s19, s18, 31
	v_lshl_add_u64 v[48:49], s[48:49], 0, v[48:49]
	v_lshl_add_u64 v[48:49], s[18:19], 2, v[48:49]
	s_lshl_b32 s18, s70, 2
	s_mov_b32 s19, s23
	v_lshl_add_u64 v[48:49], v[48:49], 0, s[18:19]
	global_store_dword v[48:49], v50, off
.LBB0_858:
	s_or_b64 exec, exec, s[58:59]
	v_add_u32_e32 v48, 0x90, v146
	s_waitcnt lgkmcnt(0)
	v_ashrrev_i32_e32 v49, 31, v48
	v_lshlrev_b64 v[50:51], 12, v[48:49]
	v_lshl_add_u64 v[50:51], s[50:51], 0, v[50:51]
	v_lshl_add_u64 v[54:55], v[144:145], 1, v[50:51]
	global_load_dwordx4 v[50:53], v[54:55], off
	s_waitcnt vmcnt(0)
	v_lshlrev_b32_e32 v56, 16, v50
	v_and_b32_e32 v57, 0xffff0000, v50
	v_lshlrev_b32_e32 v50, 16, v51
	v_and_b32_e32 v51, 0xffff0000, v51
	v_lshlrev_b32_e32 v58, 16, v52
	v_and_b32_e32 v59, 0xffff0000, v52
	v_lshlrev_b32_e32 v52, 16, v53
	v_and_b32_e32 v53, 0xffff0000, v53
	v_pk_add_f32 v[50:51], v[46:47], v[50:51]
	v_pk_add_f32 v[56:57], v[44:45], v[56:57]
	v_pk_add_f32 v[52:53], v[42:43], v[52:53]
	v_pk_add_f32 v[58:59], v[40:41], v[58:59]
	v_cvt_pk_bf16_f32 v40, v56, v57
	v_cvt_pk_bf16_f32 v41, v50, v51
	v_mul_f32_e32 v57, v57, v57
	v_cvt_pk_bf16_f32 v42, v58, v59
	v_cvt_pk_bf16_f32 v43, v52, v53
	global_load_dwordx4 v[44:47], v[54:55], off offset:256
	v_mul_f32_e32 v51, v51, v51
	v_mul_f32_e32 v59, v59, v59
	v_mul_f32_e32 v53, v53, v53
	v_fmac_f32_e32 v57, v56, v56
	v_fmac_f32_e32 v51, v50, v50
	v_fmac_f32_e32 v59, v58, v58
	v_fmac_f32_e32 v53, v52, v52
	v_add_f32_e32 v50, v57, v51
	v_add_f32_e32 v51, v59, v53
	v_add_f32_e32 v56, v50, v51
	global_store_dwordx4 v[54:55], v[40:43], off
	s_waitcnt vmcnt(1)
	v_lshlrev_b32_e32 v50, 16, v44
	v_and_b32_e32 v51, 0xffff0000, v44
	v_lshlrev_b32_e32 v44, 16, v45
	v_and_b32_e32 v45, 0xffff0000, v45
	v_lshlrev_b32_e32 v52, 16, v46
	v_and_b32_e32 v53, 0xffff0000, v46
	v_lshlrev_b32_e32 v46, 16, v47
	v_and_b32_e32 v47, 0xffff0000, v47
	v_pk_add_f32 v[38:39], v[38:39], v[44:45]
	v_pk_add_f32 v[36:37], v[36:37], v[50:51]
	v_pk_add_f32 v[44:45], v[34:35], v[46:47]
	v_pk_add_f32 v[46:47], v[32:33], v[52:53]
	v_mul_f32_e32 v32, v37, v37
	v_mul_f32_e32 v33, v39, v39
	v_mul_f32_e32 v34, v47, v47
	v_mul_f32_e32 v35, v45, v45
	v_fmac_f32_e32 v32, v36, v36
	v_fmac_f32_e32 v33, v38, v38
	v_fmac_f32_e32 v34, v46, v46
	v_fmac_f32_e32 v35, v44, v44
	v_add_f32_e32 v32, v32, v33
	v_add_f32_e32 v33, v34, v35
	v_add_f32_e32 v32, v32, v33
	v_add_f32_e32 v32, v56, v32
	v_mov_b32_e32 v33, v32
	s_nop 1
	v_permlane16_swap_b32_e32 v32, v33
	s_nop 1
	v_cvt_pk_bf16_f32 v34, v36, v37
	v_cvt_pk_bf16_f32 v35, v38, v39
	v_cvt_pk_bf16_f32 v36, v46, v47
	v_cvt_pk_bf16_f32 v37, v44, v45
	s_waitcnt lgkmcnt(0)
	v_add_f32_e32 v32, v32, v33
	v_mov_b32_e32 v33, v32
	s_nop 1
	v_permlane32_swap_b32_e32 v32, v33
	s_nop 1
	global_store_dwordx4 v[54:55], v[34:37], off offset:256
	s_and_saveexec_b64 s[58:59], s[2:3]
	s_cbranch_execz .LBB0_860
	s_waitcnt lgkmcnt(0)
	v_add_f32_e32 v34, v32, v33
	s_lshl_b32 s18, s64, 2
	v_lshlrev_b64 v[32:33], 7, v[48:49]
	s_ashr_i32 s19, s18, 31
	v_lshl_add_u64 v[32:33], s[48:49], 0, v[32:33]
	v_lshl_add_u64 v[32:33], s[18:19], 2, v[32:33]
	s_lshl_b32 s18, s70, 2
	s_mov_b32 s19, s23
	v_lshl_add_u64 v[32:33], v[32:33], 0, s[18:19]
	global_store_dword v[32:33], v34, off
; __device__ __forceinline__ unsigned cvt_pk_bf16(float lo, float hi) { unsigned r; asm volatile("v_cvt_pk_bf16_f32 %0, %1, %2" : "=v"(r) : "v"(lo), "v"(hi)); return r; }
; __device__ __forceinline__ float bf_lo(unsigned u) { return __uint_as_float(u << 16); }
; __device__ __forceinline__ float bf_hi(unsigned u) { return __uint_as_float(u & 0xffff0000u); }
;     __device__ __forceinline__ void operator()(const f32x4 (&acc)[2][2][4][2], const Unit& u, int wr, int wc, int fr, int fq) const {
;     ...
;             for (int m = 0; m < 4; ++m) { const int row = row0 + ai * HALF + m * 16; bf16_t* rowp = XB + (size_t)row * D + col0; float ss = 0.f;
; #pragma unroll
;                 for (int bj = 0; bj < 2; ++bj) { const u32x4 r = *(const u32x4*)(rowp + bj * HALF);
;                     const f32x4 o0 = (f32x4){bf_lo(r.x), bf_hi(r.x), bf_lo(r.y), bf_hi(r.y)} + acc[ai][bj][m][0] * alpha, o1 = (f32x4){bf_lo(r.z), bf_hi(r.z), bf_lo(r.w), bf_hi(r.w)} + acc[ai][bj][m][1] * alpha;
;                     ss += ((o0[0] * o0[0] + o0[1] * o0[1]) + (o0[2] * o0[2] + o0[3] * o0[3])) + ((o1[0] * o1[0] + o1[1] * o1[1]) + (o1[2] * o1[2] + o1[3] * o1[3]));
;                     u32x4 w; w.x = cvt_pk_bf16(o0[0], o0[1]); w.y = cvt_pk_bf16(o0[2], o0[3]); w.z = cvt_pk_bf16(o1[0], o1[1]); w.w = cvt_pk_bf16(o1[2], o1[3]);
;                     *(u32x4*)(rowp + bj * HALF) = w; }
;                 ss += __shfl_xor(ss, 16); ss += __shfl_xor(ss, 32);
;                 if (fq == 0) part[(size_t)row * NPART + u.pn * 4 + wc] = ss; }
.LBB0_860:
	s_or_b64 exec, exec, s[58:59]
	v_add_u32_e32 v32, 0xa0, v146
	s_waitcnt lgkmcnt(0)
	v_ashrrev_i32_e32 v33, 31, v32
	v_lshlrev_b64 v[34:35], 12, v[32:33]
	v_lshl_add_u64 v[34:35], s[50:51], 0, v[34:35]
	v_lshl_add_u64 v[38:39], v[144:145], 1, v[34:35]
	global_load_dwordx4 v[34:37], v[38:39], off
	s_waitcnt vmcnt(0)
	v_lshlrev_b32_e32 v40, 16, v34
	v_and_b32_e32 v41, 0xffff0000, v34
	v_lshlrev_b32_e32 v34, 16, v35
	v_and_b32_e32 v35, 0xffff0000, v35
	v_lshlrev_b32_e32 v42, 16, v36
	v_and_b32_e32 v43, 0xffff0000, v36
	v_lshlrev_b32_e32 v36, 16, v37
	v_and_b32_e32 v37, 0xffff0000, v37
	v_pk_add_f32 v[34:35], v[30:31], v[34:35]
	v_pk_add_f32 v[40:41], v[28:29], v[40:41]
	v_pk_add_f32 v[36:37], v[26:27], v[36:37]
	v_pk_add_f32 v[42:43], v[24:25], v[42:43]
	v_cvt_pk_bf16_f32 v24, v40, v41
	v_cvt_pk_bf16_f32 v25, v34, v35
	v_mul_f32_e32 v41, v41, v41
	v_cvt_pk_bf16_f32 v26, v42, v43
	v_cvt_pk_bf16_f32 v27, v36, v37
	global_load_dwordx4 v[28:31], v[38:39], off offset:256
	v_mul_f32_e32 v35, v35, v35
	v_mul_f32_e32 v43, v43, v43
	v_mul_f32_e32 v37, v37, v37
	v_fmac_f32_e32 v41, v40, v40
	v_fmac_f32_e32 v35, v34, v34
	v_fmac_f32_e32 v43, v42, v42
	v_fmac_f32_e32 v37, v36, v36
	v_add_f32_e32 v34, v41, v35
	v_add_f32_e32 v35, v43, v37
	v_add_f32_e32 v40, v34, v35
	global_store_dwordx4 v[38:39], v[24:27], off
	s_waitcnt vmcnt(1)
	v_lshlrev_b32_e32 v34, 16, v28
	v_and_b32_e32 v35, 0xffff0000, v28
	v_lshlrev_b32_e32 v28, 16, v29
	v_and_b32_e32 v29, 0xffff0000, v29
	v_lshlrev_b32_e32 v36, 16, v30
	v_and_b32_e32 v37, 0xffff0000, v30
	v_lshlrev_b32_e32 v30, 16, v31
	v_and_b32_e32 v31, 0xffff0000, v31
	v_pk_add_f32 v[22:23], v[22:23], v[28:29]
	v_pk_add_f32 v[20:21], v[20:21], v[34:35]
	v_pk_add_f32 v[28:29], v[18:19], v[30:31]
	v_pk_add_f32 v[30:31], v[16:17], v[36:37]
	v_mul_f32_e32 v16, v21, v21
	v_mul_f32_e32 v17, v23, v23
	v_mul_f32_e32 v18, v31, v31
	v_mul_f32_e32 v19, v29, v29
	v_fmac_f32_e32 v16, v20, v20
	v_fmac_f32_e32 v17, v22, v22
	v_fmac_f32_e32 v18, v30, v30
	v_fmac_f32_e32 v19, v28, v28
	v_add_f32_e32 v16, v16, v17
	v_add_f32_e32 v17, v18, v19
	v_add_f32_e32 v16, v16, v17
	v_add_f32_e32 v16, v40, v16
	v_mov_b32_e32 v17, v16
	s_nop 1
	v_permlane16_swap_b32_e32 v16, v17
	s_nop 1
	v_cvt_pk_bf16_f32 v18, v20, v21
	v_cvt_pk_bf16_f32 v19, v22, v23
	v_cvt_pk_bf16_f32 v20, v30, v31
	v_cvt_pk_bf16_f32 v21, v28, v29
	s_waitcnt lgkmcnt(0)
	v_add_f32_e32 v16, v16, v17
	v_mov_b32_e32 v17, v16
	s_nop 1
	v_permlane32_swap_b32_e32 v16, v17
	s_nop 1
	global_store_dwordx4 v[38:39], v[18:21], off offset:256
	s_and_saveexec_b64 s[58:59], s[2:3]
	s_cbranch_execz .LBB0_862
	s_waitcnt lgkmcnt(0)
	v_add_f32_e32 v18, v16, v17
	s_lshl_b32 s18, s64, 2
	v_lshlrev_b64 v[16:17], 7, v[32:33]
	s_ashr_i32 s19, s18, 31
	v_lshl_add_u64 v[16:17], s[48:49], 0, v[16:17]
	v_lshl_add_u64 v[16:17], s[18:19], 2, v[16:17]
	s_lshl_b32 s18, s70, 2
	s_mov_b32 s19, s23
	v_lshl_add_u64 v[16:17], v[16:17], 0, s[18:19]
	global_store_dword v[16:17], v18, off
.LBB0_862:
	s_or_b64 exec, exec, s[58:59]
	v_add_u32_e32 v16, 0xb0, v146
	s_waitcnt lgkmcnt(0)
	v_ashrrev_i32_e32 v17, 31, v16
	v_lshlrev_b64 v[18:19], 12, v[16:17]
	v_lshl_add_u64 v[18:19], s[50:51], 0, v[18:19]
	v_lshl_add_u64 v[22:23], v[144:145], 1, v[18:19]
	global_load_dwordx4 v[18:21], v[22:23], off
	s_waitcnt vmcnt(0)
	v_lshlrev_b32_e32 v24, 16, v18
	v_and_b32_e32 v25, 0xffff0000, v18
	v_lshlrev_b32_e32 v18, 16, v19
	v_and_b32_e32 v19, 0xffff0000, v19
	v_lshlrev_b32_e32 v26, 16, v20
	v_and_b32_e32 v27, 0xffff0000, v20
	v_lshlrev_b32_e32 v20, 16, v21
	v_and_b32_e32 v21, 0xffff0000, v21
	v_pk_add_f32 v[18:19], v[14:15], v[18:19]
	v_pk_add_f32 v[24:25], v[12:13], v[24:25]
	v_pk_add_f32 v[20:21], v[10:11], v[20:21]
	v_pk_add_f32 v[26:27], v[8:9], v[26:27]
	v_cvt_pk_bf16_f32 v8, v24, v25
	v_cvt_pk_bf16_f32 v9, v18, v19
	v_mul_f32_e32 v25, v25, v25
	v_cvt_pk_bf16_f32 v10, v26, v27
	v_cvt_pk_bf16_f32 v11, v20, v21
	global_load_dwordx4 v[12:15], v[22:23], off offset:256
	v_mul_f32_e32 v19, v19, v19
	v_mul_f32_e32 v27, v27, v27
	v_mul_f32_e32 v21, v21, v21
	v_fmac_f32_e32 v25, v24, v24
	v_fmac_f32_e32 v19, v18, v18
	v_fmac_f32_e32 v27, v26, v26
	v_fmac_f32_e32 v21, v20, v20
	v_add_f32_e32 v18, v25, v19
	v_add_f32_e32 v19, v27, v21
	v_add_f32_e32 v24, v18, v19
	global_store_dwordx4 v[22:23], v[8:11], off
	s_waitcnt vmcnt(1)
	v_lshlrev_b32_e32 v18, 16, v12
	v_and_b32_e32 v19, 0xffff0000, v12
	v_lshlrev_b32_e32 v12, 16, v13
	v_and_b32_e32 v13, 0xffff0000, v13
	v_lshlrev_b32_e32 v20, 16, v14
	v_and_b32_e32 v21, 0xffff0000, v14
	v_lshlrev_b32_e32 v14, 16, v15
	v_and_b32_e32 v15, 0xffff0000, v15
	v_pk_add_f32 v[6:7], v[6:7], v[12:13]
	v_pk_add_f32 v[4:5], v[4:5], v[18:19]
	v_pk_add_f32 v[12:13], v[2:3], v[14:15]
	v_pk_add_f32 v[14:15], v[0:1], v[20:21]
	v_mul_f32_e32 v0, v5, v5
	v_mul_f32_e32 v1, v7, v7
	v_mul_f32_e32 v2, v15, v15
	v_mul_f32_e32 v3, v13, v13
	v_fmac_f32_e32 v0, v4, v4
	v_fmac_f32_e32 v1, v6, v6
	v_fmac_f32_e32 v2, v14, v14
	v_fmac_f32_e32 v3, v12, v12
	v_add_f32_e32 v0, v0, v1
	v_add_f32_e32 v1, v2, v3
	v_add_f32_e32 v0, v0, v1
	v_add_f32_e32 v0, v24, v0
	v_mov_b32_e32 v1, v0
	s_nop 1
	v_permlane16_swap_b32_e32 v0, v1
	s_nop 1
	v_cvt_pk_bf16_f32 v2, v4, v5
	v_cvt_pk_bf16_f32 v3, v6, v7
	v_cvt_pk_bf16_f32 v4, v14, v15
	v_cvt_pk_bf16_f32 v5, v12, v13
	s_waitcnt lgkmcnt(0)
	v_add_f32_e32 v0, v0, v1
	v_mov_b32_e32 v1, v0
	s_nop 1
	v_permlane32_swap_b32_e32 v0, v1
	s_nop 1
	global_store_dwordx4 v[22:23], v[2:5], off offset:256
	s_and_saveexec_b64 s[58:59], s[2:3]
	s_cbranch_execz .LBB0_864
	s_waitcnt lgkmcnt(0)
	v_add_f32_e32 v2, v0, v1
	s_lshl_b32 s18, s64, 2
	v_lshlrev_b64 v[0:1], 7, v[16:17]
	s_ashr_i32 s19, s18, 31
	v_lshl_add_u64 v[0:1], s[48:49], 0, v[0:1]
	v_lshl_add_u64 v[0:1], s[18:19], 2, v[0:1]
	s_lshl_b32 s18, s70, 2
	s_mov_b32 s19, s23
	v_lshl_add_u64 v[0:1], v[0:1], 0, s[18:19]
	global_store_dword v[0:1], v2, off

; __device__ __forceinline__ void load_rstd(const float* part, int row0, int fq, float (&rs)[2][4]) {
; #pragma unroll
;     for (int ai = 0; ai < 2; ++ai)
; #pragma unroll
;         for (int m = 0; m < 4; ++m) { const float* p = part + (size_t)(row0 + ai * HALF + m * 16) * NPART + fq * 8;
;             const f32x4 a = *(const f32x4*)p, b = *(const f32x4*)(p + 4); float s = ((a[0] + a[1]) + (a[2] + a[3])) + ((b[0] + b[1]) + (b[2] + b[3]));
;             s += __shfl_xor(s, 16); s += __shfl_xor(s, 32); rs[ai][m] = rsqrtf(s * (1.0f / D) + RMS_EPS); }
;     __device__ __forceinline__ void fused(f32x4 (&acc)[2][2][4][2], const Unit& u, int wr, int wc, int fr, int fq, LAS unsigned char* lds, int wid, int lane) const {
;     ...
;         float mw[2][4]; float rs[2][4]; load_rstd(part, u.pm * BM + wr * 64 + fr, fq, rs);
.LBB0_930:
	s_lshl_b32 s58, s82, 8
	s_add_i32 s11, s11, s58
	v_or_b32_e32 v166, s11, v145
	v_ashrrev_i32_e32 v167, 31, v166
	v_or_b32_e32 v154, 16, v166
	v_lshlrev_b64 v[146:147], 7, v[166:167]
	v_ashrrev_i32_e32 v155, 31, v154
	v_lshl_add_u64 v[200:201], v[138:139], 0, v[146:147]
	v_lshlrev_b64 v[154:155], 7, v[154:155]
	s_barrier
	global_load_dwordx4 v[146:149], v[200:201], off
	global_load_dwordx4 v[150:153], v[200:201], off offset:16
	v_lshl_add_u64 v[158:159], v[138:139], 0, v[154:155]
	global_load_dwordx4 v[154:157], v[158:159], off
	s_nop 0
	global_load_dwordx4 v[158:161], v[158:159], off offset:16
	v_or_b32_e32 v168, 32, v166
	v_or_b32_e32 v166, 48, v166
	v_ashrrev_i32_e32 v169, 31, v168
	v_ashrrev_i32_e32 v167, 31, v166
	v_lshlrev_b64 v[168:169], 7, v[168:169]
	v_lshlrev_b64 v[166:167], 7, v[166:167]
	v_lshl_add_u64 v[172:173], v[138:139], 0, v[168:169]
	v_lshl_add_u64 v[166:167], v[138:139], 0, v[166:167]
	global_load_dwordx4 v[168:171], v[172:173], off
	s_nop 0
	global_load_dwordx4 v[172:175], v[172:173], off offset:16
	s_nop 0
	global_load_dwordx4 v[176:179], v[166:167], off
	global_load_dwordx4 v[180:183], v[166:167], off offset:16
	v_add_co_u32_e32 v208, vcc, s77, v200
	v_lshl_add_u64 v[166:167], v[200:201], 0, s[38:39]
	s_nop 0
	v_addc_co_u32_e32 v209, vcc, 0, v201, vcc
	global_load_dwordx4 v[184:187], v[208:209], off offset:-4096
	global_load_dwordx4 v[188:191], v[166:167], off offset:16
	v_add_co_u32_e32 v166, vcc, s69, v200
	v_and_b32_e32 v192, 64, v164
	s_nop 0
	v_addc_co_u32_e32 v167, vcc, 0, v201, vcc
	v_lshl_add_u64 v[196:197], v[200:201], 0, s[40:41]
	v_add_u32_e32 v204, 64, v192
	global_load_dwordx4 v[192:195], v[166:167], off offset:2048
	s_nop 0
	global_load_dwordx4 v[196:199], v[196:197], off offset:16
	v_xor_b32_e32 v202, 16, v164
	v_xor_b32_e32 v203, 32, v164
	v_cmp_lt_i32_e32 vcc, v202, v204
	v_lshl_add_u64 v[212:213], v[200:201], 0, s[54:55]
	s_lshl_b32 s11, s81, 3
	v_cndmask_b32_e32 v166, v164, v202, vcc
	v_cmp_lt_i32_e32 vcc, v203, v204
	v_lshlrev_b32_e32 v167, 2, v166
	s_add_i32 s11, s11, 0
	v_cndmask_b32_e32 v202, v164, v203, vcc
	v_lshlrev_b32_e32 v166, 2, v202
	v_lshl_add_u64 v[202:203], v[200:201], 0, s[42:43]
	global_load_dwordx4 v[200:203], v[202:203], off offset:16
	s_nop 0
	global_load_dwordx4 v[204:207], v[208:209], off
	s_nop 0
	global_load_dwordx4 v[208:211], v[208:209], off offset:2048
	s_nop 0
	global_load_dwordx4 v[212:215], v[212:213], off offset:16
	s_waitcnt vmcnt(0)
	v_mov_b32_e32 v216, v146
	v_mov_b32_e32 v217, v150
	v_mov_b32_e32 v150, v147
	v_mov_b32_e32 v146, v148
	v_mov_b32_e32 v147, v152
	v_mov_b32_e32 v152, v149
	v_pk_add_f32 v[148:149], v[216:217], v[150:151]
	v_pk_add_f32 v[146:147], v[146:147], v[152:153]
	v_mov_b32_e32 v150, v154
	v_mov_b32_e32 v151, v158
	v_mov_b32_e32 v158, v155
	v_mov_b32_e32 v152, v156
	v_mov_b32_e32 v153, v160
	v_mov_b32_e32 v160, v157
	v_pk_add_f32 v[146:147], v[148:149], v[146:147]
	v_pk_add_f32 v[148:149], v[150:151], v[158:159]
	v_pk_add_f32 v[150:151], v[152:153], v[160:161]
	v_mov_b32_e32 v154, v168
	v_pk_add_f32 v[148:149], v[148:149], v[150:151]
	v_mov_b32_e32 v151, v146
	v_mov_b32_e32 v150, v148
	v_mov_b32_e32 v146, v149
	v_pk_add_f32 v[146:147], v[150:151], v[146:147]
	v_mov_b32_e32 v149, v147
	s_nop 1
	v_permlane16_swap_b32_e32 v147, v149
	s_nop 1
	v_mov_b32_e32 v148, v146
	s_nop 1
	v_permlane16_swap_b32_e32 v146, v148
	s_nop 1
	v_mov_b32_e32 v155, v172
	v_mov_b32_e32 v172, v169
	v_mov_b32_e32 v156, v170
	v_mov_b32_e32 v157, v174
	s_waitcnt lgkmcnt(0)
	v_pk_add_f32 v[146:147], v[146:147], v[148:149]
	v_mov_b32_e32 v149, v147
	s_nop 1
	v_permlane32_swap_b32_e32 v147, v149
	s_nop 1
	v_mov_b32_e32 v148, v146
	s_nop 1
	v_permlane32_swap_b32_e32 v146, v148
	s_nop 1
	v_mov_b32_e32 v174, v171
	v_mov_b32_e32 v168, v176
	v_mov_b32_e32 v169, v180
	v_mov_b32_e32 v180, v177
	s_waitcnt lgkmcnt(0)
	v_pk_add_f32 v[146:147], v[146:147], v[148:149]
	v_mov_b32_e32 v170, v178
	v_mov_b32_e32 v171, v182
	v_mov_b32_e32 v182, v179
	v_pk_fma_f32 v[148:149], v[146:147], s[26:27], v[144:145] op_sel_hi:[1,0,0]
	v_pk_add_f32 v[150:151], v[154:155], v[172:173]
	v_pk_add_f32 v[152:153], v[156:157], v[174:175]
	v_pk_add_f32 v[154:155], v[168:169], v[180:181]
	v_pk_add_f32 v[156:157], v[170:171], v[182:183]
	v_mul_f32_e32 v146, 0x4b800000, v149
	v_cmp_gt_f32_e32 vcc, s76, v149
	v_pk_add_f32 v[150:151], v[150:151], v[152:153]
	v_pk_add_f32 v[152:153], v[154:155], v[156:157]
	v_cndmask_b32_e32 v146, v149, v146, vcc
	v_rsq_f32_e32 v149, v146
	v_mov_b32_e32 v146, v152
	v_mov_b32_e32 v147, v150
	v_mov_b32_e32 v150, v153
	v_mov_b32_e32 v152, v184
	v_mov_b32_e32 v153, v188
	v_mov_b32_e32 v188, v185
	v_mov_b32_e32 v154, v186
	v_mov_b32_e32 v155, v190
	v_mov_b32_e32 v190, v187
	v_pk_add_f32 v[152:153], v[152:153], v[188:189]
	v_pk_add_f32 v[154:155], v[154:155], v[190:191]
	v_mov_b32_e32 v156, v194
	v_pk_add_f32 v[152:153], v[152:153], v[154:155]
	v_mov_b32_e32 v154, v192
	v_mov_b32_e32 v155, v196
	v_mov_b32_e32 v196, v193
	v_mov_b32_e32 v157, v198
	v_mov_b32_e32 v198, v195
	v_pk_add_f32 v[154:155], v[154:155], v[196:197]
	v_pk_add_f32 v[156:157], v[156:157], v[198:199]
	v_mul_f32_e32 v158, 0x45800000, v149
	v_pk_add_f32 v[154:155], v[154:155], v[156:157]
	v_mov_b32_e32 v157, v152
	v_mov_b32_e32 v156, v154
	v_mov_b32_e32 v152, v155
	v_pk_add_f32 v[154:155], v[156:157], v[152:153]
	v_mov_b32_e32 v157, v155
	s_nop 1
	v_permlane16_swap_b32_e32 v155, v157
	s_nop 1
	v_mov_b32_e32 v156, v154
	s_nop 1
	v_permlane16_swap_b32_e32 v154, v156
	s_nop 1
	v_cndmask_b32_e32 v149, v149, v158, vcc
	v_pk_add_f32 v[146:147], v[146:147], v[150:151]
	v_mov_b32_e32 v151, v147
	s_nop 1
	v_permlane16_swap_b32_e32 v147, v151
	s_nop 1
	v_mov_b32_e32 v150, v146
	s_nop 1
	v_permlane16_swap_b32_e32 v146, v150
	s_nop 1
	s_waitcnt lgkmcnt(2)
; __device__ __forceinline__ float fast_exp2(float x) { return __builtin_amdgcn_exp2f(x); }
; __device__ __forceinline__ void load_rstd(const float* part, int row0, int fq, float (&rs)[2][4]) {
;     ...
;         for (int m = 0; m < 4; ++m) { const float* p = part + (size_t)(row0 + ai * HALF + m * 16) * NPART + fq * 8;
;             const f32x4 a = *(const f32x4*)p, b = *(const f32x4*)(p + 4); float s = ((a[0] + a[1]) + (a[2] + a[3])) + ((b[0] + b[1]) + (b[2] + b[3]));
;             s += __shfl_xor(s, 16); s += __shfl_xor(s, 32); rs[ai][m] = rsqrtf(s * (1.0f / D) + RMS_EPS); }
;     __device__ __forceinline__ void fused(f32x4 (&acc)[2][2][4][2], const Unit& u, int wr, int wc, int fr, int fq, LAS unsigned char* lds, int wid, int lane) const {
;     ...
;                 float mx = -3.0e38f;
; #pragma unroll
;                 for (int bj = 0; bj < 2; ++bj)
; #pragma unroll
;                     for (int n = 0; n < 2; ++n) { const f32x4 a = acc[ai][bj][m][n] * (rs[ai][m] * mul); acc[ai][bj][m][n] = a; mx = fmaxf(mx, fmaxf(fmaxf(a[0], a[1]), fmaxf(a[2], a[3]))); }
;                 mx = fmaxf(mx, __shfl_xor(mx, 16)); mx = fmaxf(mx, __shfl_xor(mx, 32));
;                 float s = 0.f;
; #pragma unroll
;                 for (int bj = 0; bj < 2; ++bj)
; #pragma unroll
;                     for (int n = 0; n < 2; ++n) { f32x4 a = acc[ai][bj][m][n];
; #pragma unroll
;                         for (int e = 0; e < 4; ++e) { a[e] = fast_exp2(a[e] - mx); s += a[e]; }
;                         acc[ai][bj][m][n] = a; }
;                 s += __shfl_xor(s, 16); s += __shfl_xor(s, 32);
	v_pk_add_f32 v[154:155], v[154:155], v[156:157]
	ds_bpermute_b32 v157, v166, v155
	v_mul_f32_e32 v156, 0x3d8293ee, v149
	v_mov_b32_e32 v158, v206
	s_waitcnt lgkmcnt(1)
	v_pk_add_f32 v[150:151], v[146:147], v[150:151]
	v_mov_b32_e32 v146, v204
	s_waitcnt lgkmcnt(0)
	v_pk_mul_f32 v[126:127], v[126:127], v[156:157] op_sel_hi:[1,0]
	v_pk_mul_f32 v[122:123], v[122:123], v[156:157] op_sel_hi:[1,0]
	v_pk_mul_f32 v[124:125], v[124:125], v[156:157] op_sel_hi:[1,0]
	v_max_f32_e32 v149, v126, v127
	v_pk_mul_f32 v[120:121], v[120:121], v[156:157] op_sel_hi:[1,0]
	v_max_f32_e32 v168, v122, v123
	v_max3_f32 v149, v124, v125, v149
	v_max3_f32 v168, v120, v121, v168
	v_max3_f32 v149, v149, s78, v168
	v_pk_mul_f32 v[168:169], v[118:119], v[156:157] op_sel_hi:[1,0]
	v_pk_mul_f32 v[172:173], v[114:115], v[156:157] op_sel_hi:[1,0]
	v_pk_mul_f32 v[170:171], v[116:117], v[156:157] op_sel_hi:[1,0]
	v_max_f32_e32 v116, v168, v169
	v_pk_mul_f32 v[174:175], v[112:113], v[156:157] op_sel_hi:[1,0]
	v_max_f32_e32 v112, v172, v173
	v_max3_f32 v116, v170, v171, v116
	v_max3_f32 v112, v174, v175, v112
	v_max3_f32 v116, v149, v116, v112
	v_mov_b32_e32 v147, v200
	v_mov_b32_e32 v200, v205
	v_mov_b32_e32 v159, v202
	v_mov_b32_e32 v202, v207
	ds_bpermute_b32 v117, v167, v116
	v_pk_add_f32 v[146:147], v[146:147], v[200:201]
	v_pk_add_f32 v[158:159], v[158:159], v[202:203]
	v_mov_b32_e32 v160, v210
	v_pk_add_f32 v[146:147], v[146:147], v[158:159]
	v_mov_b32_e32 v158, v208
	v_mov_b32_e32 v159, v212
	v_mov_b32_e32 v212, v209
	v_mov_b32_e32 v161, v214
	v_mov_b32_e32 v214, v211
	v_pk_add_f32 v[158:159], v[158:159], v[212:213]
	v_pk_add_f32 v[112:113], v[160:161], v[214:215]
	v_mov_b32_e32 v115, v146
	v_pk_add_f32 v[112:113], v[158:159], v[112:113]
	ds_bpermute_b32 v153, v166, v151
	v_mov_b32_e32 v114, v112
	s_waitcnt lgkmcnt(1)
	v_max_f32_e32 v112, v117, v117
	v_max_f32_e32 v112, v116, v112
	ds_bpermute_b32 v116, v166, v112
	v_mov_b32_e32 v146, v113
	v_pk_add_f32 v[158:159], v[114:115], v[146:147]
	v_mov_b32_e32 v161, v159
	s_nop 1
	v_permlane16_swap_b32_e32 v159, v161
	s_nop 1
	v_mov_b32_e32 v160, v158
	s_nop 1
	v_permlane16_swap_b32_e32 v158, v160
	s_nop 1
	s_waitcnt lgkmcnt(2)
	v_max_f32_e32 v113, v116, v116
	v_max_f32_e32 v146, v112, v113
	v_sub_f32_e32 v112, v124, v146
	v_exp_f32_e32 v112, v112
	v_sub_f32_e32 v113, v125, v146
	v_exp_f32_e32 v113, v113
	v_sub_f32_e32 v114, v126, v146
	v_exp_f32_e32 v118, v114
	v_sub_f32_e32 v114, v127, v146
	v_exp_f32_e32 v119, v114
	v_sub_f32_e32 v115, v120, v146
	v_add_f32_e32 v114, 0, v112
	v_exp_f32_e32 v116, v115
	v_sub_f32_e32 v115, v121, v146
	v_add_f32_e32 v114, v113, v114
	v_exp_f32_e32 v117, v115
	v_sub_f32_e32 v115, v122, v146
	v_add_f32_e32 v114, v118, v114
	v_exp_f32_e32 v124, v115
	v_sub_f32_e32 v115, v123, v146
	v_add_f32_e32 v114, v119, v114
	v_exp_f32_e32 v125, v115
	v_add_f32_e32 v114, v116, v114
	v_add_f32_e32 v114, v117, v114
	v_add_f32_e32 v114, v124, v114
	v_add_f32_e32 v120, v125, v114
	v_sub_f32_e32 v114, v170, v146
	v_exp_f32_e32 v114, v114
	v_sub_f32_e32 v115, v171, v146
	v_exp_f32_e32 v115, v115
	v_sub_f32_e32 v121, v168, v146
	v_exp_f32_e32 v122, v121
	v_sub_f32_e32 v121, v169, v146
	v_exp_f32_e32 v123, v121
	v_add_f32_e32 v120, v114, v120
	v_add_f32_e32 v120, v115, v120
	v_add_f32_e32 v120, v122, v120
	v_add_f32_e32 v147, v123, v120
	v_sub_f32_e32 v120, v174, v146
	v_exp_f32_e32 v120, v120
	v_sub_f32_e32 v121, v175, v146
	v_exp_f32_e32 v121, v121
	v_sub_f32_e32 v126, v172, v146
	v_exp_f32_e32 v126, v126
	v_sub_f32_e32 v127, v173, v146
	v_exp_f32_e32 v127, v127
	v_add_f32_e32 v147, v120, v147
	v_add_f32_e32 v147, v121, v147
	v_add_f32_e32 v147, v126, v147
	v_add_f32_e32 v147, v127, v147
	v_mov_b32_e32 v149, v147
	s_nop 1
	v_permlane16_swap_b32_e32 v147, v149
	s_nop 1
	s_waitcnt lgkmcnt(1)
	v_pk_add_f32 v[158:159], v[158:159], v[160:161]
	ds_bpermute_b32 v152, v166, v150
	ds_bpermute_b32 v156, v166, v154
	ds_bpermute_b32 v161, v166, v159
	s_waitcnt lgkmcnt(3)
	v_add_f32_e32 v147, v147, v149
	ds_bpermute_b32 v160, v166, v158
	v_mov_b32_e32 v149, v147
	s_nop 1
	v_permlane32_swap_b32_e32 v147, v149
	s_nop 1
	v_cmp_gt_f32_e32 vcc, s76, v148
	v_lshl_add_u32 v168, v165, 5, s11
	s_and_saveexec_b64 s[56:57], s[2:3]
	s_cbranch_execz .LBB0_932
	s_waitcnt lgkmcnt(0)
	v_add_f32_e32 v147, v147, v149
	ds_write_b64 v168, v[146:147]
; __device__ __forceinline__ float fast_exp2(float x) { return __builtin_amdgcn_exp2f(x); }
;     __device__ __forceinline__ void fused(f32x4 (&acc)[2][2][4][2], const Unit& u, int wr, int wc, int fr, int fq, LAS unsigned char* lds, int wid, int lane) const {
;     ...
;             for (int m = 0; m < 4; ++m) {
;                 float mx = -3.0e38f;
; #pragma unroll
;                 for (int bj = 0; bj < 2; ++bj)
; #pragma unroll
;                     for (int n = 0; n < 2; ++n) { const f32x4 a = acc[ai][bj][m][n] * (rs[ai][m] * mul); acc[ai][bj][m][n] = a; mx = fmaxf(mx, fmaxf(fmaxf(a[0], a[1]), fmaxf(a[2], a[3]))); }
;                 mx = fmaxf(mx, __shfl_xor(mx, 16)); mx = fmaxf(mx, __shfl_xor(mx, 32));
;                 float s = 0.f;
; #pragma unroll
;                 for (int bj = 0; bj < 2; ++bj)
; #pragma unroll
;                     for (int n = 0; n < 2; ++n) { f32x4 a = acc[ai][bj][m][n];
; #pragma unroll
;                         for (int e = 0; e < 4; ++e) { a[e] = fast_exp2(a[e] - mx); s += a[e]; }
;                         acc[ai][bj][m][n] = a; }
;                 s += __shfl_xor(s, 16); s += __shfl_xor(s, 32);
;                 mw[ai][m] = mx;
;                 if (fq == 0) X[(ai * HALF + wr * 64 + m * 16 + fr) * 4 + wc] = (f32x2){mx, s};
.LBB0_932:
	s_or_b64 exec, exec, s[56:57]
	v_mul_f32_e32 v147, 0x4b800000, v148
	v_cndmask_b32_e32 v147, v148, v147, vcc
	v_rsq_f32_e32 v147, v147
	s_nop 0
	v_mul_f32_e32 v148, 0x45800000, v147
	v_cndmask_b32_e32 v147, v147, v148, vcc
	v_mul_f32_e32 v148, 0x3d8293ee, v147
	s_waitcnt lgkmcnt(0)
	v_pk_mul_f32 v[106:107], v[106:107], v[148:149] op_sel_hi:[1,0]
	v_pk_mul_f32 v[110:111], v[110:111], v[148:149] op_sel_hi:[1,0]
	v_pk_mul_f32 v[108:109], v[108:109], v[148:149] op_sel_hi:[1,0]
	v_pk_mul_f32 v[104:105], v[104:105], v[148:149] op_sel_hi:[1,0]
	v_max_f32_e32 v149, v106, v107
	v_max3_f32 v149, v104, v105, v149
	v_max_f32_e32 v147, v110, v111
	v_pk_mul_f32 v[170:171], v[102:103], v[148:149] op_sel_hi:[1,0]
	v_pk_mul_f32 v[174:175], v[98:99], v[148:149] op_sel_hi:[1,0]
	v_max3_f32 v147, v108, v109, v147
	v_pk_mul_f32 v[172:173], v[100:101], v[148:149] op_sel_hi:[1,0]
	v_max_f32_e32 v100, v170, v171
	v_pk_mul_f32 v[176:177], v[96:97], v[148:149] op_sel_hi:[1,0]
	v_max_f32_e32 v96, v174, v175
	v_max3_f32 v147, v147, s78, v149
	v_max3_f32 v100, v172, v173, v100
	v_max3_f32 v96, v176, v177, v96
	v_max3_f32 v96, v147, v100, v96
	ds_bpermute_b32 v97, v167, v96
	s_waitcnt lgkmcnt(0)
	v_max_f32_e32 v97, v97, v97
	v_max_f32_e32 v96, v96, v97
	ds_bpermute_b32 v97, v166, v96
	s_waitcnt lgkmcnt(0)
	v_max_f32_e32 v97, v97, v97
	v_max_f32_e32 v148, v96, v97
	v_sub_f32_e32 v96, v108, v148
	v_exp_f32_e32 v96, v96
	v_sub_f32_e32 v97, v109, v148
	v_exp_f32_e32 v97, v97
	v_sub_f32_e32 v98, v110, v148
	v_exp_f32_e32 v102, v98
	v_sub_f32_e32 v98, v111, v148
	v_exp_f32_e32 v103, v98
	v_sub_f32_e32 v99, v104, v148
	v_add_f32_e32 v98, 0, v96
	v_exp_f32_e32 v100, v99
	v_sub_f32_e32 v99, v105, v148
	v_add_f32_e32 v98, v97, v98
	v_exp_f32_e32 v101, v99
	v_sub_f32_e32 v99, v106, v148
	v_add_f32_e32 v98, v102, v98
	v_exp_f32_e32 v108, v99
	v_sub_f32_e32 v99, v107, v148
	v_add_f32_e32 v98, v103, v98
	v_exp_f32_e32 v109, v99
	v_add_f32_e32 v98, v100, v98
	v_add_f32_e32 v98, v101, v98
	v_add_f32_e32 v98, v108, v98
	v_add_f32_e32 v104, v109, v98
	v_sub_f32_e32 v98, v172, v148
	v_exp_f32_e32 v98, v98
	v_sub_f32_e32 v99, v173, v148
	v_exp_f32_e32 v99, v99
	v_sub_f32_e32 v105, v170, v148
	v_exp_f32_e32 v106, v105
	v_sub_f32_e32 v105, v171, v148
	v_exp_f32_e32 v107, v105
	v_add_f32_e32 v104, v98, v104
	v_add_f32_e32 v104, v99, v104
	v_add_f32_e32 v104, v106, v104
	v_add_f32_e32 v147, v107, v104
	v_sub_f32_e32 v104, v176, v148
	v_exp_f32_e32 v104, v104
	v_sub_f32_e32 v105, v177, v148
	v_exp_f32_e32 v105, v105
	v_sub_f32_e32 v110, v174, v148
	v_exp_f32_e32 v110, v110
	v_sub_f32_e32 v111, v175, v148
	v_exp_f32_e32 v111, v111
	v_add_f32_e32 v147, v104, v147
	v_add_f32_e32 v147, v105, v147
	v_add_f32_e32 v147, v110, v147
	v_add_f32_e32 v147, v111, v147
	v_mov_b32_e32 v149, v147
	s_nop 1
	v_permlane16_swap_b32_e32 v147, v149
	s_nop 1
	s_waitcnt lgkmcnt(0)
	v_add_f32_e32 v147, v147, v149
	v_mov_b32_e32 v149, v147
	s_nop 1
	v_permlane32_swap_b32_e32 v147, v149
	s_nop 1
	s_and_saveexec_b64 s[56:57], s[2:3]
	s_cbranch_execz .LBB0_934
	s_waitcnt lgkmcnt(0)
	v_add_f32_e32 v149, v147, v149
	ds_write_b64 v168, v[148:149] offset:512
.LBB0_934:
	s_or_b64 exec, exec, s[56:57]
	v_pk_add_f32 v[150:151], v[150:151], v[152:153]
	s_nop 0
	v_pk_fma_f32 v[152:153], v[150:151], s[26:27], v[144:145] op_sel_hi:[1,0,0]
	s_nop 0
	v_mul_f32_e32 v147, 0x4b800000, v153
	v_cmp_gt_f32_e32 vcc, s76, v153
	s_nop 1
	v_cndmask_b32_e32 v147, v153, v147, vcc
	v_rsq_f32_e32 v147, v147
	s_waitcnt lgkmcnt(0)
	v_mul_f32_e32 v149, 0x45800000, v147
	v_cndmask_b32_e32 v147, v147, v149, vcc
	v_mul_f32_e32 v150, 0x3d8293ee, v147
	v_pk_mul_f32 v[94:95], v[94:95], v[150:151] op_sel_hi:[1,0]
	v_pk_mul_f32 v[90:91], v[90:91], v[150:151] op_sel_hi:[1,0]
	v_pk_mul_f32 v[92:93], v[92:93], v[150:151] op_sel_hi:[1,0]
	v_max_f32_e32 v147, v94, v95
	v_pk_mul_f32 v[88:89], v[88:89], v[150:151] op_sel_hi:[1,0]
	v_max_f32_e32 v149, v90, v91
	v_pk_mul_f32 v[170:171], v[86:87], v[150:151] op_sel_hi:[1,0]
	v_pk_mul_f32 v[174:175], v[82:83], v[150:151] op_sel_hi:[1,0]
	v_max3_f32 v147, v92, v93, v147
	v_max3_f32 v149, v88, v89, v149
	v_pk_mul_f32 v[172:173], v[84:85], v[150:151] op_sel_hi:[1,0]
	v_max_f32_e32 v84, v170, v171
	v_pk_mul_f32 v[176:177], v[80:81], v[150:151] op_sel_hi:[1,0]
	v_max_f32_e32 v80, v174, v175
	v_max3_f32 v147, v147, s78, v149
	v_max3_f32 v84, v172, v173, v84
	v_max3_f32 v80, v176, v177, v80
	v_max3_f32 v80, v147, v84, v80
	ds_bpermute_b32 v81, v167, v80
	v_cmp_gt_f32_e32 vcc, s76, v152
	s_waitcnt lgkmcnt(0)
	v_max_f32_e32 v81, v81, v81
	v_max_f32_e32 v80, v80, v81
	ds_bpermute_b32 v81, v166, v80
	s_waitcnt lgkmcnt(0)
	v_max_f32_e32 v81, v81, v81
	v_max_f32_e32 v150, v80, v81
	v_sub_f32_e32 v80, v92, v150
	v_exp_f32_e32 v80, v80
	v_sub_f32_e32 v81, v93, v150
	v_exp_f32_e32 v81, v81
	v_sub_f32_e32 v82, v94, v150
	v_exp_f32_e32 v86, v82
	v_sub_f32_e32 v82, v95, v150
	v_exp_f32_e32 v87, v82
	v_sub_f32_e32 v83, v88, v150
	v_add_f32_e32 v82, 0, v80
	v_exp_f32_e32 v84, v83
	v_sub_f32_e32 v83, v89, v150
	v_add_f32_e32 v82, v81, v82
	v_exp_f32_e32 v85, v83
	v_sub_f32_e32 v83, v90, v150
	v_add_f32_e32 v82, v86, v82
	v_exp_f32_e32 v92, v83
	v_sub_f32_e32 v83, v91, v150
	v_add_f32_e32 v82, v87, v82
	v_exp_f32_e32 v93, v83
	v_add_f32_e32 v82, v84, v82
	v_add_f32_e32 v82, v85, v82
	v_add_f32_e32 v82, v92, v82
	v_add_f32_e32 v88, v93, v82
	v_sub_f32_e32 v82, v172, v150
	v_exp_f32_e32 v82, v82
	v_sub_f32_e32 v83, v173, v150
	v_exp_f32_e32 v83, v83
	v_sub_f32_e32 v89, v170, v150
	v_exp_f32_e32 v90, v89
	v_sub_f32_e32 v89, v171, v150
	v_exp_f32_e32 v91, v89
	v_add_f32_e32 v88, v82, v88
	v_add_f32_e32 v88, v83, v88
	v_add_f32_e32 v88, v90, v88
	v_add_f32_e32 v147, v91, v88
	v_sub_f32_e32 v88, v176, v150
	v_exp_f32_e32 v88, v88
	v_sub_f32_e32 v89, v177, v150
	v_exp_f32_e32 v89, v89
	v_sub_f32_e32 v94, v174, v150
	v_exp_f32_e32 v94, v94
	v_sub_f32_e32 v95, v175, v150
	v_exp_f32_e32 v95, v95
	v_add_f32_e32 v147, v88, v147
	v_add_f32_e32 v147, v89, v147
	v_add_f32_e32 v147, v94, v147
	v_add_f32_e32 v147, v95, v147
	v_mov_b32_e32 v149, v147
	s_nop 1
	v_permlane16_swap_b32_e32 v147, v149
	s_nop 1
	s_waitcnt lgkmcnt(0)
	v_add_f32_e32 v147, v147, v149
	v_mov_b32_e32 v149, v147
	s_nop 1
	v_permlane32_swap_b32_e32 v147, v149
	s_nop 1
	s_and_saveexec_b64 s[56:57], s[2:3]
	s_cbranch_execz .LBB0_936
	s_waitcnt lgkmcnt(0)
	v_add_f32_e32 v151, v147, v149
	ds_write_b64 v168, v[150:151] offset:1024
; __device__ __forceinline__ float fast_exp2(float x) { return __builtin_amdgcn_exp2f(x); }
;     __device__ __forceinline__ void fused(f32x4 (&acc)[2][2][4][2], const Unit& u, int wr, int wc, int fr, int fq, LAS unsigned char* lds, int wid, int lane) const {
;     ...
;             for (int m = 0; m < 4; ++m) {
;                 float mx = -3.0e38f;
; #pragma unroll
;                 for (int bj = 0; bj < 2; ++bj)
; #pragma unroll
;                     for (int n = 0; n < 2; ++n) { const f32x4 a = acc[ai][bj][m][n] * (rs[ai][m] * mul); acc[ai][bj][m][n] = a; mx = fmaxf(mx, fmaxf(fmaxf(a[0], a[1]), fmaxf(a[2], a[3]))); }
;                 mx = fmaxf(mx, __shfl_xor(mx, 16)); mx = fmaxf(mx, __shfl_xor(mx, 32));
;                 float s = 0.f;
; #pragma unroll
;                 for (int bj = 0; bj < 2; ++bj)
; #pragma unroll
;                     for (int n = 0; n < 2; ++n) { f32x4 a = acc[ai][bj][m][n];
; #pragma unroll
;                         for (int e = 0; e < 4; ++e) { a[e] = fast_exp2(a[e] - mx); s += a[e]; }
;                         acc[ai][bj][m][n] = a; }
;                 s += __shfl_xor(s, 16); s += __shfl_xor(s, 32);
;                 mw[ai][m] = mx;
;                 if (fq == 0) X[(ai * HALF + wr * 64 + m * 16 + fr) * 4 + wc] = (f32x2){mx, s};
.LBB0_936:
	s_or_b64 exec, exec, s[56:57]
	v_mul_f32_e32 v147, 0x4b800000, v152
	v_cndmask_b32_e32 v147, v152, v147, vcc
	v_rsq_f32_e32 v147, v147
	s_waitcnt lgkmcnt(0)
	v_mul_f32_e32 v149, 0x45800000, v147
	v_cndmask_b32_e32 v147, v147, v149, vcc
	v_mul_f32_e32 v152, 0x3d8293ee, v147
	v_pk_mul_f32 v[78:79], v[78:79], v[152:153] op_sel_hi:[1,0]
	v_pk_mul_f32 v[74:75], v[74:75], v[152:153] op_sel_hi:[1,0]
	v_pk_mul_f32 v[76:77], v[76:77], v[152:153] op_sel_hi:[1,0]
	v_pk_mul_f32 v[72:73], v[72:73], v[152:153] op_sel_hi:[1,0]
	v_max_f32_e32 v147, v78, v79
	v_max_f32_e32 v149, v74, v75
	v_pk_mul_f32 v[170:171], v[70:71], v[152:153] op_sel_hi:[1,0]
	v_pk_mul_f32 v[174:175], v[66:67], v[152:153] op_sel_hi:[1,0]
	v_max3_f32 v147, v76, v77, v147
	v_max3_f32 v149, v72, v73, v149
	v_pk_mul_f32 v[172:173], v[68:69], v[152:153] op_sel_hi:[1,0]
	v_max_f32_e32 v68, v170, v171
	v_pk_mul_f32 v[176:177], v[64:65], v[152:153] op_sel_hi:[1,0]
	v_max_f32_e32 v64, v174, v175
	v_max3_f32 v147, v147, s78, v149
	v_max3_f32 v68, v172, v173, v68
	v_max3_f32 v64, v176, v177, v64
	v_max3_f32 v64, v147, v68, v64
	ds_bpermute_b32 v65, v167, v64
	s_waitcnt lgkmcnt(0)
	v_max_f32_e32 v65, v65, v65
	v_max_f32_e32 v64, v64, v65
	ds_bpermute_b32 v65, v166, v64
	s_waitcnt lgkmcnt(0)
	v_max_f32_e32 v65, v65, v65
	v_max_f32_e32 v152, v64, v65
	v_sub_f32_e32 v64, v76, v152
	v_exp_f32_e32 v64, v64
	v_sub_f32_e32 v65, v77, v152
	v_exp_f32_e32 v65, v65
	v_sub_f32_e32 v66, v78, v152
	v_exp_f32_e32 v70, v66
	v_sub_f32_e32 v66, v79, v152
	v_exp_f32_e32 v71, v66
	v_sub_f32_e32 v67, v72, v152
	v_add_f32_e32 v66, 0, v64
	v_exp_f32_e32 v68, v67
	v_sub_f32_e32 v67, v73, v152
	v_add_f32_e32 v66, v65, v66
	v_exp_f32_e32 v69, v67
	v_sub_f32_e32 v67, v74, v152
	v_add_f32_e32 v66, v70, v66
	v_exp_f32_e32 v76, v67
	v_sub_f32_e32 v67, v75, v152
	v_add_f32_e32 v66, v71, v66
	v_exp_f32_e32 v77, v67
	v_add_f32_e32 v66, v68, v66
	v_add_f32_e32 v66, v69, v66
	v_add_f32_e32 v66, v76, v66
	v_add_f32_e32 v72, v77, v66
	v_sub_f32_e32 v66, v172, v152
	v_exp_f32_e32 v66, v66
	v_sub_f32_e32 v67, v173, v152
	v_exp_f32_e32 v67, v67
	v_sub_f32_e32 v73, v170, v152
	v_exp_f32_e32 v74, v73
	v_sub_f32_e32 v73, v171, v152
	v_exp_f32_e32 v75, v73
	v_add_f32_e32 v72, v66, v72
	v_add_f32_e32 v72, v67, v72
	v_add_f32_e32 v72, v74, v72
	v_add_f32_e32 v147, v75, v72
	v_sub_f32_e32 v72, v176, v152
	v_exp_f32_e32 v72, v72
	v_sub_f32_e32 v73, v177, v152
	v_exp_f32_e32 v73, v73
	v_sub_f32_e32 v78, v174, v152
	v_exp_f32_e32 v78, v78
	v_sub_f32_e32 v79, v175, v152
	v_exp_f32_e32 v79, v79
	v_add_f32_e32 v147, v72, v147
	v_add_f32_e32 v147, v73, v147
	v_add_f32_e32 v147, v78, v147
	v_add_f32_e32 v147, v79, v147
	v_mov_b32_e32 v149, v147
	s_nop 1
	v_permlane16_swap_b32_e32 v147, v149
	s_nop 1
	s_waitcnt lgkmcnt(0)
	v_add_f32_e32 v147, v147, v149
	v_mov_b32_e32 v149, v147
	s_nop 1
	v_permlane32_swap_b32_e32 v147, v149
	s_nop 1
	s_and_saveexec_b64 s[56:57], s[2:3]
	s_cbranch_execz .LBB0_938
	s_waitcnt lgkmcnt(0)
	v_add_f32_e32 v153, v147, v149
	ds_write_b64 v168, v[152:153] offset:1536
.LBB0_938:
	s_or_b64 exec, exec, s[56:57]
	v_pk_add_f32 v[154:155], v[154:155], v[156:157]
	s_nop 0
	v_pk_fma_f32 v[156:157], v[154:155], s[26:27], v[144:145] op_sel_hi:[1,0,0]
	s_nop 0
	v_mul_f32_e32 v147, 0x4b800000, v157
	v_cmp_gt_f32_e32 vcc, s76, v157
	s_nop 1
	v_cndmask_b32_e32 v147, v157, v147, vcc
	v_rsq_f32_e32 v147, v147
	s_waitcnt lgkmcnt(0)
	v_mul_f32_e32 v149, 0x45800000, v147
	v_cndmask_b32_e32 v147, v147, v149, vcc
	v_mul_f32_e32 v154, 0x3d8293ee, v147
	v_pk_mul_f32 v[62:63], v[62:63], v[154:155] op_sel_hi:[1,0]
	v_pk_mul_f32 v[58:59], v[58:59], v[154:155] op_sel_hi:[1,0]
	v_pk_mul_f32 v[60:61], v[60:61], v[154:155] op_sel_hi:[1,0]
	v_max_f32_e32 v147, v62, v63
	v_pk_mul_f32 v[56:57], v[56:57], v[154:155] op_sel_hi:[1,0]
	v_max_f32_e32 v149, v58, v59
	v_pk_mul_f32 v[170:171], v[54:55], v[154:155] op_sel_hi:[1,0]
	v_pk_mul_f32 v[174:175], v[50:51], v[154:155] op_sel_hi:[1,0]
	v_max3_f32 v147, v60, v61, v147
	v_max3_f32 v149, v56, v57, v149
	v_pk_mul_f32 v[172:173], v[52:53], v[154:155] op_sel_hi:[1,0]
	v_max_f32_e32 v52, v170, v171
	v_pk_mul_f32 v[176:177], v[48:49], v[154:155] op_sel_hi:[1,0]
	v_max_f32_e32 v48, v174, v175
	v_max3_f32 v147, v147, s78, v149
	v_max3_f32 v52, v172, v173, v52
	v_max3_f32 v48, v176, v177, v48
	v_max3_f32 v48, v147, v52, v48
	ds_bpermute_b32 v49, v167, v48
	v_cmp_gt_f32_e32 vcc, s76, v156
	s_waitcnt lgkmcnt(0)
	v_max_f32_e32 v49, v49, v49
	v_max_f32_e32 v48, v48, v49
	ds_bpermute_b32 v49, v166, v48
	s_waitcnt lgkmcnt(0)
	v_max_f32_e32 v49, v49, v49
	v_max_f32_e32 v154, v48, v49
	v_sub_f32_e32 v48, v60, v154
	v_exp_f32_e32 v48, v48
	v_sub_f32_e32 v49, v61, v154
	v_exp_f32_e32 v49, v49
	v_sub_f32_e32 v50, v62, v154
	v_exp_f32_e32 v54, v50
	v_sub_f32_e32 v50, v63, v154
	v_exp_f32_e32 v55, v50
	v_sub_f32_e32 v51, v56, v154
	v_add_f32_e32 v50, 0, v48
	v_exp_f32_e32 v52, v51
	v_sub_f32_e32 v51, v57, v154
	v_add_f32_e32 v50, v49, v50
	v_exp_f32_e32 v53, v51
	v_sub_f32_e32 v51, v58, v154
	v_add_f32_e32 v50, v54, v50
	v_exp_f32_e32 v60, v51
	v_sub_f32_e32 v51, v59, v154
	v_add_f32_e32 v50, v55, v50
	v_exp_f32_e32 v61, v51
	v_add_f32_e32 v50, v52, v50
	v_add_f32_e32 v50, v53, v50
	v_add_f32_e32 v50, v60, v50
	v_add_f32_e32 v56, v61, v50
	v_sub_f32_e32 v50, v172, v154
	v_exp_f32_e32 v50, v50
	v_sub_f32_e32 v51, v173, v154
	v_exp_f32_e32 v51, v51
	v_sub_f32_e32 v57, v170, v154
	v_exp_f32_e32 v58, v57
	v_sub_f32_e32 v57, v171, v154
	v_exp_f32_e32 v59, v57
	v_add_f32_e32 v56, v50, v56
	v_add_f32_e32 v56, v51, v56
	v_add_f32_e32 v56, v58, v56
	v_add_f32_e32 v147, v59, v56
	v_sub_f32_e32 v56, v176, v154
	v_exp_f32_e32 v56, v56
	v_sub_f32_e32 v57, v177, v154
	v_exp_f32_e32 v57, v57
	v_sub_f32_e32 v62, v174, v154
	v_exp_f32_e32 v62, v62
	v_sub_f32_e32 v63, v175, v154
	v_exp_f32_e32 v63, v63
	v_add_f32_e32 v147, v56, v147
	v_add_f32_e32 v147, v57, v147
	v_add_f32_e32 v147, v62, v147
	v_add_f32_e32 v147, v63, v147
	v_mov_b32_e32 v149, v147
	s_nop 1
	v_permlane16_swap_b32_e32 v147, v149
	s_nop 1
	s_waitcnt lgkmcnt(0)
	v_add_f32_e32 v147, v147, v149
	v_mov_b32_e32 v149, v147
	s_nop 1
	v_permlane32_swap_b32_e32 v147, v149
	s_nop 1
	s_and_saveexec_b64 s[56:57], s[2:3]
	s_cbranch_execz .LBB0_940
	s_waitcnt lgkmcnt(0)
	v_add_f32_e32 v155, v147, v149
	ds_write_b64 v168, v[154:155] offset:4096
; __device__ __forceinline__ float fast_exp2(float x) { return __builtin_amdgcn_exp2f(x); }
;     __device__ __forceinline__ void fused(f32x4 (&acc)[2][2][4][2], const Unit& u, int wr, int wc, int fr, int fq, LAS unsigned char* lds, int wid, int lane) const {
;     ...
;             for (int m = 0; m < 4; ++m) {
;                 float mx = -3.0e38f;
; #pragma unroll
;                 for (int bj = 0; bj < 2; ++bj)
; #pragma unroll
;                     for (int n = 0; n < 2; ++n) { const f32x4 a = acc[ai][bj][m][n] * (rs[ai][m] * mul); acc[ai][bj][m][n] = a; mx = fmaxf(mx, fmaxf(fmaxf(a[0], a[1]), fmaxf(a[2], a[3]))); }
;                 mx = fmaxf(mx, __shfl_xor(mx, 16)); mx = fmaxf(mx, __shfl_xor(mx, 32));
;                 float s = 0.f;
; #pragma unroll
;                 for (int bj = 0; bj < 2; ++bj)
; #pragma unroll
;                     for (int n = 0; n < 2; ++n) { f32x4 a = acc[ai][bj][m][n];
; #pragma unroll
;                         for (int e = 0; e < 4; ++e) { a[e] = fast_exp2(a[e] - mx); s += a[e]; }
;                         acc[ai][bj][m][n] = a; }
;                 s += __shfl_xor(s, 16); s += __shfl_xor(s, 32);
;                 mw[ai][m] = mx;
;                 if (fq == 0) X[(ai * HALF + wr * 64 + m * 16 + fr) * 4 + wc] = (f32x2){mx, s};
.LBB0_940:
	s_or_b64 exec, exec, s[56:57]
	v_mul_f32_e32 v147, 0x4b800000, v156
	v_cndmask_b32_e32 v147, v156, v147, vcc
	v_rsq_f32_e32 v147, v147
	s_waitcnt lgkmcnt(0)
	v_mul_f32_e32 v149, 0x45800000, v147
	v_cndmask_b32_e32 v147, v147, v149, vcc
	v_mul_f32_e32 v156, 0x3d8293ee, v147
	v_pk_mul_f32 v[46:47], v[46:47], v[156:157] op_sel_hi:[1,0]
	v_pk_mul_f32 v[42:43], v[42:43], v[156:157] op_sel_hi:[1,0]
	v_pk_mul_f32 v[44:45], v[44:45], v[156:157] op_sel_hi:[1,0]
	v_pk_mul_f32 v[40:41], v[40:41], v[156:157] op_sel_hi:[1,0]
	v_max_f32_e32 v147, v46, v47
	v_max_f32_e32 v149, v42, v43
	v_pk_mul_f32 v[170:171], v[38:39], v[156:157] op_sel_hi:[1,0]
	v_pk_mul_f32 v[174:175], v[34:35], v[156:157] op_sel_hi:[1,0]
	v_max3_f32 v147, v44, v45, v147
	v_max3_f32 v149, v40, v41, v149
	v_pk_mul_f32 v[172:173], v[36:37], v[156:157] op_sel_hi:[1,0]
	v_max_f32_e32 v36, v170, v171
	v_pk_mul_f32 v[176:177], v[32:33], v[156:157] op_sel_hi:[1,0]
	v_max_f32_e32 v32, v174, v175
	v_max3_f32 v147, v147, s78, v149
	v_max3_f32 v36, v172, v173, v36
	v_max3_f32 v32, v176, v177, v32
	v_max3_f32 v32, v147, v36, v32
	ds_bpermute_b32 v33, v167, v32
	s_waitcnt lgkmcnt(0)
	v_max_f32_e32 v33, v33, v33
	v_max_f32_e32 v32, v32, v33
	ds_bpermute_b32 v33, v166, v32
	s_waitcnt lgkmcnt(0)
	v_max_f32_e32 v33, v33, v33
	v_max_f32_e32 v156, v32, v33
	v_sub_f32_e32 v32, v44, v156
	v_exp_f32_e32 v32, v32
	v_sub_f32_e32 v33, v45, v156
	v_exp_f32_e32 v33, v33
	v_sub_f32_e32 v34, v46, v156
	v_exp_f32_e32 v38, v34
	v_sub_f32_e32 v34, v47, v156
	v_exp_f32_e32 v39, v34
	v_sub_f32_e32 v35, v40, v156
	v_add_f32_e32 v34, 0, v32
	v_exp_f32_e32 v36, v35
	v_sub_f32_e32 v35, v41, v156
	v_add_f32_e32 v34, v33, v34
	v_exp_f32_e32 v37, v35
	v_sub_f32_e32 v35, v42, v156
	v_add_f32_e32 v34, v38, v34
	v_exp_f32_e32 v44, v35
	v_sub_f32_e32 v35, v43, v156
	v_add_f32_e32 v34, v39, v34
	v_exp_f32_e32 v45, v35
	v_add_f32_e32 v34, v36, v34
	v_add_f32_e32 v34, v37, v34
	v_add_f32_e32 v34, v44, v34
	v_add_f32_e32 v40, v45, v34
	v_sub_f32_e32 v34, v172, v156
	v_exp_f32_e32 v34, v34
	v_sub_f32_e32 v35, v173, v156
	v_exp_f32_e32 v35, v35
	v_sub_f32_e32 v41, v170, v156
	v_exp_f32_e32 v42, v41
	v_sub_f32_e32 v41, v171, v156
	v_exp_f32_e32 v43, v41
	v_add_f32_e32 v40, v34, v40
	v_add_f32_e32 v40, v35, v40
	v_add_f32_e32 v40, v42, v40
	v_add_f32_e32 v147, v43, v40
	v_sub_f32_e32 v40, v176, v156
	v_exp_f32_e32 v40, v40
	v_sub_f32_e32 v41, v177, v156
	v_exp_f32_e32 v41, v41
	v_sub_f32_e32 v46, v174, v156
	v_exp_f32_e32 v46, v46
	v_sub_f32_e32 v47, v175, v156
	v_exp_f32_e32 v47, v47
	v_add_f32_e32 v147, v40, v147
	v_add_f32_e32 v147, v41, v147
	v_add_f32_e32 v147, v46, v147
	v_add_f32_e32 v147, v47, v147
	v_mov_b32_e32 v149, v147
	s_nop 1
	v_permlane16_swap_b32_e32 v147, v149
	s_nop 1
	s_waitcnt lgkmcnt(0)
	v_add_f32_e32 v147, v147, v149
	v_mov_b32_e32 v149, v147
	s_nop 1
	v_permlane32_swap_b32_e32 v147, v149
	s_nop 1
	s_and_saveexec_b64 s[56:57], s[2:3]
	s_cbranch_execz .LBB0_942
	s_waitcnt lgkmcnt(0)
	v_add_f32_e32 v157, v147, v149
	ds_write_b64 v168, v[156:157] offset:4608
.LBB0_942:
	s_or_b64 exec, exec, s[56:57]
	v_pk_add_f32 v[158:159], v[158:159], v[160:161]
	s_nop 0
	v_pk_fma_f32 v[160:161], v[158:159], s[26:27], v[144:145] op_sel_hi:[1,0,0]
	s_nop 0
	v_mul_f32_e32 v147, 0x4b800000, v161
	v_cmp_gt_f32_e32 vcc, s76, v161
	s_nop 1
	v_cndmask_b32_e32 v147, v161, v147, vcc
	v_rsq_f32_e32 v147, v147
	s_waitcnt lgkmcnt(0)
	v_mul_f32_e32 v149, 0x45800000, v147
	v_cndmask_b32_e32 v147, v147, v149, vcc
	v_mul_f32_e32 v158, 0x3d8293ee, v147
	v_pk_mul_f32 v[30:31], v[30:31], v[158:159] op_sel_hi:[1,0]
	v_pk_mul_f32 v[26:27], v[26:27], v[158:159] op_sel_hi:[1,0]
	v_pk_mul_f32 v[28:29], v[28:29], v[158:159] op_sel_hi:[1,0]
	v_max_f32_e32 v147, v30, v31
	v_pk_mul_f32 v[24:25], v[24:25], v[158:159] op_sel_hi:[1,0]
	v_max_f32_e32 v149, v26, v27
	v_pk_mul_f32 v[170:171], v[22:23], v[158:159] op_sel_hi:[1,0]
	v_pk_mul_f32 v[174:175], v[18:19], v[158:159] op_sel_hi:[1,0]
	v_max3_f32 v147, v28, v29, v147
	v_max3_f32 v149, v24, v25, v149
	v_pk_mul_f32 v[172:173], v[20:21], v[158:159] op_sel_hi:[1,0]
	v_max_f32_e32 v20, v170, v171
	v_pk_mul_f32 v[176:177], v[16:17], v[158:159] op_sel_hi:[1,0]
	v_max_f32_e32 v16, v174, v175
	v_max3_f32 v147, v147, s78, v149
	v_max3_f32 v20, v172, v173, v20
	v_max3_f32 v16, v176, v177, v16
	v_max3_f32 v16, v147, v20, v16
	ds_bpermute_b32 v17, v167, v16
	v_cmp_gt_f32_e32 vcc, s76, v160
	s_waitcnt lgkmcnt(0)
	v_max_f32_e32 v17, v17, v17
	v_max_f32_e32 v16, v16, v17
	ds_bpermute_b32 v17, v166, v16
	s_waitcnt lgkmcnt(0)
	v_max_f32_e32 v17, v17, v17
	v_max_f32_e32 v158, v16, v17
	v_sub_f32_e32 v16, v28, v158
	v_exp_f32_e32 v16, v16
	v_sub_f32_e32 v17, v29, v158
	v_exp_f32_e32 v17, v17
	v_sub_f32_e32 v18, v30, v158
	v_exp_f32_e32 v22, v18
	v_sub_f32_e32 v18, v31, v158
	v_exp_f32_e32 v23, v18
	v_sub_f32_e32 v19, v24, v158
	v_add_f32_e32 v18, 0, v16
	v_exp_f32_e32 v20, v19
	v_sub_f32_e32 v19, v25, v158
	v_add_f32_e32 v18, v17, v18
	v_exp_f32_e32 v21, v19
	v_sub_f32_e32 v19, v26, v158
	v_add_f32_e32 v18, v22, v18
	v_exp_f32_e32 v28, v19
	v_sub_f32_e32 v19, v27, v158
	v_add_f32_e32 v18, v23, v18
	v_exp_f32_e32 v29, v19
	v_add_f32_e32 v18, v20, v18
	v_add_f32_e32 v18, v21, v18
	v_add_f32_e32 v18, v28, v18
	v_add_f32_e32 v24, v29, v18
	v_sub_f32_e32 v18, v172, v158
	v_exp_f32_e32 v18, v18
	v_sub_f32_e32 v19, v173, v158
	v_exp_f32_e32 v19, v19
	v_sub_f32_e32 v25, v170, v158
	v_exp_f32_e32 v26, v25
	v_sub_f32_e32 v25, v171, v158
	v_exp_f32_e32 v27, v25
	v_add_f32_e32 v24, v18, v24
	v_add_f32_e32 v24, v19, v24
	v_add_f32_e32 v24, v26, v24
	v_add_f32_e32 v147, v27, v24
	v_sub_f32_e32 v24, v176, v158
	v_exp_f32_e32 v24, v24
	v_sub_f32_e32 v25, v177, v158
	v_exp_f32_e32 v25, v25
	v_sub_f32_e32 v30, v174, v158
	v_exp_f32_e32 v30, v30
	v_sub_f32_e32 v31, v175, v158
	v_exp_f32_e32 v31, v31
	v_add_f32_e32 v147, v24, v147
	v_add_f32_e32 v147, v25, v147
	v_add_f32_e32 v147, v30, v147
	v_add_f32_e32 v147, v31, v147
	v_mov_b32_e32 v149, v147
	s_nop 1
	v_permlane16_swap_b32_e32 v147, v149
	s_nop 1
	s_waitcnt lgkmcnt(0)
	v_add_f32_e32 v147, v147, v149
	v_mov_b32_e32 v149, v147
	s_nop 1
	v_permlane32_swap_b32_e32 v147, v149
	s_nop 1
	s_and_saveexec_b64 s[56:57], s[2:3]
	s_cbranch_execz .LBB0_944
	s_waitcnt lgkmcnt(0)
	v_add_f32_e32 v159, v147, v149
	ds_write_b64 v168, v[158:159] offset:5120
; __device__ __forceinline__ float fast_exp2(float x) { return __builtin_amdgcn_exp2f(x); }
;     __device__ __forceinline__ void fused(f32x4 (&acc)[2][2][4][2], const Unit& u, int wr, int wc, int fr, int fq, LAS unsigned char* lds, int wid, int lane) const {
;     ...
;             for (int m = 0; m < 4; ++m) {
;                 float mx = -3.0e38f;
; #pragma unroll
;                 for (int bj = 0; bj < 2; ++bj)
; #pragma unroll
;                     for (int n = 0; n < 2; ++n) { const f32x4 a = acc[ai][bj][m][n] * (rs[ai][m] * mul); acc[ai][bj][m][n] = a; mx = fmaxf(mx, fmaxf(fmaxf(a[0], a[1]), fmaxf(a[2], a[3]))); }
;                 mx = fmaxf(mx, __shfl_xor(mx, 16)); mx = fmaxf(mx, __shfl_xor(mx, 32));
;                 float s = 0.f;
; #pragma unroll
;                 for (int bj = 0; bj < 2; ++bj)
; #pragma unroll
;                     for (int n = 0; n < 2; ++n) { f32x4 a = acc[ai][bj][m][n];
; #pragma unroll
;                         for (int e = 0; e < 4; ++e) { a[e] = fast_exp2(a[e] - mx); s += a[e]; }
;                         acc[ai][bj][m][n] = a; }
;                 s += __shfl_xor(s, 16); s += __shfl_xor(s, 32);
;                 mw[ai][m] = mx;
;                 if (fq == 0) X[(ai * HALF + wr * 64 + m * 16 + fr) * 4 + wc] = (f32x2){mx, s};
.LBB0_944:
	s_or_b64 exec, exec, s[56:57]
	v_mul_f32_e32 v147, 0x4b800000, v160
	v_cndmask_b32_e32 v147, v160, v147, vcc
	v_rsq_f32_e32 v147, v147
	s_waitcnt lgkmcnt(0)
	v_mul_f32_e32 v149, 0x45800000, v147
	v_cndmask_b32_e32 v147, v147, v149, vcc
	v_mul_f32_e32 v160, 0x3d8293ee, v147
	v_pk_mul_f32 v[14:15], v[14:15], v[160:161] op_sel_hi:[1,0]
	v_pk_mul_f32 v[10:11], v[10:11], v[160:161] op_sel_hi:[1,0]
	v_pk_mul_f32 v[12:13], v[12:13], v[160:161] op_sel_hi:[1,0]
	v_pk_mul_f32 v[8:9], v[8:9], v[160:161] op_sel_hi:[1,0]
	v_max_f32_e32 v147, v14, v15
	v_max_f32_e32 v149, v10, v11
	v_pk_mul_f32 v[168:169], v[6:7], v[160:161] op_sel_hi:[1,0]
	v_pk_mul_f32 v[172:173], v[2:3], v[160:161] op_sel_hi:[1,0]
	v_max3_f32 v147, v12, v13, v147
	v_max3_f32 v149, v8, v9, v149
	v_pk_mul_f32 v[170:171], v[4:5], v[160:161] op_sel_hi:[1,0]
	v_max_f32_e32 v4, v168, v169
	v_pk_mul_f32 v[174:175], v[0:1], v[160:161] op_sel_hi:[1,0]
	v_max_f32_e32 v0, v172, v173
	v_max3_f32 v147, v147, s78, v149
	v_max3_f32 v4, v170, v171, v4
	v_max3_f32 v0, v174, v175, v0
	v_max3_f32 v0, v147, v4, v0
	ds_bpermute_b32 v1, v167, v0
	s_waitcnt lgkmcnt(0)
	v_max_f32_e32 v1, v1, v1
	v_max_f32_e32 v0, v0, v1
	ds_bpermute_b32 v1, v166, v0
	s_waitcnt lgkmcnt(0)
	v_max_f32_e32 v1, v1, v1
	v_max_f32_e32 v160, v0, v1
	v_sub_f32_e32 v0, v12, v160
	v_exp_f32_e32 v0, v0
	v_sub_f32_e32 v1, v13, v160
	v_exp_f32_e32 v1, v1
	v_sub_f32_e32 v2, v14, v160
	v_exp_f32_e32 v6, v2
	v_sub_f32_e32 v2, v15, v160
	v_exp_f32_e32 v7, v2
	v_sub_f32_e32 v3, v8, v160
	v_add_f32_e32 v2, 0, v0
	v_exp_f32_e32 v4, v3
	v_sub_f32_e32 v3, v9, v160
	v_add_f32_e32 v2, v1, v2
	v_exp_f32_e32 v5, v3
	v_sub_f32_e32 v3, v10, v160
	v_add_f32_e32 v2, v6, v2
	v_exp_f32_e32 v12, v3
	v_sub_f32_e32 v3, v11, v160
	v_add_f32_e32 v2, v7, v2
	v_exp_f32_e32 v13, v3
	v_add_f32_e32 v2, v4, v2
	v_add_f32_e32 v2, v5, v2
	v_add_f32_e32 v2, v12, v2
	v_add_f32_e32 v8, v13, v2
	v_sub_f32_e32 v2, v170, v160
	v_exp_f32_e32 v2, v2
	v_sub_f32_e32 v3, v171, v160
	v_exp_f32_e32 v3, v3
	v_sub_f32_e32 v9, v168, v160
	v_exp_f32_e32 v10, v9
	v_sub_f32_e32 v9, v169, v160
	v_exp_f32_e32 v11, v9
	v_add_f32_e32 v8, v2, v8
	v_add_f32_e32 v8, v3, v8
	v_add_f32_e32 v8, v10, v8
	v_add_f32_e32 v147, v11, v8
	v_sub_f32_e32 v8, v174, v160
	v_exp_f32_e32 v8, v8
	v_sub_f32_e32 v9, v175, v160
	v_exp_f32_e32 v9, v9
	v_sub_f32_e32 v14, v172, v160
	v_exp_f32_e32 v14, v14
	v_sub_f32_e32 v15, v173, v160
	v_exp_f32_e32 v15, v15
	v_add_f32_e32 v147, v8, v147
	v_add_f32_e32 v147, v9, v147
	v_add_f32_e32 v147, v14, v147
	v_add_f32_e32 v147, v15, v147
	v_mov_b32_e32 v149, v147
	s_nop 1
	v_permlane16_swap_b32_e32 v147, v149
	s_nop 1
	s_waitcnt lgkmcnt(0)
	v_add_f32_e32 v149, v147, v149
	v_mov_b32_e32 v151, v149
	s_nop 1
	v_permlane32_swap_b32_e32 v149, v151
	s_nop 1
	v_lshlrev_b32_e32 v147, 5, v165
	s_and_saveexec_b64 s[18:19], s[4:5]
	s_xor_b64 s[56:57], exec, s[18:19]
	v_lshlrev_b32_e32 v147, 5, v165
	s_andn2_saveexec_b64 s[56:57], s[56:57]
	s_cbranch_execz .LBB0_921
	s_waitcnt lgkmcnt(0)
	v_add_f32_e32 v161, v149, v151
	v_add_u32_e32 v149, s11, v147
	ds_write_b64 v149, v[160:161] offset:5632
	s_branch .LBB0_921

; __device__ __forceinline__ unsigned cvt_pk_bf16(float lo, float hi) { unsigned r; asm volatile("v_cvt_pk_bf16_f32 %0, %1, %2" : "=v"(r) : "v"(lo), "v"(hi)); return r; }
; __device__ __forceinline__ float bf_lo(unsigned u) { return __uint_as_float(u << 16); }
; __device__ __forceinline__ float bf_hi(unsigned u) { return __uint_as_float(u & 0xffff0000u); }
;     __device__ __forceinline__ void operator()(const f32x4 (&acc)[2][2][4][2], const Unit& u, int wr, int wc, int fr, int fq) const {
;     ...
;             for (int m = 0; m < 4; ++m) { const int row = row0 + ai * HALF + m * 16; bf16_t* rowp = XB + (size_t)row * D + col0; float ss = 0.f;
; #pragma unroll
;                 for (int bj = 0; bj < 2; ++bj) { const u32x4 r = *(const u32x4*)(rowp + bj * HALF);
;                     const f32x4 o0 = (f32x4){bf_lo(r.x), bf_hi(r.x), bf_lo(r.y), bf_hi(r.y)} + acc[ai][bj][m][0] * alpha, o1 = (f32x4){bf_lo(r.z), bf_hi(r.z), bf_lo(r.w), bf_hi(r.w)} + acc[ai][bj][m][1] * alpha;
;                     ss += ((o0[0] * o0[0] + o0[1] * o0[1]) + (o0[2] * o0[2] + o0[3] * o0[3])) + ((o1[0] * o1[0] + o1[1] * o1[1]) + (o1[2] * o1[2] + o1[3] * o1[3]));
;                     u32x4 w; w.x = cvt_pk_bf16(o0[0], o0[1]); w.y = cvt_pk_bf16(o0[2], o0[3]); w.z = cvt_pk_bf16(o1[0], o1[1]); w.w = cvt_pk_bf16(o1[2], o1[3]);
;                     *(u32x4*)(rowp + bj * HALF) = w; }
;                 ss += __shfl_xor(ss, 16); ss += __shfl_xor(ss, 32);
;                 if (fq == 0) part[(size_t)row * NPART + u.pn * 4 + wc] = ss; }
.LBB0_1068:
	v_lshl_add_u32 v146, s79, 8, v148
	v_ashrrev_i32_e32 v147, 31, v146
	v_lshl_or_b32 v144, s58, 8, v150
	v_lshlrev_b64 v[156:157], 12, v[146:147]
	v_ashrrev_i32_e32 v145, 31, v144
	v_lshl_add_u64 v[156:157], s[50:51], 0, v[156:157]
	v_lshl_add_u64 v[160:161], v[144:145], 1, v[156:157]
	global_load_dwordx4 v[156:159], v[160:161], off
	v_xor_b32_e32 v155, 32, v154
	s_waitcnt vmcnt(0)
	v_lshlrev_b32_e32 v162, 16, v156
	v_and_b32_e32 v163, 0xffff0000, v156
	v_lshlrev_b32_e32 v156, 16, v157
	v_and_b32_e32 v157, 0xffff0000, v157
	v_lshlrev_b32_e32 v164, 16, v158
	v_and_b32_e32 v165, 0xffff0000, v158
	v_lshlrev_b32_e32 v158, 16, v159
	v_and_b32_e32 v159, 0xffff0000, v159
	v_pk_add_f32 v[126:127], v[126:127], v[156:157]
	v_pk_add_f32 v[162:163], v[124:125], v[162:163]
	v_pk_add_f32 v[166:167], v[122:123], v[158:159]
	v_pk_add_f32 v[164:165], v[120:121], v[164:165]
	v_cvt_pk_bf16_f32 v122, v162, v163
	v_cvt_pk_bf16_f32 v123, v126, v127
	v_mul_f32_e32 v163, v163, v163
	v_cvt_pk_bf16_f32 v124, v164, v165
	v_cvt_pk_bf16_f32 v125, v166, v167
	global_load_dwordx4 v[156:159], v[160:161], off offset:256
	v_mul_f32_e32 v127, v127, v127
	v_mul_f32_e32 v165, v165, v165
	v_mul_f32_e32 v167, v167, v167
	v_fmac_f32_e32 v163, v162, v162
	v_fmac_f32_e32 v127, v126, v126
	v_fmac_f32_e32 v165, v164, v164
	v_fmac_f32_e32 v167, v166, v166
	v_add_f32_e32 v126, v163, v127
	v_add_f32_e32 v127, v165, v167
	v_add_f32_e32 v164, v126, v127
	v_and_b32_e32 v121, 64, v154
	v_xor_b32_e32 v120, 16, v154
	v_add_u32_e32 v121, 64, v121
	v_cmp_lt_i32_e32 vcc, v120, v121
	global_store_dwordx4 v[160:161], v[122:125], off
	s_waitcnt vmcnt(0)
	v_lshlrev_b32_e32 v126, 16, v156
	v_and_b32_e32 v127, 0xffff0000, v156
	v_lshlrev_b32_e32 v156, 16, v157
	v_and_b32_e32 v157, 0xffff0000, v157
	v_lshlrev_b32_e32 v162, 16, v158
	v_and_b32_e32 v163, 0xffff0000, v158
	v_lshlrev_b32_e32 v158, 16, v159
	v_and_b32_e32 v159, 0xffff0000, v159
	v_pk_add_f32 v[118:119], v[118:119], v[156:157]
	v_pk_add_f32 v[116:117], v[116:117], v[126:127]
	v_pk_add_f32 v[126:127], v[114:115], v[158:159]
	v_pk_add_f32 v[156:157], v[112:113], v[162:163]
	v_mul_f32_e32 v112, v117, v117
	v_mul_f32_e32 v113, v119, v119
	v_mul_f32_e32 v114, v157, v157
	v_mul_f32_e32 v115, v127, v127
	v_fmac_f32_e32 v112, v116, v116
	v_fmac_f32_e32 v113, v118, v118
	v_fmac_f32_e32 v114, v156, v156
	v_fmac_f32_e32 v115, v126, v126
	v_add_f32_e32 v112, v112, v113
	v_add_f32_e32 v113, v114, v115
	v_cndmask_b32_e32 v120, v154, v120, vcc
	v_add_f32_e32 v112, v112, v113
	v_lshlrev_b32_e32 v120, 2, v120
	v_add_f32_e32 v112, v164, v112
	v_mov_b32_e32 v113, v112
	s_nop 1
	v_permlane16_swap_b32_e32 v112, v113
	s_nop 1
	v_cmp_lt_i32_e32 vcc, v155, v121
	v_cvt_pk_bf16_f32 v116, v116, v117
	v_cvt_pk_bf16_f32 v117, v118, v119
	v_cvt_pk_bf16_f32 v118, v156, v157
	s_waitcnt lgkmcnt(0)
	v_add_f32_e32 v112, v112, v113
	v_cvt_pk_bf16_f32 v119, v126, v127
	v_cndmask_b32_e32 v114, v154, v155, vcc
	v_lshlrev_b32_e32 v114, 2, v114
	v_mov_b32_e32 v113, v112
	s_nop 1
	v_permlane32_swap_b32_e32 v112, v113
	s_nop 1
	global_store_dwordx4 v[160:161], v[116:119], off offset:256
	s_and_saveexec_b64 s[52:53], s[2:3]
	s_cbranch_execz .LBB0_1070
	s_waitcnt lgkmcnt(0)
	v_add_f32_e32 v115, v112, v113
	s_lshl_b32 s18, s58, 2
	v_lshlrev_b64 v[112:113], 7, v[146:147]
	s_ashr_i32 s19, s18, 31
	v_lshl_add_u64 v[112:113], s[48:49], 0, v[112:113]
	v_lshl_add_u64 v[112:113], s[18:19], 2, v[112:113]
	s_lshl_b32 s18, s64, 2
	s_mov_b32 s19, s21
	v_lshl_add_u64 v[112:113], v[112:113], 0, s[18:19]
	global_store_dword v[112:113], v115, off
.LBB0_1070:
	s_or_b64 exec, exec, s[52:53]
	v_or_b32_e32 v112, 16, v146
	s_waitcnt lgkmcnt(0)
	v_ashrrev_i32_e32 v113, 31, v112
	v_lshlrev_b64 v[116:117], 12, v[112:113]
	v_lshl_add_u64 v[116:117], s[50:51], 0, v[116:117]
	v_lshl_add_u64 v[122:123], v[144:145], 1, v[116:117]
	global_load_dwordx4 v[116:119], v[122:123], off
	s_waitcnt vmcnt(0)
	v_lshlrev_b32_e32 v124, 16, v116
	v_and_b32_e32 v125, 0xffff0000, v116
	v_lshlrev_b32_e32 v116, 16, v117
	v_and_b32_e32 v117, 0xffff0000, v117
	v_lshlrev_b32_e32 v126, 16, v118
	v_and_b32_e32 v127, 0xffff0000, v118
	v_lshlrev_b32_e32 v118, 16, v119
	v_and_b32_e32 v119, 0xffff0000, v119
	v_pk_add_f32 v[116:117], v[110:111], v[116:117]
	v_pk_add_f32 v[124:125], v[108:109], v[124:125]
	v_pk_add_f32 v[118:119], v[106:107], v[118:119]
	v_pk_add_f32 v[126:127], v[104:105], v[126:127]
	v_cvt_pk_bf16_f32 v104, v124, v125
	v_cvt_pk_bf16_f32 v105, v116, v117
	v_mul_f32_e32 v115, v125, v125
	v_cvt_pk_bf16_f32 v106, v126, v127
	v_cvt_pk_bf16_f32 v107, v118, v119
	global_load_dwordx4 v[108:111], v[122:123], off offset:256
	v_mul_f32_e32 v117, v117, v117
	v_mul_f32_e32 v121, v127, v127
	v_mul_f32_e32 v119, v119, v119
	v_fmac_f32_e32 v115, v124, v124
	v_fmac_f32_e32 v117, v116, v116
	v_fmac_f32_e32 v121, v126, v126
	v_fmac_f32_e32 v119, v118, v118
	v_add_f32_e32 v115, v115, v117
	v_add_f32_e32 v116, v121, v119
	v_add_f32_e32 v115, v115, v116
	global_store_dwordx4 v[122:123], v[104:107], off
	s_waitcnt vmcnt(1)
	v_lshlrev_b32_e32 v116, 16, v108
	v_and_b32_e32 v117, 0xffff0000, v108
	v_lshlrev_b32_e32 v108, 16, v109
	v_and_b32_e32 v109, 0xffff0000, v109
	v_lshlrev_b32_e32 v118, 16, v110
	v_and_b32_e32 v119, 0xffff0000, v110
	v_lshlrev_b32_e32 v110, 16, v111
	v_and_b32_e32 v111, 0xffff0000, v111
	v_pk_add_f32 v[102:103], v[102:103], v[108:109]
	v_pk_add_f32 v[100:101], v[100:101], v[116:117]
	v_pk_add_f32 v[108:109], v[98:99], v[110:111]
	v_pk_add_f32 v[110:111], v[96:97], v[118:119]
	v_mul_f32_e32 v96, v101, v101
	v_mul_f32_e32 v97, v103, v103
	v_mul_f32_e32 v98, v111, v111
	v_mul_f32_e32 v99, v109, v109
	v_fmac_f32_e32 v96, v100, v100
	v_fmac_f32_e32 v97, v102, v102
	v_fmac_f32_e32 v98, v110, v110
	v_fmac_f32_e32 v99, v108, v108
	v_add_f32_e32 v96, v96, v97
	v_add_f32_e32 v97, v98, v99
	v_add_f32_e32 v96, v96, v97
	v_add_f32_e32 v96, v115, v96
	v_mov_b32_e32 v97, v96
	s_nop 1
	v_permlane16_swap_b32_e32 v96, v97
	s_nop 1
	v_cvt_pk_bf16_f32 v98, v100, v101
	v_cvt_pk_bf16_f32 v99, v102, v103
	v_cvt_pk_bf16_f32 v100, v110, v111
	v_cvt_pk_bf16_f32 v101, v108, v109
	s_waitcnt lgkmcnt(0)
	v_add_f32_e32 v96, v96, v97
	v_mov_b32_e32 v97, v96
	s_nop 1
	v_permlane32_swap_b32_e32 v96, v97
	s_nop 1
	global_store_dwordx4 v[122:123], v[98:101], off offset:256
	s_and_saveexec_b64 s[52:53], s[2:3]
	s_cbranch_execz .LBB0_1072
	s_waitcnt lgkmcnt(0)
	v_add_f32_e32 v98, v96, v97
	s_lshl_b32 s18, s58, 2
	v_lshlrev_b64 v[96:97], 7, v[112:113]
	s_ashr_i32 s19, s18, 31
	v_lshl_add_u64 v[96:97], s[48:49], 0, v[96:97]
	v_lshl_add_u64 v[96:97], s[18:19], 2, v[96:97]
	s_lshl_b32 s18, s64, 2
	s_mov_b32 s19, s21
	v_lshl_add_u64 v[96:97], v[96:97], 0, s[18:19]
	global_store_dword v[96:97], v98, off
; __device__ __forceinline__ unsigned cvt_pk_bf16(float lo, float hi) { unsigned r; asm volatile("v_cvt_pk_bf16_f32 %0, %1, %2" : "=v"(r) : "v"(lo), "v"(hi)); return r; }
; __device__ __forceinline__ float bf_lo(unsigned u) { return __uint_as_float(u << 16); }
; __device__ __forceinline__ float bf_hi(unsigned u) { return __uint_as_float(u & 0xffff0000u); }
;     __device__ __forceinline__ void operator()(const f32x4 (&acc)[2][2][4][2], const Unit& u, int wr, int wc, int fr, int fq) const {
;     ...
;             for (int m = 0; m < 4; ++m) { const int row = row0 + ai * HALF + m * 16; bf16_t* rowp = XB + (size_t)row * D + col0; float ss = 0.f;
; #pragma unroll
;                 for (int bj = 0; bj < 2; ++bj) { const u32x4 r = *(const u32x4*)(rowp + bj * HALF);
;                     const f32x4 o0 = (f32x4){bf_lo(r.x), bf_hi(r.x), bf_lo(r.y), bf_hi(r.y)} + acc[ai][bj][m][0] * alpha, o1 = (f32x4){bf_lo(r.z), bf_hi(r.z), bf_lo(r.w), bf_hi(r.w)} + acc[ai][bj][m][1] * alpha;
;                     ss += ((o0[0] * o0[0] + o0[1] * o0[1]) + (o0[2] * o0[2] + o0[3] * o0[3])) + ((o1[0] * o1[0] + o1[1] * o1[1]) + (o1[2] * o1[2] + o1[3] * o1[3]));
;                     u32x4 w; w.x = cvt_pk_bf16(o0[0], o0[1]); w.y = cvt_pk_bf16(o0[2], o0[3]); w.z = cvt_pk_bf16(o1[0], o1[1]); w.w = cvt_pk_bf16(o1[2], o1[3]);
;                     *(u32x4*)(rowp + bj * HALF) = w; }
;                 ss += __shfl_xor(ss, 16); ss += __shfl_xor(ss, 32);
;                 if (fq == 0) part[(size_t)row * NPART + u.pn * 4 + wc] = ss; }
.LBB0_1072:
	s_or_b64 exec, exec, s[52:53]
	v_or_b32_e32 v96, 32, v146
	s_waitcnt lgkmcnt(0)
	v_ashrrev_i32_e32 v97, 31, v96
	v_lshlrev_b64 v[98:99], 12, v[96:97]
	v_lshl_add_u64 v[98:99], s[50:51], 0, v[98:99]
	v_lshl_add_u64 v[102:103], v[144:145], 1, v[98:99]
	global_load_dwordx4 v[98:101], v[102:103], off
	s_waitcnt vmcnt(0)
	v_lshlrev_b32_e32 v104, 16, v98
	v_and_b32_e32 v105, 0xffff0000, v98
	v_lshlrev_b32_e32 v98, 16, v99
	v_and_b32_e32 v99, 0xffff0000, v99
	v_lshlrev_b32_e32 v106, 16, v100
	v_and_b32_e32 v107, 0xffff0000, v100
	v_lshlrev_b32_e32 v100, 16, v101
	v_and_b32_e32 v101, 0xffff0000, v101
	v_pk_add_f32 v[98:99], v[94:95], v[98:99]
	v_pk_add_f32 v[104:105], v[92:93], v[104:105]
	v_pk_add_f32 v[100:101], v[90:91], v[100:101]
	v_pk_add_f32 v[106:107], v[88:89], v[106:107]
	v_cvt_pk_bf16_f32 v88, v104, v105
	v_cvt_pk_bf16_f32 v89, v98, v99
	v_mul_f32_e32 v105, v105, v105
	v_cvt_pk_bf16_f32 v90, v106, v107
	v_cvt_pk_bf16_f32 v91, v100, v101
	global_load_dwordx4 v[92:95], v[102:103], off offset:256
	v_mul_f32_e32 v99, v99, v99
	v_mul_f32_e32 v107, v107, v107
	v_mul_f32_e32 v101, v101, v101
	v_fmac_f32_e32 v105, v104, v104
	v_fmac_f32_e32 v99, v98, v98
	v_fmac_f32_e32 v107, v106, v106
	v_fmac_f32_e32 v101, v100, v100
	v_add_f32_e32 v98, v105, v99
	v_add_f32_e32 v99, v107, v101
	v_add_f32_e32 v104, v98, v99
	global_store_dwordx4 v[102:103], v[88:91], off
	s_waitcnt vmcnt(1)
	v_lshlrev_b32_e32 v98, 16, v92
	v_and_b32_e32 v99, 0xffff0000, v92
	v_lshlrev_b32_e32 v92, 16, v93
	v_and_b32_e32 v93, 0xffff0000, v93
	v_lshlrev_b32_e32 v100, 16, v94
	v_and_b32_e32 v101, 0xffff0000, v94
	v_lshlrev_b32_e32 v94, 16, v95
	v_and_b32_e32 v95, 0xffff0000, v95
	v_pk_add_f32 v[86:87], v[86:87], v[92:93]
	v_pk_add_f32 v[84:85], v[84:85], v[98:99]
	v_pk_add_f32 v[92:93], v[82:83], v[94:95]
	v_pk_add_f32 v[94:95], v[80:81], v[100:101]
	v_mul_f32_e32 v80, v85, v85
	v_mul_f32_e32 v81, v87, v87
	v_mul_f32_e32 v82, v95, v95
	v_mul_f32_e32 v83, v93, v93
	v_fmac_f32_e32 v80, v84, v84
	v_fmac_f32_e32 v81, v86, v86
	v_fmac_f32_e32 v82, v94, v94
	v_fmac_f32_e32 v83, v92, v92
	v_add_f32_e32 v80, v80, v81
	v_add_f32_e32 v81, v82, v83
	v_add_f32_e32 v80, v80, v81
	v_add_f32_e32 v80, v104, v80
	v_mov_b32_e32 v81, v80
	s_nop 1
	v_permlane16_swap_b32_e32 v80, v81
	s_nop 1
	v_cvt_pk_bf16_f32 v82, v84, v85
	v_cvt_pk_bf16_f32 v83, v86, v87
	v_cvt_pk_bf16_f32 v84, v94, v95
	v_cvt_pk_bf16_f32 v85, v92, v93
	s_waitcnt lgkmcnt(0)
	v_add_f32_e32 v80, v80, v81
	v_mov_b32_e32 v81, v80
	s_nop 1
	v_permlane32_swap_b32_e32 v80, v81
	s_nop 1
	global_store_dwordx4 v[102:103], v[82:85], off offset:256
	s_and_saveexec_b64 s[52:53], s[2:3]
	s_cbranch_execz .LBB0_1074
	s_waitcnt lgkmcnt(0)
	v_add_f32_e32 v82, v80, v81
	s_lshl_b32 s18, s58, 2
	v_lshlrev_b64 v[80:81], 7, v[96:97]
	s_ashr_i32 s19, s18, 31
	v_lshl_add_u64 v[80:81], s[48:49], 0, v[80:81]
	v_lshl_add_u64 v[80:81], s[18:19], 2, v[80:81]
	s_lshl_b32 s18, s64, 2
	s_mov_b32 s19, s21
	v_lshl_add_u64 v[80:81], v[80:81], 0, s[18:19]
	global_store_dword v[80:81], v82, off
.LBB0_1074:
	s_or_b64 exec, exec, s[52:53]
	v_or_b32_e32 v80, 48, v146
	s_waitcnt lgkmcnt(0)
	v_ashrrev_i32_e32 v81, 31, v80
	v_lshlrev_b64 v[82:83], 12, v[80:81]
	v_lshl_add_u64 v[82:83], s[50:51], 0, v[82:83]
	v_lshl_add_u64 v[86:87], v[144:145], 1, v[82:83]
	global_load_dwordx4 v[82:85], v[86:87], off
	s_waitcnt vmcnt(0)
	v_lshlrev_b32_e32 v88, 16, v82
	v_and_b32_e32 v89, 0xffff0000, v82
	v_lshlrev_b32_e32 v82, 16, v83
	v_and_b32_e32 v83, 0xffff0000, v83
	v_lshlrev_b32_e32 v90, 16, v84
	v_and_b32_e32 v91, 0xffff0000, v84
	v_lshlrev_b32_e32 v84, 16, v85
	v_and_b32_e32 v85, 0xffff0000, v85
	v_pk_add_f32 v[82:83], v[78:79], v[82:83]
	v_pk_add_f32 v[88:89], v[76:77], v[88:89]
	v_pk_add_f32 v[84:85], v[74:75], v[84:85]
	v_pk_add_f32 v[90:91], v[72:73], v[90:91]
	v_cvt_pk_bf16_f32 v72, v88, v89
	v_cvt_pk_bf16_f32 v73, v82, v83
	v_mul_f32_e32 v89, v89, v89
	v_cvt_pk_bf16_f32 v74, v90, v91
	v_cvt_pk_bf16_f32 v75, v84, v85
	global_load_dwordx4 v[76:79], v[86:87], off offset:256
	v_mul_f32_e32 v83, v83, v83
	v_mul_f32_e32 v91, v91, v91
	v_mul_f32_e32 v85, v85, v85
	v_fmac_f32_e32 v89, v88, v88
	v_fmac_f32_e32 v83, v82, v82
	v_fmac_f32_e32 v91, v90, v90
	v_fmac_f32_e32 v85, v84, v84
	v_add_f32_e32 v82, v89, v83
	v_add_f32_e32 v83, v91, v85
	v_add_f32_e32 v88, v82, v83
	global_store_dwordx4 v[86:87], v[72:75], off
	s_waitcnt vmcnt(1)
	v_lshlrev_b32_e32 v82, 16, v76
	v_and_b32_e32 v83, 0xffff0000, v76
	v_lshlrev_b32_e32 v76, 16, v77
	v_and_b32_e32 v77, 0xffff0000, v77
	v_lshlrev_b32_e32 v84, 16, v78
	v_and_b32_e32 v85, 0xffff0000, v78
	v_lshlrev_b32_e32 v78, 16, v79
	v_and_b32_e32 v79, 0xffff0000, v79
	v_pk_add_f32 v[70:71], v[70:71], v[76:77]
	v_pk_add_f32 v[68:69], v[68:69], v[82:83]
	v_pk_add_f32 v[76:77], v[66:67], v[78:79]
	v_pk_add_f32 v[78:79], v[64:65], v[84:85]
	v_mul_f32_e32 v64, v69, v69
	v_mul_f32_e32 v65, v71, v71
	v_mul_f32_e32 v66, v79, v79
	v_mul_f32_e32 v67, v77, v77
	v_fmac_f32_e32 v64, v68, v68
	v_fmac_f32_e32 v65, v70, v70
	v_fmac_f32_e32 v66, v78, v78
	v_fmac_f32_e32 v67, v76, v76
	v_add_f32_e32 v64, v64, v65
	v_add_f32_e32 v65, v66, v67
	v_add_f32_e32 v64, v64, v65
	v_add_f32_e32 v64, v88, v64
	v_mov_b32_e32 v65, v64
	s_nop 1
	v_permlane16_swap_b32_e32 v64, v65
	s_nop 1
	v_cvt_pk_bf16_f32 v66, v68, v69
	v_cvt_pk_bf16_f32 v67, v70, v71
	v_cvt_pk_bf16_f32 v68, v78, v79
	v_cvt_pk_bf16_f32 v69, v76, v77
	s_waitcnt lgkmcnt(0)
	v_add_f32_e32 v64, v64, v65
	v_mov_b32_e32 v65, v64
	s_nop 1
	v_permlane32_swap_b32_e32 v64, v65
	s_nop 1
	global_store_dwordx4 v[86:87], v[66:69], off offset:256
	s_and_saveexec_b64 s[52:53], s[2:3]
	s_cbranch_execz .LBB0_1076
	s_waitcnt lgkmcnt(0)
	v_add_f32_e32 v66, v64, v65
	s_lshl_b32 s18, s58, 2
	v_lshlrev_b64 v[64:65], 7, v[80:81]
	s_ashr_i32 s19, s18, 31
	v_lshl_add_u64 v[64:65], s[48:49], 0, v[64:65]
	v_lshl_add_u64 v[64:65], s[18:19], 2, v[64:65]
	s_lshl_b32 s18, s64, 2
	s_mov_b32 s19, s21
	v_lshl_add_u64 v[64:65], v[64:65], 0, s[18:19]
	global_store_dword v[64:65], v66, off
; __device__ __forceinline__ unsigned cvt_pk_bf16(float lo, float hi) { unsigned r; asm volatile("v_cvt_pk_bf16_f32 %0, %1, %2" : "=v"(r) : "v"(lo), "v"(hi)); return r; }
; __device__ __forceinline__ float bf_lo(unsigned u) { return __uint_as_float(u << 16); }
; __device__ __forceinline__ float bf_hi(unsigned u) { return __uint_as_float(u & 0xffff0000u); }
;     __device__ __forceinline__ void operator()(const f32x4 (&acc)[2][2][4][2], const Unit& u, int wr, int wc, int fr, int fq) const {
;     ...
;             for (int m = 0; m < 4; ++m) { const int row = row0 + ai * HALF + m * 16; bf16_t* rowp = XB + (size_t)row * D + col0; float ss = 0.f;
; #pragma unroll
;                 for (int bj = 0; bj < 2; ++bj) { const u32x4 r = *(const u32x4*)(rowp + bj * HALF);
;                     const f32x4 o0 = (f32x4){bf_lo(r.x), bf_hi(r.x), bf_lo(r.y), bf_hi(r.y)} + acc[ai][bj][m][0] * alpha, o1 = (f32x4){bf_lo(r.z), bf_hi(r.z), bf_lo(r.w), bf_hi(r.w)} + acc[ai][bj][m][1] * alpha;
;                     ss += ((o0[0] * o0[0] + o0[1] * o0[1]) + (o0[2] * o0[2] + o0[3] * o0[3])) + ((o1[0] * o1[0] + o1[1] * o1[1]) + (o1[2] * o1[2] + o1[3] * o1[3]));
;                     u32x4 w; w.x = cvt_pk_bf16(o0[0], o0[1]); w.y = cvt_pk_bf16(o0[2], o0[3]); w.z = cvt_pk_bf16(o1[0], o1[1]); w.w = cvt_pk_bf16(o1[2], o1[3]);
;                     *(u32x4*)(rowp + bj * HALF) = w; }
;                 ss += __shfl_xor(ss, 16); ss += __shfl_xor(ss, 32);
;                 if (fq == 0) part[(size_t)row * NPART + u.pn * 4 + wc] = ss; }
.LBB0_1076:
	s_or_b64 exec, exec, s[52:53]
	v_add_u32_e32 v64, 0x80, v146
	s_waitcnt lgkmcnt(0)
	v_ashrrev_i32_e32 v65, 31, v64
	v_lshlrev_b64 v[66:67], 12, v[64:65]
	v_lshl_add_u64 v[66:67], s[50:51], 0, v[66:67]
	v_lshl_add_u64 v[70:71], v[144:145], 1, v[66:67]
	global_load_dwordx4 v[66:69], v[70:71], off
	s_waitcnt vmcnt(0)
	v_lshlrev_b32_e32 v72, 16, v66
	v_and_b32_e32 v73, 0xffff0000, v66
	v_lshlrev_b32_e32 v66, 16, v67
	v_and_b32_e32 v67, 0xffff0000, v67
	v_lshlrev_b32_e32 v74, 16, v68
	v_and_b32_e32 v75, 0xffff0000, v68
	v_lshlrev_b32_e32 v68, 16, v69
	v_and_b32_e32 v69, 0xffff0000, v69
	v_pk_add_f32 v[66:67], v[62:63], v[66:67]
	v_pk_add_f32 v[72:73], v[60:61], v[72:73]
	v_pk_add_f32 v[68:69], v[58:59], v[68:69]
	v_pk_add_f32 v[74:75], v[56:57], v[74:75]
	v_cvt_pk_bf16_f32 v56, v72, v73
	v_cvt_pk_bf16_f32 v57, v66, v67
	v_mul_f32_e32 v73, v73, v73
	v_cvt_pk_bf16_f32 v58, v74, v75
	v_cvt_pk_bf16_f32 v59, v68, v69
	global_load_dwordx4 v[60:63], v[70:71], off offset:256
	v_mul_f32_e32 v67, v67, v67
	v_mul_f32_e32 v75, v75, v75
	v_mul_f32_e32 v69, v69, v69
	v_fmac_f32_e32 v73, v72, v72
	v_fmac_f32_e32 v67, v66, v66
	v_fmac_f32_e32 v75, v74, v74
	v_fmac_f32_e32 v69, v68, v68
	v_add_f32_e32 v66, v73, v67
	v_add_f32_e32 v67, v75, v69
	v_add_f32_e32 v72, v66, v67
	global_store_dwordx4 v[70:71], v[56:59], off
	s_waitcnt vmcnt(1)
	v_lshlrev_b32_e32 v66, 16, v60
	v_and_b32_e32 v67, 0xffff0000, v60
	v_lshlrev_b32_e32 v60, 16, v61
	v_and_b32_e32 v61, 0xffff0000, v61
	v_lshlrev_b32_e32 v68, 16, v62
	v_and_b32_e32 v69, 0xffff0000, v62
	v_lshlrev_b32_e32 v62, 16, v63
	v_and_b32_e32 v63, 0xffff0000, v63
	v_pk_add_f32 v[54:55], v[54:55], v[60:61]
	v_pk_add_f32 v[52:53], v[52:53], v[66:67]
	v_pk_add_f32 v[60:61], v[50:51], v[62:63]
	v_pk_add_f32 v[62:63], v[48:49], v[68:69]
	v_mul_f32_e32 v48, v53, v53
	v_mul_f32_e32 v49, v55, v55
	v_mul_f32_e32 v50, v63, v63
	v_mul_f32_e32 v51, v61, v61
	v_fmac_f32_e32 v48, v52, v52
	v_fmac_f32_e32 v49, v54, v54
	v_fmac_f32_e32 v50, v62, v62
	v_fmac_f32_e32 v51, v60, v60
	v_add_f32_e32 v48, v48, v49
	v_add_f32_e32 v49, v50, v51
	v_add_f32_e32 v48, v48, v49
	v_add_f32_e32 v48, v72, v48
	v_mov_b32_e32 v49, v48
	s_nop 1
	v_permlane16_swap_b32_e32 v48, v49
	s_nop 1
	v_cvt_pk_bf16_f32 v50, v52, v53
	v_cvt_pk_bf16_f32 v51, v54, v55
	v_cvt_pk_bf16_f32 v52, v62, v63
	v_cvt_pk_bf16_f32 v53, v60, v61
	s_waitcnt lgkmcnt(0)
	v_add_f32_e32 v48, v48, v49
	v_mov_b32_e32 v49, v48
	s_nop 1
	v_permlane32_swap_b32_e32 v48, v49
	s_nop 1
	global_store_dwordx4 v[70:71], v[50:53], off offset:256
	s_and_saveexec_b64 s[52:53], s[2:3]
	s_cbranch_execz .LBB0_1078
	s_waitcnt lgkmcnt(0)
	v_add_f32_e32 v50, v48, v49
	s_lshl_b32 s18, s58, 2
	v_lshlrev_b64 v[48:49], 7, v[64:65]
	s_ashr_i32 s19, s18, 31
	v_lshl_add_u64 v[48:49], s[48:49], 0, v[48:49]
	v_lshl_add_u64 v[48:49], s[18:19], 2, v[48:49]
	s_lshl_b32 s18, s64, 2
	s_mov_b32 s19, s21
	v_lshl_add_u64 v[48:49], v[48:49], 0, s[18:19]
	global_store_dword v[48:49], v50, off
.LBB0_1078:
	s_or_b64 exec, exec, s[52:53]
	v_add_u32_e32 v48, 0x90, v146
	s_waitcnt lgkmcnt(0)
	v_ashrrev_i32_e32 v49, 31, v48
	v_lshlrev_b64 v[50:51], 12, v[48:49]
	v_lshl_add_u64 v[50:51], s[50:51], 0, v[50:51]
	v_lshl_add_u64 v[54:55], v[144:145], 1, v[50:51]
	global_load_dwordx4 v[50:53], v[54:55], off
	s_waitcnt vmcnt(0)
	v_lshlrev_b32_e32 v56, 16, v50
	v_and_b32_e32 v57, 0xffff0000, v50
	v_lshlrev_b32_e32 v50, 16, v51
	v_and_b32_e32 v51, 0xffff0000, v51
	v_lshlrev_b32_e32 v58, 16, v52
	v_and_b32_e32 v59, 0xffff0000, v52
	v_lshlrev_b32_e32 v52, 16, v53
	v_and_b32_e32 v53, 0xffff0000, v53
	v_pk_add_f32 v[50:51], v[46:47], v[50:51]
	v_pk_add_f32 v[56:57], v[44:45], v[56:57]
	v_pk_add_f32 v[52:53], v[42:43], v[52:53]
	v_pk_add_f32 v[58:59], v[40:41], v[58:59]
	v_cvt_pk_bf16_f32 v40, v56, v57
	v_cvt_pk_bf16_f32 v41, v50, v51
	v_mul_f32_e32 v57, v57, v57
	v_cvt_pk_bf16_f32 v42, v58, v59
	v_cvt_pk_bf16_f32 v43, v52, v53
	global_load_dwordx4 v[44:47], v[54:55], off offset:256
	v_mul_f32_e32 v51, v51, v51
	v_mul_f32_e32 v59, v59, v59
	v_mul_f32_e32 v53, v53, v53
	v_fmac_f32_e32 v57, v56, v56
	v_fmac_f32_e32 v51, v50, v50
	v_fmac_f32_e32 v59, v58, v58
	v_fmac_f32_e32 v53, v52, v52
	v_add_f32_e32 v50, v57, v51
	v_add_f32_e32 v51, v59, v53
	v_add_f32_e32 v56, v50, v51
	global_store_dwordx4 v[54:55], v[40:43], off
	s_waitcnt vmcnt(1)
	v_lshlrev_b32_e32 v50, 16, v44
	v_and_b32_e32 v51, 0xffff0000, v44
	v_lshlrev_b32_e32 v44, 16, v45
	v_and_b32_e32 v45, 0xffff0000, v45
	v_lshlrev_b32_e32 v52, 16, v46
	v_and_b32_e32 v53, 0xffff0000, v46
	v_lshlrev_b32_e32 v46, 16, v47
	v_and_b32_e32 v47, 0xffff0000, v47
	v_pk_add_f32 v[38:39], v[38:39], v[44:45]
	v_pk_add_f32 v[36:37], v[36:37], v[50:51]
	v_pk_add_f32 v[44:45], v[34:35], v[46:47]
	v_pk_add_f32 v[46:47], v[32:33], v[52:53]
	v_mul_f32_e32 v32, v37, v37
	v_mul_f32_e32 v33, v39, v39
	v_mul_f32_e32 v34, v47, v47
	v_mul_f32_e32 v35, v45, v45
	v_fmac_f32_e32 v32, v36, v36
	v_fmac_f32_e32 v33, v38, v38
	v_fmac_f32_e32 v34, v46, v46
	v_fmac_f32_e32 v35, v44, v44
	v_add_f32_e32 v32, v32, v33
	v_add_f32_e32 v33, v34, v35
	v_add_f32_e32 v32, v32, v33
	v_add_f32_e32 v32, v56, v32
	v_mov_b32_e32 v33, v32
	s_nop 1
	v_permlane16_swap_b32_e32 v32, v33
	s_nop 1
	v_cvt_pk_bf16_f32 v34, v36, v37
	v_cvt_pk_bf16_f32 v35, v38, v39
	v_cvt_pk_bf16_f32 v36, v46, v47
	v_cvt_pk_bf16_f32 v37, v44, v45
	s_waitcnt lgkmcnt(0)
	v_add_f32_e32 v32, v32, v33
	v_mov_b32_e32 v33, v32
	s_nop 1
	v_permlane32_swap_b32_e32 v32, v33
	s_nop 1
	global_store_dwordx4 v[54:55], v[34:37], off offset:256
	s_and_saveexec_b64 s[52:53], s[2:3]
	s_cbranch_execz .LBB0_1080
	s_waitcnt lgkmcnt(0)
	v_add_f32_e32 v34, v32, v33
	s_lshl_b32 s18, s58, 2
	v_lshlrev_b64 v[32:33], 7, v[48:49]
	s_ashr_i32 s19, s18, 31
	v_lshl_add_u64 v[32:33], s[48:49], 0, v[32:33]
	v_lshl_add_u64 v[32:33], s[18:19], 2, v[32:33]
	s_lshl_b32 s18, s64, 2
	s_mov_b32 s19, s21
	v_lshl_add_u64 v[32:33], v[32:33], 0, s[18:19]
	global_store_dword v[32:33], v34, off
; __device__ __forceinline__ unsigned cvt_pk_bf16(float lo, float hi) { unsigned r; asm volatile("v_cvt_pk_bf16_f32 %0, %1, %2" : "=v"(r) : "v"(lo), "v"(hi)); return r; }
; __device__ __forceinline__ float bf_lo(unsigned u) { return __uint_as_float(u << 16); }
; __device__ __forceinline__ float bf_hi(unsigned u) { return __uint_as_float(u & 0xffff0000u); }
;     __device__ __forceinline__ void operator()(const f32x4 (&acc)[2][2][4][2], const Unit& u, int wr, int wc, int fr, int fq) const {
;     ...
;             for (int m = 0; m < 4; ++m) { const int row = row0 + ai * HALF + m * 16; bf16_t* rowp = XB + (size_t)row * D + col0; float ss = 0.f;
; #pragma unroll
;                 for (int bj = 0; bj < 2; ++bj) { const u32x4 r = *(const u32x4*)(rowp + bj * HALF);
;                     const f32x4 o0 = (f32x4){bf_lo(r.x), bf_hi(r.x), bf_lo(r.y), bf_hi(r.y)} + acc[ai][bj][m][0] * alpha, o1 = (f32x4){bf_lo(r.z), bf_hi(r.z), bf_lo(r.w), bf_hi(r.w)} + acc[ai][bj][m][1] * alpha;
;                     ss += ((o0[0] * o0[0] + o0[1] * o0[1]) + (o0[2] * o0[2] + o0[3] * o0[3])) + ((o1[0] * o1[0] + o1[1] * o1[1]) + (o1[2] * o1[2] + o1[3] * o1[3]));
;                     u32x4 w; w.x = cvt_pk_bf16(o0[0], o0[1]); w.y = cvt_pk_bf16(o0[2], o0[3]); w.z = cvt_pk_bf16(o1[0], o1[1]); w.w = cvt_pk_bf16(o1[2], o1[3]);
;                     *(u32x4*)(rowp + bj * HALF) = w; }
;                 ss += __shfl_xor(ss, 16); ss += __shfl_xor(ss, 32);
;                 if (fq == 0) part[(size_t)row * NPART + u.pn * 4 + wc] = ss; }
.LBB0_1080:
	s_or_b64 exec, exec, s[52:53]
	v_add_u32_e32 v32, 0xa0, v146
	s_waitcnt lgkmcnt(0)
	v_ashrrev_i32_e32 v33, 31, v32
	v_lshlrev_b64 v[34:35], 12, v[32:33]
	v_lshl_add_u64 v[34:35], s[50:51], 0, v[34:35]
	v_lshl_add_u64 v[38:39], v[144:145], 1, v[34:35]
	global_load_dwordx4 v[34:37], v[38:39], off
	s_waitcnt vmcnt(0)
	v_lshlrev_b32_e32 v40, 16, v34
	v_and_b32_e32 v41, 0xffff0000, v34
	v_lshlrev_b32_e32 v34, 16, v35
	v_and_b32_e32 v35, 0xffff0000, v35
	v_lshlrev_b32_e32 v42, 16, v36
	v_and_b32_e32 v43, 0xffff0000, v36
	v_lshlrev_b32_e32 v36, 16, v37
	v_and_b32_e32 v37, 0xffff0000, v37
	v_pk_add_f32 v[34:35], v[30:31], v[34:35]
	v_pk_add_f32 v[40:41], v[28:29], v[40:41]
	v_pk_add_f32 v[36:37], v[26:27], v[36:37]
	v_pk_add_f32 v[42:43], v[24:25], v[42:43]
	v_cvt_pk_bf16_f32 v24, v40, v41
	v_cvt_pk_bf16_f32 v25, v34, v35
	v_mul_f32_e32 v41, v41, v41
	v_cvt_pk_bf16_f32 v26, v42, v43
	v_cvt_pk_bf16_f32 v27, v36, v37
	global_load_dwordx4 v[28:31], v[38:39], off offset:256
	v_mul_f32_e32 v35, v35, v35
	v_mul_f32_e32 v43, v43, v43
	v_mul_f32_e32 v37, v37, v37
	v_fmac_f32_e32 v41, v40, v40
	v_fmac_f32_e32 v35, v34, v34
	v_fmac_f32_e32 v43, v42, v42
	v_fmac_f32_e32 v37, v36, v36
	v_add_f32_e32 v34, v41, v35
	v_add_f32_e32 v35, v43, v37
	v_add_f32_e32 v40, v34, v35
	global_store_dwordx4 v[38:39], v[24:27], off
	s_waitcnt vmcnt(1)
	v_lshlrev_b32_e32 v34, 16, v28
	v_and_b32_e32 v35, 0xffff0000, v28
	v_lshlrev_b32_e32 v28, 16, v29
	v_and_b32_e32 v29, 0xffff0000, v29
	v_lshlrev_b32_e32 v36, 16, v30
	v_and_b32_e32 v37, 0xffff0000, v30
	v_lshlrev_b32_e32 v30, 16, v31
	v_and_b32_e32 v31, 0xffff0000, v31
	v_pk_add_f32 v[22:23], v[22:23], v[28:29]
	v_pk_add_f32 v[20:21], v[20:21], v[34:35]
	v_pk_add_f32 v[28:29], v[18:19], v[30:31]
	v_pk_add_f32 v[30:31], v[16:17], v[36:37]
	v_mul_f32_e32 v16, v21, v21
	v_mul_f32_e32 v17, v23, v23
	v_mul_f32_e32 v18, v31, v31
	v_mul_f32_e32 v19, v29, v29
	v_fmac_f32_e32 v16, v20, v20
	v_fmac_f32_e32 v17, v22, v22
	v_fmac_f32_e32 v18, v30, v30
	v_fmac_f32_e32 v19, v28, v28
	v_add_f32_e32 v16, v16, v17
	v_add_f32_e32 v17, v18, v19
	v_add_f32_e32 v16, v16, v17
	v_add_f32_e32 v16, v40, v16
	v_mov_b32_e32 v17, v16
	s_nop 1
	v_permlane16_swap_b32_e32 v16, v17
	s_nop 1
	v_cvt_pk_bf16_f32 v18, v20, v21
	v_cvt_pk_bf16_f32 v19, v22, v23
	v_cvt_pk_bf16_f32 v20, v30, v31
	v_cvt_pk_bf16_f32 v21, v28, v29
	s_waitcnt lgkmcnt(0)
	v_add_f32_e32 v16, v16, v17
	v_mov_b32_e32 v17, v16
	s_nop 1
	v_permlane32_swap_b32_e32 v16, v17
	s_nop 1
	global_store_dwordx4 v[38:39], v[18:21], off offset:256
	s_and_saveexec_b64 s[52:53], s[2:3]
	s_cbranch_execz .LBB0_1082
	s_waitcnt lgkmcnt(0)
	v_add_f32_e32 v18, v16, v17
	s_lshl_b32 s18, s58, 2
	v_lshlrev_b64 v[16:17], 7, v[32:33]
	s_ashr_i32 s19, s18, 31
	v_lshl_add_u64 v[16:17], s[48:49], 0, v[16:17]
	v_lshl_add_u64 v[16:17], s[18:19], 2, v[16:17]
	s_lshl_b32 s18, s64, 2
	s_mov_b32 s19, s21
	v_lshl_add_u64 v[16:17], v[16:17], 0, s[18:19]
	global_store_dword v[16:17], v18, off
.LBB0_1082:
	s_or_b64 exec, exec, s[52:53]
	v_add_u32_e32 v16, 0xb0, v146
	s_waitcnt lgkmcnt(0)
	v_ashrrev_i32_e32 v17, 31, v16
	v_lshlrev_b64 v[18:19], 12, v[16:17]
	v_lshl_add_u64 v[18:19], s[50:51], 0, v[18:19]
	v_lshl_add_u64 v[22:23], v[144:145], 1, v[18:19]
	global_load_dwordx4 v[18:21], v[22:23], off
	s_waitcnt vmcnt(0)
	v_lshlrev_b32_e32 v24, 16, v18
	v_and_b32_e32 v25, 0xffff0000, v18
	v_lshlrev_b32_e32 v18, 16, v19
	v_and_b32_e32 v19, 0xffff0000, v19
	v_lshlrev_b32_e32 v26, 16, v20
	v_and_b32_e32 v27, 0xffff0000, v20
	v_lshlrev_b32_e32 v20, 16, v21
	v_and_b32_e32 v21, 0xffff0000, v21
	v_pk_add_f32 v[18:19], v[14:15], v[18:19]
	v_pk_add_f32 v[24:25], v[12:13], v[24:25]
	v_pk_add_f32 v[20:21], v[10:11], v[20:21]
	v_pk_add_f32 v[26:27], v[8:9], v[26:27]
	v_cvt_pk_bf16_f32 v8, v24, v25
	v_cvt_pk_bf16_f32 v9, v18, v19
	v_mul_f32_e32 v25, v25, v25
	v_cvt_pk_bf16_f32 v10, v26, v27
	v_cvt_pk_bf16_f32 v11, v20, v21
	global_load_dwordx4 v[12:15], v[22:23], off offset:256
	v_mul_f32_e32 v19, v19, v19
	v_mul_f32_e32 v27, v27, v27
	v_mul_f32_e32 v21, v21, v21
	v_fmac_f32_e32 v25, v24, v24
	v_fmac_f32_e32 v19, v18, v18
	v_fmac_f32_e32 v27, v26, v26
	v_fmac_f32_e32 v21, v20, v20
	v_add_f32_e32 v18, v25, v19
	v_add_f32_e32 v19, v27, v21
	v_add_f32_e32 v24, v18, v19
	global_store_dwordx4 v[22:23], v[8:11], off
	s_waitcnt vmcnt(1)
	v_lshlrev_b32_e32 v18, 16, v12
	v_and_b32_e32 v19, 0xffff0000, v12
	v_lshlrev_b32_e32 v12, 16, v13
	v_and_b32_e32 v13, 0xffff0000, v13
	v_lshlrev_b32_e32 v20, 16, v14
	v_and_b32_e32 v21, 0xffff0000, v14
	v_lshlrev_b32_e32 v14, 16, v15
	v_and_b32_e32 v15, 0xffff0000, v15
	v_pk_add_f32 v[6:7], v[6:7], v[12:13]
	v_pk_add_f32 v[4:5], v[4:5], v[18:19]
	v_pk_add_f32 v[12:13], v[2:3], v[14:15]
	v_pk_add_f32 v[14:15], v[0:1], v[20:21]
	v_mul_f32_e32 v0, v5, v5
	v_mul_f32_e32 v1, v7, v7
	v_mul_f32_e32 v2, v15, v15
	v_mul_f32_e32 v3, v13, v13
	v_fmac_f32_e32 v0, v4, v4
	v_fmac_f32_e32 v1, v6, v6
	v_fmac_f32_e32 v2, v14, v14
	v_fmac_f32_e32 v3, v12, v12
	v_add_f32_e32 v0, v0, v1
	v_add_f32_e32 v1, v2, v3
	v_add_f32_e32 v0, v0, v1
	v_add_f32_e32 v0, v24, v0
	v_mov_b32_e32 v1, v0
	s_nop 1
	v_permlane16_swap_b32_e32 v0, v1
	s_nop 1
	v_cvt_pk_bf16_f32 v2, v4, v5
	v_cvt_pk_bf16_f32 v3, v6, v7
	v_cvt_pk_bf16_f32 v4, v14, v15
	v_cvt_pk_bf16_f32 v5, v12, v13
	s_waitcnt lgkmcnt(0)
	v_add_f32_e32 v0, v0, v1
	v_mov_b32_e32 v1, v0
	s_nop 1
	v_permlane32_swap_b32_e32 v0, v1
	s_nop 1
	global_store_dwordx4 v[22:23], v[2:5], off offset:256
	s_and_saveexec_b64 s[52:53], s[2:3]
	s_cbranch_execz .LBB0_1084
	s_waitcnt lgkmcnt(0)
	v_add_f32_e32 v2, v0, v1
	s_lshl_b32 s18, s58, 2
	v_lshlrev_b64 v[0:1], 7, v[16:17]
	s_ashr_i32 s19, s18, 31
	v_lshl_add_u64 v[0:1], s[48:49], 0, v[0:1]
	v_lshl_add_u64 v[0:1], s[18:19], 2, v[0:1]
	s_lshl_b32 s18, s64, 2
	s_mov_b32 s19, s21
	v_lshl_add_u64 v[0:1], v[0:1], 0, s[18:19]
	global_store_dword v[0:1], v2, off

; __device__ __forceinline__ unsigned cvt_pk_bf16(float lo, float hi) { unsigned r; asm volatile("v_cvt_pk_bf16_f32 %0, %1, %2" : "=v"(r) : "v"(lo), "v"(hi)); return r; }
; __device__ __forceinline__ float bf_lo(unsigned u) { return __uint_as_float(u << 16); }
; __device__ __forceinline__ float bf_hi(unsigned u) { return __uint_as_float(u & 0xffff0000u); }
;     __device__ __forceinline__ void operator()(const f32x4 (&acc)[2][2][4][2], const Unit& u, int wr, int wc, int fr, int fq) const {
;     ...
;             for (int m = 0; m < 4; ++m) { const int row = row0 + ai * HALF + m * 16; bf16_t* rowp = XB + (size_t)row * D + col0; float ss = 0.f;
; #pragma unroll
;                 for (int bj = 0; bj < 2; ++bj) { const u32x4 r = *(const u32x4*)(rowp + bj * HALF);
;                     const f32x4 o0 = (f32x4){bf_lo(r.x), bf_hi(r.x), bf_lo(r.y), bf_hi(r.y)} + acc[ai][bj][m][0] * alpha, o1 = (f32x4){bf_lo(r.z), bf_hi(r.z), bf_lo(r.w), bf_hi(r.w)} + acc[ai][bj][m][1] * alpha;
;                     ss += ((o0[0] * o0[0] + o0[1] * o0[1]) + (o0[2] * o0[2] + o0[3] * o0[3])) + ((o1[0] * o1[0] + o1[1] * o1[1]) + (o1[2] * o1[2] + o1[3] * o1[3]));
;                     u32x4 w; w.x = cvt_pk_bf16(o0[0], o0[1]); w.y = cvt_pk_bf16(o0[2], o0[3]); w.z = cvt_pk_bf16(o1[0], o1[1]); w.w = cvt_pk_bf16(o1[2], o1[3]);
;                     *(u32x4*)(rowp + bj * HALF) = w; }
;                 ss += __shfl_xor(ss, 16); ss += __shfl_xor(ss, 32);
;                 if (fq == 0) part[(size_t)row * NPART + u.pn * 4 + wc] = ss; }
.LBB0_1237:
	v_lshl_add_u32 v146, s11, 8, v148
	v_ashrrev_i32_e32 v147, 31, v146
	v_lshl_or_b32 v144, s53, 8, v150
	v_lshlrev_b64 v[156:157], 12, v[146:147]
	v_ashrrev_i32_e32 v145, 31, v144
	v_lshl_add_u64 v[156:157], s[50:51], 0, v[156:157]
	v_lshl_add_u64 v[160:161], v[144:145], 1, v[156:157]
	global_load_dwordx4 v[156:159], v[160:161], off
	v_xor_b32_e32 v155, 32, v154
	s_waitcnt vmcnt(0)
	v_lshlrev_b32_e32 v162, 16, v156
	v_and_b32_e32 v163, 0xffff0000, v156
	v_lshlrev_b32_e32 v156, 16, v157
	v_and_b32_e32 v157, 0xffff0000, v157
	v_lshlrev_b32_e32 v164, 16, v158
	v_and_b32_e32 v165, 0xffff0000, v158
	v_lshlrev_b32_e32 v158, 16, v159
	v_and_b32_e32 v159, 0xffff0000, v159
	v_pk_fma_f32 v[126:127], v[126:127], 0.5, v[156:157] op_sel_hi:[1,0,1]
	v_pk_fma_f32 v[162:163], v[124:125], 0.5, v[162:163] op_sel_hi:[1,0,1]
	v_pk_fma_f32 v[166:167], v[122:123], 0.5, v[158:159] op_sel_hi:[1,0,1]
	v_pk_fma_f32 v[164:165], v[120:121], 0.5, v[164:165] op_sel_hi:[1,0,1]
	v_cvt_pk_bf16_f32 v122, v162, v163
	v_cvt_pk_bf16_f32 v123, v126, v127
	v_mul_f32_e32 v163, v163, v163
	v_cvt_pk_bf16_f32 v124, v164, v165
	v_cvt_pk_bf16_f32 v125, v166, v167
	global_load_dwordx4 v[156:159], v[160:161], off offset:256
	v_mul_f32_e32 v127, v127, v127
	v_mul_f32_e32 v165, v165, v165
	v_mul_f32_e32 v167, v167, v167
	v_fmac_f32_e32 v163, v162, v162
	v_fmac_f32_e32 v127, v126, v126
	v_fmac_f32_e32 v165, v164, v164
	v_fmac_f32_e32 v167, v166, v166
	v_add_f32_e32 v126, v163, v127
	v_add_f32_e32 v127, v165, v167
	v_add_f32_e32 v164, v126, v127
	v_and_b32_e32 v121, 64, v154
	v_xor_b32_e32 v120, 16, v154
	v_add_u32_e32 v121, 64, v121
	v_cmp_lt_i32_e32 vcc, v120, v121
	global_store_dwordx4 v[160:161], v[122:125], off
	s_waitcnt vmcnt(1)
	v_lshlrev_b32_e32 v126, 16, v156
	v_and_b32_e32 v127, 0xffff0000, v156
	v_lshlrev_b32_e32 v156, 16, v157
	v_and_b32_e32 v157, 0xffff0000, v157
	v_lshlrev_b32_e32 v162, 16, v158
	v_and_b32_e32 v163, 0xffff0000, v158
	v_lshlrev_b32_e32 v158, 16, v159
	v_and_b32_e32 v159, 0xffff0000, v159
	v_pk_fma_f32 v[118:119], v[118:119], 0.5, v[156:157] op_sel_hi:[1,0,1]
	v_pk_fma_f32 v[116:117], v[116:117], 0.5, v[126:127] op_sel_hi:[1,0,1]
	v_pk_fma_f32 v[126:127], v[114:115], 0.5, v[158:159] op_sel_hi:[1,0,1]
	v_pk_fma_f32 v[156:157], v[112:113], 0.5, v[162:163] op_sel_hi:[1,0,1]
	v_mul_f32_e32 v112, v117, v117
	v_mul_f32_e32 v113, v119, v119
	v_mul_f32_e32 v114, v157, v157
	v_mul_f32_e32 v115, v127, v127
	v_fmac_f32_e32 v112, v116, v116
	v_fmac_f32_e32 v113, v118, v118
	v_fmac_f32_e32 v114, v156, v156
	v_fmac_f32_e32 v115, v126, v126
	v_add_f32_e32 v112, v112, v113
	v_add_f32_e32 v113, v114, v115
	v_cndmask_b32_e32 v120, v154, v120, vcc
	v_add_f32_e32 v112, v112, v113
	v_lshlrev_b32_e32 v120, 2, v120
	v_add_f32_e32 v112, v164, v112
	v_mov_b32_e32 v113, v112
	s_nop 1
	v_permlane16_swap_b32_e32 v112, v113
	s_nop 1
	v_cmp_lt_i32_e32 vcc, v155, v121
	v_cvt_pk_bf16_f32 v116, v116, v117
	v_cvt_pk_bf16_f32 v117, v118, v119
	v_cvt_pk_bf16_f32 v118, v156, v157
	s_waitcnt lgkmcnt(0)
	v_add_f32_e32 v112, v112, v113
	v_cvt_pk_bf16_f32 v119, v126, v127
	v_cndmask_b32_e32 v114, v154, v155, vcc
	v_lshlrev_b32_e32 v114, 2, v114
	v_mov_b32_e32 v113, v112
	s_nop 1
	v_permlane32_swap_b32_e32 v112, v113
	s_nop 1
	global_store_dwordx4 v[160:161], v[116:119], off offset:256
	s_and_saveexec_b64 s[38:39], s[2:3]
	s_cbranch_execz .LBB0_1239
	s_waitcnt lgkmcnt(0)
	v_add_f32_e32 v115, v112, v113
	s_lshl_b32 s18, s53, 2
	v_lshlrev_b64 v[112:113], 7, v[146:147]
	s_ashr_i32 s19, s18, 31
	v_lshl_add_u64 v[112:113], s[48:49], 0, v[112:113]
	v_lshl_add_u64 v[112:113], s[18:19], 2, v[112:113]
	s_lshl_b32 s18, s59, 2
	s_mov_b32 s19, s7
	v_lshl_add_u64 v[112:113], v[112:113], 0, s[18:19]
	global_store_dword v[112:113], v115, off
.LBB0_1239:
	s_or_b64 exec, exec, s[38:39]
	v_or_b32_e32 v112, 16, v146
	s_waitcnt lgkmcnt(0)
	v_ashrrev_i32_e32 v113, 31, v112
	v_lshlrev_b64 v[116:117], 12, v[112:113]
	v_lshl_add_u64 v[116:117], s[50:51], 0, v[116:117]
	v_lshl_add_u64 v[122:123], v[144:145], 1, v[116:117]
	global_load_dwordx4 v[116:119], v[122:123], off
	s_waitcnt vmcnt(0)
	v_lshlrev_b32_e32 v124, 16, v116
	v_and_b32_e32 v125, 0xffff0000, v116
	v_lshlrev_b32_e32 v116, 16, v117
	v_and_b32_e32 v117, 0xffff0000, v117
	v_lshlrev_b32_e32 v126, 16, v118
	v_and_b32_e32 v127, 0xffff0000, v118
	v_lshlrev_b32_e32 v118, 16, v119
	v_and_b32_e32 v119, 0xffff0000, v119
	v_pk_fma_f32 v[116:117], v[110:111], 0.5, v[116:117] op_sel_hi:[1,0,1]
	v_pk_fma_f32 v[124:125], v[108:109], 0.5, v[124:125] op_sel_hi:[1,0,1]
	v_pk_fma_f32 v[118:119], v[106:107], 0.5, v[118:119] op_sel_hi:[1,0,1]
	v_pk_fma_f32 v[126:127], v[104:105], 0.5, v[126:127] op_sel_hi:[1,0,1]
	v_cvt_pk_bf16_f32 v104, v124, v125
	v_cvt_pk_bf16_f32 v105, v116, v117
	v_mul_f32_e32 v115, v125, v125
	v_cvt_pk_bf16_f32 v106, v126, v127
	v_cvt_pk_bf16_f32 v107, v118, v119
	global_load_dwordx4 v[108:111], v[122:123], off offset:256
	v_mul_f32_e32 v117, v117, v117
	v_mul_f32_e32 v121, v127, v127
	v_mul_f32_e32 v119, v119, v119
	v_fmac_f32_e32 v115, v124, v124
	v_fmac_f32_e32 v117, v116, v116
	v_fmac_f32_e32 v121, v126, v126
	v_fmac_f32_e32 v119, v118, v118
	v_add_f32_e32 v115, v115, v117
	v_add_f32_e32 v116, v121, v119
	v_add_f32_e32 v115, v115, v116
	global_store_dwordx4 v[122:123], v[104:107], off
	s_waitcnt vmcnt(1)
	v_lshlrev_b32_e32 v116, 16, v108
	v_and_b32_e32 v117, 0xffff0000, v108
	v_lshlrev_b32_e32 v108, 16, v109
	v_and_b32_e32 v109, 0xffff0000, v109
	v_lshlrev_b32_e32 v118, 16, v110
	v_and_b32_e32 v119, 0xffff0000, v110
	v_lshlrev_b32_e32 v110, 16, v111
	v_and_b32_e32 v111, 0xffff0000, v111
	v_pk_fma_f32 v[102:103], v[102:103], 0.5, v[108:109] op_sel_hi:[1,0,1]
	v_pk_fma_f32 v[100:101], v[100:101], 0.5, v[116:117] op_sel_hi:[1,0,1]
	v_pk_fma_f32 v[108:109], v[98:99], 0.5, v[110:111] op_sel_hi:[1,0,1]
	v_pk_fma_f32 v[110:111], v[96:97], 0.5, v[118:119] op_sel_hi:[1,0,1]
	v_mul_f32_e32 v96, v101, v101
	v_mul_f32_e32 v97, v103, v103
	v_mul_f32_e32 v98, v111, v111
	v_mul_f32_e32 v99, v109, v109
	v_fmac_f32_e32 v96, v100, v100
	v_fmac_f32_e32 v97, v102, v102
	v_fmac_f32_e32 v98, v110, v110
	v_fmac_f32_e32 v99, v108, v108
	v_add_f32_e32 v96, v96, v97
	v_add_f32_e32 v97, v98, v99
	v_add_f32_e32 v96, v96, v97
	v_add_f32_e32 v96, v115, v96
	v_mov_b32_e32 v97, v96
	s_nop 1
	v_permlane16_swap_b32_e32 v96, v97
	s_nop 1
	v_cvt_pk_bf16_f32 v98, v100, v101
	v_cvt_pk_bf16_f32 v99, v102, v103
	v_cvt_pk_bf16_f32 v100, v110, v111
	v_cvt_pk_bf16_f32 v101, v108, v109
	s_waitcnt lgkmcnt(0)
	v_add_f32_e32 v96, v96, v97
	v_mov_b32_e32 v97, v96
	s_nop 1
	v_permlane32_swap_b32_e32 v96, v97
	s_nop 1
	global_store_dwordx4 v[122:123], v[98:101], off offset:256
	s_and_saveexec_b64 s[38:39], s[2:3]
	s_cbranch_execz .LBB0_1241
; __device__ __forceinline__ unsigned cvt_pk_bf16(float lo, float hi) { unsigned r; asm volatile("v_cvt_pk_bf16_f32 %0, %1, %2" : "=v"(r) : "v"(lo), "v"(hi)); return r; }
; __device__ __forceinline__ float bf_lo(unsigned u) { return __uint_as_float(u << 16); }
; __device__ __forceinline__ float bf_hi(unsigned u) { return __uint_as_float(u & 0xffff0000u); }
;     __device__ __forceinline__ void operator()(const f32x4 (&acc)[2][2][4][2], const Unit& u, int wr, int wc, int fr, int fq) const {
;     ...
;             for (int m = 0; m < 4; ++m) { const int row = row0 + ai * HALF + m * 16; bf16_t* rowp = XB + (size_t)row * D + col0; float ss = 0.f;
; #pragma unroll
;                 for (int bj = 0; bj < 2; ++bj) { const u32x4 r = *(const u32x4*)(rowp + bj * HALF);
;                     const f32x4 o0 = (f32x4){bf_lo(r.x), bf_hi(r.x), bf_lo(r.y), bf_hi(r.y)} + acc[ai][bj][m][0] * alpha, o1 = (f32x4){bf_lo(r.z), bf_hi(r.z), bf_lo(r.w), bf_hi(r.w)} + acc[ai][bj][m][1] * alpha;
;                     ss += ((o0[0] * o0[0] + o0[1] * o0[1]) + (o0[2] * o0[2] + o0[3] * o0[3])) + ((o1[0] * o1[0] + o1[1] * o1[1]) + (o1[2] * o1[2] + o1[3] * o1[3]));
;                     u32x4 w; w.x = cvt_pk_bf16(o0[0], o0[1]); w.y = cvt_pk_bf16(o0[2], o0[3]); w.z = cvt_pk_bf16(o1[0], o1[1]); w.w = cvt_pk_bf16(o1[2], o1[3]);
;                     *(u32x4*)(rowp + bj * HALF) = w; }
;                 ss += __shfl_xor(ss, 16); ss += __shfl_xor(ss, 32);
;                 if (fq == 0) part[(size_t)row * NPART + u.pn * 4 + wc] = ss; }
	s_waitcnt lgkmcnt(0)
	v_add_f32_e32 v98, v96, v97
	s_lshl_b32 s18, s53, 2
	v_lshlrev_b64 v[96:97], 7, v[112:113]
	s_ashr_i32 s19, s18, 31
	v_lshl_add_u64 v[96:97], s[48:49], 0, v[96:97]
	v_lshl_add_u64 v[96:97], s[18:19], 2, v[96:97]
	s_lshl_b32 s18, s59, 2
	s_mov_b32 s19, s7
	v_lshl_add_u64 v[96:97], v[96:97], 0, s[18:19]
	global_store_dword v[96:97], v98, off
.LBB0_1241:
	s_or_b64 exec, exec, s[38:39]
	v_or_b32_e32 v96, 32, v146
	s_waitcnt lgkmcnt(0)
	v_ashrrev_i32_e32 v97, 31, v96
	v_lshlrev_b64 v[98:99], 12, v[96:97]
	v_lshl_add_u64 v[98:99], s[50:51], 0, v[98:99]
	v_lshl_add_u64 v[102:103], v[144:145], 1, v[98:99]
	global_load_dwordx4 v[98:101], v[102:103], off
	s_waitcnt vmcnt(0)
	v_lshlrev_b32_e32 v104, 16, v98
	v_and_b32_e32 v105, 0xffff0000, v98
	v_lshlrev_b32_e32 v98, 16, v99
	v_and_b32_e32 v99, 0xffff0000, v99
	v_lshlrev_b32_e32 v106, 16, v100
	v_and_b32_e32 v107, 0xffff0000, v100
	v_lshlrev_b32_e32 v100, 16, v101
	v_and_b32_e32 v101, 0xffff0000, v101
	v_pk_fma_f32 v[98:99], v[94:95], 0.5, v[98:99] op_sel_hi:[1,0,1]
	v_pk_fma_f32 v[104:105], v[92:93], 0.5, v[104:105] op_sel_hi:[1,0,1]
	v_pk_fma_f32 v[100:101], v[90:91], 0.5, v[100:101] op_sel_hi:[1,0,1]
	v_pk_fma_f32 v[106:107], v[88:89], 0.5, v[106:107] op_sel_hi:[1,0,1]
	v_cvt_pk_bf16_f32 v88, v104, v105
	v_cvt_pk_bf16_f32 v89, v98, v99
	v_mul_f32_e32 v105, v105, v105
	v_cvt_pk_bf16_f32 v90, v106, v107
	v_cvt_pk_bf16_f32 v91, v100, v101
	global_load_dwordx4 v[92:95], v[102:103], off offset:256
	v_mul_f32_e32 v99, v99, v99
	v_mul_f32_e32 v107, v107, v107
	v_mul_f32_e32 v101, v101, v101
	v_fmac_f32_e32 v105, v104, v104
	v_fmac_f32_e32 v99, v98, v98
	v_fmac_f32_e32 v107, v106, v106
	v_fmac_f32_e32 v101, v100, v100
	v_add_f32_e32 v98, v105, v99
	v_add_f32_e32 v99, v107, v101
	v_add_f32_e32 v104, v98, v99
	global_store_dwordx4 v[102:103], v[88:91], off
	s_waitcnt vmcnt(1)
	v_lshlrev_b32_e32 v98, 16, v92
	v_and_b32_e32 v99, 0xffff0000, v92
	v_lshlrev_b32_e32 v92, 16, v93
	v_and_b32_e32 v93, 0xffff0000, v93
	v_lshlrev_b32_e32 v100, 16, v94
	v_and_b32_e32 v101, 0xffff0000, v94
	v_lshlrev_b32_e32 v94, 16, v95
	v_and_b32_e32 v95, 0xffff0000, v95
	v_pk_fma_f32 v[86:87], v[86:87], 0.5, v[92:93] op_sel_hi:[1,0,1]
	v_pk_fma_f32 v[84:85], v[84:85], 0.5, v[98:99] op_sel_hi:[1,0,1]
	v_pk_fma_f32 v[92:93], v[82:83], 0.5, v[94:95] op_sel_hi:[1,0,1]
	v_pk_fma_f32 v[94:95], v[80:81], 0.5, v[100:101] op_sel_hi:[1,0,1]
	v_mul_f32_e32 v80, v85, v85
	v_mul_f32_e32 v81, v87, v87
	v_mul_f32_e32 v82, v95, v95
	v_mul_f32_e32 v83, v93, v93
	v_fmac_f32_e32 v80, v84, v84
	v_fmac_f32_e32 v81, v86, v86
	v_fmac_f32_e32 v82, v94, v94
	v_fmac_f32_e32 v83, v92, v92
	v_add_f32_e32 v80, v80, v81
	v_add_f32_e32 v81, v82, v83
	v_add_f32_e32 v80, v80, v81
	v_add_f32_e32 v80, v104, v80
	v_mov_b32_e32 v81, v80
	s_nop 1
	v_permlane16_swap_b32_e32 v80, v81
	s_nop 1
	v_cvt_pk_bf16_f32 v82, v84, v85
	v_cvt_pk_bf16_f32 v83, v86, v87
	v_cvt_pk_bf16_f32 v84, v94, v95
	v_cvt_pk_bf16_f32 v85, v92, v93
	s_waitcnt lgkmcnt(0)
	v_add_f32_e32 v80, v80, v81
	v_mov_b32_e32 v81, v80
	s_nop 1
	v_permlane32_swap_b32_e32 v80, v81
	s_nop 1
	global_store_dwordx4 v[102:103], v[82:85], off offset:256
	s_and_saveexec_b64 s[38:39], s[2:3]
	s_cbranch_execz .LBB0_1243
	s_waitcnt lgkmcnt(0)
	v_add_f32_e32 v82, v80, v81
	s_lshl_b32 s18, s53, 2
	v_lshlrev_b64 v[80:81], 7, v[96:97]
	s_ashr_i32 s19, s18, 31
	v_lshl_add_u64 v[80:81], s[48:49], 0, v[80:81]
	v_lshl_add_u64 v[80:81], s[18:19], 2, v[80:81]
	s_lshl_b32 s18, s59, 2
	s_mov_b32 s19, s7
	v_lshl_add_u64 v[80:81], v[80:81], 0, s[18:19]
	global_store_dword v[80:81], v82, off
.LBB0_1243:
	s_or_b64 exec, exec, s[38:39]
	v_or_b32_e32 v80, 48, v146
	s_waitcnt lgkmcnt(0)
	v_ashrrev_i32_e32 v81, 31, v80
	v_lshlrev_b64 v[82:83], 12, v[80:81]
	v_lshl_add_u64 v[82:83], s[50:51], 0, v[82:83]
	v_lshl_add_u64 v[86:87], v[144:145], 1, v[82:83]
	global_load_dwordx4 v[82:85], v[86:87], off
	s_waitcnt vmcnt(0)
	v_lshlrev_b32_e32 v88, 16, v82
	v_and_b32_e32 v89, 0xffff0000, v82
	v_lshlrev_b32_e32 v82, 16, v83
	v_and_b32_e32 v83, 0xffff0000, v83
	v_lshlrev_b32_e32 v90, 16, v84
	v_and_b32_e32 v91, 0xffff0000, v84
	v_lshlrev_b32_e32 v84, 16, v85
	v_and_b32_e32 v85, 0xffff0000, v85
	v_pk_fma_f32 v[82:83], v[78:79], 0.5, v[82:83] op_sel_hi:[1,0,1]
	v_pk_fma_f32 v[88:89], v[76:77], 0.5, v[88:89] op_sel_hi:[1,0,1]
	v_pk_fma_f32 v[84:85], v[74:75], 0.5, v[84:85] op_sel_hi:[1,0,1]
	v_pk_fma_f32 v[90:91], v[72:73], 0.5, v[90:91] op_sel_hi:[1,0,1]
	v_cvt_pk_bf16_f32 v72, v88, v89
	v_cvt_pk_bf16_f32 v73, v82, v83
	v_mul_f32_e32 v89, v89, v89
	v_cvt_pk_bf16_f32 v74, v90, v91
	v_cvt_pk_bf16_f32 v75, v84, v85
	global_load_dwordx4 v[76:79], v[86:87], off offset:256
	v_mul_f32_e32 v83, v83, v83
	v_mul_f32_e32 v91, v91, v91
	v_mul_f32_e32 v85, v85, v85
	v_fmac_f32_e32 v89, v88, v88
	v_fmac_f32_e32 v83, v82, v82
	v_fmac_f32_e32 v91, v90, v90
	v_fmac_f32_e32 v85, v84, v84
	v_add_f32_e32 v82, v89, v83
	v_add_f32_e32 v83, v91, v85
	v_add_f32_e32 v88, v82, v83
	global_store_dwordx4 v[86:87], v[72:75], off
	s_waitcnt vmcnt(1)
	v_lshlrev_b32_e32 v82, 16, v76
	v_and_b32_e32 v83, 0xffff0000, v76
	v_lshlrev_b32_e32 v76, 16, v77
	v_and_b32_e32 v77, 0xffff0000, v77
	v_lshlrev_b32_e32 v84, 16, v78
	v_and_b32_e32 v85, 0xffff0000, v78
	v_lshlrev_b32_e32 v78, 16, v79
	v_and_b32_e32 v79, 0xffff0000, v79
	v_pk_fma_f32 v[70:71], v[70:71], 0.5, v[76:77] op_sel_hi:[1,0,1]
	v_pk_fma_f32 v[68:69], v[68:69], 0.5, v[82:83] op_sel_hi:[1,0,1]
	v_pk_fma_f32 v[76:77], v[66:67], 0.5, v[78:79] op_sel_hi:[1,0,1]
	v_pk_fma_f32 v[78:79], v[64:65], 0.5, v[84:85] op_sel_hi:[1,0,1]
	v_mul_f32_e32 v64, v69, v69
	v_mul_f32_e32 v65, v71, v71
	v_mul_f32_e32 v66, v79, v79
	v_mul_f32_e32 v67, v77, v77
	v_fmac_f32_e32 v64, v68, v68
	v_fmac_f32_e32 v65, v70, v70
	v_fmac_f32_e32 v66, v78, v78
	v_fmac_f32_e32 v67, v76, v76
	v_add_f32_e32 v64, v64, v65
	v_add_f32_e32 v65, v66, v67
	v_add_f32_e32 v64, v64, v65
	v_add_f32_e32 v64, v88, v64
	v_mov_b32_e32 v65, v64
	s_nop 1
	v_permlane16_swap_b32_e32 v64, v65
	s_nop 1
	v_cvt_pk_bf16_f32 v66, v68, v69
	v_cvt_pk_bf16_f32 v67, v70, v71
	v_cvt_pk_bf16_f32 v68, v78, v79
	v_cvt_pk_bf16_f32 v69, v76, v77
	s_waitcnt lgkmcnt(0)
	v_add_f32_e32 v64, v64, v65
	v_mov_b32_e32 v65, v64
	s_nop 1
	v_permlane32_swap_b32_e32 v64, v65
	s_nop 1
	global_store_dwordx4 v[86:87], v[66:69], off offset:256
	s_and_saveexec_b64 s[38:39], s[2:3]
	s_cbranch_execz .LBB0_1245
	s_waitcnt lgkmcnt(0)
	v_add_f32_e32 v66, v64, v65
	s_lshl_b32 s18, s53, 2
	v_lshlrev_b64 v[64:65], 7, v[80:81]
	s_ashr_i32 s19, s18, 31
	v_lshl_add_u64 v[64:65], s[48:49], 0, v[64:65]
	v_lshl_add_u64 v[64:65], s[18:19], 2, v[64:65]
	s_lshl_b32 s18, s59, 2
	s_mov_b32 s19, s7
	v_lshl_add_u64 v[64:65], v[64:65], 0, s[18:19]
	global_store_dword v[64:65], v66, off
; __device__ __forceinline__ unsigned cvt_pk_bf16(float lo, float hi) { unsigned r; asm volatile("v_cvt_pk_bf16_f32 %0, %1, %2" : "=v"(r) : "v"(lo), "v"(hi)); return r; }
; __device__ __forceinline__ float bf_lo(unsigned u) { return __uint_as_float(u << 16); }
; __device__ __forceinline__ float bf_hi(unsigned u) { return __uint_as_float(u & 0xffff0000u); }
;     __device__ __forceinline__ void operator()(const f32x4 (&acc)[2][2][4][2], const Unit& u, int wr, int wc, int fr, int fq) const {
;     ...
;             for (int m = 0; m < 4; ++m) { const int row = row0 + ai * HALF + m * 16; bf16_t* rowp = XB + (size_t)row * D + col0; float ss = 0.f;
; #pragma unroll
;                 for (int bj = 0; bj < 2; ++bj) { const u32x4 r = *(const u32x4*)(rowp + bj * HALF);
;                     const f32x4 o0 = (f32x4){bf_lo(r.x), bf_hi(r.x), bf_lo(r.y), bf_hi(r.y)} + acc[ai][bj][m][0] * alpha, o1 = (f32x4){bf_lo(r.z), bf_hi(r.z), bf_lo(r.w), bf_hi(r.w)} + acc[ai][bj][m][1] * alpha;
;                     ss += ((o0[0] * o0[0] + o0[1] * o0[1]) + (o0[2] * o0[2] + o0[3] * o0[3])) + ((o1[0] * o1[0] + o1[1] * o1[1]) + (o1[2] * o1[2] + o1[3] * o1[3]));
;                     u32x4 w; w.x = cvt_pk_bf16(o0[0], o0[1]); w.y = cvt_pk_bf16(o0[2], o0[3]); w.z = cvt_pk_bf16(o1[0], o1[1]); w.w = cvt_pk_bf16(o1[2], o1[3]);
;                     *(u32x4*)(rowp + bj * HALF) = w; }
;                 ss += __shfl_xor(ss, 16); ss += __shfl_xor(ss, 32);
;                 if (fq == 0) part[(size_t)row * NPART + u.pn * 4 + wc] = ss; }
.LBB0_1245:
	s_or_b64 exec, exec, s[38:39]
	v_add_u32_e32 v64, 0x80, v146
	s_waitcnt lgkmcnt(0)
	v_ashrrev_i32_e32 v65, 31, v64
	v_lshlrev_b64 v[66:67], 12, v[64:65]
	v_lshl_add_u64 v[66:67], s[50:51], 0, v[66:67]
	v_lshl_add_u64 v[70:71], v[144:145], 1, v[66:67]
	global_load_dwordx4 v[66:69], v[70:71], off
	s_waitcnt vmcnt(0)
	v_lshlrev_b32_e32 v72, 16, v66
	v_and_b32_e32 v73, 0xffff0000, v66
	v_lshlrev_b32_e32 v66, 16, v67
	v_and_b32_e32 v67, 0xffff0000, v67
	v_lshlrev_b32_e32 v74, 16, v68
	v_and_b32_e32 v75, 0xffff0000, v68
	v_lshlrev_b32_e32 v68, 16, v69
	v_and_b32_e32 v69, 0xffff0000, v69
	v_pk_fma_f32 v[66:67], v[62:63], 0.5, v[66:67] op_sel_hi:[1,0,1]
	v_pk_fma_f32 v[72:73], v[60:61], 0.5, v[72:73] op_sel_hi:[1,0,1]
	v_pk_fma_f32 v[68:69], v[58:59], 0.5, v[68:69] op_sel_hi:[1,0,1]
	v_pk_fma_f32 v[74:75], v[56:57], 0.5, v[74:75] op_sel_hi:[1,0,1]
	v_cvt_pk_bf16_f32 v56, v72, v73
	v_cvt_pk_bf16_f32 v57, v66, v67
	v_mul_f32_e32 v73, v73, v73
	v_cvt_pk_bf16_f32 v58, v74, v75
	v_cvt_pk_bf16_f32 v59, v68, v69
	global_load_dwordx4 v[60:63], v[70:71], off offset:256
	v_mul_f32_e32 v67, v67, v67
	v_mul_f32_e32 v75, v75, v75
	v_mul_f32_e32 v69, v69, v69
	v_fmac_f32_e32 v73, v72, v72
	v_fmac_f32_e32 v67, v66, v66
	v_fmac_f32_e32 v75, v74, v74
	v_fmac_f32_e32 v69, v68, v68
	v_add_f32_e32 v66, v73, v67
	v_add_f32_e32 v67, v75, v69
	v_add_f32_e32 v72, v66, v67
	global_store_dwordx4 v[70:71], v[56:59], off
	s_waitcnt vmcnt(1)
	v_lshlrev_b32_e32 v66, 16, v60
	v_and_b32_e32 v67, 0xffff0000, v60
	v_lshlrev_b32_e32 v60, 16, v61
	v_and_b32_e32 v61, 0xffff0000, v61
	v_lshlrev_b32_e32 v68, 16, v62
	v_and_b32_e32 v69, 0xffff0000, v62
	v_lshlrev_b32_e32 v62, 16, v63
	v_and_b32_e32 v63, 0xffff0000, v63
	v_pk_fma_f32 v[54:55], v[54:55], 0.5, v[60:61] op_sel_hi:[1,0,1]
	v_pk_fma_f32 v[52:53], v[52:53], 0.5, v[66:67] op_sel_hi:[1,0,1]
	v_pk_fma_f32 v[60:61], v[50:51], 0.5, v[62:63] op_sel_hi:[1,0,1]
	v_pk_fma_f32 v[62:63], v[48:49], 0.5, v[68:69] op_sel_hi:[1,0,1]
	v_mul_f32_e32 v48, v53, v53
	v_mul_f32_e32 v49, v55, v55
	v_mul_f32_e32 v50, v63, v63
	v_mul_f32_e32 v51, v61, v61
	v_fmac_f32_e32 v48, v52, v52
	v_fmac_f32_e32 v49, v54, v54
	v_fmac_f32_e32 v50, v62, v62
	v_fmac_f32_e32 v51, v60, v60
	v_add_f32_e32 v48, v48, v49
	v_add_f32_e32 v49, v50, v51
	v_add_f32_e32 v48, v48, v49
	v_add_f32_e32 v48, v72, v48
	v_mov_b32_e32 v49, v48
	s_nop 1
	v_permlane16_swap_b32_e32 v48, v49
	s_nop 1
	v_cvt_pk_bf16_f32 v50, v52, v53
	v_cvt_pk_bf16_f32 v51, v54, v55
	v_cvt_pk_bf16_f32 v52, v62, v63
	v_cvt_pk_bf16_f32 v53, v60, v61
	s_waitcnt lgkmcnt(0)
	v_add_f32_e32 v48, v48, v49
	v_mov_b32_e32 v49, v48
	s_nop 1
	v_permlane32_swap_b32_e32 v48, v49
	s_nop 1
	global_store_dwordx4 v[70:71], v[50:53], off offset:256
	s_and_saveexec_b64 s[38:39], s[2:3]
	s_cbranch_execz .LBB0_1247
	s_waitcnt lgkmcnt(0)
	v_add_f32_e32 v50, v48, v49
	s_lshl_b32 s18, s53, 2
	v_lshlrev_b64 v[48:49], 7, v[64:65]
	s_ashr_i32 s19, s18, 31
	v_lshl_add_u64 v[48:49], s[48:49], 0, v[48:49]
	v_lshl_add_u64 v[48:49], s[18:19], 2, v[48:49]
	s_lshl_b32 s18, s59, 2
	s_mov_b32 s19, s7
	v_lshl_add_u64 v[48:49], v[48:49], 0, s[18:19]
	global_store_dword v[48:49], v50, off
.LBB0_1247:
	s_or_b64 exec, exec, s[38:39]
	v_add_u32_e32 v48, 0x90, v146
	s_waitcnt lgkmcnt(0)
	v_ashrrev_i32_e32 v49, 31, v48
	v_lshlrev_b64 v[50:51], 12, v[48:49]
	v_lshl_add_u64 v[50:51], s[50:51], 0, v[50:51]
	v_lshl_add_u64 v[54:55], v[144:145], 1, v[50:51]
	global_load_dwordx4 v[50:53], v[54:55], off
	s_waitcnt vmcnt(0)
	v_lshlrev_b32_e32 v56, 16, v50
	v_and_b32_e32 v57, 0xffff0000, v50
	v_lshlrev_b32_e32 v50, 16, v51
	v_and_b32_e32 v51, 0xffff0000, v51
	v_lshlrev_b32_e32 v58, 16, v52
	v_and_b32_e32 v59, 0xffff0000, v52
	v_lshlrev_b32_e32 v52, 16, v53
	v_and_b32_e32 v53, 0xffff0000, v53
	v_pk_fma_f32 v[50:51], v[46:47], 0.5, v[50:51] op_sel_hi:[1,0,1]
	v_pk_fma_f32 v[56:57], v[44:45], 0.5, v[56:57] op_sel_hi:[1,0,1]
	v_pk_fma_f32 v[52:53], v[42:43], 0.5, v[52:53] op_sel_hi:[1,0,1]
	v_pk_fma_f32 v[58:59], v[40:41], 0.5, v[58:59] op_sel_hi:[1,0,1]
	v_cvt_pk_bf16_f32 v40, v56, v57
	v_cvt_pk_bf16_f32 v41, v50, v51
	v_mul_f32_e32 v57, v57, v57
	v_cvt_pk_bf16_f32 v42, v58, v59
	v_cvt_pk_bf16_f32 v43, v52, v53
	global_load_dwordx4 v[44:47], v[54:55], off offset:256
	v_mul_f32_e32 v51, v51, v51
	v_mul_f32_e32 v59, v59, v59
	v_mul_f32_e32 v53, v53, v53
	v_fmac_f32_e32 v57, v56, v56
	v_fmac_f32_e32 v51, v50, v50
	v_fmac_f32_e32 v59, v58, v58
	v_fmac_f32_e32 v53, v52, v52
	v_add_f32_e32 v50, v57, v51
	v_add_f32_e32 v51, v59, v53
	v_add_f32_e32 v56, v50, v51
	global_store_dwordx4 v[54:55], v[40:43], off
	s_waitcnt vmcnt(1)
	v_lshlrev_b32_e32 v50, 16, v44
	v_and_b32_e32 v51, 0xffff0000, v44
	v_lshlrev_b32_e32 v44, 16, v45
	v_and_b32_e32 v45, 0xffff0000, v45
	v_lshlrev_b32_e32 v52, 16, v46
	v_and_b32_e32 v53, 0xffff0000, v46
	v_lshlrev_b32_e32 v46, 16, v47
	v_and_b32_e32 v47, 0xffff0000, v47
	v_pk_fma_f32 v[38:39], v[38:39], 0.5, v[44:45] op_sel_hi:[1,0,1]
	v_pk_fma_f32 v[36:37], v[36:37], 0.5, v[50:51] op_sel_hi:[1,0,1]
	v_pk_fma_f32 v[44:45], v[34:35], 0.5, v[46:47] op_sel_hi:[1,0,1]
	v_pk_fma_f32 v[46:47], v[32:33], 0.5, v[52:53] op_sel_hi:[1,0,1]
	v_mul_f32_e32 v32, v37, v37
	v_mul_f32_e32 v33, v39, v39
	v_mul_f32_e32 v34, v47, v47
	v_mul_f32_e32 v35, v45, v45
	v_fmac_f32_e32 v32, v36, v36
	v_fmac_f32_e32 v33, v38, v38
	v_fmac_f32_e32 v34, v46, v46
	v_fmac_f32_e32 v35, v44, v44
	v_add_f32_e32 v32, v32, v33
	v_add_f32_e32 v33, v34, v35
	v_add_f32_e32 v32, v32, v33
	v_add_f32_e32 v32, v56, v32
	v_mov_b32_e32 v33, v32
	s_nop 1
	v_permlane16_swap_b32_e32 v32, v33
	s_nop 1
	v_cvt_pk_bf16_f32 v34, v36, v37
	v_cvt_pk_bf16_f32 v35, v38, v39
	v_cvt_pk_bf16_f32 v36, v46, v47
	v_cvt_pk_bf16_f32 v37, v44, v45
	s_waitcnt lgkmcnt(0)
	v_add_f32_e32 v32, v32, v33
	v_mov_b32_e32 v33, v32
	s_nop 1
	v_permlane32_swap_b32_e32 v32, v33
	s_nop 1
	global_store_dwordx4 v[54:55], v[34:37], off offset:256
	s_and_saveexec_b64 s[38:39], s[2:3]
	s_cbranch_execz .LBB0_1249
	s_waitcnt lgkmcnt(0)
	v_add_f32_e32 v34, v32, v33
	s_lshl_b32 s18, s53, 2
	v_lshlrev_b64 v[32:33], 7, v[48:49]
	s_ashr_i32 s19, s18, 31
	v_lshl_add_u64 v[32:33], s[48:49], 0, v[32:33]
	v_lshl_add_u64 v[32:33], s[18:19], 2, v[32:33]
	s_lshl_b32 s18, s59, 2
	s_mov_b32 s19, s7
	v_lshl_add_u64 v[32:33], v[32:33], 0, s[18:19]
	global_store_dword v[32:33], v34, off
; __device__ __forceinline__ unsigned cvt_pk_bf16(float lo, float hi) { unsigned r; asm volatile("v_cvt_pk_bf16_f32 %0, %1, %2" : "=v"(r) : "v"(lo), "v"(hi)); return r; }
; __device__ __forceinline__ float bf_lo(unsigned u) { return __uint_as_float(u << 16); }
; __device__ __forceinline__ float bf_hi(unsigned u) { return __uint_as_float(u & 0xffff0000u); }
;     __device__ __forceinline__ void operator()(const f32x4 (&acc)[2][2][4][2], const Unit& u, int wr, int wc, int fr, int fq) const {
;     ...
;             for (int m = 0; m < 4; ++m) { const int row = row0 + ai * HALF + m * 16; bf16_t* rowp = XB + (size_t)row * D + col0; float ss = 0.f;
; #pragma unroll
;                 for (int bj = 0; bj < 2; ++bj) { const u32x4 r = *(const u32x4*)(rowp + bj * HALF);
;                     const f32x4 o0 = (f32x4){bf_lo(r.x), bf_hi(r.x), bf_lo(r.y), bf_hi(r.y)} + acc[ai][bj][m][0] * alpha, o1 = (f32x4){bf_lo(r.z), bf_hi(r.z), bf_lo(r.w), bf_hi(r.w)} + acc[ai][bj][m][1] * alpha;
;                     ss += ((o0[0] * o0[0] + o0[1] * o0[1]) + (o0[2] * o0[2] + o0[3] * o0[3])) + ((o1[0] * o1[0] + o1[1] * o1[1]) + (o1[2] * o1[2] + o1[3] * o1[3]));
;                     u32x4 w; w.x = cvt_pk_bf16(o0[0], o0[1]); w.y = cvt_pk_bf16(o0[2], o0[3]); w.z = cvt_pk_bf16(o1[0], o1[1]); w.w = cvt_pk_bf16(o1[2], o1[3]);
;                     *(u32x4*)(rowp + bj * HALF) = w; }
;                 ss += __shfl_xor(ss, 16); ss += __shfl_xor(ss, 32);
;                 if (fq == 0) part[(size_t)row * NPART + u.pn * 4 + wc] = ss; }
.LBB0_1249:
	s_or_b64 exec, exec, s[38:39]
	v_add_u32_e32 v32, 0xa0, v146
	s_waitcnt lgkmcnt(0)
	v_ashrrev_i32_e32 v33, 31, v32
	v_lshlrev_b64 v[34:35], 12, v[32:33]
	v_lshl_add_u64 v[34:35], s[50:51], 0, v[34:35]
	v_lshl_add_u64 v[38:39], v[144:145], 1, v[34:35]
	global_load_dwordx4 v[34:37], v[38:39], off
	s_waitcnt vmcnt(0)
	v_lshlrev_b32_e32 v40, 16, v34
	v_and_b32_e32 v41, 0xffff0000, v34
	v_lshlrev_b32_e32 v34, 16, v35
	v_and_b32_e32 v35, 0xffff0000, v35
	v_lshlrev_b32_e32 v42, 16, v36
	v_and_b32_e32 v43, 0xffff0000, v36
	v_lshlrev_b32_e32 v36, 16, v37
	v_and_b32_e32 v37, 0xffff0000, v37
	v_pk_fma_f32 v[34:35], v[30:31], 0.5, v[34:35] op_sel_hi:[1,0,1]
	v_pk_fma_f32 v[40:41], v[28:29], 0.5, v[40:41] op_sel_hi:[1,0,1]
	v_pk_fma_f32 v[36:37], v[26:27], 0.5, v[36:37] op_sel_hi:[1,0,1]
	v_pk_fma_f32 v[42:43], v[24:25], 0.5, v[42:43] op_sel_hi:[1,0,1]
	v_cvt_pk_bf16_f32 v24, v40, v41
	v_cvt_pk_bf16_f32 v25, v34, v35
	v_mul_f32_e32 v41, v41, v41
	v_cvt_pk_bf16_f32 v26, v42, v43
	v_cvt_pk_bf16_f32 v27, v36, v37
	global_load_dwordx4 v[28:31], v[38:39], off offset:256
	v_mul_f32_e32 v35, v35, v35
	v_mul_f32_e32 v43, v43, v43
	v_mul_f32_e32 v37, v37, v37
	v_fmac_f32_e32 v41, v40, v40
	v_fmac_f32_e32 v35, v34, v34
	v_fmac_f32_e32 v43, v42, v42
	v_fmac_f32_e32 v37, v36, v36
	v_add_f32_e32 v34, v41, v35
	v_add_f32_e32 v35, v43, v37
	v_add_f32_e32 v40, v34, v35
	global_store_dwordx4 v[38:39], v[24:27], off
	s_waitcnt vmcnt(1)
	v_lshlrev_b32_e32 v34, 16, v28
	v_and_b32_e32 v35, 0xffff0000, v28
	v_lshlrev_b32_e32 v28, 16, v29
	v_and_b32_e32 v29, 0xffff0000, v29
	v_lshlrev_b32_e32 v36, 16, v30
	v_and_b32_e32 v37, 0xffff0000, v30
	v_lshlrev_b32_e32 v30, 16, v31
	v_and_b32_e32 v31, 0xffff0000, v31
	v_pk_fma_f32 v[22:23], v[22:23], 0.5, v[28:29] op_sel_hi:[1,0,1]
	v_pk_fma_f32 v[20:21], v[20:21], 0.5, v[34:35] op_sel_hi:[1,0,1]
	v_pk_fma_f32 v[28:29], v[18:19], 0.5, v[30:31] op_sel_hi:[1,0,1]
	v_pk_fma_f32 v[30:31], v[16:17], 0.5, v[36:37] op_sel_hi:[1,0,1]
	v_mul_f32_e32 v16, v21, v21
	v_mul_f32_e32 v17, v23, v23
	v_mul_f32_e32 v18, v31, v31
	v_mul_f32_e32 v19, v29, v29
	v_fmac_f32_e32 v16, v20, v20
	v_fmac_f32_e32 v17, v22, v22
	v_fmac_f32_e32 v18, v30, v30
	v_fmac_f32_e32 v19, v28, v28
	v_add_f32_e32 v16, v16, v17
	v_add_f32_e32 v17, v18, v19
	v_add_f32_e32 v16, v16, v17
	v_add_f32_e32 v16, v40, v16
	v_mov_b32_e32 v17, v16
	s_nop 1
	v_permlane16_swap_b32_e32 v16, v17
	s_nop 1
	v_cvt_pk_bf16_f32 v18, v20, v21
	v_cvt_pk_bf16_f32 v19, v22, v23
	v_cvt_pk_bf16_f32 v20, v30, v31
	v_cvt_pk_bf16_f32 v21, v28, v29
	s_waitcnt lgkmcnt(0)
	v_add_f32_e32 v16, v16, v17
	v_mov_b32_e32 v17, v16
	s_nop 1
	v_permlane32_swap_b32_e32 v16, v17
	s_nop 1
	global_store_dwordx4 v[38:39], v[18:21], off offset:256
	s_and_saveexec_b64 s[38:39], s[2:3]
	s_cbranch_execz .LBB0_1251
	s_waitcnt lgkmcnt(0)
	v_add_f32_e32 v18, v16, v17
	s_lshl_b32 s18, s53, 2
	v_lshlrev_b64 v[16:17], 7, v[32:33]
	s_ashr_i32 s19, s18, 31
	v_lshl_add_u64 v[16:17], s[48:49], 0, v[16:17]
	v_lshl_add_u64 v[16:17], s[18:19], 2, v[16:17]
	s_lshl_b32 s18, s59, 2
	s_mov_b32 s19, s7
	v_lshl_add_u64 v[16:17], v[16:17], 0, s[18:19]
	global_store_dword v[16:17], v18, off
.LBB0_1251:
	s_or_b64 exec, exec, s[38:39]
	v_add_u32_e32 v16, 0xb0, v146
	s_waitcnt lgkmcnt(0)
	v_ashrrev_i32_e32 v17, 31, v16
	v_lshlrev_b64 v[18:19], 12, v[16:17]
	v_lshl_add_u64 v[18:19], s[50:51], 0, v[18:19]
	v_lshl_add_u64 v[22:23], v[144:145], 1, v[18:19]
	global_load_dwordx4 v[18:21], v[22:23], off
	s_waitcnt vmcnt(0)
	v_lshlrev_b32_e32 v24, 16, v18
	v_and_b32_e32 v25, 0xffff0000, v18
	v_lshlrev_b32_e32 v18, 16, v19
	v_and_b32_e32 v19, 0xffff0000, v19
	v_lshlrev_b32_e32 v26, 16, v20
	v_and_b32_e32 v27, 0xffff0000, v20
	v_lshlrev_b32_e32 v20, 16, v21
	v_and_b32_e32 v21, 0xffff0000, v21
	v_pk_fma_f32 v[18:19], v[14:15], 0.5, v[18:19] op_sel_hi:[1,0,1]
	v_pk_fma_f32 v[24:25], v[12:13], 0.5, v[24:25] op_sel_hi:[1,0,1]
	v_pk_fma_f32 v[20:21], v[10:11], 0.5, v[20:21] op_sel_hi:[1,0,1]
	v_pk_fma_f32 v[26:27], v[8:9], 0.5, v[26:27] op_sel_hi:[1,0,1]
	v_cvt_pk_bf16_f32 v8, v24, v25
	v_cvt_pk_bf16_f32 v9, v18, v19
	v_mul_f32_e32 v25, v25, v25
	v_cvt_pk_bf16_f32 v10, v26, v27
	v_cvt_pk_bf16_f32 v11, v20, v21
	global_load_dwordx4 v[12:15], v[22:23], off offset:256
	v_mul_f32_e32 v19, v19, v19
	v_mul_f32_e32 v27, v27, v27
	v_mul_f32_e32 v21, v21, v21
	v_fmac_f32_e32 v25, v24, v24
	v_fmac_f32_e32 v19, v18, v18
	v_fmac_f32_e32 v27, v26, v26
	v_fmac_f32_e32 v21, v20, v20
	v_add_f32_e32 v18, v25, v19
	v_add_f32_e32 v19, v27, v21
	v_add_f32_e32 v24, v18, v19
	global_store_dwordx4 v[22:23], v[8:11], off
	s_waitcnt vmcnt(1)
	v_lshlrev_b32_e32 v18, 16, v12
	v_and_b32_e32 v19, 0xffff0000, v12
	v_lshlrev_b32_e32 v12, 16, v13
	v_and_b32_e32 v13, 0xffff0000, v13
	v_lshlrev_b32_e32 v20, 16, v14
	v_and_b32_e32 v21, 0xffff0000, v14
	v_lshlrev_b32_e32 v14, 16, v15
	v_and_b32_e32 v15, 0xffff0000, v15
	v_pk_fma_f32 v[6:7], v[6:7], 0.5, v[12:13] op_sel_hi:[1,0,1]
	v_pk_fma_f32 v[4:5], v[4:5], 0.5, v[18:19] op_sel_hi:[1,0,1]
	v_pk_fma_f32 v[12:13], v[2:3], 0.5, v[14:15] op_sel_hi:[1,0,1]
	v_pk_fma_f32 v[14:15], v[0:1], 0.5, v[20:21] op_sel_hi:[1,0,1]
	v_mul_f32_e32 v0, v5, v5
	v_mul_f32_e32 v1, v7, v7
	v_mul_f32_e32 v2, v15, v15
	v_mul_f32_e32 v3, v13, v13
	v_fmac_f32_e32 v0, v4, v4
	v_fmac_f32_e32 v1, v6, v6
	v_fmac_f32_e32 v2, v14, v14
	v_fmac_f32_e32 v3, v12, v12
	v_add_f32_e32 v0, v0, v1
	v_add_f32_e32 v1, v2, v3
	v_add_f32_e32 v0, v0, v1
	v_add_f32_e32 v0, v24, v0
	v_mov_b32_e32 v1, v0
	s_nop 1
	v_permlane16_swap_b32_e32 v0, v1
	s_nop 1
	v_cvt_pk_bf16_f32 v2, v4, v5
	v_cvt_pk_bf16_f32 v3, v6, v7
	v_cvt_pk_bf16_f32 v4, v14, v15
	v_cvt_pk_bf16_f32 v5, v12, v13
	s_waitcnt lgkmcnt(0)
	v_add_f32_e32 v0, v0, v1
	v_mov_b32_e32 v1, v0
	s_nop 1
	v_permlane32_swap_b32_e32 v0, v1
	s_nop 1
	global_store_dwordx4 v[22:23], v[2:5], off offset:256
	s_and_saveexec_b64 s[38:39], s[2:3]
	s_cbranch_execz .LBB0_1253
	s_waitcnt lgkmcnt(0)
	v_add_f32_e32 v2, v0, v1
	s_lshl_b32 s18, s53, 2
	v_lshlrev_b64 v[0:1], 7, v[16:17]
	s_ashr_i32 s19, s18, 31
	v_lshl_add_u64 v[0:1], s[48:49], 0, v[0:1]
	v_lshl_add_u64 v[0:1], s[18:19], 2, v[0:1]
	s_lshl_b32 s18, s59, 2
	s_mov_b32 s19, s7
	v_lshl_add_u64 v[0:1], v[0:1], 0, s[18:19]
	global_store_dword v[0:1], v2, off

; __device__ __forceinline__ float bf_lo(unsigned u) { return __uint_as_float(u << 16); }
; __device__ __forceinline__ float bf_hi(unsigned u) { return __uint_as_float(u & 0xffff0000u); }
;     __device__ __forceinline__ void operator()(f32x4 (&acc)[2][2][4][2], const Unit& u, int wr, int wc, int fr, int fq) const {
;     ...
;             for (int m = 0; m < 4; ++m) { const int row = row0 + ai * HALF + m * 16; const bf16_t* rowp = XB + (size_t)row * D + col0; float ss = 0.f;
; #pragma unroll
;                 for (int bj = 0; bj < 2; ++bj) { const u32x4 r = *(const u32x4*)(rowp + bj * HALF);
;                     const f32x4 o0 = (f32x4){bf_lo(r.x), bf_hi(r.x), bf_lo(r.y), bf_hi(r.y)} + acc[ai][bj][m][0] * alpha, o1 = (f32x4){bf_lo(r.z), bf_hi(r.z), bf_lo(r.w), bf_hi(r.w)} + acc[ai][bj][m][1] * alpha;
;                     ss += ((o0[0] * o0[0] + o0[1] * o0[1]) + (o0[2] * o0[2] + o0[3] * o0[3])) + ((o1[0] * o1[0] + o1[1] * o1[1]) + (o1[2] * o1[2] + o1[3] * o1[3]));
;                     acc[ai][bj][m][0] = o0; acc[ai][bj][m][1] = o1; }
;                 ss += __shfl_xor(ss, 16); ss += __shfl_xor(ss, 32);
;                 if (fq == 0) __hip_atomic_store(part + (size_t)row * NPART + u.pn * 4 + wc, ss, __ATOMIC_RELAXED, __HIP_MEMORY_SCOPE_AGENT); }
.LBB0_1281:
	s_lshl_b32 s39, s76, 8
	v_add_u32_e32 v146, s39, v161
	v_ashrrev_i32_e32 v147, 31, v146
	v_lshl_or_b32 v148, s77, 8, v165
	v_lshlrev_b64 v[150:151], 12, v[146:147]
	v_ashrrev_i32_e32 v149, 31, v148
	v_lshl_add_u64 v[150:151], s[50:51], 0, v[150:151]
	v_lshl_add_u64 v[154:155], v[148:149], 1, v[150:151]
	global_load_dwordx4 v[150:153], v[154:155], off
	s_nop 0
	global_load_dwordx4 v[154:157], v[154:155], off offset:256
	v_and_b32_e32 v158, 64, v189
	v_add_u32_e32 v160, 64, v158
	v_xor_b32_e32 v136, 16, v189
	v_cmp_lt_i32_e32 vcc, v136, v160
	s_lshl_b32 s54, s77, 2
	s_ashr_i32 s55, s54, 31
	v_cndmask_b32_e32 v136, v189, v136, vcc
	v_lshlrev_b32_e32 v136, 2, v136
	s_waitcnt vmcnt(0)
	v_lshlrev_b32_e32 v158, 16, v150
	v_and_b32_e32 v159, 0xffff0000, v150
	v_lshlrev_b32_e32 v150, 16, v151
	v_and_b32_e32 v151, 0xffff0000, v151
	v_lshlrev_b32_e32 v192, 16, v152
	v_and_b32_e32 v193, 0xffff0000, v152
	v_lshlrev_b32_e32 v152, 16, v153
	v_and_b32_e32 v153, 0xffff0000, v153
	v_lshlrev_b32_e32 v194, 16, v154
	v_and_b32_e32 v195, 0xffff0000, v154
	v_lshlrev_b32_e32 v154, 16, v155
	v_and_b32_e32 v155, 0xffff0000, v155
	v_lshlrev_b32_e32 v196, 16, v156
	v_and_b32_e32 v197, 0xffff0000, v156
	v_lshlrev_b32_e32 v156, 16, v157
	v_and_b32_e32 v157, 0xffff0000, v157
	v_pk_fma_f32 v[126:127], v[126:127], 0.5, v[150:151] op_sel_hi:[1,0,1]
	v_pk_fma_f32 v[124:125], v[124:125], 0.5, v[158:159] op_sel_hi:[1,0,1]
	v_pk_fma_f32 v[122:123], v[122:123], 0.5, v[152:153] op_sel_hi:[1,0,1]
	v_pk_fma_f32 v[120:121], v[120:121], 0.5, v[192:193] op_sel_hi:[1,0,1]
	v_pk_fma_f32 v[118:119], v[118:119], 0.5, v[154:155] op_sel_hi:[1,0,1]
	v_pk_fma_f32 v[116:117], v[116:117], 0.5, v[194:195] op_sel_hi:[1,0,1]
	v_pk_fma_f32 v[114:115], v[114:115], 0.5, v[156:157] op_sel_hi:[1,0,1]
	v_pk_fma_f32 v[112:113], v[112:113], 0.5, v[196:197] op_sel_hi:[1,0,1]
	v_mul_f32_e32 v150, v125, v125
	v_mul_f32_e32 v151, v127, v127
	v_mul_f32_e32 v152, v121, v121
	v_mul_f32_e32 v153, v123, v123
	v_mul_f32_e32 v154, v117, v117
	v_mul_f32_e32 v155, v119, v119
	v_mul_f32_e32 v156, v113, v113
	v_mul_f32_e32 v157, v115, v115
	v_fmac_f32_e32 v150, v124, v124
	v_fmac_f32_e32 v151, v126, v126
	v_fmac_f32_e32 v152, v120, v120
	v_fmac_f32_e32 v153, v122, v122
	v_fmac_f32_e32 v154, v116, v116
	v_fmac_f32_e32 v155, v118, v118
	v_fmac_f32_e32 v156, v112, v112
	v_fmac_f32_e32 v157, v114, v114
	v_add_f32_e32 v150, v150, v151
	v_add_f32_e32 v151, v152, v153
	v_add_f32_e32 v152, v154, v155
	v_add_f32_e32 v153, v156, v157
	v_add_f32_e32 v150, v150, v151
	v_add_f32_e32 v151, v152, v153
	v_add_f32_e32 v150, v150, v151
	v_mov_b32_e32 v151, v150
	s_nop 1
	v_permlane16_swap_b32_e32 v150, v151
	s_nop 1
	v_xor_b32_e32 v152, 32, v189
	v_cmp_lt_i32_e32 vcc, v152, v160
	s_waitcnt lgkmcnt(0)
	v_add_f32_e32 v150, v150, v151
	v_cndmask_b32_e32 v152, v189, v152, vcc
	v_lshlrev_b32_e32 v160, 2, v152
	v_mov_b32_e32 v151, v150
	s_nop 1
	v_permlane32_swap_b32_e32 v150, v151
	s_nop 1
	s_and_saveexec_b64 s[56:57], s[2:3]
	s_cbranch_execz .LBB0_1283
	s_waitcnt lgkmcnt(0)
	v_add_f32_e32 v152, v150, v151
	v_lshlrev_b64 v[150:151], 7, v[146:147]
	v_lshl_add_u64 v[150:151], s[48:49], 0, v[150:151]
	v_lshl_add_u64 v[150:151], s[54:55], 2, v[150:151]
	s_lshl_b32 s18, s67, 2
	s_mov_b32 s19, s25
	v_lshl_add_u64 v[150:151], v[150:151], 0, s[18:19]
	global_store_dword v[150:151], v152, off sc1
.LBB0_1283:
	s_or_b64 exec, exec, s[56:57]
	v_or_b32_e32 v150, 16, v146
	s_waitcnt lgkmcnt(0)
	v_ashrrev_i32_e32 v151, 31, v150
	v_lshlrev_b64 v[152:153], 12, v[150:151]
	v_lshl_add_u64 v[152:153], s[50:51], 0, v[152:153]
	v_lshl_add_u64 v[156:157], v[148:149], 1, v[152:153]
	global_load_dwordx4 v[152:155], v[156:157], off
	s_nop 0
	global_load_dwordx4 v[156:159], v[156:157], off offset:256
	s_waitcnt vmcnt(1)
	v_lshlrev_b32_e32 v192, 16, v152
	v_and_b32_e32 v193, 0xffff0000, v152
	v_lshlrev_b32_e32 v152, 16, v153
	v_and_b32_e32 v153, 0xffff0000, v153
	v_lshlrev_b32_e32 v194, 16, v154
	v_and_b32_e32 v195, 0xffff0000, v154
	v_lshlrev_b32_e32 v154, 16, v155
	v_and_b32_e32 v155, 0xffff0000, v155
	s_waitcnt vmcnt(0)
	v_lshlrev_b32_e32 v196, 16, v156
	v_and_b32_e32 v197, 0xffff0000, v156
	v_lshlrev_b32_e32 v156, 16, v157
	v_and_b32_e32 v157, 0xffff0000, v157
	v_lshlrev_b32_e32 v198, 16, v158
	v_and_b32_e32 v199, 0xffff0000, v158
	v_lshlrev_b32_e32 v158, 16, v159
	v_and_b32_e32 v159, 0xffff0000, v159
	v_pk_fma_f32 v[110:111], v[110:111], 0.5, v[152:153] op_sel_hi:[1,0,1]
	v_pk_fma_f32 v[108:109], v[108:109], 0.5, v[192:193] op_sel_hi:[1,0,1]
	v_pk_fma_f32 v[106:107], v[106:107], 0.5, v[154:155] op_sel_hi:[1,0,1]
	v_pk_fma_f32 v[104:105], v[104:105], 0.5, v[194:195] op_sel_hi:[1,0,1]
	v_pk_fma_f32 v[102:103], v[102:103], 0.5, v[156:157] op_sel_hi:[1,0,1]
	v_pk_fma_f32 v[100:101], v[100:101], 0.5, v[196:197] op_sel_hi:[1,0,1]
	v_pk_fma_f32 v[98:99], v[98:99], 0.5, v[158:159] op_sel_hi:[1,0,1]
	v_pk_fma_f32 v[96:97], v[96:97], 0.5, v[198:199] op_sel_hi:[1,0,1]
	v_mul_f32_e32 v152, v109, v109
	v_mul_f32_e32 v153, v111, v111
	v_mul_f32_e32 v154, v105, v105
	v_mul_f32_e32 v155, v107, v107
	v_mul_f32_e32 v156, v101, v101
	v_mul_f32_e32 v157, v103, v103
	v_mul_f32_e32 v158, v97, v97
	v_mul_f32_e32 v159, v99, v99
	v_fmac_f32_e32 v152, v108, v108
	v_fmac_f32_e32 v153, v110, v110
	v_fmac_f32_e32 v154, v104, v104
	v_fmac_f32_e32 v155, v106, v106
	v_fmac_f32_e32 v156, v100, v100
	v_fmac_f32_e32 v157, v102, v102
	v_fmac_f32_e32 v158, v96, v96
	v_fmac_f32_e32 v159, v98, v98
	v_add_f32_e32 v152, v152, v153
	v_add_f32_e32 v153, v154, v155
	v_add_f32_e32 v154, v156, v157
	v_add_f32_e32 v155, v158, v159
	v_add_f32_e32 v152, v152, v153
	v_add_f32_e32 v153, v154, v155
	v_add_f32_e32 v152, v152, v153
	v_mov_b32_e32 v153, v152
	s_nop 1
	v_permlane16_swap_b32_e32 v152, v153
	s_nop 1
	s_waitcnt lgkmcnt(0)
	v_add_f32_e32 v152, v152, v153
	v_mov_b32_e32 v153, v152
	s_nop 1
	v_permlane32_swap_b32_e32 v152, v153
	s_nop 1
	s_and_saveexec_b64 s[56:57], s[2:3]
	s_cbranch_execz .LBB0_1285
	v_lshlrev_b64 v[150:151], 7, v[150:151]
	v_lshl_add_u64 v[150:151], s[48:49], 0, v[150:151]
	v_lshl_add_u64 v[150:151], s[54:55], 2, v[150:151]
	s_lshl_b32 s18, s67, 2
	s_mov_b32 s19, s25
	s_waitcnt lgkmcnt(0)
	v_add_f32_e32 v152, v152, v153
	v_lshl_add_u64 v[150:151], v[150:151], 0, s[18:19]
	global_store_dword v[150:151], v152, off sc1
; __device__ __forceinline__ float bf_lo(unsigned u) { return __uint_as_float(u << 16); }
; __device__ __forceinline__ float bf_hi(unsigned u) { return __uint_as_float(u & 0xffff0000u); }
;     __device__ __forceinline__ void operator()(f32x4 (&acc)[2][2][4][2], const Unit& u, int wr, int wc, int fr, int fq) const {
;     ...
;             for (int m = 0; m < 4; ++m) { const int row = row0 + ai * HALF + m * 16; const bf16_t* rowp = XB + (size_t)row * D + col0; float ss = 0.f;
; #pragma unroll
;                 for (int bj = 0; bj < 2; ++bj) { const u32x4 r = *(const u32x4*)(rowp + bj * HALF);
;                     const f32x4 o0 = (f32x4){bf_lo(r.x), bf_hi(r.x), bf_lo(r.y), bf_hi(r.y)} + acc[ai][bj][m][0] * alpha, o1 = (f32x4){bf_lo(r.z), bf_hi(r.z), bf_lo(r.w), bf_hi(r.w)} + acc[ai][bj][m][1] * alpha;
;                     ss += ((o0[0] * o0[0] + o0[1] * o0[1]) + (o0[2] * o0[2] + o0[3] * o0[3])) + ((o1[0] * o1[0] + o1[1] * o1[1]) + (o1[2] * o1[2] + o1[3] * o1[3]));
;                     acc[ai][bj][m][0] = o0; acc[ai][bj][m][1] = o1; }
;                 ss += __shfl_xor(ss, 16); ss += __shfl_xor(ss, 32);
;                 if (fq == 0) __hip_atomic_store(part + (size_t)row * NPART + u.pn * 4 + wc, ss, __ATOMIC_RELAXED, __HIP_MEMORY_SCOPE_AGENT); }
.LBB0_1285:
	s_or_b64 exec, exec, s[56:57]
	v_or_b32_e32 v150, 32, v146
	v_ashrrev_i32_e32 v151, 31, v150
	s_waitcnt lgkmcnt(0)
	v_lshlrev_b64 v[152:153], 12, v[150:151]
	v_lshl_add_u64 v[152:153], s[50:51], 0, v[152:153]
	v_lshl_add_u64 v[156:157], v[148:149], 1, v[152:153]
	global_load_dwordx4 v[152:155], v[156:157], off
	s_nop 0
	global_load_dwordx4 v[156:159], v[156:157], off offset:256
	s_waitcnt vmcnt(1)
	v_lshlrev_b32_e32 v192, 16, v152
	v_and_b32_e32 v193, 0xffff0000, v152
	v_lshlrev_b32_e32 v152, 16, v153
	v_and_b32_e32 v153, 0xffff0000, v153
	v_lshlrev_b32_e32 v194, 16, v154
	v_and_b32_e32 v195, 0xffff0000, v154
	v_lshlrev_b32_e32 v154, 16, v155
	v_and_b32_e32 v155, 0xffff0000, v155
	s_waitcnt vmcnt(0)
	v_lshlrev_b32_e32 v196, 16, v156
	v_and_b32_e32 v197, 0xffff0000, v156
	v_lshlrev_b32_e32 v156, 16, v157
	v_and_b32_e32 v157, 0xffff0000, v157
	v_lshlrev_b32_e32 v198, 16, v158
	v_and_b32_e32 v199, 0xffff0000, v158
	v_lshlrev_b32_e32 v158, 16, v159
	v_and_b32_e32 v159, 0xffff0000, v159
	v_pk_fma_f32 v[94:95], v[94:95], 0.5, v[152:153] op_sel_hi:[1,0,1]
	v_pk_fma_f32 v[92:93], v[92:93], 0.5, v[192:193] op_sel_hi:[1,0,1]
	v_pk_fma_f32 v[90:91], v[90:91], 0.5, v[154:155] op_sel_hi:[1,0,1]
	v_pk_fma_f32 v[88:89], v[88:89], 0.5, v[194:195] op_sel_hi:[1,0,1]
	v_pk_fma_f32 v[86:87], v[86:87], 0.5, v[156:157] op_sel_hi:[1,0,1]
	v_pk_fma_f32 v[84:85], v[84:85], 0.5, v[196:197] op_sel_hi:[1,0,1]
	v_pk_fma_f32 v[82:83], v[82:83], 0.5, v[158:159] op_sel_hi:[1,0,1]
	v_pk_fma_f32 v[80:81], v[80:81], 0.5, v[198:199] op_sel_hi:[1,0,1]
	v_mul_f32_e32 v152, v93, v93
	v_mul_f32_e32 v153, v95, v95
	v_mul_f32_e32 v154, v89, v89
	v_mul_f32_e32 v155, v91, v91
	v_mul_f32_e32 v156, v85, v85
	v_mul_f32_e32 v157, v87, v87
	v_mul_f32_e32 v158, v81, v81
	v_mul_f32_e32 v159, v83, v83
	v_fmac_f32_e32 v152, v92, v92
	v_fmac_f32_e32 v153, v94, v94
	v_fmac_f32_e32 v154, v88, v88
	v_fmac_f32_e32 v155, v90, v90
	v_fmac_f32_e32 v156, v84, v84
	v_fmac_f32_e32 v157, v86, v86
	v_fmac_f32_e32 v158, v80, v80
	v_fmac_f32_e32 v159, v82, v82
	v_add_f32_e32 v152, v152, v153
	v_add_f32_e32 v153, v154, v155
	v_add_f32_e32 v154, v156, v157
	v_add_f32_e32 v155, v158, v159
	v_add_f32_e32 v152, v152, v153
	v_add_f32_e32 v153, v154, v155
	v_add_f32_e32 v152, v152, v153
	v_mov_b32_e32 v153, v152
	s_nop 1
	v_permlane16_swap_b32_e32 v152, v153
	s_nop 1
	s_waitcnt lgkmcnt(0)
	v_add_f32_e32 v152, v152, v153
	v_mov_b32_e32 v153, v152
	s_nop 1
	v_permlane32_swap_b32_e32 v152, v153
	s_nop 1
	s_and_saveexec_b64 s[56:57], s[2:3]
	s_cbranch_execz .LBB0_1287
	v_lshlrev_b64 v[150:151], 7, v[150:151]
	v_lshl_add_u64 v[150:151], s[48:49], 0, v[150:151]
	v_lshl_add_u64 v[150:151], s[54:55], 2, v[150:151]
	s_lshl_b32 s18, s67, 2
	s_mov_b32 s19, s25
	s_waitcnt lgkmcnt(0)
	v_add_f32_e32 v152, v152, v153
	v_lshl_add_u64 v[150:151], v[150:151], 0, s[18:19]
	global_store_dword v[150:151], v152, off sc1
.LBB0_1287:
	s_or_b64 exec, exec, s[56:57]
	v_or_b32_e32 v150, 48, v146
	v_ashrrev_i32_e32 v151, 31, v150
	s_waitcnt lgkmcnt(0)
	v_lshlrev_b64 v[152:153], 12, v[150:151]
	v_lshl_add_u64 v[152:153], s[50:51], 0, v[152:153]
	v_lshl_add_u64 v[156:157], v[148:149], 1, v[152:153]
	global_load_dwordx4 v[152:155], v[156:157], off
	s_nop 0
	global_load_dwordx4 v[156:159], v[156:157], off offset:256
	s_waitcnt vmcnt(1)
	v_lshlrev_b32_e32 v192, 16, v152
	v_and_b32_e32 v193, 0xffff0000, v152
	v_lshlrev_b32_e32 v152, 16, v153
	v_and_b32_e32 v153, 0xffff0000, v153
	v_lshlrev_b32_e32 v194, 16, v154
	v_and_b32_e32 v195, 0xffff0000, v154
	v_lshlrev_b32_e32 v154, 16, v155
	v_and_b32_e32 v155, 0xffff0000, v155
	s_waitcnt vmcnt(0)
	v_lshlrev_b32_e32 v196, 16, v156
	v_and_b32_e32 v197, 0xffff0000, v156
	v_lshlrev_b32_e32 v156, 16, v157
	v_and_b32_e32 v157, 0xffff0000, v157
	v_lshlrev_b32_e32 v198, 16, v158
	v_and_b32_e32 v199, 0xffff0000, v158
	v_lshlrev_b32_e32 v158, 16, v159
	v_and_b32_e32 v159, 0xffff0000, v159
	v_pk_fma_f32 v[78:79], v[78:79], 0.5, v[152:153] op_sel_hi:[1,0,1]
	v_pk_fma_f32 v[76:77], v[76:77], 0.5, v[192:193] op_sel_hi:[1,0,1]
	v_pk_fma_f32 v[74:75], v[74:75], 0.5, v[154:155] op_sel_hi:[1,0,1]
	v_pk_fma_f32 v[72:73], v[72:73], 0.5, v[194:195] op_sel_hi:[1,0,1]
	v_pk_fma_f32 v[70:71], v[70:71], 0.5, v[156:157] op_sel_hi:[1,0,1]
	v_pk_fma_f32 v[68:69], v[68:69], 0.5, v[196:197] op_sel_hi:[1,0,1]
	v_pk_fma_f32 v[66:67], v[66:67], 0.5, v[158:159] op_sel_hi:[1,0,1]
	v_pk_fma_f32 v[64:65], v[64:65], 0.5, v[198:199] op_sel_hi:[1,0,1]
	v_mul_f32_e32 v152, v77, v77
	v_mul_f32_e32 v153, v79, v79
	v_mul_f32_e32 v154, v73, v73
	v_mul_f32_e32 v155, v75, v75
	v_mul_f32_e32 v156, v69, v69
	v_mul_f32_e32 v157, v71, v71
	v_mul_f32_e32 v158, v65, v65
	v_mul_f32_e32 v159, v67, v67
	v_fmac_f32_e32 v152, v76, v76
	v_fmac_f32_e32 v153, v78, v78
	v_fmac_f32_e32 v154, v72, v72
	v_fmac_f32_e32 v155, v74, v74
	v_fmac_f32_e32 v156, v68, v68
	v_fmac_f32_e32 v157, v70, v70
	v_fmac_f32_e32 v158, v64, v64
	v_fmac_f32_e32 v159, v66, v66
	v_add_f32_e32 v152, v152, v153
	v_add_f32_e32 v153, v154, v155
	v_add_f32_e32 v154, v156, v157
	v_add_f32_e32 v155, v158, v159
	v_add_f32_e32 v152, v152, v153
	v_add_f32_e32 v153, v154, v155
	v_add_f32_e32 v152, v152, v153
	v_mov_b32_e32 v153, v152
	s_nop 1
	v_permlane16_swap_b32_e32 v152, v153
	s_nop 1
	s_waitcnt lgkmcnt(0)
	v_add_f32_e32 v152, v152, v153
	v_mov_b32_e32 v153, v152
	s_nop 1
	v_permlane32_swap_b32_e32 v152, v153
	s_nop 1
	s_and_saveexec_b64 s[56:57], s[2:3]
	s_cbranch_execz .LBB0_1289
	v_lshlrev_b64 v[150:151], 7, v[150:151]
	v_lshl_add_u64 v[150:151], s[48:49], 0, v[150:151]
	v_lshl_add_u64 v[150:151], s[54:55], 2, v[150:151]
	s_lshl_b32 s18, s67, 2
	s_mov_b32 s19, s25
	s_waitcnt lgkmcnt(0)
	v_add_f32_e32 v152, v152, v153
	v_lshl_add_u64 v[150:151], v[150:151], 0, s[18:19]
	global_store_dword v[150:151], v152, off sc1
; __device__ __forceinline__ float bf_lo(unsigned u) { return __uint_as_float(u << 16); }
; __device__ __forceinline__ float bf_hi(unsigned u) { return __uint_as_float(u & 0xffff0000u); }
;     __device__ __forceinline__ void operator()(f32x4 (&acc)[2][2][4][2], const Unit& u, int wr, int wc, int fr, int fq) const {
;     ...
;             for (int m = 0; m < 4; ++m) { const int row = row0 + ai * HALF + m * 16; const bf16_t* rowp = XB + (size_t)row * D + col0; float ss = 0.f;
; #pragma unroll
;                 for (int bj = 0; bj < 2; ++bj) { const u32x4 r = *(const u32x4*)(rowp + bj * HALF);
;                     const f32x4 o0 = (f32x4){bf_lo(r.x), bf_hi(r.x), bf_lo(r.y), bf_hi(r.y)} + acc[ai][bj][m][0] * alpha, o1 = (f32x4){bf_lo(r.z), bf_hi(r.z), bf_lo(r.w), bf_hi(r.w)} + acc[ai][bj][m][1] * alpha;
;                     ss += ((o0[0] * o0[0] + o0[1] * o0[1]) + (o0[2] * o0[2] + o0[3] * o0[3])) + ((o1[0] * o1[0] + o1[1] * o1[1]) + (o1[2] * o1[2] + o1[3] * o1[3]));
;                     acc[ai][bj][m][0] = o0; acc[ai][bj][m][1] = o1; }
;                 ss += __shfl_xor(ss, 16); ss += __shfl_xor(ss, 32);
;                 if (fq == 0) __hip_atomic_store(part + (size_t)row * NPART + u.pn * 4 + wc, ss, __ATOMIC_RELAXED, __HIP_MEMORY_SCOPE_AGENT); }
.LBB0_1289:
	s_or_b64 exec, exec, s[56:57]
	v_add_u32_e32 v150, 0x80, v146
	v_ashrrev_i32_e32 v151, 31, v150
	s_waitcnt lgkmcnt(0)
	v_lshlrev_b64 v[152:153], 12, v[150:151]
	v_lshl_add_u64 v[152:153], s[50:51], 0, v[152:153]
	v_lshl_add_u64 v[156:157], v[148:149], 1, v[152:153]
	global_load_dwordx4 v[152:155], v[156:157], off
	s_nop 0
	global_load_dwordx4 v[156:159], v[156:157], off offset:256
	s_waitcnt vmcnt(1)
	v_lshlrev_b32_e32 v192, 16, v152
	v_and_b32_e32 v193, 0xffff0000, v152
	v_lshlrev_b32_e32 v152, 16, v153
	v_and_b32_e32 v153, 0xffff0000, v153
	v_lshlrev_b32_e32 v194, 16, v154
	v_and_b32_e32 v195, 0xffff0000, v154
	v_lshlrev_b32_e32 v154, 16, v155
	v_and_b32_e32 v155, 0xffff0000, v155
	s_waitcnt vmcnt(0)
	v_lshlrev_b32_e32 v196, 16, v156
	v_and_b32_e32 v197, 0xffff0000, v156
	v_lshlrev_b32_e32 v156, 16, v157
	v_and_b32_e32 v157, 0xffff0000, v157
	v_lshlrev_b32_e32 v198, 16, v158
	v_and_b32_e32 v199, 0xffff0000, v158
	v_lshlrev_b32_e32 v158, 16, v159
	v_and_b32_e32 v159, 0xffff0000, v159
	v_pk_fma_f32 v[62:63], v[62:63], 0.5, v[152:153] op_sel_hi:[1,0,1]
	v_pk_fma_f32 v[60:61], v[60:61], 0.5, v[192:193] op_sel_hi:[1,0,1]
	v_pk_fma_f32 v[58:59], v[58:59], 0.5, v[154:155] op_sel_hi:[1,0,1]
	v_pk_fma_f32 v[56:57], v[56:57], 0.5, v[194:195] op_sel_hi:[1,0,1]
	v_pk_fma_f32 v[54:55], v[54:55], 0.5, v[156:157] op_sel_hi:[1,0,1]
	v_pk_fma_f32 v[52:53], v[52:53], 0.5, v[196:197] op_sel_hi:[1,0,1]
	v_pk_fma_f32 v[50:51], v[50:51], 0.5, v[158:159] op_sel_hi:[1,0,1]
	v_pk_fma_f32 v[48:49], v[48:49], 0.5, v[198:199] op_sel_hi:[1,0,1]
	v_mul_f32_e32 v152, v61, v61
	v_mul_f32_e32 v153, v63, v63
	v_mul_f32_e32 v154, v57, v57
	v_mul_f32_e32 v155, v59, v59
	v_mul_f32_e32 v156, v53, v53
	v_mul_f32_e32 v157, v55, v55
	v_mul_f32_e32 v158, v49, v49
	v_mul_f32_e32 v159, v51, v51
	v_fmac_f32_e32 v152, v60, v60
	v_fmac_f32_e32 v153, v62, v62
	v_fmac_f32_e32 v154, v56, v56
	v_fmac_f32_e32 v155, v58, v58
	v_fmac_f32_e32 v156, v52, v52
	v_fmac_f32_e32 v157, v54, v54
	v_fmac_f32_e32 v158, v48, v48
	v_fmac_f32_e32 v159, v50, v50
	v_add_f32_e32 v152, v152, v153
	v_add_f32_e32 v153, v154, v155
	v_add_f32_e32 v154, v156, v157
	v_add_f32_e32 v155, v158, v159
	v_add_f32_e32 v152, v152, v153
	v_add_f32_e32 v153, v154, v155
	v_add_f32_e32 v152, v152, v153
	v_mov_b32_e32 v153, v152
	s_nop 1
	v_permlane16_swap_b32_e32 v152, v153
	s_nop 1
	s_waitcnt lgkmcnt(0)
	v_add_f32_e32 v152, v152, v153
	v_mov_b32_e32 v153, v152
	s_nop 1
	v_permlane32_swap_b32_e32 v152, v153
	s_nop 1
	s_and_saveexec_b64 s[56:57], s[2:3]
	s_cbranch_execz .LBB0_1291
	v_lshlrev_b64 v[150:151], 7, v[150:151]
	v_lshl_add_u64 v[150:151], s[48:49], 0, v[150:151]
	v_lshl_add_u64 v[150:151], s[54:55], 2, v[150:151]
	s_lshl_b32 s18, s67, 2
	s_mov_b32 s19, s25
	s_waitcnt lgkmcnt(0)
	v_add_f32_e32 v152, v152, v153
	v_lshl_add_u64 v[150:151], v[150:151], 0, s[18:19]
	global_store_dword v[150:151], v152, off sc1
.LBB0_1291:
	s_or_b64 exec, exec, s[56:57]
	v_add_u32_e32 v150, 0x90, v146
	v_ashrrev_i32_e32 v151, 31, v150
	s_waitcnt lgkmcnt(0)
	v_lshlrev_b64 v[152:153], 12, v[150:151]
	v_lshl_add_u64 v[152:153], s[50:51], 0, v[152:153]
	v_lshl_add_u64 v[156:157], v[148:149], 1, v[152:153]
	global_load_dwordx4 v[152:155], v[156:157], off
	s_nop 0
	global_load_dwordx4 v[156:159], v[156:157], off offset:256
	s_waitcnt vmcnt(1)
	v_lshlrev_b32_e32 v192, 16, v152
	v_and_b32_e32 v193, 0xffff0000, v152
	v_lshlrev_b32_e32 v152, 16, v153
	v_and_b32_e32 v153, 0xffff0000, v153
	v_lshlrev_b32_e32 v194, 16, v154
	v_and_b32_e32 v195, 0xffff0000, v154
	v_lshlrev_b32_e32 v154, 16, v155
	v_and_b32_e32 v155, 0xffff0000, v155
	s_waitcnt vmcnt(0)
	v_lshlrev_b32_e32 v196, 16, v156
	v_and_b32_e32 v197, 0xffff0000, v156
	v_lshlrev_b32_e32 v156, 16, v157
	v_and_b32_e32 v157, 0xffff0000, v157
	v_lshlrev_b32_e32 v198, 16, v158
	v_and_b32_e32 v199, 0xffff0000, v158
	v_lshlrev_b32_e32 v158, 16, v159
	v_and_b32_e32 v159, 0xffff0000, v159
	v_pk_fma_f32 v[46:47], v[46:47], 0.5, v[152:153] op_sel_hi:[1,0,1]
	v_pk_fma_f32 v[44:45], v[44:45], 0.5, v[192:193] op_sel_hi:[1,0,1]
	v_pk_fma_f32 v[42:43], v[42:43], 0.5, v[154:155] op_sel_hi:[1,0,1]
	v_pk_fma_f32 v[40:41], v[40:41], 0.5, v[194:195] op_sel_hi:[1,0,1]
	v_pk_fma_f32 v[38:39], v[38:39], 0.5, v[156:157] op_sel_hi:[1,0,1]
	v_pk_fma_f32 v[36:37], v[36:37], 0.5, v[196:197] op_sel_hi:[1,0,1]
	v_pk_fma_f32 v[34:35], v[34:35], 0.5, v[158:159] op_sel_hi:[1,0,1]
	v_pk_fma_f32 v[32:33], v[32:33], 0.5, v[198:199] op_sel_hi:[1,0,1]
	v_mul_f32_e32 v152, v45, v45
	v_mul_f32_e32 v153, v47, v47
	v_mul_f32_e32 v154, v41, v41
	v_mul_f32_e32 v155, v43, v43
	v_mul_f32_e32 v156, v37, v37
	v_mul_f32_e32 v157, v39, v39
	v_mul_f32_e32 v158, v33, v33
	v_mul_f32_e32 v159, v35, v35
	v_fmac_f32_e32 v152, v44, v44
	v_fmac_f32_e32 v153, v46, v46
	v_fmac_f32_e32 v154, v40, v40
	v_fmac_f32_e32 v155, v42, v42
	v_fmac_f32_e32 v156, v36, v36
	v_fmac_f32_e32 v157, v38, v38
	v_fmac_f32_e32 v158, v32, v32
	v_fmac_f32_e32 v159, v34, v34
	v_add_f32_e32 v152, v152, v153
	v_add_f32_e32 v153, v154, v155
	v_add_f32_e32 v154, v156, v157
	v_add_f32_e32 v155, v158, v159
	v_add_f32_e32 v152, v152, v153
	v_add_f32_e32 v153, v154, v155
	v_add_f32_e32 v152, v152, v153
	v_mov_b32_e32 v153, v152
	s_nop 1
	v_permlane16_swap_b32_e32 v152, v153
	s_nop 1
	s_waitcnt lgkmcnt(0)
	v_add_f32_e32 v152, v152, v153
	v_mov_b32_e32 v153, v152
	s_nop 1
	v_permlane32_swap_b32_e32 v152, v153
	s_nop 1
	s_and_saveexec_b64 s[56:57], s[2:3]
	s_cbranch_execz .LBB0_1293
	v_lshlrev_b64 v[150:151], 7, v[150:151]
	v_lshl_add_u64 v[150:151], s[48:49], 0, v[150:151]
	v_lshl_add_u64 v[150:151], s[54:55], 2, v[150:151]
	s_lshl_b32 s18, s67, 2
	s_mov_b32 s19, s25
	s_waitcnt lgkmcnt(0)
	v_add_f32_e32 v152, v152, v153
	v_lshl_add_u64 v[150:151], v[150:151], 0, s[18:19]
	global_store_dword v[150:151], v152, off sc1
; __device__ __forceinline__ float bf_lo(unsigned u) { return __uint_as_float(u << 16); }
; __device__ __forceinline__ float bf_hi(unsigned u) { return __uint_as_float(u & 0xffff0000u); }
;     __device__ __forceinline__ void operator()(f32x4 (&acc)[2][2][4][2], const Unit& u, int wr, int wc, int fr, int fq) const {
;     ...
;             for (int m = 0; m < 4; ++m) { const int row = row0 + ai * HALF + m * 16; const bf16_t* rowp = XB + (size_t)row * D + col0; float ss = 0.f;
; #pragma unroll
;                 for (int bj = 0; bj < 2; ++bj) { const u32x4 r = *(const u32x4*)(rowp + bj * HALF);
;                     const f32x4 o0 = (f32x4){bf_lo(r.x), bf_hi(r.x), bf_lo(r.y), bf_hi(r.y)} + acc[ai][bj][m][0] * alpha, o1 = (f32x4){bf_lo(r.z), bf_hi(r.z), bf_lo(r.w), bf_hi(r.w)} + acc[ai][bj][m][1] * alpha;
;                     ss += ((o0[0] * o0[0] + o0[1] * o0[1]) + (o0[2] * o0[2] + o0[3] * o0[3])) + ((o1[0] * o1[0] + o1[1] * o1[1]) + (o1[2] * o1[2] + o1[3] * o1[3]));
;                     acc[ai][bj][m][0] = o0; acc[ai][bj][m][1] = o1; }
;                 ss += __shfl_xor(ss, 16); ss += __shfl_xor(ss, 32);
;                 if (fq == 0) __hip_atomic_store(part + (size_t)row * NPART + u.pn * 4 + wc, ss, __ATOMIC_RELAXED, __HIP_MEMORY_SCOPE_AGENT); }
.LBB0_1293:
	s_or_b64 exec, exec, s[56:57]
	v_add_u32_e32 v150, 0xa0, v146
	v_ashrrev_i32_e32 v151, 31, v150
	s_waitcnt lgkmcnt(0)
	v_lshlrev_b64 v[152:153], 12, v[150:151]
	v_lshl_add_u64 v[152:153], s[50:51], 0, v[152:153]
	v_lshl_add_u64 v[156:157], v[148:149], 1, v[152:153]
	global_load_dwordx4 v[152:155], v[156:157], off
	s_nop 0
	global_load_dwordx4 v[156:159], v[156:157], off offset:256
	s_waitcnt vmcnt(1)
	v_lshlrev_b32_e32 v192, 16, v152
	v_and_b32_e32 v193, 0xffff0000, v152
	v_lshlrev_b32_e32 v152, 16, v153
	v_and_b32_e32 v153, 0xffff0000, v153
	v_lshlrev_b32_e32 v194, 16, v154
	v_and_b32_e32 v195, 0xffff0000, v154
	v_lshlrev_b32_e32 v154, 16, v155
	v_and_b32_e32 v155, 0xffff0000, v155
	s_waitcnt vmcnt(0)
	v_lshlrev_b32_e32 v196, 16, v156
	v_and_b32_e32 v197, 0xffff0000, v156
	v_lshlrev_b32_e32 v156, 16, v157
	v_and_b32_e32 v157, 0xffff0000, v157
	v_lshlrev_b32_e32 v198, 16, v158
	v_and_b32_e32 v199, 0xffff0000, v158
	v_lshlrev_b32_e32 v158, 16, v159
	v_and_b32_e32 v159, 0xffff0000, v159
	v_pk_fma_f32 v[30:31], v[30:31], 0.5, v[152:153] op_sel_hi:[1,0,1]
	v_pk_fma_f32 v[28:29], v[28:29], 0.5, v[192:193] op_sel_hi:[1,0,1]
	v_pk_fma_f32 v[26:27], v[26:27], 0.5, v[154:155] op_sel_hi:[1,0,1]
	v_pk_fma_f32 v[24:25], v[24:25], 0.5, v[194:195] op_sel_hi:[1,0,1]
	v_pk_fma_f32 v[22:23], v[22:23], 0.5, v[156:157] op_sel_hi:[1,0,1]
	v_pk_fma_f32 v[20:21], v[20:21], 0.5, v[196:197] op_sel_hi:[1,0,1]
	v_pk_fma_f32 v[18:19], v[18:19], 0.5, v[158:159] op_sel_hi:[1,0,1]
	v_pk_fma_f32 v[16:17], v[16:17], 0.5, v[198:199] op_sel_hi:[1,0,1]
	v_mul_f32_e32 v152, v29, v29
	v_mul_f32_e32 v153, v31, v31
	v_mul_f32_e32 v154, v25, v25
	v_mul_f32_e32 v155, v27, v27
	v_mul_f32_e32 v156, v21, v21
	v_mul_f32_e32 v157, v23, v23
	v_mul_f32_e32 v158, v17, v17
	v_mul_f32_e32 v159, v19, v19
	v_fmac_f32_e32 v152, v28, v28
	v_fmac_f32_e32 v153, v30, v30
	v_fmac_f32_e32 v154, v24, v24
	v_fmac_f32_e32 v155, v26, v26
	v_fmac_f32_e32 v156, v20, v20
	v_fmac_f32_e32 v157, v22, v22
	v_fmac_f32_e32 v158, v16, v16
	v_fmac_f32_e32 v159, v18, v18
	v_add_f32_e32 v152, v152, v153
	v_add_f32_e32 v153, v154, v155
	v_add_f32_e32 v154, v156, v157
	v_add_f32_e32 v155, v158, v159
	v_add_f32_e32 v152, v152, v153
	v_add_f32_e32 v153, v154, v155
	v_add_f32_e32 v152, v152, v153
	v_mov_b32_e32 v153, v152
	s_nop 1
	v_permlane16_swap_b32_e32 v152, v153
	s_nop 1
	s_waitcnt lgkmcnt(0)
	v_add_f32_e32 v152, v152, v153
	v_mov_b32_e32 v153, v152
	s_nop 1
	v_permlane32_swap_b32_e32 v152, v153
	s_nop 1
	s_and_saveexec_b64 s[56:57], s[2:3]
	s_cbranch_execz .LBB0_1295
	v_lshlrev_b64 v[150:151], 7, v[150:151]
	v_lshl_add_u64 v[150:151], s[48:49], 0, v[150:151]
	v_lshl_add_u64 v[150:151], s[54:55], 2, v[150:151]
	s_lshl_b32 s18, s67, 2
	s_mov_b32 s19, s25
	s_waitcnt lgkmcnt(0)
	v_add_f32_e32 v152, v152, v153
	v_lshl_add_u64 v[150:151], v[150:151], 0, s[18:19]
	global_store_dword v[150:151], v152, off sc1
.LBB0_1295:
	s_or_b64 exec, exec, s[56:57]
	v_add_u32_e32 v158, 0xb0, v146
	v_ashrrev_i32_e32 v159, 31, v158
	v_lshlrev_b64 v[150:151], 12, v[158:159]
	v_lshl_add_u64 v[150:151], s[50:51], 0, v[150:151]
	v_lshl_add_u64 v[154:155], v[148:149], 1, v[150:151]
	s_waitcnt lgkmcnt(0)
	global_load_dwordx4 v[150:153], v[154:155], off
	s_nop 0
	global_load_dwordx4 v[154:157], v[154:155], off offset:256
	s_waitcnt vmcnt(1)
	v_lshlrev_b32_e32 v192, 16, v150
	v_and_b32_e32 v193, 0xffff0000, v150
	v_lshlrev_b32_e32 v150, 16, v151
	v_and_b32_e32 v151, 0xffff0000, v151
	v_lshlrev_b32_e32 v194, 16, v152
	v_and_b32_e32 v195, 0xffff0000, v152
	v_lshlrev_b32_e32 v152, 16, v153
	v_and_b32_e32 v153, 0xffff0000, v153
	s_waitcnt vmcnt(0)
	v_lshlrev_b32_e32 v196, 16, v154
	v_and_b32_e32 v197, 0xffff0000, v154
	v_lshlrev_b32_e32 v198, 16, v155
	v_and_b32_e32 v199, 0xffff0000, v155
	v_lshlrev_b32_e32 v200, 16, v156
	v_and_b32_e32 v201, 0xffff0000, v156
	v_lshlrev_b32_e32 v202, 16, v157
	v_and_b32_e32 v203, 0xffff0000, v157
	v_pk_fma_f32 v[154:155], v[14:15], 0.5, v[150:151] op_sel_hi:[1,0,1]
	v_pk_fma_f32 v[156:157], v[12:13], 0.5, v[192:193] op_sel_hi:[1,0,1]
	v_pk_fma_f32 v[150:151], v[10:11], 0.5, v[152:153] op_sel_hi:[1,0,1]
	v_pk_fma_f32 v[152:153], v[8:9], 0.5, v[194:195] op_sel_hi:[1,0,1]
	v_pk_fma_f32 v[8:9], v[6:7], 0.5, v[198:199] op_sel_hi:[1,0,1]
	v_pk_fma_f32 v[10:11], v[4:5], 0.5, v[196:197] op_sel_hi:[1,0,1]
	v_pk_fma_f32 v[12:13], v[2:3], 0.5, v[202:203] op_sel_hi:[1,0,1]
	v_pk_fma_f32 v[14:15], v[0:1], 0.5, v[200:201] op_sel_hi:[1,0,1]
	v_mul_f32_e32 v0, v157, v157
	v_mul_f32_e32 v1, v155, v155
	v_mul_f32_e32 v2, v153, v153
	v_mul_f32_e32 v3, v151, v151
	v_mul_f32_e32 v4, v11, v11
	v_mul_f32_e32 v5, v9, v9
	v_mul_f32_e32 v6, v15, v15
	v_mul_f32_e32 v7, v13, v13
	v_fmac_f32_e32 v0, v156, v156
	v_fmac_f32_e32 v1, v154, v154
	v_fmac_f32_e32 v2, v152, v152
	v_fmac_f32_e32 v3, v150, v150
	v_fmac_f32_e32 v4, v10, v10
	v_fmac_f32_e32 v5, v8, v8
	v_fmac_f32_e32 v6, v14, v14
	v_fmac_f32_e32 v7, v12, v12
	v_add_f32_e32 v0, v0, v1
	v_add_f32_e32 v1, v2, v3
	v_add_f32_e32 v2, v4, v5
	v_add_f32_e32 v3, v6, v7
	v_add_f32_e32 v0, v0, v1
	v_add_f32_e32 v1, v2, v3
	v_add_f32_e32 v0, v0, v1
	v_mov_b32_e32 v1, v0
	s_nop 1
	v_permlane16_swap_b32_e32 v0, v1
	s_nop 1
	s_waitcnt lgkmcnt(0)
	v_add_f32_e32 v0, v0, v1
	v_mov_b32_e32 v1, v0
	s_nop 1
	v_permlane32_swap_b32_e32 v0, v1
	s_nop 1
	s_and_saveexec_b64 s[56:57], s[2:3]
	s_cbranch_execz .LBB0_1297
	s_waitcnt lgkmcnt(0)
	v_add_f32_e32 v2, v0, v1
	v_lshlrev_b64 v[0:1], 7, v[158:159]
	v_lshl_add_u64 v[0:1], s[48:49], 0, v[0:1]
	v_lshl_add_u64 v[0:1], s[54:55], 2, v[0:1]
	s_lshl_b32 s18, s67, 2
	s_mov_b32 s19, s25
	v_lshl_add_u64 v[0:1], v[0:1], 0, s[18:19]
	global_store_dword v[0:1], v2, off sc1

; __device__ __forceinline__ float bf_lo(unsigned u) { return __uint_as_float(u << 16); }
; __device__ __forceinline__ float bf_hi(unsigned u) { return __uint_as_float(u & 0xffff0000u); }
; #define KIN(i) (*(const float* const __attribute__((address_space(4)))*)(kp + kz + 8 * (i)))
; __global__ void __launch_bounds__(NTHR, 2) fwd_megakernel(Args args) {
;     ...
;         for (int m = gw; m < T; m += NGW) {
;             const u32x4* xr = (const u32x4*)(XB + (size_t)m * D) + lane; const float* gr = KIN(I_FINAL_NORM); float* o = args.out + (size_t)m * D;
;             f32x4 v[8]; float s = 0.f;
; #pragma unroll
;             for (int j = 0; j < 4; ++j) { const u32x4 r = xr[64 * j]; v[2 * j] = (f32x4){bf_lo(r.x), bf_hi(r.x), bf_lo(r.y), bf_hi(r.y)}; v[2 * j + 1] = (f32x4){bf_lo(r.z), bf_hi(r.z), bf_lo(r.w), bf_hi(r.w)};
;                 s += ((v[2 * j][0] * v[2 * j][0] + v[2 * j][1] * v[2 * j][1]) + (v[2 * j][2] * v[2 * j][2] + v[2 * j][3] * v[2 * j][3])) + ((v[2 * j + 1][0] * v[2 * j + 1][0] + v[2 * j + 1][1] * v[2 * j + 1][1]) + (v[2 * j + 1][2] * v[2 * j + 1][2] + v[2 * j + 1][3] * v[2 * j + 1][3])); }
;             const float rstd = rsqrtf(wave_sum(s) * (1.0f / D) + RMS_EPS);
.LBB0_1372:
	global_load_dwordx4 v[18:21], v[6:7], off offset:-3072
	global_load_dwordx4 v[22:25], v[6:7], off offset:-2048
	global_load_dwordx4 v[26:29], v[6:7], off offset:-1024
	global_load_dwordx4 v[30:33], v[6:7], off
	global_load_dwordx4 v[34:37], v[0:1], off offset:16
	global_load_dwordx4 v[38:41], v[0:1], off
	v_add_co_u32_e32 v42, vcc, s5, v8
	s_add_i32 s2, s2, s4
	s_nop 0
	v_addc_co_u32_e32 v43, vcc, -1, v9, vcc
	v_lshl_add_u64 v[6:7], v[6:7], 0, s[0:1]
	s_cmpk_lt_i32 s2, 0x2000
	s_waitcnt vmcnt(0)
	v_lshlrev_b32_e32 v45, 16, v19
	v_lshlrev_b32_e32 v44, 16, v18
	v_and_b32_e32 v19, 0xffff0000, v19
	v_and_b32_e32 v18, 0xffff0000, v18
	v_lshlrev_b32_e32 v47, 16, v21
	v_lshlrev_b32_e32 v46, 16, v20
	v_and_b32_e32 v21, 0xffff0000, v21
	v_and_b32_e32 v20, 0xffff0000, v20
	v_and_b32_e32 v51, 0xffff0000, v23
	v_and_b32_e32 v50, 0xffff0000, v22
	v_and_b32_e32 v55, 0xffff0000, v25
	v_and_b32_e32 v54, 0xffff0000, v24
	v_lshlrev_b32_e32 v49, 16, v23
	v_lshlrev_b32_e32 v48, 16, v22
	v_lshlrev_b32_e32 v53, 16, v25
	v_lshlrev_b32_e32 v52, 16, v24
	v_lshlrev_b32_e32 v56, 16, v26
	v_and_b32_e32 v57, 0xffff0000, v26
	v_lshlrev_b32_e32 v26, 16, v27
	v_and_b32_e32 v27, 0xffff0000, v27
	v_lshlrev_b32_e32 v58, 16, v28
	v_and_b32_e32 v59, 0xffff0000, v28
	v_lshlrev_b32_e32 v28, 16, v29
	v_and_b32_e32 v29, 0xffff0000, v29
	v_lshlrev_b32_e32 v60, 16, v30
	v_and_b32_e32 v61, 0xffff0000, v30
	v_lshlrev_b32_e32 v30, 16, v31
	v_pk_mul_f32 v[22:23], v[18:19], v[18:19]
	v_pk_mul_f32 v[24:25], v[20:21], v[20:21]
	v_pk_mul_f32 v[64:65], v[50:51], v[50:51]
	v_pk_mul_f32 v[66:67], v[54:55], v[54:55]
	v_and_b32_e32 v31, 0xffff0000, v31
	v_lshlrev_b32_e32 v62, 16, v32
	v_and_b32_e32 v63, 0xffff0000, v32
	v_lshlrev_b32_e32 v32, 16, v33
	v_and_b32_e32 v33, 0xffff0000, v33
	v_mul_f32_e32 v73, v61, v61
	v_mul_f32_e32 v75, v30, v30
	v_mul_f32_e32 v68, v59, v59
	v_mul_f32_e32 v70, v29, v29
	v_mul_f32_e32 v72, v57, v57
	v_mul_f32_e32 v74, v27, v27
	v_mov_b32_e32 v76, v44
	v_mov_b32_e32 v77, v18
	v_mov_b32_e32 v18, v45
	v_mov_b32_e32 v78, v46
	v_mov_b32_e32 v79, v20
	v_mov_b32_e32 v20, v47
	v_pk_fma_f32 v[22:23], v[44:45], v[44:45], v[22:23]
	v_pk_fma_f32 v[24:25], v[46:47], v[46:47], v[24:25]
	v_pk_fma_f32 v[44:45], v[48:49], v[48:49], v[64:65]
	v_pk_fma_f32 v[46:47], v[52:53], v[52:53], v[66:67]
	v_mul_f32_e32 v17, v60, v60
	v_mul_f32_e32 v80, v31, v31
	v_mul_f32_e32 v81, v62, v62
	v_mul_f32_e32 v82, v63, v63
	v_mul_f32_e32 v83, v32, v32
	v_mul_f32_e32 v84, v33, v33
	v_pk_fma_f32 v[64:65], v[58:59], v[58:59], v[68:69] op_sel_hi:[1,1,0]
	v_pk_fma_f32 v[66:67], v[28:29], v[28:29], v[70:71] op_sel_hi:[1,1,0]
	v_pk_fma_f32 v[68:69], v[56:57], v[56:57], v[72:73] op_sel_hi:[1,1,0]
	v_pk_fma_f32 v[70:71], v[26:27], v[26:27], v[74:75] op_sel_hi:[1,1,0]
	v_pk_add_f32 v[24:25], v[24:25], v[24:25] op_sel:[0,1] op_sel_hi:[1,0]
	v_pk_add_f32 v[22:23], v[22:23], v[22:23] op_sel:[0,1] op_sel_hi:[1,0]
	v_pk_add_f32 v[46:47], v[46:47], v[46:47] op_sel:[0,1] op_sel_hi:[1,0]
	v_pk_add_f32 v[44:45], v[44:45], v[44:45] op_sel:[0,1] op_sel_hi:[1,0]
	v_mov_b32_e32 v65, v17
	v_mov_b32_e32 v67, v73
	v_mov_b32_e32 v69, v75
	v_mov_b32_e32 v71, v80
	v_mov_b32_e32 v25, v81
	v_mov_b32_e32 v23, v82
	v_mov_b32_e32 v47, v83
	v_mov_b32_e32 v45, v84
	v_pk_add_f32 v[64:65], v[64:65], v[66:67]
	v_pk_add_f32 v[66:67], v[68:69], v[70:71]
	v_pk_add_f32 v[22:23], v[24:25], v[22:23]
	v_pk_add_f32 v[24:25], v[46:47], v[44:45]
	v_pk_add_f32 v[64:65], v[64:65], v[66:67]
	v_pk_add_f32 v[22:23], v[22:23], v[24:25]
	s_nop 0
	v_pk_add_f32 v[22:23], v[22:23], v[64:65]
	s_nop 0
	v_add_f32_e32 v17, v22, v23
	ds_bpermute_b32 v22, v10, v17
	s_waitcnt lgkmcnt(0)
; __global__ void __launch_bounds__(NTHR, 2) fwd_megakernel(Args args) {
;     ...
;             const float rstd = rsqrtf(wave_sum(s) * (1.0f / D) + RMS_EPS);
; #pragma unroll
;             for (int j = 0; j < 4; ++j) { const int c = 512 * j + 8 * lane; const f32x4 g0 = *(const f32x4*)(gr + c), g1 = *(const f32x4*)(gr + c + 4);
;                 *(f32x4*)(o + c) = v[2 * j] * rstd * g0; *(f32x4*)(o + c + 4) = v[2 * j + 1] * rstd * g1; }
	v_add_f32_e32 v17, v17, v22
	ds_bpermute_b32 v22, v11, v17
	s_waitcnt lgkmcnt(0)
	v_add_f32_e32 v17, v17, v22
	ds_bpermute_b32 v22, v12, v17
	s_waitcnt lgkmcnt(0)
	v_add_f32_e32 v17, v17, v22
	ds_bpermute_b32 v22, v13, v17
	s_waitcnt lgkmcnt(0)
	v_add_f32_e32 v17, v17, v22
	v_mov_b32_e32 v22, v17
	s_nop 1
	v_permlane16_swap_b32_e32 v17, v22
	s_nop 1
	s_waitcnt lgkmcnt(0)
	v_add_f32_e32 v17, v17, v22
	v_mov_b32_e32 v22, v17
	s_nop 1
	v_permlane32_swap_b32_e32 v17, v22
	s_nop 1
	s_waitcnt lgkmcnt(0)
	v_add_f32_e32 v17, v17, v22
	v_fmamk_f32 v17, v17, 0x3a000000, v16
	v_mul_f32_e32 v22, 0x4b800000, v17
	v_cmp_gt_f32_e32 vcc, s3, v17
	s_nop 1
	v_cndmask_b32_e32 v17, v17, v22, vcc
	v_rsq_f32_e32 v17, v17
	s_nop 0
	v_mul_f32_e32 v22, 0x45800000, v17
	v_cndmask_b32_e32 v44, v17, v22, vcc
	v_pk_mul_f32 v[22:23], v[44:45], v[76:77] op_sel_hi:[0,1]
	v_pk_mul_f32 v[18:19], v[44:45], v[18:19] op_sel_hi:[0,1]
	v_pk_mul_f32 v[46:47], v[44:45], v[78:79] op_sel_hi:[0,1]
	v_pk_mul_f32 v[24:25], v[44:45], v[20:21] op_sel_hi:[0,1]
	v_pk_mul_f32 v[20:21], v[40:41], v[18:19]
	v_pk_mul_f32 v[18:19], v[38:39], v[22:23]
	v_pk_mul_f32 v[24:25], v[36:37], v[24:25]
	v_pk_mul_f32 v[22:23], v[34:35], v[46:47]
	global_store_dwordx4 v[42:43], v[18:21], off offset:-2064
	global_store_dwordx4 v[42:43], v[22:25], off offset:-2048
	global_load_dwordx4 v[18:21], v[0:1], off offset:2048
	s_nop 0
	global_load_dwordx4 v[22:25], v[0:1], off offset:2064
	v_mov_b32_e32 v34, v49
	v_mov_b32_e32 v35, v51
	v_mov_b32_e32 v49, v50
	v_mov_b32_e32 v36, v53
	v_mov_b32_e32 v37, v55
	v_mov_b32_e32 v53, v54
	v_pk_mul_f32 v[34:35], v[44:45], v[34:35] op_sel_hi:[0,1]
	v_pk_mul_f32 v[38:39], v[44:45], v[48:49] op_sel_hi:[0,1]
	v_pk_mul_f32 v[36:37], v[44:45], v[36:37] op_sel_hi:[0,1]
	v_pk_mul_f32 v[40:41], v[44:45], v[52:53] op_sel_hi:[0,1]
	v_pk_mul_f32 v[26:27], v[44:45], v[26:27] op_sel_hi:[0,1]
	v_pk_mul_f32 v[28:29], v[44:45], v[28:29] op_sel_hi:[0,1]
	s_waitcnt vmcnt(1)
	v_pk_mul_f32 v[18:19], v[18:19], v[38:39]
	v_pk_mul_f32 v[20:21], v[20:21], v[34:35]
	s_waitcnt vmcnt(0)
	v_pk_mul_f32 v[22:23], v[22:23], v[40:41]
	v_pk_mul_f32 v[24:25], v[24:25], v[36:37]
	global_store_dwordx4 v[42:43], v[18:21], off offset:-16
	global_store_dwordx4 v[8:9], v[22:25], off offset:-4096
	global_load_dwordx4 v[18:21], v[2:3], off
	s_nop 0
	global_load_dwordx4 v[22:25], v[2:3], off offset:16
	v_pk_mul_f32 v[34:35], v[44:45], v[56:57] op_sel_hi:[0,1]
	v_pk_mul_f32 v[36:37], v[44:45], v[58:59] op_sel_hi:[0,1]
	s_waitcnt vmcnt(1)
	v_pk_mul_f32 v[18:19], v[18:19], v[34:35]
	v_pk_mul_f32 v[20:21], v[20:21], v[26:27]
	s_waitcnt vmcnt(0)
	v_pk_mul_f32 v[22:23], v[22:23], v[36:37]
	v_pk_mul_f32 v[24:25], v[24:25], v[28:29]
	global_store_dwordx4 v[8:9], v[18:21], off offset:-2064
	global_store_dwordx4 v[8:9], v[22:25], off offset:-2048
	global_load_dwordx4 v[18:21], v[4:5], off
	s_nop 0
	global_load_dwordx4 v[22:25], v[4:5], off offset:16
	v_pk_mul_f32 v[26:27], v[44:45], v[30:31] op_sel_hi:[0,1]
	v_pk_mul_f32 v[28:29], v[44:45], v[60:61] op_sel_hi:[0,1]
	v_pk_mul_f32 v[30:31], v[44:45], v[32:33] op_sel_hi:[0,1]
	v_pk_mul_f32 v[32:33], v[44:45], v[62:63] op_sel_hi:[0,1]
	s_waitcnt vmcnt(1)
	v_pk_mul_f32 v[18:19], v[18:19], v[28:29]
	v_pk_mul_f32 v[20:21], v[20:21], v[26:27]
	s_waitcnt vmcnt(0)
	v_pk_mul_f32 v[22:23], v[22:23], v[32:33]
	v_pk_mul_f32 v[24:25], v[24:25], v[30:31]
	global_store_dwordx4 v[8:9], v[18:21], off offset:-16
	global_store_dwordx4 v[8:9], v[22:25], off
	v_lshl_add_u64 v[8:9], v[8:9], 0, s[6:7]
	s_cbranch_scc1 .LBB0_1372
